# remove defensive s_nop 0/1 pairs around v_cvt_pk_bf16_f32 (966 removed; kept where trans/DPP/MFMA adjacency)
# speedup vs baseline: 1.0309x; 1.0098x over previous
.LBB0_33:
	v_mov_b32_e32 v130, v208
	v_lshrrev_b32_e32 v248, 1, v208
	v_and_b32_e32 v248, 16, v248
	global_load_dwordx4 v[156:159], v248, s[40:41] offset:32
	global_load_dwordx4 v[160:163], v248, s[40:41] offset:64
	global_load_dwordx4 v[164:167], v248, s[40:41] offset:96
	global_load_dwordx4 v[168:171], v248, s[40:41] offset:128
	global_load_dwordx4 v[172:175], v248, s[40:41] offset:160
	global_load_dwordx4 v[176:179], v248, s[40:41] offset:192
	global_load_dwordx4 v[180:183], v248, s[40:41] offset:224
	global_load_dwordx4 v[184:187], v248, s[40:41] offset:256
	global_load_dwordx4 v[216:219], v248, s[40:41] offset:288
	global_load_dwordx4 v[220:223], v248, s[40:41] offset:320
	global_load_dwordx4 v[224:227], v248, s[40:41] offset:352
	global_load_dwordx4 v[228:231], v248, s[40:41] offset:384
	global_load_dwordx4 v[232:235], v248, s[40:41] offset:416
	global_load_dwordx4 v[236:239], v248, s[40:41] offset:448
	global_load_dwordx4 v[240:243], v248, s[40:41] offset:480
	v_and_b32_e32 v131, 64, v214
	v_and_b32_e32 v128, 63, v130
	v_lshlrev_b32_e32 v128, 2, v128
	global_load_dword v129, v128, s[42:43]
	global_load_dword v132, v128, s[44:45]
	global_load_dword v134, v128, s[46:47]
	s_nop 0
	global_load_dword v128, v128, s[50:51]
	v_add_u32_e32 v136, 64, v131
	v_xor_b32_e32 v131, 32, v214
	v_cmp_lt_i32_e32 vcc, v131, v136
	v_readfirstlane_b32 s27, v130
	s_ashr_i32 s86, s27, 1
	v_cndmask_b32_e32 v131, v214, v131, vcc
	v_lshlrev_b32_e32 v131, 2, v131
	s_andn2_b32 s86, s86, 31
	s_mov_b32 s27, 0x5400000
	s_waitcnt vmcnt(2)
	v_mul_f32_e32 v133, v129, v132
	ds_bpermute_b32 v133, v131, v133
	s_waitcnt vmcnt(0)
	v_mul_f32_e32 v135, v134, v128
	ds_bpermute_b32 v135, v131, v135
	s_waitcnt lgkmcnt(1)
	v_fmac_f32_e32 v133, v129, v132
	v_xor_b32_e32 v129, 16, v214
	v_cmp_lt_i32_e32 vcc, v129, v136
	s_waitcnt lgkmcnt(0)
	v_fmac_f32_e32 v135, v134, v128
	v_cndmask_b32_e32 v129, v214, v129, vcc
	v_lshlrev_b32_e32 v129, 2, v129
	ds_bpermute_b32 v132, v129, v133
	ds_bpermute_b32 v128, v129, v135
	s_waitcnt lgkmcnt(1)
	v_add_f32_e32 v132, v133, v132
	v_xor_b32_e32 v133, 8, v214
	v_cmp_lt_i32_e32 vcc, v133, v136
	s_waitcnt lgkmcnt(0)
	v_add_f32_e32 v128, v135, v128
	v_cndmask_b32_e32 v133, v214, v133, vcc
	v_lshlrev_b32_e32 v133, 2, v133
	ds_bpermute_b32 v137, v133, v132
	ds_bpermute_b32 v129, v133, v128
	s_waitcnt lgkmcnt(1)
	v_add_f32_e32 v132, v132, v137
	v_xor_b32_e32 v137, 4, v214
	v_cmp_lt_i32_e32 vcc, v137, v136
	s_waitcnt lgkmcnt(0)
	v_add_f32_e32 v128, v128, v129
	v_cndmask_b32_e32 v137, v214, v137, vcc
	v_lshlrev_b32_e32 v137, 2, v137
	ds_bpermute_b32 v138, v137, v132
	ds_bpermute_b32 v129, v137, v128
	s_waitcnt lgkmcnt(1)
	v_add_f32_e32 v132, v132, v138
	v_xor_b32_e32 v138, 2, v214
	v_cmp_lt_i32_e32 vcc, v138, v136
	s_waitcnt lgkmcnt(0)
	v_add_f32_e32 v128, v128, v129
	v_cndmask_b32_e32 v138, v214, v138, vcc
	v_lshlrev_b32_e32 v138, 2, v138
	ds_bpermute_b32 v139, v138, v132
	ds_bpermute_b32 v129, v138, v128
	s_waitcnt lgkmcnt(1)
	v_add_f32_e32 v132, v132, v139
	v_xor_b32_e32 v139, 1, v214
	v_cmp_lt_i32_e32 vcc, v139, v136
	s_waitcnt lgkmcnt(0)
	v_add_f32_e32 v128, v128, v129
	v_cndmask_b32_e32 v136, v214, v139, vcc
	v_lshlrev_b32_e32 v136, 2, v136
	ds_bpermute_b32 v139, v136, v132
	ds_bpermute_b32 v129, v136, v128
	s_waitcnt lgkmcnt(1)
	v_add_f32_e32 v132, v132, v139
	s_waitcnt lgkmcnt(0)
	v_add_f32_e32 v128, v128, v129
	v_mul_f32_e32 v129, 0x3fb8aa3b, v132
	v_fma_f32 v133, v132, s23, -v129
	v_rndne_f32_e32 v134, v129
	v_fmac_f32_e32 v133, 0x32a5705f, v132
	v_sub_f32_e32 v129, v129, v134
	v_add_f32_e32 v129, v129, v133
	v_exp_f32_e32 v129, v129
	v_cvt_i32_f32_e32 v133, v134
	v_cmp_ngt_f32_e32 vcc, s17, v132
	v_ldexp_f32 v129, v129, v133
	s_nop 0
	v_cndmask_b32_e32 v129, 0, v129, vcc
	v_cmp_nlt_f32_e32 vcc, s21, v132
	v_mul_f32_e32 v132, 0x3fb8aa3b, v128
	v_fma_f32 v133, v128, s23, -v132
	v_rndne_f32_e32 v134, v132
	v_fmac_f32_e32 v133, 0x32a5705f, v128
	v_sub_f32_e32 v132, v132, v134
	v_add_f32_e32 v132, v132, v133
	v_exp_f32_e32 v132, v132
	v_cvt_i32_f32_e32 v133, v134
	v_cndmask_b32_e32 v129, v213, v129, vcc
	v_cmp_ngt_f32_e32 vcc, s17, v128
	v_ldexp_f32 v132, v132, v133
	s_nop 0
	v_cndmask_b32_e32 v132, 0, v132, vcc
	v_cmp_nlt_f32_e32 vcc, s21, v128
	s_nop 1
	v_cndmask_b32_e32 v128, v213, v132, vcc
	v_sub_f32_e32 v128, v129, v128
	v_add_f32_e32 v132, v194, v128
	ds_bpermute_b32 v128, v131, v150
	ds_bpermute_b32 v129, v131, v151
	s_waitcnt lgkmcnt(0)
	v_pk_add_f32 v[128:129], v[150:151], v[128:129]
	s_nop 0
	v_div_scale_f32 v133, s[56:57], v129, v129, v132
	v_rcp_f32_e32 v134, v133
	s_nop 0
	v_fma_f32 v135, -v133, v134, 1.0
	v_fmac_f32_e32 v134, v135, v134
	v_div_scale_f32 v135, vcc, v132, v129, v132
	v_mul_f32_e32 v136, v135, v134
	v_fma_f32 v137, -v133, v136, v135
	v_fmac_f32_e32 v136, v137, v134
	v_fma_f32 v133, -v133, v136, v135
	v_div_fmas_f32 v133, v133, v134, v136
	v_div_fixup_f32 v129, v133, v129, v132
	v_div_scale_f32 v132, s[56:57], v128, v128, 1.0
	v_rcp_f32_e32 v133, v132
	s_mov_b64 s[56:57], 0x5400400
	v_fma_f32 v134, -v132, v133, 1.0
	v_fmac_f32_e32 v133, v134, v133
	v_div_scale_f32 v134, vcc, 1.0, v128, 1.0
	v_mul_f32_e32 v135, v134, v133
	v_fma_f32 v136, -v132, v135, v134
	v_fmac_f32_e32 v135, v136, v133
	v_fma_f32 v132, -v132, v135, v134
	v_div_fmas_f32 v132, v132, v133, v135
	v_div_fixup_f32 v128, v132, v128, 1.0
	v_mov_b32_e32 v133, v96
	v_mov_b32_e32 v96, v113
	v_pk_mul_f32 v[96:97], v[96:97], v[128:129]
	v_mov_b32_e32 v132, v112
	v_sub_f32_e32 v113, v96, v97
	v_mov_b32_e32 v96, v114
	v_mov_b32_e32 v97, v98
	v_pk_mul_f32 v[96:97], v[96:97], v[128:129]
	v_mov_b32_e32 v98, v115
	v_sub_f32_e32 v114, v96, v97
	v_pk_mul_f32 v[96:97], v[98:99], v[128:129]
	v_pk_mul_f32 v[132:133], v[132:133], v[128:129]
	v_sub_f32_e32 v115, v96, v97
	v_mov_b32_e32 v96, v116
	v_mov_b32_e32 v97, v100
	v_pk_mul_f32 v[96:97], v[96:97], v[128:129]
	v_mov_b32_e32 v100, v117
	v_sub_f32_e32 v98, v96, v97
	v_pk_mul_f32 v[96:97], v[100:101], v[128:129]
	v_mov_b32_e32 v116, v124
	v_sub_f32_e32 v99, v96, v97
	v_mov_b32_e32 v96, v118
	v_mov_b32_e32 v97, v102
	v_pk_mul_f32 v[96:97], v[96:97], v[128:129]
	v_mov_b32_e32 v102, v119
	v_sub_f32_e32 v100, v96, v97
	v_pk_mul_f32 v[96:97], v[102:103], v[128:129]
	v_mov_b32_e32 v117, v108
	v_sub_f32_e32 v101, v96, v97
	v_mov_b32_e32 v97, v104
	v_mov_b32_e32 v104, v121
	v_pk_mul_f32 v[102:103], v[104:105], v[128:129]
	v_mov_b32_e32 v105, v106
	v_mov_b32_e32 v106, v123
	v_pk_mul_f32 v[106:107], v[106:107], v[128:129]
	v_pk_mul_f32 v[116:117], v[116:117], v[128:129]
	v_sub_f32_e32 v107, v106, v107
	v_sub_f32_e32 v106, v116, v117
	v_mov_b32_e32 v108, v125
	v_mov_b32_e32 v116, v126
	v_mov_b32_e32 v117, v110
	v_mov_b32_e32 v110, v127
	v_pk_mul_f32 v[108:109], v[108:109], v[128:129]
	v_pk_mul_f32 v[116:117], v[116:117], v[128:129]
	v_pk_mul_f32 v[110:111], v[110:111], v[128:129]
	v_sub_f32_e32 v108, v108, v109
	v_sub_f32_e32 v109, v116, v117
	v_sub_f32_e32 v116, v110, v111
	v_mov_b32_e32 v110, v80
	v_mov_b32_e32 v111, v64
	v_mov_b32_e32 v64, v81
	v_pk_mul_f32 v[110:111], v[110:111], v[128:129]
	v_pk_mul_f32 v[64:65], v[64:65], v[128:129]
	v_mov_b32_e32 v104, v122
	v_sub_f32_e32 v111, v110, v111
	v_sub_f32_e32 v110, v64, v65
	v_mov_b32_e32 v64, v82
	v_mov_b32_e32 v65, v66
	v_pk_mul_f32 v[104:105], v[104:105], v[128:129]
	v_pk_mul_f32 v[64:65], v[64:65], v[128:129]
	v_mov_b32_e32 v66, v83
	v_sub_f32_e32 v104, v104, v105
	v_sub_f32_e32 v105, v64, v65
	v_pk_mul_f32 v[64:65], v[66:67], v[128:129]
	v_mov_b32_e32 v96, v120
	v_sub_f32_e32 v102, v102, v103
	v_sub_f32_e32 v103, v64, v65
	v_mov_b32_e32 v64, v84
	v_mov_b32_e32 v65, v68
	v_pk_mul_f32 v[96:97], v[96:97], v[128:129]
	v_pk_mul_f32 v[64:65], v[64:65], v[128:129]
	v_mov_b32_e32 v68, v85
	v_sub_f32_e32 v97, v96, v97
	v_sub_f32_e32 v96, v64, v65
	v_pk_mul_f32 v[64:65], v[68:69], v[128:129]
	v_sub_f32_e32 v112, v132, v133
	v_sub_f32_e32 v85, v64, v65
	v_mov_b32_e32 v64, v86
	v_mov_b32_e32 v65, v70
	v_pk_mul_f32 v[64:65], v[64:65], v[128:129]
	v_mov_b32_e32 v70, v87
	v_sub_f32_e32 v84, v64, v65
	v_pk_mul_f32 v[64:65], v[70:71], v[128:129]
	s_nop 0
	v_sub_f32_e32 v83, v64, v65
	v_mov_b32_e32 v64, v88
	v_mov_b32_e32 v65, v72
	v_pk_mul_f32 v[64:65], v[64:65], v[128:129]
	v_mov_b32_e32 v72, v89
	v_sub_f32_e32 v82, v64, v65
	v_pk_mul_f32 v[64:65], v[72:73], v[128:129]
	s_nop 0
	v_sub_f32_e32 v81, v64, v65
	v_mov_b32_e32 v64, v90
	v_mov_b32_e32 v65, v74
	v_pk_mul_f32 v[64:65], v[64:65], v[128:129]
	v_mov_b32_e32 v74, v91
	v_sub_f32_e32 v80, v64, v65
	v_pk_mul_f32 v[64:65], v[74:75], v[128:129]
	s_nop 0
	v_sub_f32_e32 v73, v64, v65
	v_mov_b32_e32 v64, v92
	v_mov_b32_e32 v65, v76
	v_pk_mul_f32 v[64:65], v[64:65], v[128:129]
	v_mov_b32_e32 v76, v93
	v_sub_f32_e32 v72, v64, v65
	v_pk_mul_f32 v[64:65], v[76:77], v[128:129]
	s_nop 0
	v_sub_f32_e32 v71, v64, v65
	v_mov_b32_e32 v64, v94
	v_mov_b32_e32 v65, v78
	v_pk_mul_f32 v[64:65], v[64:65], v[128:129]
	v_mov_b32_e32 v78, v95
	v_sub_f32_e32 v70, v64, v65
	v_pk_mul_f32 v[64:65], v[78:79], v[128:129]
	s_nop 0
	v_sub_f32_e32 v69, v64, v65
	v_mov_b32_e32 v65, v32
	v_mov_b32_e32 v32, v49
	v_pk_mul_f32 v[32:33], v[32:33], v[128:129]
	v_mov_b32_e32 v64, v48
	v_sub_f32_e32 v67, v32, v33
	v_mov_b32_e32 v32, v50
	v_mov_b32_e32 v33, v34
	v_pk_mul_f32 v[32:33], v[32:33], v[128:129]
	v_mov_b32_e32 v34, v51
	v_pk_mul_f32 v[64:65], v[64:65], v[128:129]
	v_sub_f32_e32 v66, v32, v33
	v_pk_mul_f32 v[32:33], v[34:35], v[128:129]
	v_sub_f32_e32 v68, v64, v65
	v_sub_f32_e32 v65, v32, v33
	v_mov_b32_e32 v32, v52
	v_mov_b32_e32 v33, v36
	v_pk_mul_f32 v[32:33], v[32:33], v[128:129]
	v_mov_b32_e32 v36, v53
	v_sub_f32_e32 v64, v32, v33
	v_pk_mul_f32 v[32:33], v[36:37], v[128:129]
	s_nop 0
	v_sub_f32_e32 v53, v32, v33
	v_mov_b32_e32 v32, v54
	v_mov_b32_e32 v33, v38
	v_pk_mul_f32 v[32:33], v[32:33], v[128:129]
	v_mov_b32_e32 v38, v55
	v_sub_f32_e32 v52, v32, v33
	v_pk_mul_f32 v[32:33], v[38:39], v[128:129]
	s_nop 0
	v_sub_f32_e32 v51, v32, v33
	v_mov_b32_e32 v32, v56
	v_mov_b32_e32 v33, v40
	v_pk_mul_f32 v[32:33], v[32:33], v[128:129]
	v_mov_b32_e32 v40, v57
	v_sub_f32_e32 v50, v32, v33
	v_pk_mul_f32 v[32:33], v[40:41], v[128:129]
	s_nop 0
	v_sub_f32_e32 v49, v32, v33
	v_mov_b32_e32 v32, v58
	v_mov_b32_e32 v33, v42
	v_pk_mul_f32 v[32:33], v[32:33], v[128:129]
	v_mov_b32_e32 v42, v59
	v_sub_f32_e32 v48, v32, v33
	v_pk_mul_f32 v[32:33], v[42:43], v[128:129]
	s_nop 0
	v_sub_f32_e32 v41, v32, v33
	v_mov_b32_e32 v32, v60
	v_mov_b32_e32 v33, v44
	v_pk_mul_f32 v[32:33], v[32:33], v[128:129]
	v_mov_b32_e32 v44, v61
	v_sub_f32_e32 v40, v32, v33
	v_pk_mul_f32 v[32:33], v[44:45], v[128:129]
	s_nop 0
	v_sub_f32_e32 v39, v32, v33
	v_mov_b32_e32 v32, v62
	v_mov_b32_e32 v33, v46
	v_pk_mul_f32 v[32:33], v[32:33], v[128:129]
	v_mov_b32_e32 v46, v63
	v_sub_f32_e32 v38, v32, v33
	v_pk_mul_f32 v[32:33], v[46:47], v[128:129]
	s_nop 0
	v_sub_f32_e32 v37, v32, v33
	v_mov_b32_e32 v33, v0
	v_mov_b32_e32 v0, v17
	v_pk_mul_f32 v[0:1], v[0:1], v[128:129]
	v_mov_b32_e32 v32, v16
	v_sub_f32_e32 v35, v0, v1
	v_mov_b32_e32 v0, v18
	v_mov_b32_e32 v1, v2
	v_pk_mul_f32 v[0:1], v[0:1], v[128:129]
	v_mov_b32_e32 v2, v19
	v_pk_mul_f32 v[32:33], v[32:33], v[128:129]
	v_sub_f32_e32 v34, v0, v1
	v_pk_mul_f32 v[0:1], v[2:3], v[128:129]
	v_sub_f32_e32 v36, v32, v33
	v_sub_f32_e32 v33, v0, v1
	v_mov_b32_e32 v1, v4
	v_mov_b32_e32 v4, v21
	v_mul_f32_e32 v21, v112, v112
	v_fmac_f32_e32 v21, v113, v113
	v_fmac_f32_e32 v21, v114, v114
	v_fmac_f32_e32 v21, v115, v115
	v_fmac_f32_e32 v21, v98, v98
	v_fmac_f32_e32 v21, v99, v99
	v_fmac_f32_e32 v21, v100, v100
	v_fmac_f32_e32 v21, v101, v101
	v_fmac_f32_e32 v21, v97, v97
	v_fmac_f32_e32 v21, v102, v102
	v_fmac_f32_e32 v21, v104, v104
	v_fmac_f32_e32 v21, v107, v107
	v_fmac_f32_e32 v21, v106, v106
	v_fmac_f32_e32 v21, v108, v108
	v_fmac_f32_e32 v21, v109, v109
	v_fmac_f32_e32 v21, v116, v116
	v_fmac_f32_e32 v21, v111, v111
	v_fmac_f32_e32 v21, v110, v110
	v_fmac_f32_e32 v21, v105, v105
	v_fmac_f32_e32 v21, v103, v103
	v_fmac_f32_e32 v21, v96, v96
	v_fmac_f32_e32 v21, v85, v85
	v_fmac_f32_e32 v21, v84, v84
	v_fmac_f32_e32 v21, v83, v83
	v_fmac_f32_e32 v21, v82, v82
	v_fmac_f32_e32 v21, v81, v81
	v_fmac_f32_e32 v21, v80, v80
	v_fmac_f32_e32 v21, v73, v73
	v_fmac_f32_e32 v21, v72, v72
	v_fmac_f32_e32 v21, v71, v71
	v_fmac_f32_e32 v21, v70, v70
	v_fmac_f32_e32 v21, v69, v69
	v_fmac_f32_e32 v21, v68, v68
	v_fmac_f32_e32 v21, v67, v67
	v_fmac_f32_e32 v21, v66, v66
	v_fmac_f32_e32 v21, v65, v65
	v_fmac_f32_e32 v21, v64, v64
	v_fmac_f32_e32 v21, v53, v53
	v_fmac_f32_e32 v21, v52, v52
	v_fmac_f32_e32 v21, v51, v51
	v_fmac_f32_e32 v21, v50, v50
	v_fmac_f32_e32 v21, v49, v49
	v_fmac_f32_e32 v21, v48, v48
	v_fmac_f32_e32 v21, v41, v41
	v_fmac_f32_e32 v21, v40, v40
	v_mov_b32_e32 v0, v20
	v_fmac_f32_e32 v21, v39, v39
	v_pk_mul_f32 v[0:1], v[0:1], v[128:129]
	v_fmac_f32_e32 v21, v38, v38
	v_sub_f32_e32 v32, v0, v1
	v_pk_mul_f32 v[0:1], v[4:5], v[128:129]
	v_fmac_f32_e32 v21, v37, v37
	v_sub_f32_e32 v20, v0, v1
	v_mov_b32_e32 v0, v22
	v_mov_b32_e32 v1, v6
	v_mov_b32_e32 v6, v23
	v_fmac_f32_e32 v21, v36, v36
	v_pk_mul_f32 v[0:1], v[0:1], v[128:129]
	v_pk_mul_f32 v[2:3], v[6:7], v[128:129]
	v_fmac_f32_e32 v21, v35, v35
	v_mov_b32_e32 v4, v2
	v_mov_b32_e32 v5, v0
	v_mov_b32_e32 v0, v3
	v_mov_b32_e32 v2, v24
	v_mov_b32_e32 v3, v8
	v_mov_b32_e32 v8, v25
	v_fmac_f32_e32 v21, v34, v34
	v_pk_add_f32 v[18:19], v[4:5], v[0:1] neg_lo:[0,1] neg_hi:[0,1]
	v_pk_mul_f32 v[2:3], v[2:3], v[128:129]
	v_pk_mul_f32 v[4:5], v[8:9], v[128:129]
	v_fmac_f32_e32 v21, v33, v33
	v_mov_b32_e32 v6, v4
	v_mov_b32_e32 v7, v2
	v_mov_b32_e32 v2, v5
	v_mov_b32_e32 v4, v26
	v_mov_b32_e32 v5, v10
	v_mov_b32_e32 v10, v27
	v_fmac_f32_e32 v21, v32, v32
	v_pk_mul_f32 v[0:1], v[18:19], v[18:19]
	v_pk_add_f32 v[16:17], v[6:7], v[2:3] neg_lo:[0,1] neg_hi:[0,1]
	v_pk_mul_f32 v[4:5], v[4:5], v[128:129]
	v_pk_mul_f32 v[6:7], v[10:11], v[128:129]
	v_fmac_f32_e32 v21, v20, v20
	v_mov_b32_e32 v8, v6
	v_mov_b32_e32 v9, v4
	v_mov_b32_e32 v4, v7
	v_add_f32_e32 v1, v1, v21
	v_pk_mul_f32 v[2:3], v[16:17], v[16:17]
	v_pk_add_f32 v[8:9], v[8:9], v[4:5] neg_lo:[0,1] neg_hi:[0,1]
	v_mov_b32_e32 v4, v28
	v_mov_b32_e32 v5, v12
	v_mov_b32_e32 v12, v29
	v_add_f32_e32 v0, v0, v1
	v_pk_mul_f32 v[4:5], v[4:5], v[128:129]
	v_pk_mul_f32 v[6:7], v[12:13], v[128:129]
	v_add_f32_e32 v0, v3, v0
	v_pk_mul_f32 v[10:11], v[8:9], v[8:9]
	v_mov_b32_e32 v12, v6
	v_mov_b32_e32 v13, v4
	v_mov_b32_e32 v4, v7
	v_add_f32_e32 v0, v2, v0
	v_pk_add_f32 v[4:5], v[12:13], v[4:5] neg_lo:[0,1] neg_hi:[0,1]
	v_mov_b32_e32 v6, v129
	v_add_f32_e32 v0, v11, v0
	v_pk_mul_f32 v[12:13], v[4:5], v[4:5]
	v_pk_mul_f32 v[6:7], v[14:15], v[6:7] op_sel_hi:[1,0]
	v_add_f32_e32 v0, v10, v0
	v_pk_fma_f32 v[6:7], v[30:31], v[128:129], v[6:7] op_sel_hi:[1,0,1] neg_lo:[0,0,1] neg_hi:[0,0,1]
	v_add_f32_e32 v0, v13, v0
	v_pk_mul_f32 v[14:15], v[6:7], v[6:7]
	v_add_f32_e32 v0, v12, v0
	v_add_f32_e32 v0, v14, v0
	v_add_f32_e32 v0, v15, v0
	ds_bpermute_b32 v1, v131, v0
	s_waitcnt lgkmcnt(0)
	v_add_f32_e32 v0, v0, v1
	v_fmamk_f32 v0, v0, 0x3c000000, v210
	v_cmp_gt_f32_e32 vcc, s89, v0
	v_mul_f32_e32 v1, 0x4b800000, v0
	s_nop 0
	v_cndmask_b32_e32 v0, v0, v1, vcc
	v_rsq_f32_e32 v0, v0
	s_nop 0
	v_mul_f32_e32 v1, 0x45800000, v0
	v_cndmask_b32_e32 v0, v0, v1, vcc
	v_mul_f32_e32 v12, v195, v0
	v_and_or_b32 v0, v130, 31, s53
	v_add_u32_e32 v0, s86, v0
	v_ashrrev_i32_e32 v1, 31, v0
	v_lshlrev_b64 v[0:1], 11, v[0:1]
	v_lshl_add_u64 v[0:1], s[38:39], 0, v[0:1]
	v_lshl_add_u64 v[10:11], v[0:1], 0, s[98:99]
	v_lshrrev_b32_e32 v0, 3, v130
	v_and_b32_e32 v21, 4, v0
	v_lshlrev_b32_e32 v13, 2, v21
	global_load_dwordx4 v[0:3], v13, s[40:41]
	v_mul_f32_e32 v14, v112, v12
	v_lshlrev_b32_e32 v144, 1, v21
	v_mul_f32_e32 v8, v8, v12
	s_mov_b64 s[86:87], 0
	s_waitcnt vmcnt(0)
	v_mul_f32_e32 v0, v0, v14
	v_mul_f32_e32 v14, v113, v12
	v_mul_f32_e32 v1, v1, v14
	v_cvt_pk_bf16_f32 v14, v0, v1
	v_mul_f32_e32 v0, v114, v12
	v_mul_f32_e32 v1, v115, v12
	v_mul_f32_e32 v0, v2, v0
	v_mul_f32_e32 v1, v3, v1
	v_lshl_add_u64 v[2:3], v[10:11], 0, v[144:145]
	v_cvt_pk_bf16_f32 v15, v0, v1
	v_lshl_add_u64 v[0:1], v[2:3], 0, s[56:57]
	v_add_co_u32_e32 v2, vcc, s27, v2
	v_mul_f32_e32 v10, v101, v12
	s_nop 0
	v_addc_co_u32_e32 v3, vcc, 0, v3, vcc
	global_store_dwordx2 v[2:3], v[14:15], off offset:1024
	v_mul_f32_e32 v2, v98, v12
	v_mul_f32_e32 v3, v99, v12
	s_and_b64 vcc, exec, s[84:85]
	v_mul_f32_e32 v2, v156, v2
	v_mul_f32_e32 v3, v157, v3
	v_cvt_pk_bf16_f32 v2, v2, v3
	v_mul_f32_e32 v3, v100, v12
	v_mul_f32_e32 v3, v158, v3
	v_mul_f32_e32 v10, v159, v10
	v_cvt_pk_bf16_f32 v3, v3, v10
	global_store_dwordx2 v[0:1], v[2:3], off offset:16
	v_mul_f32_e32 v2, v97, v12
	v_mul_f32_e32 v3, v102, v12
	v_mul_f32_e32 v10, v107, v12
	v_mul_f32_e32 v2, v160, v2
	v_mul_f32_e32 v3, v161, v3
	v_cvt_pk_bf16_f32 v2, v2, v3
	v_mul_f32_e32 v3, v104, v12
	v_mul_f32_e32 v3, v162, v3
	v_mul_f32_e32 v10, v163, v10
	v_cvt_pk_bf16_f32 v3, v3, v10
	global_store_dwordx2 v[0:1], v[2:3], off offset:32
	v_mul_f32_e32 v2, v106, v12
	v_mul_f32_e32 v3, v108, v12
	v_mul_f32_e32 v10, v116, v12
	v_mul_f32_e32 v2, v164, v2
	v_mul_f32_e32 v3, v165, v3
	v_cvt_pk_bf16_f32 v2, v2, v3
	v_mul_f32_e32 v3, v109, v12
	v_mul_f32_e32 v3, v166, v3
	v_mul_f32_e32 v10, v167, v10
	v_cvt_pk_bf16_f32 v3, v3, v10
	global_store_dwordx2 v[0:1], v[2:3], off offset:48
	v_mul_f32_e32 v2, v111, v12
	v_mul_f32_e32 v3, v110, v12
	v_mul_f32_e32 v10, v103, v12
	v_mul_f32_e32 v2, v168, v2
	v_mul_f32_e32 v3, v169, v3
	v_cvt_pk_bf16_f32 v2, v2, v3
	v_mul_f32_e32 v3, v105, v12
	v_mul_f32_e32 v3, v170, v3
	v_mul_f32_e32 v10, v171, v10
	v_cvt_pk_bf16_f32 v3, v3, v10
	global_store_dwordx2 v[0:1], v[2:3], off offset:64
	v_mul_f32_e32 v2, v96, v12
	v_mul_f32_e32 v3, v85, v12
	v_mul_f32_e32 v10, v83, v12
	v_mul_f32_e32 v2, v172, v2
	v_mul_f32_e32 v3, v173, v3
	v_cvt_pk_bf16_f32 v2, v2, v3
	v_mul_f32_e32 v3, v84, v12
	v_mul_f32_e32 v3, v174, v3
	v_mul_f32_e32 v10, v175, v10
	v_cvt_pk_bf16_f32 v3, v3, v10
	global_store_dwordx2 v[0:1], v[2:3], off offset:80
	v_mul_f32_e32 v2, v82, v12
	v_mul_f32_e32 v3, v81, v12
	v_mul_f32_e32 v10, v73, v12
	v_mul_f32_e32 v2, v176, v2
	v_mul_f32_e32 v3, v177, v3
	v_cvt_pk_bf16_f32 v2, v2, v3
	v_mul_f32_e32 v3, v80, v12
	v_mul_f32_e32 v3, v178, v3
	v_mul_f32_e32 v10, v179, v10
	v_cvt_pk_bf16_f32 v3, v3, v10
	global_store_dwordx2 v[0:1], v[2:3], off offset:96
	v_mul_f32_e32 v2, v72, v12
	v_mul_f32_e32 v3, v71, v12
	v_mul_f32_e32 v10, v69, v12
	v_mul_f32_e32 v2, v180, v2
	v_mul_f32_e32 v3, v181, v3
	v_cvt_pk_bf16_f32 v2, v2, v3
	v_mul_f32_e32 v3, v70, v12
	v_mul_f32_e32 v3, v182, v3
	v_mul_f32_e32 v10, v183, v10
	v_cvt_pk_bf16_f32 v3, v3, v10
	global_store_dwordx2 v[0:1], v[2:3], off offset:112
	v_mul_f32_e32 v2, v68, v12
	v_mul_f32_e32 v3, v67, v12
	v_mul_f32_e32 v10, v65, v12
	v_mul_f32_e32 v2, v184, v2
	v_mul_f32_e32 v3, v185, v3
	v_cvt_pk_bf16_f32 v2, v2, v3
	v_mul_f32_e32 v3, v66, v12
	v_mul_f32_e32 v3, v186, v3
	v_mul_f32_e32 v10, v187, v10
	v_cvt_pk_bf16_f32 v3, v3, v10
	global_store_dwordx2 v[0:1], v[2:3], off offset:128
	v_mul_f32_e32 v2, v64, v12
	v_mul_f32_e32 v3, v53, v12
	v_mul_f32_e32 v10, v51, v12
	v_mul_f32_e32 v2, v216, v2
	v_mul_f32_e32 v3, v217, v3
	v_cvt_pk_bf16_f32 v2, v2, v3
	v_mul_f32_e32 v3, v52, v12
	v_mul_f32_e32 v3, v218, v3
	v_mul_f32_e32 v10, v219, v10
	v_cvt_pk_bf16_f32 v3, v3, v10
	global_store_dwordx2 v[0:1], v[2:3], off offset:144
	v_mul_f32_e32 v2, v50, v12
	v_mul_f32_e32 v3, v49, v12
	v_mul_f32_e32 v10, v41, v12
	v_mul_f32_e32 v2, v220, v2
	v_mul_f32_e32 v3, v221, v3
	v_cvt_pk_bf16_f32 v2, v2, v3
	v_mul_f32_e32 v3, v48, v12
	v_mul_f32_e32 v3, v222, v3
	v_mul_f32_e32 v10, v223, v10
	v_cvt_pk_bf16_f32 v3, v3, v10
	global_store_dwordx2 v[0:1], v[2:3], off offset:160
	v_mul_f32_e32 v2, v40, v12
	v_mul_f32_e32 v3, v39, v12
	v_mul_f32_e32 v10, v37, v12
	v_mul_f32_e32 v2, v224, v2
	v_mul_f32_e32 v3, v225, v3
	v_cvt_pk_bf16_f32 v2, v2, v3
	v_mul_f32_e32 v3, v38, v12
	v_mul_f32_e32 v3, v226, v3
	v_mul_f32_e32 v10, v227, v10
	v_cvt_pk_bf16_f32 v3, v3, v10
	global_store_dwordx2 v[0:1], v[2:3], off offset:176
	v_mul_f32_e32 v2, v36, v12
	v_mul_f32_e32 v3, v35, v12
	v_mul_f32_e32 v10, v33, v12
	v_mul_f32_e32 v2, v228, v2
	v_mul_f32_e32 v3, v229, v3
	v_cvt_pk_bf16_f32 v2, v2, v3
	v_mul_f32_e32 v3, v34, v12
	v_mul_f32_e32 v3, v230, v3
	v_mul_f32_e32 v10, v231, v10
	v_cvt_pk_bf16_f32 v3, v3, v10
	global_store_dwordx2 v[0:1], v[2:3], off offset:192
	v_mul_f32_e32 v2, v32, v12
	v_mul_f32_e32 v3, v20, v12
	v_mul_f32_e32 v10, v18, v12
	v_mul_f32_e32 v2, v232, v2
	v_mul_f32_e32 v3, v233, v3
	v_cvt_pk_bf16_f32 v2, v2, v3
	v_mul_f32_e32 v3, v19, v12
	v_mul_f32_e32 v3, v234, v3
	v_mul_f32_e32 v10, v235, v10
	v_cvt_pk_bf16_f32 v3, v3, v10
	global_store_dwordx2 v[0:1], v[2:3], off offset:208
	v_mul_f32_e32 v2, v17, v12
	v_mul_f32_e32 v3, v16, v12
	v_mul_f32_e32 v2, v236, v2
	v_mul_f32_e32 v3, v237, v3
	v_cvt_pk_bf16_f32 v2, v2, v3
	v_mul_f32_e32 v3, v9, v12
	v_mul_f32_e32 v3, v238, v3
	v_mul_f32_e32 v8, v239, v8
	v_cvt_pk_bf16_f32 v3, v3, v8
	global_store_dwordx2 v[0:1], v[2:3], off offset:224
	v_mul_f32_e32 v2, v5, v12
	v_mul_f32_e32 v3, v4, v12
	v_mul_f32_e32 v4, v7, v12
	v_mul_f32_e32 v2, v240, v2
	v_mul_f32_e32 v3, v241, v3
	v_cvt_pk_bf16_f32 v2, v2, v3
	v_mul_f32_e32 v3, v6, v12
	v_mul_f32_e32 v3, v242, v3
	v_mul_f32_e32 v4, v243, v4
	v_cvt_pk_bf16_f32 v3, v3, v4
	s_nop 1
	global_store_dwordx2 v[0:1], v[2:3], off offset:240
	s_cbranch_vccnz .LBB0_31

.LBB0_59:
	v_lshlrev_b32_e32 v16, 16, v140
	v_fma_f32 v17, v32, v40, v138
	v_mul_f32_e32 v32, v17, v16
	v_and_b32_e32 v16, 0xffff0000, v140
	v_fma_f32 v17, v33, v41, v138
	v_mul_f32_e32 v33, v17, v16
	v_lshlrev_b32_e32 v16, 16, v141
	v_fma_f32 v17, v34, v42, v138
	v_mul_f32_e32 v34, v17, v16
	v_and_b32_e32 v16, 0xffff0000, v141
	v_fma_f32 v17, v35, v43, v138
	v_mul_f32_e32 v35, v17, v16
	v_mul_f32_e32 v16, v33, v33
	v_mul_f32_e32 v17, v34, v34
	v_fmac_f32_e32 v16, v32, v32
	v_fmac_f32_e32 v17, v35, v35
	v_add_f32_e32 v16, v16, v17
	v_lshlrev_b32_e32 v17, 16, v136
	v_fma_f32 v18, v36, v52, v138
	v_mul_f32_e32 v36, v18, v17
	v_and_b32_e32 v17, 0xffff0000, v136
	v_fma_f32 v18, v37, v53, v138
	v_mul_f32_e32 v37, v18, v17
	v_lshlrev_b32_e32 v17, 16, v137
	v_fma_f32 v18, v38, v54, v138
	v_mul_f32_e32 v38, v18, v17
	v_and_b32_e32 v17, 0xffff0000, v137
	v_fma_f32 v18, v39, v55, v138
	v_mul_f32_e32 v39, v18, v17
	v_mul_f32_e32 v17, v37, v37
	v_mul_f32_e32 v18, v38, v38
	v_fmac_f32_e32 v17, v36, v36
	v_fmac_f32_e32 v18, v39, v39
	v_add_f32_e32 v17, v17, v18
	v_add_f32_e32 v16, v16, v17
	v_lshlrev_b32_e32 v17, 16, v134
	v_fma_f32 v18, v44, v60, v138
	v_mul_f32_e32 v40, v18, v17
	v_and_b32_e32 v17, 0xffff0000, v134
	v_fma_f32 v18, v45, v61, v138
	v_mul_f32_e32 v41, v18, v17
	v_lshlrev_b32_e32 v17, 16, v135
	v_fma_f32 v18, v46, v62, v138
	v_mul_f32_e32 v42, v18, v17
	v_and_b32_e32 v17, 0xffff0000, v135
	v_fma_f32 v18, v47, v63, v138
	v_mul_f32_e32 v43, v18, v17
	v_mul_f32_e32 v17, v41, v41
	v_mul_f32_e32 v18, v42, v42
	v_fmac_f32_e32 v17, v40, v40
	v_fmac_f32_e32 v18, v43, v43
	v_add_f32_e32 v17, v17, v18
	v_add_f32_e32 v16, v16, v17
	v_lshlrev_b32_e32 v17, 16, v132
	v_fma_f32 v18, v48, v68, v138
	v_mul_f32_e32 v44, v18, v17
	v_and_b32_e32 v17, 0xffff0000, v132
	v_fma_f32 v18, v49, v69, v138
	v_mul_f32_e32 v45, v18, v17
	v_lshlrev_b32_e32 v17, 16, v133
	v_fma_f32 v18, v50, v70, v138
	v_mul_f32_e32 v46, v18, v17
	v_and_b32_e32 v17, 0xffff0000, v133
	v_fma_f32 v18, v51, v71, v138
	v_mul_f32_e32 v47, v18, v17
	v_mul_f32_e32 v17, v45, v45
	v_mul_f32_e32 v18, v46, v46
	v_fmac_f32_e32 v17, v44, v44
	v_fmac_f32_e32 v18, v47, v47
	v_add_f32_e32 v17, v17, v18
	v_add_f32_e32 v16, v16, v17
	v_lshlrev_b32_e32 v17, 16, v130
	v_fma_f32 v18, v56, v76, v138
	v_mul_f32_e32 v48, v18, v17
	v_and_b32_e32 v17, 0xffff0000, v130
	v_fma_f32 v18, v57, v77, v138
	v_mul_f32_e32 v49, v18, v17
	v_lshlrev_b32_e32 v17, 16, v131
	v_fma_f32 v18, v58, v78, v138
	v_mul_f32_e32 v50, v18, v17
	v_and_b32_e32 v17, 0xffff0000, v131
	v_fma_f32 v18, v59, v79, v138
	v_mul_f32_e32 v51, v18, v17
	v_mul_f32_e32 v17, v49, v49
	v_mul_f32_e32 v18, v50, v50
	v_fmac_f32_e32 v17, v48, v48
	v_fmac_f32_e32 v18, v51, v51
	v_add_f32_e32 v17, v17, v18
	v_add_f32_e32 v16, v16, v17
	v_lshlrev_b32_e32 v17, 16, v128
	v_fma_f32 v18, v64, v80, v138
	v_mul_f32_e32 v52, v18, v17
	v_and_b32_e32 v17, 0xffff0000, v128
	v_fma_f32 v18, v65, v81, v138
	v_mul_f32_e32 v53, v18, v17
	v_lshlrev_b32_e32 v17, 16, v129
	v_fma_f32 v18, v66, v82, v138
	v_mul_f32_e32 v54, v18, v17
	v_and_b32_e32 v17, 0xffff0000, v129
	v_fma_f32 v18, v67, v83, v138
	v_mul_f32_e32 v55, v18, v17
	v_mul_f32_e32 v17, v53, v53
	v_mul_f32_e32 v18, v54, v54
	v_fmac_f32_e32 v17, v52, v52
	v_fmac_f32_e32 v18, v55, v55
	v_add_f32_e32 v17, v17, v18
	v_add_f32_e32 v16, v16, v17
	v_lshlrev_b32_e32 v17, 16, v126
	s_waitcnt lgkmcnt(0)
	v_fma_f32 v18, v72, v28, v138
	v_mul_f32_e32 v28, v18, v17
	v_and_b32_e32 v17, 0xffff0000, v126
	v_fma_f32 v18, v73, v29, v138
	v_mul_f32_e32 v29, v18, v17
	v_lshlrev_b32_e32 v17, 16, v127
	v_fma_f32 v18, v74, v30, v138
	v_mul_f32_e32 v30, v18, v17
	v_and_b32_e32 v17, 0xffff0000, v127
	v_fma_f32 v18, v75, v31, v138
	v_mul_f32_e32 v31, v18, v17
	v_mul_f32_e32 v17, v29, v29
	v_mul_f32_e32 v18, v30, v30
	v_fmac_f32_e32 v17, v28, v28
	v_fmac_f32_e32 v18, v31, v31
	v_add_f32_e32 v17, v17, v18
	v_add_f32_e32 v21, v16, v17
	ds_read_b128 v[16:19], v89 offset:448
	v_and_b32_e32 v22, 0xffff0000, v124
	v_lshlrev_b32_e32 v23, 16, v125
	s_and_b32 s27, s33, 0xffffff80
	v_add_u32_e32 v20, s27, v102
	s_waitcnt lgkmcnt(0)
	v_pk_mul_f32 v[18:19], v[26:27], v[18:19]
	v_pk_mul_f32 v[24:25], v[24:25], v[16:17]
	v_lshl_add_u32 v27, s36, 2, v143
	v_pk_mov_b32 v[16:17], v[24:25], v[18:19] op_sel:[1,0]
	v_mov_b32_e32 v25, v19
	v_pk_add_f32 v[16:17], v[138:139], v[16:17] op_sel_hi:[0,1]
	v_pk_mul_f32 v[16:17], v[16:17], v[22:23]
	v_lshlrev_b32_e32 v22, 16, v124
	v_and_b32_e32 v23, 0xffff0000, v125
	v_pk_add_f32 v[18:19], v[138:139], v[24:25] op_sel_hi:[0,1]
	v_pk_mul_f32 v[18:19], v[18:19], v[22:23]
	v_pk_mul_f32 v[22:23], v[16:17], v[16:17]
	s_lshl_b32 s98, s36, 1
	v_pk_fma_f32 v[22:23], v[18:19], v[18:19], v[22:23]
	v_lshlrev_b32_e32 v144, 1, v85
	v_add_f32_e32 v22, v22, v23
	v_and_b32_e32 v23, 64, v214
	v_add_f32_e32 v21, v21, v22
	v_xor_b32_e32 v22, 16, v214
	v_add_u32_e32 v23, 64, v23
	v_cmp_lt_i32_e32 vcc, v22, v23
	s_xor_b32 s35, s35, 1
	s_add_i32 s33, s33, 32
	v_cndmask_b32_e32 v22, v214, v22, vcc
	v_lshlrev_b32_e32 v22, 2, v22
	ds_bpermute_b32 v22, v22, v21
	s_addk_i32 s34, 0x80
	s_waitcnt vmcnt(0)
	v_mov_b64_e32 v[140:141], v[120:121]
	v_mov_b64_e32 v[136:137], v[118:119]
	v_mov_b64_e32 v[134:135], v[116:117]
	s_waitcnt lgkmcnt(0)
	v_add_f32_e32 v21, v21, v22
	v_xor_b32_e32 v22, 32, v214
	v_cmp_lt_i32_e32 vcc, v22, v23
	v_mov_b64_e32 v[132:133], v[114:115]
	v_mov_b64_e32 v[130:131], v[112:113]
	v_cndmask_b32_e32 v22, v214, v22, vcc
	v_lshlrev_b32_e32 v22, 2, v22
	ds_bpermute_b32 v22, v22, v21
	v_mov_b64_e32 v[128:129], v[110:111]
	v_mov_b64_e32 v[126:127], v[108:109]
	v_mov_b64_e32 v[124:125], v[106:107]
	s_waitcnt lgkmcnt(0)
	v_add_f32_e32 v21, v21, v22
	v_fmamk_f32 v21, v21, 0x3c000000, v210
	v_cmp_gt_f32_e32 vcc, s89, v21
	v_mul_f32_e32 v22, 0x4b800000, v21
	s_nop 0
	v_cndmask_b32_e32 v21, v21, v22, vcc
	v_rsq_f32_e32 v21, v21
	s_nop 0
	v_mul_f32_e32 v22, 0x45800000, v21
	v_cndmask_b32_e32 v26, v21, v22, vcc
	ds_read_b128 v[22:25], v27
	v_mul_f32_e32 v32, v32, v26
	v_ashrrev_i32_e32 v21, 31, v20
	v_lshlrev_b64 v[20:21], 11, v[20:21]
	v_lshl_add_u64 v[20:21], s[44:45], 0, v[20:21]
	s_waitcnt lgkmcnt(0)
	v_mul_f32_e32 v22, v22, v32
	v_mul_f32_e32 v32, v33, v26
	v_mul_f32_e32 v23, v23, v32
	v_cvt_pk_bf16_f32 v22, v22, v23
	v_mul_f32_e32 v23, v34, v26
	v_mul_f32_e32 v23, v24, v23
	v_mul_f32_e32 v24, v35, v26
	v_lshl_add_u64 v[20:21], v[20:21], 0, s[98:99]
	v_mul_f32_e32 v24, v25, v24
	v_cvt_pk_bf16_f32 v23, v23, v24
	v_lshl_add_u64 v[24:25], v[20:21], 0, v[144:145]
	global_store_dwordx2 v[24:25], v[22:23], off
	ds_read_b128 v[20:23], v27 offset:64
	v_mul_f32_e32 v32, v36, v26
	v_mul_f32_e32 v28, v28, v26
	v_mul_f32_e32 v18, v18, v26
	v_mul_f32_e32 v16, v16, v26
	s_waitcnt lgkmcnt(0)
	v_mul_f32_e32 v20, v20, v32
	v_mul_f32_e32 v32, v37, v26
	v_mul_f32_e32 v21, v21, v32
	v_cvt_pk_bf16_f32 v20, v20, v21
	v_mul_f32_e32 v21, v38, v26
	v_mul_f32_e32 v21, v22, v21
	v_mul_f32_e32 v22, v39, v26
	v_mul_f32_e32 v22, v23, v22
	v_cvt_pk_bf16_f32 v21, v21, v22
	global_store_dwordx2 v[24:25], v[20:21], off offset:32
	ds_read_b128 v[20:23], v27 offset:128
	v_mul_f32_e32 v32, v40, v26
	v_mul_f32_e32 v17, v17, v26
	s_and_b64 vcc, exec, s[46:47]
	s_waitcnt lgkmcnt(0)
	v_mul_f32_e32 v20, v20, v32
	v_mul_f32_e32 v32, v41, v26
	v_mul_f32_e32 v21, v21, v32
	v_cvt_pk_bf16_f32 v20, v20, v21
	v_mul_f32_e32 v21, v42, v26
	v_mul_f32_e32 v21, v22, v21
	v_mul_f32_e32 v22, v43, v26
	v_mul_f32_e32 v22, v23, v22
	v_cvt_pk_bf16_f32 v21, v21, v22
	global_store_dwordx2 v[24:25], v[20:21], off offset:64
	ds_read_b128 v[20:23], v27 offset:192
	v_mul_f32_e32 v32, v44, v26
	s_waitcnt lgkmcnt(0)
	v_mul_f32_e32 v20, v20, v32
	v_mul_f32_e32 v32, v45, v26
	v_mul_f32_e32 v21, v21, v32
	v_cvt_pk_bf16_f32 v20, v20, v21
	v_mul_f32_e32 v21, v46, v26
	v_mul_f32_e32 v21, v22, v21
	v_mul_f32_e32 v22, v47, v26
	v_mul_f32_e32 v22, v23, v22
	v_cvt_pk_bf16_f32 v21, v21, v22
	global_store_dwordx2 v[24:25], v[20:21], off offset:96
	ds_read_b128 v[20:23], v27 offset:256
	v_mul_f32_e32 v32, v48, v26
	s_waitcnt lgkmcnt(0)
	v_mul_f32_e32 v20, v32, v20
	v_mul_f32_e32 v32, v49, v26
	v_mul_f32_e32 v21, v32, v21
	v_cvt_pk_bf16_f32 v20, v20, v21
	v_mul_f32_e32 v21, v50, v26
	v_mul_f32_e32 v21, v21, v22
	v_mul_f32_e32 v22, v51, v26
	v_mul_f32_e32 v22, v22, v23
	v_cvt_pk_bf16_f32 v21, v21, v22
	global_store_dwordx2 v[24:25], v[20:21], off offset:128
	ds_read_b128 v[20:23], v27 offset:320
	v_mul_f32_e32 v32, v52, v26
	s_waitcnt lgkmcnt(0)
	v_mul_f32_e32 v20, v32, v20
	v_mul_f32_e32 v32, v53, v26
	v_mul_f32_e32 v21, v32, v21
	v_cvt_pk_bf16_f32 v20, v20, v21
	v_mul_f32_e32 v21, v54, v26
	v_mul_f32_e32 v21, v21, v22
	v_mul_f32_e32 v22, v55, v26
	v_mul_f32_e32 v22, v22, v23
	v_cvt_pk_bf16_f32 v21, v21, v22
	global_store_dwordx2 v[24:25], v[20:21], off offset:160
	ds_read_b128 v[20:23], v27 offset:384
	v_mov_b64_e32 v[32:33], v[122:123]
	s_waitcnt lgkmcnt(0)
	v_mul_f32_e32 v20, v28, v20
	v_mul_f32_e32 v28, v29, v26
	v_mul_f32_e32 v21, v28, v21
	v_cvt_pk_bf16_f32 v20, v20, v21
	v_mul_f32_e32 v21, v30, v26
	v_mul_f32_e32 v21, v21, v22
	v_mul_f32_e32 v22, v31, v26
	v_mul_f32_e32 v22, v22, v23
	v_cvt_pk_bf16_f32 v21, v21, v22
	global_store_dwordx2 v[24:25], v[20:21], off offset:192
	ds_read_b128 v[20:23], v27 offset:448
	v_mov_b64_e32 v[30:31], v[6:7]
	v_mov_b64_e32 v[28:29], v[4:5]
	s_waitcnt lgkmcnt(0)
	v_mul_f32_e32 v18, v18, v20
	v_mul_f32_e32 v16, v16, v21
	v_cvt_pk_bf16_f32 v16, v18, v16
	v_mul_f32_e32 v17, v17, v22
	v_mul_f32_e32 v18, v19, v26
	v_mul_f32_e32 v18, v18, v23
	v_cvt_pk_bf16_f32 v17, v17, v18
	global_store_dwordx2 v[24:25], v[16:17], off offset:224
	s_waitcnt vmcnt(8)
	v_mov_b64_e32 v[26:27], v[2:3]
	v_mov_b64_e32 v[22:23], v[10:11]
	v_mov_b64_e32 v[18:19], v[14:15]
	v_mov_b64_e32 v[24:25], v[0:1]
	v_mov_b64_e32 v[20:21], v[8:9]
	v_mov_b64_e32 v[16:17], v[12:13]
	s_barrier
	s_cbranch_vccnz .LBB0_103

.LBB0_71:
	s_or_b64 exec, exec, s[50:51]
	s_waitcnt lgkmcnt(0)
	s_barrier
	ds_read_b64 v[32:33], v148
	v_lshlrev_b32_e32 v34, 16, v28
	v_and_b32_e32 v28, 0xffff0000, v28
	s_lshl_b32 s27, s35, 15
	s_add_i32 s27, s27, 0
	s_waitcnt lgkmcnt(0)
	v_mul_f32_e32 v32, v32, v34
	v_mul_f32_e32 v28, v33, v28
	v_cvt_pk_bf16_f32 v28, v32, v28
	ds_read_b64 v[32:33], v148 offset:8
	v_lshlrev_b32_e32 v34, 16, v29
	v_and_b32_e32 v29, 0xffff0000, v29
	v_add_u32_e32 v101, s27, v87
	v_add_u32_e32 v144, s27, v103
	s_waitcnt lgkmcnt(0)
	v_mul_f32_e32 v32, v32, v34
	v_mul_f32_e32 v29, v33, v29
	v_cvt_pk_bf16_f32 v29, v32, v29
	ds_read_b64 v[32:33], v148 offset:16
	v_lshlrev_b32_e32 v34, 16, v30
	v_and_b32_e32 v30, 0xffff0000, v30
	s_and_b64 vcc, exec, s[38:39]
	v_add_u32_e32 v93, s27, v139
	s_waitcnt lgkmcnt(0)
	v_mul_f32_e32 v32, v32, v34
	v_mul_f32_e32 v30, v33, v30
	v_cvt_pk_bf16_f32 v30, v32, v30
	ds_read_b64 v[32:33], v148 offset:24
	v_lshlrev_b32_e32 v34, 16, v31
	v_and_b32_e32 v31, 0xffff0000, v31
	s_waitcnt lgkmcnt(0)
	v_mul_f32_e32 v32, v32, v34
	v_mul_f32_e32 v31, v33, v31
	v_cvt_pk_bf16_f32 v31, v32, v31
	ds_read_b64 v[32:33], v148 offset:128
	v_lshlrev_b32_e32 v34, 16, v24
	v_and_b32_e32 v24, 0xffff0000, v24
	s_waitcnt lgkmcnt(0)
	v_mul_f32_e32 v32, v32, v34
	v_mul_f32_e32 v24, v33, v24
	v_cvt_pk_bf16_f32 v24, v32, v24
	ds_read_b64 v[32:33], v148 offset:136
	v_lshlrev_b32_e32 v34, 16, v25
	v_and_b32_e32 v25, 0xffff0000, v25
	s_waitcnt lgkmcnt(0)
	v_mul_f32_e32 v32, v32, v34
	v_mul_f32_e32 v25, v33, v25
	v_cvt_pk_bf16_f32 v25, v32, v25
	ds_read_b64 v[32:33], v148 offset:144
	v_lshlrev_b32_e32 v34, 16, v26
	v_and_b32_e32 v26, 0xffff0000, v26
	s_waitcnt lgkmcnt(0)
	v_mul_f32_e32 v32, v32, v34
	v_mul_f32_e32 v26, v33, v26
	v_cvt_pk_bf16_f32 v26, v32, v26
	ds_read_b64 v[32:33], v148 offset:152
	v_lshlrev_b32_e32 v34, 16, v27
	v_and_b32_e32 v27, 0xffff0000, v27
	s_waitcnt lgkmcnt(0)
	v_mul_f32_e32 v32, v32, v34
	v_mul_f32_e32 v27, v33, v27
	v_cvt_pk_bf16_f32 v27, v32, v27
	ds_read_b64 v[32:33], v148 offset:256
	v_lshlrev_b32_e32 v34, 16, v20
	v_and_b32_e32 v20, 0xffff0000, v20
	s_waitcnt lgkmcnt(0)
	v_mul_f32_e32 v32, v32, v34
	v_mul_f32_e32 v20, v33, v20
	v_cvt_pk_bf16_f32 v20, v32, v20
	ds_read_b64 v[32:33], v148 offset:264
	v_lshlrev_b32_e32 v34, 16, v21
	v_and_b32_e32 v21, 0xffff0000, v21
	s_waitcnt lgkmcnt(0)
	v_mul_f32_e32 v32, v32, v34
	v_mul_f32_e32 v21, v33, v21
	v_cvt_pk_bf16_f32 v21, v32, v21
	ds_read_b64 v[32:33], v148 offset:272
	v_lshlrev_b32_e32 v34, 16, v22
	v_and_b32_e32 v22, 0xffff0000, v22
	s_waitcnt lgkmcnt(0)
	v_mul_f32_e32 v32, v32, v34
	v_mul_f32_e32 v22, v33, v22
	v_cvt_pk_bf16_f32 v22, v32, v22
	ds_read_b64 v[32:33], v148 offset:280
	v_lshlrev_b32_e32 v34, 16, v23
	v_and_b32_e32 v23, 0xffff0000, v23
	s_waitcnt lgkmcnt(0)
	v_mul_f32_e32 v32, v32, v34
	v_mul_f32_e32 v23, v33, v23
	v_cvt_pk_bf16_f32 v23, v32, v23
	ds_read_b64 v[32:33], v148 offset:384
	v_lshlrev_b32_e32 v34, 16, v16
	v_and_b32_e32 v16, 0xffff0000, v16
	s_waitcnt lgkmcnt(0)
	v_mul_f32_e32 v32, v32, v34
	v_mul_f32_e32 v16, v33, v16
	v_cvt_pk_bf16_f32 v16, v32, v16
	ds_read_b64 v[32:33], v148 offset:392
	v_lshlrev_b32_e32 v34, 16, v17
	v_and_b32_e32 v17, 0xffff0000, v17
	s_waitcnt lgkmcnt(0)
	v_mul_f32_e32 v32, v32, v34
	v_mul_f32_e32 v17, v33, v17
	v_cvt_pk_bf16_f32 v17, v32, v17
	ds_read_b64 v[32:33], v148 offset:400
	v_lshlrev_b32_e32 v34, 16, v18
	v_and_b32_e32 v18, 0xffff0000, v18
	s_waitcnt lgkmcnt(0)
	v_mul_f32_e32 v32, v32, v34
	v_mul_f32_e32 v18, v33, v18
	v_cvt_pk_bf16_f32 v18, v32, v18
	ds_read_b64 v[32:33], v148 offset:408
	v_lshlrev_b32_e32 v34, 16, v19
	v_and_b32_e32 v19, 0xffff0000, v19
	s_waitcnt lgkmcnt(0)
	v_mul_f32_e32 v32, v32, v34
	v_mul_f32_e32 v19, v33, v19
	v_cvt_pk_bf16_f32 v19, v32, v19
	ds_read_b128 v[32:35], v101
	ds_read_b128 v[36:39], v144
	s_waitcnt lgkmcnt(1)
	v_mfma_f32_16x16x32_bf16 v[32:35], v[32:35], v[28:31], 0
	s_waitcnt lgkmcnt(0)
	v_mfma_f32_16x16x32_bf16 v[32:35], v[36:39], v[24:27], v[32:35]
	s_cbranch_vccnz .LBB0_73
	ds_read_b128 v[36:39], v93
	s_waitcnt lgkmcnt(0)
	v_mfma_f32_16x16x32_bf16 v[32:35], v[36:39], v[20:23], v[32:35]

.LBB0_156:
	s_or_b64 exec, exec, s[72:73]
	s_waitcnt vmcnt(0)
	v_mul_f32_e32 v8, 0xbfb8aa3b, v0
	v_exp_f32_e32 v8, v8
	s_movk_i32 s11, 0x1600
	v_add_u32_e32 v22, 0x4000, v22
	v_cmp_le_i32_e32 vcc, s10, v22
	v_add_f32_e32 v8, 1.0, v8
	v_rcp_f32_e32 v8, v8
	v_add_u32_e32 v23, 0x10000, v23
	s_or_b64 s[52:53], vcc, s[52:53]
	v_mul_f32_e32 v0, v0, v8
	v_mul_f32_e32 v0, v32, v0
	v_mul_f32_e32 v4, 0xbfb8aa3b, v1
	v_exp_f32_e32 v4, v4
	s_nop 0
	v_add_f32_e32 v4, 1.0, v4
	v_rcp_f32_e32 v4, v4
	s_nop 0
	v_mul_f32_e32 v1, v1, v4
	v_mul_f32_e32 v4, 0xbfb8aa3b, v2
	v_exp_f32_e32 v4, v4
	v_mul_f32_e32 v1, v33, v1
	v_cvt_pk_bf16_f32 v0, v0, v1
	v_add_f32_e32 v4, 1.0, v4
	v_rcp_f32_e32 v4, v4
	s_nop 0
	v_mul_f32_e32 v2, v2, v4
	v_mul_f32_e32 v4, 0xbfb8aa3b, v3
	v_exp_f32_e32 v4, v4
	v_mul_f32_e32 v2, v34, v2
	v_add_f32_e32 v4, 1.0, v4
	v_rcp_f32_e32 v4, v4
	s_nop 0
	v_mul_f32_e32 v3, v3, v4
	v_mul_f32_e32 v3, v35, v3
	v_cvt_pk_bf16_f32 v1, v2, v3
	v_lshl_or_b32 v4, v25, 6, v24
	v_mov_b64_e32 v[2:3], s[46:47]
	v_mad_i64_i32 v[2:3], s[30:31], v4, s11, v[2:3]
	v_lshl_add_u64 v[2:3], v[16:17], 1, v[2:3]
	global_store_dwordx2 v[2:3], v[0:1], off
	s_andn2_b64 exec, exec, s[52:53]
	s_cbranch_execz .LBB0_163

.LBB0_196:
	s_add_i32 s56, s27, 2
	s_add_u32 s44, s42, 0x80
	s_addc_u32 s45, s43, 0
	s_add_i32 s57, 0, 0x10000
	v_add_u32_e32 v140, s57, v207
	ds_read_b128 v[128:131], v140
	ds_read_b128 v[132:135], v140 offset:1024
	ds_read_b128 v[136:139], v140 offset:2048
	ds_read_b128 v[140:143], v140 offset:3072
	s_cmp_eq_u32 s82, s27
	s_cselect_b32 s45, s77, s45
	s_cselect_b32 s44, s76, s44
	s_cselect_b32 s79, s1, s37
	s_cselect_b32 s78, s0, s33
	v_lshl_add_u64 v[176:177], s[42:43], 0, v[190:191]
	s_add_i32 m0, s85, 0xc000
	ds_read_b128 v[146:149], v217
	ds_read_b128 v[150:153], v217 offset:1024
	ds_read_b128 v[154:157], v217 offset:2048
	ds_read_b128 v[158:161], v217 offset:3072
	ds_read_b128 v[162:165], v217 offset:4096
	ds_read_b128 v[166:169], v217 offset:5120
	ds_read_b128 v[194:197], v217 offset:6144
	ds_read_b128 v[198:201], v217 offset:7168
	global_load_lds_dwordx4 v[176:177], off
	v_lshl_add_u64 v[176:177], s[42:43], 0, v[192:193]
	s_add_i32 m0, s85, 0xe000
	s_nop 0
	global_load_lds_dwordx4 v[176:177], off
	s_waitcnt lgkmcnt(8)
	s_barrier
	s_waitcnt lgkmcnt(0)
	s_setprio 1
	s_waitcnt lgkmcnt(0)
	v_mfma_f32_16x16x32_bf16 v[124:127], v[128:131], v[146:149], v[124:127]
	v_mfma_f32_16x16x32_bf16 v[120:123], v[136:139], v[146:149], v[120:123]
	v_mfma_f32_16x16x32_bf16 v[108:111], v[128:131], v[154:157], v[108:111]
	v_mfma_f32_16x16x32_bf16 v[104:107], v[136:139], v[154:157], v[104:107]
	v_mfma_f32_16x16x32_bf16 v[92:95], v[128:131], v[162:165], v[92:95]
	v_mfma_f32_16x16x32_bf16 v[88:91], v[136:139], v[162:165], v[88:91]
	v_mfma_f32_16x16x32_bf16 v[76:79], v[128:131], v[194:197], v[76:79]
	v_mfma_f32_16x16x32_bf16 v[72:75], v[136:139], v[194:197], v[72:75]
	v_mfma_f32_16x16x32_bf16 v[124:127], v[132:135], v[150:153], v[124:127]
	v_mfma_f32_16x16x32_bf16 v[120:123], v[140:143], v[150:153], v[120:123]
	v_mfma_f32_16x16x32_bf16 v[108:111], v[132:135], v[158:161], v[108:111]
	v_mfma_f32_16x16x32_bf16 v[104:107], v[140:143], v[158:161], v[104:107]
	v_mfma_f32_16x16x32_bf16 v[92:95], v[132:135], v[166:169], v[92:95]
	v_mfma_f32_16x16x32_bf16 v[88:91], v[140:143], v[166:169], v[88:91]
	v_mfma_f32_16x16x32_bf16 v[76:79], v[132:135], v[198:201], v[76:79]
	v_mfma_f32_16x16x32_bf16 v[72:75], v[140:143], v[198:201], v[72:75]
	s_setprio 0
	s_barrier
	s_add_i32 s27, 0, 0x14000
	v_add_u32_e32 v176, s27, v207
	s_add_i32 s57, s57, s84
	ds_read_b128 v[202:205], v176
	ds_read_b128 v[218:221], v176 offset:1024
	ds_read_b128 v[222:225], v176 offset:2048
	ds_read_b128 v[228:231], v176 offset:3072
	v_lshl_add_u64 v[176:177], s[78:79], 0, v[144:145]
	s_mov_b32 m0, s57
	v_lshl_add_u64 v[232:233], s[78:79], 0, v[188:189]
	global_load_lds_dwordx4 v[176:177], off
	s_add_i32 m0, s57, 0x2000
	s_nop 0
	global_load_lds_dwordx4 v[232:233], off
	s_barrier
	s_waitcnt lgkmcnt(0)
	s_setprio 1
	s_waitcnt lgkmcnt(0)
	v_mfma_f32_16x16x32_bf16 v[116:119], v[202:205], v[146:149], v[116:119]
	v_mfma_f32_16x16x32_bf16 v[112:115], v[222:225], v[146:149], v[112:115]
	v_mfma_f32_16x16x32_bf16 v[100:103], v[202:205], v[154:157], v[100:103]
	v_mfma_f32_16x16x32_bf16 v[96:99], v[222:225], v[154:157], v[96:99]
	v_mfma_f32_16x16x32_bf16 v[84:87], v[202:205], v[162:165], v[84:87]
	v_mfma_f32_16x16x32_bf16 v[80:83], v[222:225], v[162:165], v[80:83]
	v_mfma_f32_16x16x32_bf16 v[68:71], v[202:205], v[194:197], v[68:71]
	v_mfma_f32_16x16x32_bf16 v[64:67], v[222:225], v[194:197], v[64:67]
	v_mfma_f32_16x16x32_bf16 v[116:119], v[218:221], v[150:153], v[116:119]
	v_mfma_f32_16x16x32_bf16 v[112:115], v[228:231], v[150:153], v[112:115]
	v_mfma_f32_16x16x32_bf16 v[100:103], v[218:221], v[158:161], v[100:103]
	v_mfma_f32_16x16x32_bf16 v[96:99], v[228:231], v[158:161], v[96:99]
	v_mfma_f32_16x16x32_bf16 v[84:87], v[218:221], v[166:169], v[84:87]
	v_mfma_f32_16x16x32_bf16 v[80:83], v[228:231], v[166:169], v[80:83]
	v_mfma_f32_16x16x32_bf16 v[68:71], v[218:221], v[198:201], v[68:71]
	v_mfma_f32_16x16x32_bf16 v[64:67], v[228:231], v[198:201], v[64:67]
	s_setprio 0
	s_mov_b32 m0, s85
	v_lshl_add_u64 v[234:235], s[44:45], 0, v[144:145]
	s_barrier
	ds_read_b128 v[146:149], v217 offset:16384
	ds_read_b128 v[150:153], v217 offset:17408
	ds_read_b128 v[154:157], v217 offset:18432
	ds_read_b128 v[158:161], v217 offset:19456
	ds_read_b128 v[162:165], v217 offset:20480
	ds_read_b128 v[166:169], v217 offset:21504
	ds_read_b128 v[194:197], v217 offset:22528
	ds_read_b128 v[198:201], v217 offset:23552
	global_load_lds_dwordx4 v[234:235], off
	v_lshl_add_u64 v[236:237], s[44:45], 0, v[188:189]
	s_mov_b32 m0, s86
	s_nop 0
	global_load_lds_dwordx4 v[236:237], off
	s_barrier
	s_waitcnt lgkmcnt(0)
	s_setprio 1
	s_waitcnt lgkmcnt(0)
	v_mfma_f32_16x16x32_bf16 v[60:63], v[128:131], v[146:149], v[60:63]
	v_mfma_f32_16x16x32_bf16 v[56:59], v[136:139], v[146:149], v[56:59]
	v_mfma_f32_16x16x32_bf16 v[44:47], v[128:131], v[154:157], v[44:47]
	v_mfma_f32_16x16x32_bf16 v[40:43], v[136:139], v[154:157], v[40:43]
	v_mfma_f32_16x16x32_bf16 v[28:31], v[128:131], v[162:165], v[28:31]
	v_mfma_f32_16x16x32_bf16 v[24:27], v[136:139], v[162:165], v[24:27]
	v_mfma_f32_16x16x32_bf16 v[12:15], v[128:131], v[194:197], v[12:15]
	v_mfma_f32_16x16x32_bf16 v[8:11], v[136:139], v[194:197], v[8:11]
	v_mfma_f32_16x16x32_bf16 v[60:63], v[132:135], v[150:153], v[60:63]
	v_mfma_f32_16x16x32_bf16 v[56:59], v[140:143], v[150:153], v[56:59]
	v_mfma_f32_16x16x32_bf16 v[44:47], v[132:135], v[158:161], v[44:47]
	v_mfma_f32_16x16x32_bf16 v[40:43], v[140:143], v[158:161], v[40:43]
	v_mfma_f32_16x16x32_bf16 v[28:31], v[132:135], v[166:169], v[28:31]
	v_mfma_f32_16x16x32_bf16 v[24:27], v[140:143], v[166:169], v[24:27]
	v_mfma_f32_16x16x32_bf16 v[12:15], v[132:135], v[198:201], v[12:15]
	v_mfma_f32_16x16x32_bf16 v[8:11], v[140:143], v[198:201], v[8:11]
	s_setprio 0
	s_barrier
	s_add_u32 s58, s78, s98
	s_addc_u32 s59, s79, 0
	s_add_i32 s27, s27, s84
	v_lshl_add_u64 v[238:239], s[58:59], 0, v[144:145]
	s_mov_b32 m0, s27
	v_lshl_add_u64 v[240:241], s[58:59], 0, v[188:189]
	global_load_lds_dwordx4 v[238:239], off
	s_add_i32 m0, s27, 0x2000
	s_nop 0
	global_load_lds_dwordx4 v[240:241], off
	s_waitcnt vmcnt(6)
	s_barrier
	s_setprio 1
	v_mfma_f32_16x16x32_bf16 v[52:55], v[202:205], v[146:149], v[52:55]
	v_mfma_f32_16x16x32_bf16 v[48:51], v[222:225], v[146:149], v[48:51]
	v_mfma_f32_16x16x32_bf16 v[36:39], v[202:205], v[154:157], v[36:39]
	v_mfma_f32_16x16x32_bf16 v[32:35], v[222:225], v[154:157], v[32:35]
	v_mfma_f32_16x16x32_bf16 v[20:23], v[202:205], v[162:165], v[20:23]
	v_mfma_f32_16x16x32_bf16 v[16:19], v[222:225], v[162:165], v[16:19]
	v_mfma_f32_16x16x32_bf16 v[4:7], v[202:205], v[194:197], v[4:7]
	v_mfma_f32_16x16x32_bf16 v[0:3], v[222:225], v[194:197], v[0:3]
	v_mfma_f32_16x16x32_bf16 v[52:55], v[218:221], v[150:153], v[52:55]
	v_mfma_f32_16x16x32_bf16 v[48:51], v[228:231], v[150:153], v[48:51]
	v_mfma_f32_16x16x32_bf16 v[36:39], v[218:221], v[158:161], v[36:39]
	v_mfma_f32_16x16x32_bf16 v[32:35], v[228:231], v[158:161], v[32:35]
	v_mfma_f32_16x16x32_bf16 v[20:23], v[218:221], v[166:169], v[20:23]
	v_mfma_f32_16x16x32_bf16 v[16:19], v[228:231], v[166:169], v[16:19]
	v_mfma_f32_16x16x32_bf16 v[4:7], v[218:221], v[198:201], v[4:7]
	v_mfma_f32_16x16x32_bf16 v[0:3], v[228:231], v[198:201], v[0:3]
	s_setprio 0
	s_add_i32 s27, 0, 0x18000
	v_add_u32_e32 v140, s27, v207
	s_barrier
	ds_read_b128 v[128:131], v140
	ds_read_b128 v[132:135], v140 offset:1024
	ds_read_b128 v[136:139], v140 offset:2048
	ds_read_b128 v[140:143], v140 offset:3072
	s_add_u32 s44, s44, s98
	s_addc_u32 s45, s45, 0
	s_mov_b32 m0, s87
	v_lshl_add_u64 v[202:203], s[44:45], 0, v[144:145]
	ds_read_b128 v[146:149], v217 offset:32768
	ds_read_b128 v[150:153], v217 offset:33792
	ds_read_b128 v[154:157], v217 offset:34816
	ds_read_b128 v[158:161], v217 offset:35840
	ds_read_b128 v[162:165], v217 offset:36864
	ds_read_b128 v[166:169], v217 offset:37888
	ds_read_b128 v[194:197], v217 offset:38912
	ds_read_b128 v[198:201], v217 offset:39936
	global_load_lds_dwordx4 v[202:203], off
	v_lshl_add_u64 v[202:203], s[44:45], 0, v[188:189]
	s_mov_b32 m0, s80
	s_nop 0
	global_load_lds_dwordx4 v[202:203], off
	s_waitcnt lgkmcnt(8)
	s_barrier
	s_waitcnt lgkmcnt(0)
	s_setprio 1
	s_waitcnt lgkmcnt(0)
	v_mfma_f32_16x16x32_bf16 v[124:127], v[128:131], v[146:149], v[124:127]
	v_mfma_f32_16x16x32_bf16 v[120:123], v[136:139], v[146:149], v[120:123]
	v_mfma_f32_16x16x32_bf16 v[108:111], v[128:131], v[154:157], v[108:111]
	v_mfma_f32_16x16x32_bf16 v[104:107], v[136:139], v[154:157], v[104:107]
	v_mfma_f32_16x16x32_bf16 v[92:95], v[128:131], v[162:165], v[92:95]
	v_mfma_f32_16x16x32_bf16 v[88:91], v[136:139], v[162:165], v[88:91]
	v_mfma_f32_16x16x32_bf16 v[76:79], v[128:131], v[194:197], v[76:79]
	v_mfma_f32_16x16x32_bf16 v[72:75], v[136:139], v[194:197], v[72:75]
	v_mfma_f32_16x16x32_bf16 v[124:127], v[132:135], v[150:153], v[124:127]
	v_mfma_f32_16x16x32_bf16 v[120:123], v[140:143], v[150:153], v[120:123]
	v_mfma_f32_16x16x32_bf16 v[108:111], v[132:135], v[158:161], v[108:111]
	v_mfma_f32_16x16x32_bf16 v[104:107], v[140:143], v[158:161], v[104:107]
	v_mfma_f32_16x16x32_bf16 v[92:95], v[132:135], v[166:169], v[92:95]
	v_mfma_f32_16x16x32_bf16 v[88:91], v[140:143], v[166:169], v[88:91]
	v_mfma_f32_16x16x32_bf16 v[76:79], v[132:135], v[198:201], v[76:79]
	v_mfma_f32_16x16x32_bf16 v[72:75], v[140:143], v[198:201], v[72:75]
	s_setprio 0
	s_barrier
	s_add_i32 s44, 0, 0x1c000
	s_add_i32 s27, s27, s84
	v_add_u32_e32 v228, s44, v207
	v_lshl_add_u64 v[176:177], v[176:177], 0, s[18:19]
	s_mov_b32 m0, s27
	ds_read_b128 v[202:205], v228
	ds_read_b128 v[218:221], v228 offset:1024
	ds_read_b128 v[222:225], v228 offset:2048
	ds_read_b128 v[228:231], v228 offset:3072
	global_load_lds_dwordx4 v[176:177], off
	v_lshl_add_u64 v[176:177], v[232:233], 0, s[18:19]
	s_add_i32 m0, s27, 0x2000
	s_nop 0
	global_load_lds_dwordx4 v[176:177], off
	s_barrier
	s_waitcnt lgkmcnt(0)
	s_setprio 1
	s_waitcnt lgkmcnt(0)
	v_mfma_f32_16x16x32_bf16 v[116:119], v[202:205], v[146:149], v[116:119]
	v_mfma_f32_16x16x32_bf16 v[112:115], v[222:225], v[146:149], v[112:115]
	v_mfma_f32_16x16x32_bf16 v[100:103], v[202:205], v[154:157], v[100:103]
	v_mfma_f32_16x16x32_bf16 v[96:99], v[222:225], v[154:157], v[96:99]
	v_mfma_f32_16x16x32_bf16 v[84:87], v[202:205], v[162:165], v[84:87]
	v_mfma_f32_16x16x32_bf16 v[80:83], v[222:225], v[162:165], v[80:83]
	v_mfma_f32_16x16x32_bf16 v[68:71], v[202:205], v[194:197], v[68:71]
	v_mfma_f32_16x16x32_bf16 v[64:67], v[222:225], v[194:197], v[64:67]
	v_mfma_f32_16x16x32_bf16 v[116:119], v[218:221], v[150:153], v[116:119]
	v_mfma_f32_16x16x32_bf16 v[112:115], v[228:231], v[150:153], v[112:115]
	v_mfma_f32_16x16x32_bf16 v[100:103], v[218:221], v[158:161], v[100:103]
	v_mfma_f32_16x16x32_bf16 v[96:99], v[228:231], v[158:161], v[96:99]
	v_mfma_f32_16x16x32_bf16 v[84:87], v[218:221], v[166:169], v[84:87]
	v_mfma_f32_16x16x32_bf16 v[80:83], v[228:231], v[166:169], v[80:83]
	v_mfma_f32_16x16x32_bf16 v[68:71], v[218:221], v[198:201], v[68:71]
	v_mfma_f32_16x16x32_bf16 v[64:67], v[228:231], v[198:201], v[64:67]
	s_setprio 0
	s_mov_b32 m0, s30
	v_lshl_add_u64 v[176:177], v[234:235], 0, s[18:19]
	s_barrier
	ds_read_b128 v[146:149], v217 offset:49152
	ds_read_b128 v[150:153], v217 offset:50176
	ds_read_b128 v[154:157], v217 offset:51200
	ds_read_b128 v[158:161], v217 offset:52224
	ds_read_b128 v[162:165], v217 offset:53248
	ds_read_b128 v[166:169], v217 offset:54272
	ds_read_b128 v[194:197], v217 offset:55296
	ds_read_b128 v[198:201], v217 offset:56320
	global_load_lds_dwordx4 v[176:177], off
	v_lshl_add_u64 v[176:177], v[236:237], 0, s[18:19]
	s_mov_b32 m0, s31
	s_nop 0
	global_load_lds_dwordx4 v[176:177], off
	s_barrier
	s_waitcnt lgkmcnt(0)
	s_setprio 1
	s_waitcnt lgkmcnt(0)
	v_mfma_f32_16x16x32_bf16 v[60:63], v[128:131], v[146:149], v[60:63]
	v_mfma_f32_16x16x32_bf16 v[56:59], v[136:139], v[146:149], v[56:59]
	v_mfma_f32_16x16x32_bf16 v[44:47], v[128:131], v[154:157], v[44:47]
	v_mfma_f32_16x16x32_bf16 v[40:43], v[136:139], v[154:157], v[40:43]
	v_mfma_f32_16x16x32_bf16 v[28:31], v[128:131], v[162:165], v[28:31]
	v_mfma_f32_16x16x32_bf16 v[24:27], v[136:139], v[162:165], v[24:27]
	v_mfma_f32_16x16x32_bf16 v[12:15], v[128:131], v[194:197], v[12:15]
	v_mfma_f32_16x16x32_bf16 v[8:11], v[136:139], v[194:197], v[8:11]
	v_mfma_f32_16x16x32_bf16 v[60:63], v[132:135], v[150:153], v[60:63]
	v_mfma_f32_16x16x32_bf16 v[56:59], v[140:143], v[150:153], v[56:59]
	v_mfma_f32_16x16x32_bf16 v[44:47], v[132:135], v[158:161], v[44:47]
	v_mfma_f32_16x16x32_bf16 v[40:43], v[140:143], v[158:161], v[40:43]
	v_mfma_f32_16x16x32_bf16 v[28:31], v[132:135], v[166:169], v[28:31]
	v_mfma_f32_16x16x32_bf16 v[24:27], v[140:143], v[166:169], v[24:27]
	v_mfma_f32_16x16x32_bf16 v[12:15], v[132:135], v[198:201], v[12:15]
	v_mfma_f32_16x16x32_bf16 v[8:11], v[140:143], v[198:201], v[8:11]
	s_setprio 0
	s_barrier
	s_add_i32 s27, s44, s84
	v_lshl_add_u64 v[128:129], v[238:239], 0, s[18:19]
	s_mov_b32 m0, s27
	s_nop 0
	global_load_lds_dwordx4 v[128:129], off
	v_lshl_add_u64 v[128:129], v[240:241], 0, s[18:19]
	s_add_i32 m0, s27, 0x2000
	s_nop 0
	global_load_lds_dwordx4 v[128:129], off
	s_waitcnt vmcnt(6)
	s_barrier
	s_setprio 1
	v_mfma_f32_16x16x32_bf16 v[52:55], v[202:205], v[146:149], v[52:55]
	v_mfma_f32_16x16x32_bf16 v[48:51], v[222:225], v[146:149], v[48:51]
	v_mfma_f32_16x16x32_bf16 v[36:39], v[202:205], v[154:157], v[36:39]
	v_mfma_f32_16x16x32_bf16 v[32:35], v[222:225], v[154:157], v[32:35]
	v_mfma_f32_16x16x32_bf16 v[20:23], v[202:205], v[162:165], v[20:23]
	v_mfma_f32_16x16x32_bf16 v[16:19], v[222:225], v[162:165], v[16:19]
	v_mfma_f32_16x16x32_bf16 v[4:7], v[202:205], v[194:197], v[4:7]
	v_mfma_f32_16x16x32_bf16 v[0:3], v[222:225], v[194:197], v[0:3]
	v_mfma_f32_16x16x32_bf16 v[52:55], v[218:221], v[150:153], v[52:55]
	v_mfma_f32_16x16x32_bf16 v[48:51], v[228:231], v[150:153], v[48:51]
	v_mfma_f32_16x16x32_bf16 v[36:39], v[218:221], v[158:161], v[36:39]
	v_mfma_f32_16x16x32_bf16 v[32:35], v[228:231], v[158:161], v[32:35]
	v_mfma_f32_16x16x32_bf16 v[20:23], v[218:221], v[166:169], v[20:23]
	v_mfma_f32_16x16x32_bf16 v[16:19], v[228:231], v[166:169], v[16:19]
	v_mfma_f32_16x16x32_bf16 v[4:7], v[218:221], v[198:201], v[4:7]
	v_mfma_f32_16x16x32_bf16 v[0:3], v[228:231], v[198:201], v[0:3]
	s_setprio 0
	s_add_u32 s42, s42, 0x100
	s_addc_u32 s43, s43, 0
	s_add_u32 s33, s33, 0x100
	s_addc_u32 s37, s37, 0
	s_cmp_ge_u32 s56, s34
	s_mov_b32 s27, s56
	s_barrier
	s_cbranch_scc0 .LBB0_196
	v_lshl_add_u32 v194, s11, 8, v206
	v_ashrrev_i32_e32 v195, 31, v194
	v_lshl_or_b32 v196, s10, 8, v216
	v_lshlrev_b64 v[128:129], 11, v[194:195]
	v_ashrrev_i32_e32 v197, 31, v196
	s_and_b64 vcc, exec, s[92:93]
	v_or_b32_e32 v198, 16, v194
	v_lshl_add_u64 v[200:201], s[54:55], 0, v[128:129]
	s_cbranch_vccz .LBB0_215
	v_lshlrev_b64 v[128:129], 12, v[194:195]
	v_lshl_add_u64 v[128:129], s[50:51], 0, v[128:129]
	v_lshlrev_b64 v[130:131], 2, v[196:197]
	v_lshl_add_u64 v[128:129], v[128:129], 0, v[130:131]
	global_load_dwordx4 v[146:149], v[128:129], off offset:16
	global_load_dwordx4 v[150:153], v[128:129], off
	global_load_dwordx4 v[154:157], v[128:129], off offset:528
	global_load_dwordx4 v[158:161], v[128:129], off offset:512
	v_ashrrev_i32_e32 v199, 31, v198
	v_lshlrev_b64 v[128:129], 12, v[198:199]
	v_lshl_add_u64 v[128:129], s[50:51], 0, v[128:129]
	v_lshl_add_u64 v[132:133], v[128:129], 0, v[130:131]
	global_load_dwordx4 v[136:139], v[132:133], off offset:16
	global_load_dwordx4 v[140:143], v[132:133], off
	global_load_dwordx4 v[128:131], v[132:133], off offset:528
	s_nop 0
	global_load_dwordx4 v[132:135], v[132:133], off offset:512
	v_lshl_add_u64 v[166:167], v[196:197], 1, v[200:201]
	s_waitcnt vmcnt(0)
	v_pk_add_f32 v[164:165], v[120:121], v[146:147]
	v_pk_add_f32 v[152:153], v[126:127], v[152:153]
	v_pk_add_f32 v[150:151], v[124:125], v[150:151]
	v_pk_add_f32 v[162:163], v[122:123], v[148:149]
	v_cvt_pk_bf16_f32 v146, v150, v151
	v_cvt_pk_bf16_f32 v147, v152, v153
	v_cvt_pk_bf16_f32 v148, v164, v165
	v_pk_add_f32 v[156:157], v[114:115], v[156:157]
	v_cvt_pk_bf16_f32 v149, v162, v163
	global_store_dwordx4 v[166:167], v[146:149], off
	v_pk_add_f32 v[154:155], v[112:113], v[154:155]
	s_nop 0
	v_mul_f32_e32 v146, v151, v151
	v_mul_f32_e32 v147, v153, v153
	v_fmac_f32_e32 v146, v150, v150
	v_fmac_f32_e32 v147, v152, v152
	v_add_f32_e32 v146, v146, v147
	v_mul_f32_e32 v147, v165, v165
	v_mul_f32_e32 v148, v163, v163
	v_fmac_f32_e32 v147, v164, v164
	v_fmac_f32_e32 v148, v162, v162
	v_add_f32_e32 v147, v147, v148
	v_add_f32_e32 v162, v146, v147
	v_pk_add_f32 v[150:151], v[118:119], v[160:161]
	v_pk_add_f32 v[152:153], v[116:117], v[158:159]
	s_nop 0
	v_cvt_pk_bf16_f32 v146, v152, v153
	v_cvt_pk_bf16_f32 v147, v150, v151
	v_cvt_pk_bf16_f32 v148, v154, v155
	v_cvt_pk_bf16_f32 v149, v156, v157
	global_store_dwordx4 v[166:167], v[146:149], off offset:256
	s_nop 1
	v_mul_f32_e32 v146, v153, v153
	v_mul_f32_e32 v147, v151, v151
	v_fmac_f32_e32 v146, v152, v152
	v_fmac_f32_e32 v147, v150, v150
	v_add_f32_e32 v146, v146, v147
	v_mul_f32_e32 v147, v155, v155
	v_mul_f32_e32 v148, v157, v157
	v_fmac_f32_e32 v147, v154, v154
	v_fmac_f32_e32 v148, v156, v156
	v_add_f32_e32 v147, v147, v148
	v_and_b32_e32 v148, 64, v214
	v_add_f32_e32 v146, v146, v147
	v_xor_b32_e32 v147, 16, v214
	v_add_u32_e32 v148, 64, v148
	v_cmp_lt_i32_e32 vcc, v147, v148
	v_add_f32_e32 v146, v162, v146
	s_nop 0
	v_cndmask_b32_e32 v147, v214, v147, vcc
	v_lshlrev_b32_e32 v218, 2, v147
	ds_bpermute_b32 v147, v218, v146
	s_waitcnt lgkmcnt(0)
	v_add_f32_e32 v146, v146, v147
	v_xor_b32_e32 v147, 32, v214
	v_cmp_lt_i32_e32 vcc, v147, v148
	s_nop 1
	v_cndmask_b32_e32 v147, v214, v147, vcc
	v_lshlrev_b32_e32 v219, 2, v147
	ds_bpermute_b32 v147, v219, v146
	s_and_saveexec_b64 s[42:43], s[38:39]
	s_cbranch_execz .LBB0_200
	s_waitcnt lgkmcnt(0)
	v_add_f32_e32 v146, v146, v147
	v_fma_f32 v146, v146, s91, 0.5
	v_trunc_f32_e32 v146, v146
	v_mul_f32_e32 v147, 0x2f800000, v146
	v_floor_f32_e32 v147, v147
	v_fmac_f32_e32 v146, 0xcf800000, v147
	v_cvt_u32_f32_e32 v146, v146
	v_cvt_u32_f32_e32 v147, v147
	v_lshl_add_u64 v[148:149], v[194:195], 3, s[52:53]
	global_atomic_add_x2 v[148:149], v[146:147], off
.LBB0_200:
	s_or_b64 exec, exec, s[42:43]
	v_or_b32_e32 v202, 32, v194
	v_ashrrev_i32_e32 v203, 31, v202
	s_waitcnt lgkmcnt(0)
	v_lshlrev_b64 v[146:147], 12, v[202:203]
	v_lshl_add_u64 v[146:147], s[50:51], 0, v[146:147]
	v_lshl_add_u64 v[150:151], v[196:197], 2, v[146:147]
	global_load_dwordx4 v[154:157], v[150:151], off offset:16
	global_load_dwordx4 v[166:169], v[150:151], off
	global_load_dwordx4 v[146:149], v[150:151], off offset:528
	s_nop 0
	global_load_dwordx4 v[150:153], v[150:151], off offset:512
	v_pk_add_f32 v[140:141], v[108:109], v[140:141]
	v_pk_add_f32 v[142:143], v[110:111], v[142:143]
	v_pk_add_f32 v[162:163], v[104:105], v[136:137]
	v_cvt_pk_bf16_f32 v136, v140, v141
	v_mul_f32_e32 v141, v141, v141
	v_fmac_f32_e32 v141, v140, v140
	v_mul_f32_e32 v140, v143, v143
	v_pk_add_f32 v[160:161], v[106:107], v[138:139]
	v_fmac_f32_e32 v140, v142, v142
	v_cvt_pk_bf16_f32 v137, v142, v143
	v_add_f32_e32 v140, v141, v140
	v_mul_f32_e32 v141, v163, v163
	v_mul_f32_e32 v142, v161, v161
	v_fmac_f32_e32 v141, v162, v162
	v_fmac_f32_e32 v142, v160, v160
	v_pk_add_f32 v[134:135], v[102:103], v[134:135]
	v_pk_add_f32 v[132:133], v[100:101], v[132:133]
	v_add_f32_e32 v141, v141, v142
	v_pk_add_f32 v[142:143], v[96:97], v[128:129]
	v_mul_f32_e32 v128, v133, v133
	v_mul_f32_e32 v129, v135, v135
	v_cvt_pk_bf16_f32 v138, v162, v163
	v_cvt_pk_bf16_f32 v139, v160, v161
	v_add_f32_e32 v160, v140, v141
	v_pk_add_f32 v[140:141], v[98:99], v[130:131]
	v_fmac_f32_e32 v128, v132, v132
	v_fmac_f32_e32 v129, v134, v134
	v_add_f32_e32 v128, v128, v129
	v_mul_f32_e32 v129, v143, v143
	v_mul_f32_e32 v130, v141, v141
	v_fmac_f32_e32 v129, v142, v142
	v_fmac_f32_e32 v130, v140, v140
	v_add_f32_e32 v129, v129, v130
	v_add_f32_e32 v128, v128, v129
	v_add_f32_e32 v131, v160, v128
	ds_bpermute_b32 v160, v218, v131
	v_lshlrev_b64 v[158:159], 11, v[198:199]
	v_lshl_add_u64 v[128:129], s[54:55], 0, v[158:159]
	v_lshl_add_u64 v[158:159], v[196:197], 1, v[128:129]
	global_store_dwordx4 v[158:159], v[136:139], off
	s_waitcnt lgkmcnt(0)
	v_add_f32_e32 v128, v131, v160
	ds_bpermute_b32 v129, v219, v128
	v_cvt_pk_bf16_f32 v130, v132, v133
	v_cvt_pk_bf16_f32 v131, v134, v135
	v_cvt_pk_bf16_f32 v132, v142, v143
	v_cvt_pk_bf16_f32 v133, v140, v141
	global_store_dwordx4 v[158:159], v[130:133], off offset:256
	s_and_saveexec_b64 s[42:43], s[38:39]
	s_cbranch_execz .LBB0_202
	s_waitcnt lgkmcnt(0)
	v_add_f32_e32 v128, v128, v129
	v_fma_f32 v128, v128, s91, 0.5
	v_trunc_f32_e32 v128, v128
	v_mul_f32_e32 v129, 0x2f800000, v128
	v_floor_f32_e32 v129, v129
	v_fmac_f32_e32 v128, 0xcf800000, v129
	v_cvt_u32_f32_e32 v128, v128
	v_cvt_u32_f32_e32 v129, v129
	v_lshl_add_u64 v[130:131], v[194:195], 3, s[52:53]
	global_atomic_add_x2 v[130:131], v[128:129], off offset:128
.LBB0_202:
	s_or_b64 exec, exec, s[42:43]
	v_or_b32_e32 v204, 48, v194
	v_ashrrev_i32_e32 v205, 31, v204
	s_waitcnt lgkmcnt(0)
	v_lshlrev_b64 v[128:129], 12, v[204:205]
	v_lshl_add_u64 v[128:129], s[50:51], 0, v[128:129]
	v_lshl_add_u64 v[132:133], v[196:197], 2, v[128:129]
	global_load_dwordx4 v[158:161], v[132:133], off offset:16
	global_load_dwordx4 v[162:165], v[132:133], off
	global_load_dwordx4 v[128:131], v[132:133], off offset:528
	global_load_dwordx4 v[140:143], v[132:133], off offset:512
	s_waitcnt vmcnt(8)
	v_pk_add_f32 v[138:139], v[94:95], v[168:169]
	v_pk_add_f32 v[166:167], v[92:93], v[166:167]
	v_pk_add_f32 v[154:155], v[88:89], v[154:155]
	v_cvt_pk_bf16_f32 v132, v166, v167
	v_cvt_pk_bf16_f32 v133, v138, v139
	v_mul_f32_e32 v167, v167, v167
	v_mul_f32_e32 v139, v139, v139
	v_fmac_f32_e32 v167, v166, v166
	v_fmac_f32_e32 v139, v138, v138
	v_pk_add_f32 v[156:157], v[90:91], v[156:157]
	v_add_f32_e32 v138, v167, v139
	v_mul_f32_e32 v139, v155, v155
	v_cvt_pk_bf16_f32 v134, v154, v155
	v_fmac_f32_e32 v139, v154, v154
	v_mul_f32_e32 v154, v157, v157
	v_fmac_f32_e32 v154, v156, v156
	v_add_f32_e32 v139, v139, v154
	v_add_f32_e32 v154, v138, v139
	s_waitcnt vmcnt(6)
	v_pk_add_f32 v[138:139], v[86:87], v[152:153]
	v_pk_add_f32 v[150:151], v[84:85], v[150:151]
	v_mul_f32_e32 v153, v139, v139
	v_mul_f32_e32 v152, v151, v151
	v_pk_add_f32 v[148:149], v[82:83], v[148:149]
	v_pk_add_f32 v[146:147], v[80:81], v[146:147]
	v_fmac_f32_e32 v152, v150, v150
	v_fmac_f32_e32 v153, v138, v138
	v_add_f32_e32 v152, v152, v153
	v_mul_f32_e32 v153, v147, v147
	v_mul_f32_e32 v155, v149, v149
	v_fmac_f32_e32 v153, v146, v146
	v_fmac_f32_e32 v155, v148, v148
	v_add_f32_e32 v153, v153, v155
	v_add_f32_e32 v152, v152, v153
	v_add_f32_e32 v154, v154, v152
	ds_bpermute_b32 v155, v218, v154
	v_lshlrev_b64 v[136:137], 11, v[202:203]
	v_lshl_add_u64 v[136:137], s[54:55], 0, v[136:137]
	v_lshl_add_u64 v[152:153], v[196:197], 1, v[136:137]
	v_cvt_pk_bf16_f32 v135, v156, v157
	global_store_dwordx4 v[152:153], v[132:135], off
	s_waitcnt lgkmcnt(0)
	s_nop 0
	v_add_f32_e32 v132, v154, v155
	ds_bpermute_b32 v133, v219, v132
	v_cvt_pk_bf16_f32 v134, v150, v151
	v_cvt_pk_bf16_f32 v135, v138, v139
	v_cvt_pk_bf16_f32 v136, v146, v147
	v_cvt_pk_bf16_f32 v137, v148, v149
	global_store_dwordx4 v[152:153], v[134:137], off offset:256
	s_and_saveexec_b64 s[42:43], s[38:39]
	s_cbranch_execz .LBB0_204
	s_waitcnt lgkmcnt(0)
	v_add_f32_e32 v132, v132, v133
	v_fma_f32 v132, v132, s91, 0.5
	v_trunc_f32_e32 v132, v132
	v_mul_f32_e32 v133, 0x2f800000, v132
	v_floor_f32_e32 v133, v133
	v_fmac_f32_e32 v132, 0xcf800000, v133
	v_cvt_u32_f32_e32 v132, v132
	v_cvt_u32_f32_e32 v133, v133
	v_lshl_add_u64 v[134:135], v[194:195], 3, s[52:53]
	global_atomic_add_x2 v[134:135], v[132:133], off offset:256
.LBB0_204:
	s_or_b64 exec, exec, s[42:43]
	v_add_u32_e32 v166, 0x80, v194
	v_ashrrev_i32_e32 v167, 31, v166
	s_waitcnt lgkmcnt(0)
	v_lshlrev_b64 v[132:133], 12, v[166:167]
	v_lshl_add_u64 v[132:133], s[50:51], 0, v[132:133]
	v_lshl_add_u64 v[136:137], v[196:197], 2, v[132:133]
	global_load_dwordx4 v[146:149], v[136:137], off offset:16
	global_load_dwordx4 v[154:157], v[136:137], off
	global_load_dwordx4 v[132:135], v[136:137], off offset:528
	s_nop 0
	global_load_dwordx4 v[136:139], v[136:137], off offset:512
	s_waitcnt vmcnt(8)
	v_pk_add_f32 v[162:163], v[76:77], v[162:163]
	v_pk_add_f32 v[158:159], v[72:73], v[158:159]
	v_pk_add_f32 v[164:165], v[78:79], v[164:165]
	v_pk_add_f32 v[160:161], v[74:75], v[160:161]
	v_cvt_pk_bf16_f32 v150, v162, v163
	v_cvt_pk_bf16_f32 v151, v164, v165
	v_cvt_pk_bf16_f32 v152, v158, v159
	v_mul_f32_e32 v163, v163, v163
	v_mul_f32_e32 v159, v159, v159
	v_fmac_f32_e32 v163, v162, v162
	v_mul_f32_e32 v162, v165, v165
	v_fmac_f32_e32 v159, v158, v158
	v_mul_f32_e32 v158, v161, v161
	v_fmac_f32_e32 v162, v164, v164
	v_fmac_f32_e32 v158, v160, v160
	v_add_f32_e32 v162, v163, v162
	v_add_f32_e32 v158, v159, v158
	s_waitcnt vmcnt(6)
	v_pk_add_f32 v[142:143], v[70:71], v[142:143]
	v_pk_add_f32 v[140:141], v[68:69], v[140:141]
	v_cvt_pk_bf16_f32 v153, v160, v161
	v_add_f32_e32 v160, v162, v158
	v_pk_add_f32 v[158:159], v[64:65], v[128:129]
	v_mul_f32_e32 v128, v141, v141
	v_mul_f32_e32 v129, v143, v143
	v_pk_add_f32 v[130:131], v[66:67], v[130:131]
	v_fmac_f32_e32 v128, v140, v140
	v_fmac_f32_e32 v129, v142, v142
	v_add_f32_e32 v128, v128, v129
	v_mul_f32_e32 v129, v159, v159
	v_mul_f32_e32 v161, v131, v131
	v_fmac_f32_e32 v129, v158, v158
	v_fmac_f32_e32 v161, v130, v130
	v_add_f32_e32 v129, v129, v161
	v_add_f32_e32 v128, v128, v129
	v_add_f32_e32 v162, v160, v128
	ds_bpermute_b32 v163, v218, v162
	v_lshlrev_b64 v[168:169], 11, v[204:205]
	v_lshl_add_u64 v[128:129], s[54:55], 0, v[168:169]
	v_lshl_add_u64 v[160:161], v[196:197], 1, v[128:129]
	global_store_dwordx4 v[160:161], v[150:153], off
	s_waitcnt lgkmcnt(0)
	v_add_f32_e32 v128, v162, v163
	ds_bpermute_b32 v129, v219, v128
	v_cvt_pk_bf16_f32 v140, v140, v141
	v_cvt_pk_bf16_f32 v141, v142, v143
	v_cvt_pk_bf16_f32 v142, v158, v159
	v_cvt_pk_bf16_f32 v143, v130, v131
	global_store_dwordx4 v[160:161], v[140:143], off offset:256
	s_and_saveexec_b64 s[42:43], s[38:39]
	s_cbranch_execz .LBB0_206
	s_waitcnt lgkmcnt(0)
	v_add_f32_e32 v128, v128, v129
	v_fma_f32 v128, v128, s91, 0.5
	v_trunc_f32_e32 v128, v128
	v_mul_f32_e32 v129, 0x2f800000, v128
	v_floor_f32_e32 v129, v129
	v_fmac_f32_e32 v128, 0xcf800000, v129
	v_cvt_u32_f32_e32 v128, v128
	v_cvt_u32_f32_e32 v129, v129
	v_lshl_add_u64 v[130:131], v[194:195], 3, s[52:53]
	global_atomic_add_x2 v[130:131], v[128:129], off offset:384
.LBB0_206:
	s_or_b64 exec, exec, s[42:43]
	v_or_b32_e32 v162, 16, v166
	v_ashrrev_i32_e32 v163, 31, v162
	s_waitcnt lgkmcnt(0)
	v_lshlrev_b64 v[128:129], 12, v[162:163]
	v_lshl_add_u64 v[128:129], s[50:51], 0, v[128:129]
	v_lshl_add_u64 v[140:141], v[196:197], 2, v[128:129]
	global_load_dwordx4 v[150:153], v[140:141], off offset:16
	global_load_dwordx4 v[158:161], v[140:141], off
	global_load_dwordx4 v[128:131], v[140:141], off offset:528
	s_nop 0
	global_load_dwordx4 v[140:143], v[140:141], off offset:512
	s_waitcnt vmcnt(8)
	v_pk_add_f32 v[154:155], v[60:61], v[154:155]
	v_pk_add_f32 v[156:157], v[62:63], v[156:157]
	v_pk_add_f32 v[176:177], v[56:57], v[146:147]
	v_cvt_pk_bf16_f32 v146, v154, v155
	v_mul_f32_e32 v155, v155, v155
	v_fmac_f32_e32 v155, v154, v154
	v_mul_f32_e32 v154, v157, v157
	v_pk_add_f32 v[168:169], v[58:59], v[148:149]
	v_fmac_f32_e32 v154, v156, v156
	v_cvt_pk_bf16_f32 v147, v156, v157
	v_add_f32_e32 v154, v155, v154
	v_mul_f32_e32 v155, v177, v177
	v_mul_f32_e32 v156, v169, v169
	v_fmac_f32_e32 v155, v176, v176
	v_fmac_f32_e32 v156, v168, v168
	s_waitcnt vmcnt(6)
	v_pk_add_f32 v[138:139], v[54:55], v[138:139]
	v_pk_add_f32 v[136:137], v[52:53], v[136:137]
	v_add_f32_e32 v155, v155, v156
	v_pk_add_f32 v[156:157], v[48:49], v[132:133]
	v_mul_f32_e32 v132, v137, v137
	v_mul_f32_e32 v133, v139, v139
	v_lshlrev_b64 v[164:165], 11, v[166:167]
	v_add_f32_e32 v167, v154, v155
	v_pk_add_f32 v[154:155], v[50:51], v[134:135]
	v_fmac_f32_e32 v132, v136, v136
	v_fmac_f32_e32 v133, v138, v138
	v_add_f32_e32 v132, v132, v133
	v_mul_f32_e32 v133, v157, v157
	v_mul_f32_e32 v134, v155, v155
	v_fmac_f32_e32 v133, v156, v156
	v_fmac_f32_e32 v134, v154, v154
	v_add_f32_e32 v133, v133, v134
	v_add_f32_e32 v132, v132, v133
	v_add_f32_e32 v135, v167, v132
	ds_bpermute_b32 v167, v218, v135
	v_lshl_add_u64 v[132:133], s[54:55], 0, v[164:165]
	v_lshl_add_u64 v[164:165], v[196:197], 1, v[132:133]
	v_cvt_pk_bf16_f32 v148, v176, v177
	v_cvt_pk_bf16_f32 v149, v168, v169
	s_waitcnt lgkmcnt(0)
	v_add_f32_e32 v132, v135, v167
	ds_bpermute_b32 v133, v219, v132
	global_store_dwordx4 v[164:165], v[146:149], off
	v_cvt_pk_bf16_f32 v134, v136, v137
	v_cvt_pk_bf16_f32 v135, v138, v139
	v_cvt_pk_bf16_f32 v136, v156, v157
	v_cvt_pk_bf16_f32 v137, v154, v155
	global_store_dwordx4 v[164:165], v[134:137], off offset:256
	s_and_saveexec_b64 s[42:43], s[38:39]
	s_cbranch_execz .LBB0_208
	s_waitcnt lgkmcnt(0)
	v_add_f32_e32 v132, v132, v133
	v_fma_f32 v132, v132, s91, 0.5
	v_trunc_f32_e32 v132, v132
	v_mul_f32_e32 v133, 0x2f800000, v132
	v_floor_f32_e32 v133, v133
	v_fmac_f32_e32 v132, 0xcf800000, v133
	v_cvt_u32_f32_e32 v132, v132
	v_cvt_u32_f32_e32 v133, v133
	v_lshl_add_u64 v[134:135], v[194:195], 3, s[52:53]
	global_atomic_add_x2 v[134:135], v[132:133], off offset:1024
.LBB0_208:
	s_or_b64 exec, exec, s[42:43]
	v_or_b32_e32 v164, 32, v166
	v_ashrrev_i32_e32 v165, 31, v164
	s_waitcnt lgkmcnt(0)
	v_lshlrev_b64 v[132:133], 12, v[164:165]
	v_lshl_add_u64 v[132:133], s[50:51], 0, v[132:133]
	v_lshl_add_u64 v[136:137], v[196:197], 2, v[132:133]
	global_load_dwordx4 v[146:149], v[136:137], off offset:16
	global_load_dwordx4 v[154:157], v[136:137], off
	global_load_dwordx4 v[132:135], v[136:137], off offset:528
	s_nop 0
	global_load_dwordx4 v[136:139], v[136:137], off offset:512
	s_waitcnt vmcnt(8)
	v_pk_add_f32 v[158:159], v[44:45], v[158:159]
	v_pk_add_f32 v[160:161], v[46:47], v[160:161]
	v_pk_add_f32 v[176:177], v[40:41], v[150:151]
	v_cvt_pk_bf16_f32 v150, v158, v159
	v_mul_f32_e32 v159, v159, v159
	v_fmac_f32_e32 v159, v158, v158
	v_mul_f32_e32 v158, v161, v161
	v_pk_add_f32 v[168:169], v[42:43], v[152:153]
	v_fmac_f32_e32 v158, v160, v160
	v_cvt_pk_bf16_f32 v151, v160, v161
	v_add_f32_e32 v158, v159, v158
	v_mul_f32_e32 v159, v177, v177
	v_mul_f32_e32 v160, v169, v169
	v_fmac_f32_e32 v159, v176, v176
	v_fmac_f32_e32 v160, v168, v168
	v_add_f32_e32 v159, v159, v160
	s_waitcnt vmcnt(6)
	v_pk_add_f32 v[142:143], v[38:39], v[142:143]
	v_pk_add_f32 v[140:141], v[36:37], v[140:141]
	v_add_f32_e32 v160, v158, v159
	v_pk_add_f32 v[158:159], v[32:33], v[128:129]
	v_mul_f32_e32 v128, v141, v141
	v_mul_f32_e32 v129, v143, v143
	v_pk_add_f32 v[130:131], v[34:35], v[130:131]
	v_fmac_f32_e32 v128, v140, v140
	v_fmac_f32_e32 v129, v142, v142
	v_add_f32_e32 v128, v128, v129
	v_mul_f32_e32 v129, v159, v159
	v_mul_f32_e32 v161, v131, v131
	v_fmac_f32_e32 v129, v158, v158
	v_fmac_f32_e32 v161, v130, v130
	v_add_f32_e32 v129, v129, v161
	v_add_f32_e32 v128, v128, v129
	v_add_f32_e32 v167, v160, v128
	v_cvt_pk_bf16_f32 v152, v176, v177
	v_cvt_pk_bf16_f32 v153, v168, v169
	ds_bpermute_b32 v168, v218, v167
	v_lshlrev_b64 v[162:163], 11, v[162:163]
	v_lshl_add_u64 v[128:129], s[54:55], 0, v[162:163]
	v_lshl_add_u64 v[160:161], v[196:197], 1, v[128:129]
	global_store_dwordx4 v[160:161], v[150:153], off
	s_waitcnt lgkmcnt(0)
	v_add_f32_e32 v128, v167, v168
	ds_bpermute_b32 v129, v219, v128
	v_cvt_pk_bf16_f32 v140, v140, v141
	v_cvt_pk_bf16_f32 v141, v142, v143
	v_cvt_pk_bf16_f32 v142, v158, v159
	v_cvt_pk_bf16_f32 v143, v130, v131
	global_store_dwordx4 v[160:161], v[140:143], off offset:256
	s_and_saveexec_b64 s[42:43], s[38:39]
	s_cbranch_execz .LBB0_210
	s_waitcnt lgkmcnt(0)
	v_add_f32_e32 v128, v128, v129
	v_fma_f32 v128, v128, s91, 0.5
	v_trunc_f32_e32 v128, v128
	v_mul_f32_e32 v129, 0x2f800000, v128
	v_floor_f32_e32 v129, v129
	v_fmac_f32_e32 v128, 0xcf800000, v129
	v_cvt_u32_f32_e32 v128, v128
	v_cvt_u32_f32_e32 v129, v129
	v_lshl_add_u64 v[130:131], v[194:195], 3, s[52:53]
	global_atomic_add_x2 v[130:131], v[128:129], off offset:1152
.LBB0_210:
	s_or_b64 exec, exec, s[42:43]
	v_or_b32_e32 v162, 48, v166
	v_ashrrev_i32_e32 v163, 31, v162
	s_waitcnt lgkmcnt(0)
	v_lshlrev_b64 v[128:129], 12, v[162:163]
	v_lshl_add_u64 v[128:129], s[50:51], 0, v[128:129]
	v_lshl_add_u64 v[140:141], v[196:197], 2, v[128:129]
	global_load_dwordx4 v[150:153], v[140:141], off offset:16
	global_load_dwordx4 v[158:161], v[140:141], off
	global_load_dwordx4 v[128:131], v[140:141], off offset:528
	s_nop 0
	global_load_dwordx4 v[140:143], v[140:141], off offset:512
	s_waitcnt vmcnt(8)
	v_pk_add_f32 v[154:155], v[28:29], v[154:155]
	v_pk_add_f32 v[156:157], v[30:31], v[156:157]
	v_pk_add_f32 v[168:169], v[24:25], v[146:147]
	v_cvt_pk_bf16_f32 v146, v154, v155
	v_mul_f32_e32 v155, v155, v155
	v_fmac_f32_e32 v155, v154, v154
	v_mul_f32_e32 v154, v157, v157
	v_pk_add_f32 v[166:167], v[26:27], v[148:149]
	v_fmac_f32_e32 v154, v156, v156
	v_cvt_pk_bf16_f32 v147, v156, v157
	v_add_f32_e32 v154, v155, v154
	v_mul_f32_e32 v155, v169, v169
	v_mul_f32_e32 v156, v167, v167
	v_fmac_f32_e32 v155, v168, v168
	v_fmac_f32_e32 v156, v166, v166
	s_waitcnt vmcnt(6)
	v_pk_add_f32 v[138:139], v[22:23], v[138:139]
	v_pk_add_f32 v[136:137], v[20:21], v[136:137]
	v_add_f32_e32 v155, v155, v156
	v_pk_add_f32 v[156:157], v[16:17], v[132:133]
	v_mul_f32_e32 v132, v137, v137
	v_mul_f32_e32 v133, v139, v139
	v_cvt_pk_bf16_f32 v148, v168, v169
	v_cvt_pk_bf16_f32 v149, v166, v167
	v_add_f32_e32 v166, v154, v155
	v_pk_add_f32 v[154:155], v[18:19], v[134:135]
	v_fmac_f32_e32 v132, v136, v136
	v_fmac_f32_e32 v133, v138, v138
	v_add_f32_e32 v132, v132, v133
	v_mul_f32_e32 v133, v157, v157
	v_mul_f32_e32 v134, v155, v155
	v_fmac_f32_e32 v133, v156, v156
	v_fmac_f32_e32 v134, v154, v154
	v_add_f32_e32 v133, v133, v134
	v_add_f32_e32 v132, v132, v133
	v_add_f32_e32 v135, v166, v132
	ds_bpermute_b32 v166, v218, v135
	v_lshlrev_b64 v[164:165], 11, v[164:165]
	v_lshl_add_u64 v[132:133], s[54:55], 0, v[164:165]
	v_lshl_add_u64 v[164:165], v[196:197], 1, v[132:133]
	global_store_dwordx4 v[164:165], v[146:149], off
	s_waitcnt lgkmcnt(0)
	v_add_f32_e32 v132, v135, v166
	ds_bpermute_b32 v133, v219, v132
	v_cvt_pk_bf16_f32 v134, v136, v137
	v_cvt_pk_bf16_f32 v135, v138, v139
	v_cvt_pk_bf16_f32 v136, v156, v157
	v_cvt_pk_bf16_f32 v137, v154, v155
	global_store_dwordx4 v[164:165], v[134:137], off offset:256
	s_and_saveexec_b64 s[42:43], s[38:39]
	s_cbranch_execz .LBB0_212
	s_waitcnt lgkmcnt(0)
	v_add_f32_e32 v132, v132, v133
	v_fma_f32 v132, v132, s91, 0.5
	v_trunc_f32_e32 v132, v132
	v_mul_f32_e32 v133, 0x2f800000, v132
	v_floor_f32_e32 v133, v133
	v_fmac_f32_e32 v132, 0xcf800000, v133
	v_cvt_u32_f32_e32 v132, v132
	v_cvt_u32_f32_e32 v133, v133
	v_lshl_add_u64 v[134:135], v[194:195], 3, s[52:53]
	global_atomic_add_x2 v[134:135], v[132:133], off offset:1280
.LBB0_212:
	s_or_b64 exec, exec, s[42:43]
	s_waitcnt vmcnt(4)
	v_pk_add_f32 v[138:139], v[14:15], v[160:161]
	v_pk_add_f32 v[146:147], v[12:13], v[158:159]
	v_pk_add_f32 v[148:149], v[10:11], v[152:153]
	v_cvt_pk_bf16_f32 v132, v146, v147
	s_waitcnt lgkmcnt(0)
	v_cvt_pk_bf16_f32 v133, v138, v139
	v_mul_f32_e32 v147, v147, v147
	v_mul_f32_e32 v139, v139, v139
	v_pk_add_f32 v[150:151], v[8:9], v[150:151]
	v_fmac_f32_e32 v147, v146, v146
	v_fmac_f32_e32 v139, v138, v138
	v_add_f32_e32 v138, v147, v139
	v_mul_f32_e32 v139, v151, v151
	v_mul_f32_e32 v146, v149, v149
	v_fmac_f32_e32 v139, v150, v150
	v_fmac_f32_e32 v146, v148, v148
	v_add_f32_e32 v139, v139, v146
	v_cvt_pk_bf16_f32 v134, v150, v151
	v_cvt_pk_bf16_f32 v135, v148, v149
	v_add_f32_e32 v148, v138, v139
	s_waitcnt vmcnt(2)
	v_pk_add_f32 v[138:139], v[6:7], v[142:143]
	v_pk_add_f32 v[140:141], v[4:5], v[140:141]
	v_pk_add_f32 v[146:147], v[0:1], v[128:129]
	v_mul_f32_e32 v128, v141, v141
	v_mul_f32_e32 v129, v139, v139
	v_pk_add_f32 v[142:143], v[2:3], v[130:131]
	v_fmac_f32_e32 v128, v140, v140
	v_fmac_f32_e32 v129, v138, v138
	v_add_f32_e32 v128, v128, v129
	v_mul_f32_e32 v129, v147, v147
	v_mul_f32_e32 v130, v143, v143
	v_fmac_f32_e32 v129, v146, v146
	v_fmac_f32_e32 v130, v142, v142
	v_add_f32_e32 v129, v129, v130
	v_add_f32_e32 v128, v128, v129
	v_add_f32_e32 v131, v148, v128
	ds_bpermute_b32 v148, v218, v131
	v_lshlrev_b64 v[136:137], 11, v[162:163]
	v_lshl_add_u64 v[128:129], s[54:55], 0, v[136:137]
	v_lshl_add_u64 v[136:137], v[196:197], 1, v[128:129]
	global_store_dwordx4 v[136:137], v[132:135], off
	s_waitcnt lgkmcnt(0)
	v_add_f32_e32 v128, v131, v148
	ds_bpermute_b32 v129, v219, v128
	v_cvt_pk_bf16_f32 v130, v140, v141
	v_cvt_pk_bf16_f32 v131, v138, v139
	v_cvt_pk_bf16_f32 v132, v146, v147
	v_cvt_pk_bf16_f32 v133, v142, v143
	global_store_dwordx4 v[136:137], v[130:133], off offset:256
	s_and_saveexec_b64 s[42:43], s[38:39]
	s_cbranch_execz .LBB0_214
	s_waitcnt lgkmcnt(0)
	v_add_f32_e32 v128, v128, v129
	v_fma_f32 v128, v128, s91, 0.5
	v_trunc_f32_e32 v128, v128
	v_mul_f32_e32 v129, 0x2f800000, v128
	v_floor_f32_e32 v129, v129
	v_fmac_f32_e32 v128, 0xcf800000, v129
	v_cvt_u32_f32_e32 v128, v128
	v_cvt_u32_f32_e32 v129, v129
	v_lshl_add_u64 v[130:131], v[194:195], 3, s[52:53]
	global_atomic_add_x2 v[130:131], v[128:129], off offset:1408

.LBB0_218:
	s_andn2_b64 vcc, exec, s[42:43]
	v_mov_b32_e32 v148, 0
	s_cbranch_vccnz .LBB0_220
	v_cvt_pk_bf16_f32 v148, v124, v125
	v_cvt_pk_bf16_f32 v149, v126, v127
	v_cvt_pk_bf16_f32 v150, v120, v121
	v_cvt_pk_bf16_f32 v151, v122, v123
	global_store_dwordx4 v[142:143], v[148:151], off
	s_nop 1
	v_mov_b32_e32 v149, v120
	v_mov_b32_e32 v120, v125
	v_mov_b32_e32 v125, v122
	v_mov_b32_e32 v122, v127
	v_mov_b32_e32 v148, v124
	v_pk_mul_f32 v[120:121], v[120:121], v[120:121]
	v_mov_b32_e32 v124, v126
	v_pk_mul_f32 v[122:123], v[122:123], v[122:123]
	v_pk_fma_f32 v[120:121], v[148:149], v[148:149], v[120:121]
	v_pk_fma_f32 v[122:123], v[124:125], v[124:125], v[122:123]
	s_nop 0
	v_pk_add_f32 v[120:121], v[120:121], v[122:123]
	s_nop 0
	v_add_f32_e32 v148, v120, v121

.LBB0_224:
	s_nop 0
	v_cvt_pk_bf16_f32 v120, v116, v117
	v_cvt_pk_bf16_f32 v121, v118, v119
	v_cvt_pk_bf16_f32 v122, v112, v113
	v_cvt_pk_bf16_f32 v123, v114, v115
	global_store_dwordx4 v[142:143], v[120:123], off offset:256
	s_nop 1
	v_mov_b32_e32 v121, v112
	v_mov_b32_e32 v112, v117
	v_mov_b32_e32 v117, v114
	v_mov_b32_e32 v114, v119
	v_mov_b32_e32 v120, v116
	v_pk_mul_f32 v[112:113], v[112:113], v[112:113]
	v_mov_b32_e32 v116, v118
	v_pk_mul_f32 v[114:115], v[114:115], v[114:115]
	v_pk_fma_f32 v[112:113], v[120:121], v[120:121], v[112:113]
	v_pk_fma_f32 v[114:115], v[116:117], v[116:117], v[114:115]
	s_nop 0
	v_pk_add_f32 v[112:113], v[112:113], v[114:115]
	s_nop 0
	v_add_f32_e32 v112, v112, v113
	v_add_f32_e32 v148, v112, v148
	v_cndmask_b32_e64 v112, 0, 1, s[72:73]
	v_cmp_ne_u32_e64 s[44:45], 1, v112
	s_andn2_b64 vcc, exec, s[72:73]
	s_cbranch_vccnz .LBB0_228

.LBB0_230:
	s_andn2_b64 vcc, exec, s[78:79]
	v_mov_b32_e32 v126, 0
	s_cbranch_vccnz .LBB0_232
	v_cvt_pk_bf16_f32 v132, v108, v109
	v_cvt_pk_bf16_f32 v133, v110, v111
	v_cvt_pk_bf16_f32 v134, v104, v105
	v_cvt_pk_bf16_f32 v135, v106, v107
	v_mov_b32_e32 v127, v104
	v_mov_b32_e32 v104, v109
	v_mov_b32_e32 v109, v106
	v_mov_b32_e32 v106, v111
	v_mov_b32_e32 v126, v108
	v_pk_mul_f32 v[104:105], v[104:105], v[104:105]
	v_mov_b32_e32 v108, v110
	v_pk_mul_f32 v[106:107], v[106:107], v[106:107]
	v_pk_fma_f32 v[104:105], v[126:127], v[126:127], v[104:105]
	v_pk_fma_f32 v[106:107], v[108:109], v[108:109], v[106:107]
	global_store_dwordx4 v[140:141], v[132:135], off
	v_pk_add_f32 v[104:105], v[104:105], v[106:107]
	s_nop 0
	v_add_f32_e32 v126, v104, v105

.LBB0_236:
	s_nop 0
	v_cvt_pk_bf16_f32 v104, v100, v101
	v_cvt_pk_bf16_f32 v105, v102, v103
	v_cvt_pk_bf16_f32 v106, v96, v97
	v_cvt_pk_bf16_f32 v107, v98, v99
	global_store_dwordx4 v[140:141], v[104:107], off offset:256
	s_nop 1
	v_mov_b32_e32 v105, v96
	v_mov_b32_e32 v96, v101
	v_mov_b32_e32 v101, v98
	v_mov_b32_e32 v98, v103
	v_mov_b32_e32 v104, v100
	v_pk_mul_f32 v[96:97], v[96:97], v[96:97]
	v_mov_b32_e32 v100, v102
	v_pk_mul_f32 v[98:99], v[98:99], v[98:99]
	v_pk_fma_f32 v[96:97], v[104:105], v[104:105], v[96:97]
	v_pk_fma_f32 v[98:99], v[100:101], v[100:101], v[98:99]
	s_nop 0
	v_pk_add_f32 v[96:97], v[96:97], v[98:99]
	s_nop 0
	v_add_f32_e32 v96, v96, v97
	v_add_f32_e32 v126, v96, v126
	s_and_b64 vcc, exec, s[44:45]
	s_cbranch_vccnz .LBB0_240

.LBB0_242:
	s_andn2_b64 vcc, exec, s[78:79]
	v_mov_b32_e32 v110, 0
	s_cbranch_vccnz .LBB0_244
	v_cvt_pk_bf16_f32 v116, v92, v93
	v_cvt_pk_bf16_f32 v117, v94, v95
	v_cvt_pk_bf16_f32 v118, v88, v89
	v_cvt_pk_bf16_f32 v119, v90, v91
	v_mov_b32_e32 v111, v88
	v_mov_b32_e32 v88, v93
	v_mov_b32_e32 v93, v90
	v_mov_b32_e32 v90, v95
	v_mov_b32_e32 v110, v92
	v_pk_mul_f32 v[88:89], v[88:89], v[88:89]
	v_mov_b32_e32 v92, v94
	v_pk_mul_f32 v[90:91], v[90:91], v[90:91]
	v_pk_fma_f32 v[88:89], v[110:111], v[110:111], v[88:89]
	v_pk_fma_f32 v[90:91], v[92:93], v[92:93], v[90:91]
	global_store_dwordx4 v[120:121], v[116:119], off
	v_pk_add_f32 v[88:89], v[88:89], v[90:91]
	s_nop 0
	v_add_f32_e32 v110, v88, v89

.LBB0_248:
	s_nop 0
	v_cvt_pk_bf16_f32 v88, v84, v85
	v_cvt_pk_bf16_f32 v89, v86, v87
	v_cvt_pk_bf16_f32 v90, v80, v81
	v_cvt_pk_bf16_f32 v91, v82, v83
	global_store_dwordx4 v[120:121], v[88:91], off offset:256
	s_nop 1
	v_mov_b32_e32 v89, v80
	v_mov_b32_e32 v80, v85
	v_mov_b32_e32 v85, v82
	v_mov_b32_e32 v82, v87
	v_mov_b32_e32 v88, v84
	v_pk_mul_f32 v[80:81], v[80:81], v[80:81]
	v_mov_b32_e32 v84, v86
	v_pk_mul_f32 v[82:83], v[82:83], v[82:83]
	v_pk_fma_f32 v[80:81], v[88:89], v[88:89], v[80:81]
	v_pk_fma_f32 v[82:83], v[84:85], v[84:85], v[82:83]
	s_nop 0
	v_pk_add_f32 v[80:81], v[80:81], v[82:83]
	s_nop 0
	v_add_f32_e32 v80, v80, v81
	v_add_f32_e32 v110, v80, v110
	s_and_b64 vcc, exec, s[44:45]
	s_cbranch_vccnz .LBB0_252

.LBB0_254:
	s_andn2_b64 vcc, exec, s[78:79]
	v_mov_b32_e32 v94, 0
	s_cbranch_vccnz .LBB0_256
	v_cvt_pk_bf16_f32 v100, v76, v77
	v_cvt_pk_bf16_f32 v101, v78, v79
	v_cvt_pk_bf16_f32 v102, v72, v73
	v_cvt_pk_bf16_f32 v103, v74, v75
	v_mov_b32_e32 v95, v72
	v_mov_b32_e32 v72, v77
	v_mov_b32_e32 v77, v74
	v_mov_b32_e32 v74, v79
	v_mov_b32_e32 v94, v76
	v_pk_mul_f32 v[72:73], v[72:73], v[72:73]
	v_mov_b32_e32 v76, v78
	v_pk_mul_f32 v[74:75], v[74:75], v[74:75]
	v_pk_fma_f32 v[72:73], v[94:95], v[94:95], v[72:73]
	v_pk_fma_f32 v[74:75], v[76:77], v[76:77], v[74:75]
	global_store_dwordx4 v[104:105], v[100:103], off
	v_pk_add_f32 v[72:73], v[72:73], v[74:75]
	s_nop 0
	v_add_f32_e32 v94, v72, v73

.LBB0_260:
	s_nop 0
	v_cvt_pk_bf16_f32 v72, v68, v69
	v_cvt_pk_bf16_f32 v73, v70, v71
	v_cvt_pk_bf16_f32 v74, v64, v65
	v_cvt_pk_bf16_f32 v75, v66, v67
	global_store_dwordx4 v[104:105], v[72:75], off offset:256
	s_nop 1
	v_mov_b32_e32 v73, v64
	v_mov_b32_e32 v64, v69
	v_mov_b32_e32 v69, v66
	v_mov_b32_e32 v66, v71
	v_mov_b32_e32 v72, v68
	v_pk_mul_f32 v[64:65], v[64:65], v[64:65]
	v_mov_b32_e32 v68, v70
	v_pk_mul_f32 v[66:67], v[66:67], v[66:67]
	v_pk_fma_f32 v[64:65], v[72:73], v[72:73], v[64:65]
	v_pk_fma_f32 v[66:67], v[68:69], v[68:69], v[66:67]
	s_nop 0
	v_pk_add_f32 v[64:65], v[64:65], v[66:67]
	s_nop 0
	v_add_f32_e32 v64, v64, v65
	v_add_f32_e32 v94, v64, v94
	s_and_b64 vcc, exec, s[44:45]
	s_cbranch_vccnz .LBB0_264

.LBB0_266:
	s_andn2_b64 vcc, exec, s[78:79]
	v_mov_b32_e32 v78, 0
	s_cbranch_vccnz .LBB0_268
	v_cvt_pk_bf16_f32 v84, v60, v61
	v_cvt_pk_bf16_f32 v85, v62, v63
	v_cvt_pk_bf16_f32 v86, v56, v57
	v_cvt_pk_bf16_f32 v87, v58, v59
	v_mov_b32_e32 v79, v56
	v_mov_b32_e32 v56, v61
	v_mov_b32_e32 v61, v58
	v_mov_b32_e32 v58, v63
	v_mov_b32_e32 v78, v60
	v_pk_mul_f32 v[56:57], v[56:57], v[56:57]
	v_mov_b32_e32 v60, v62
	v_pk_mul_f32 v[58:59], v[58:59], v[58:59]
	v_pk_fma_f32 v[56:57], v[78:79], v[78:79], v[56:57]
	v_pk_fma_f32 v[58:59], v[60:61], v[60:61], v[58:59]
	global_store_dwordx4 v[90:91], v[84:87], off
	v_pk_add_f32 v[56:57], v[56:57], v[58:59]
	s_nop 0
	v_add_f32_e32 v78, v56, v57

.LBB0_272:
	s_nop 0
	v_cvt_pk_bf16_f32 v56, v52, v53
	v_cvt_pk_bf16_f32 v57, v54, v55
	v_cvt_pk_bf16_f32 v58, v48, v49
	v_cvt_pk_bf16_f32 v59, v50, v51
	global_store_dwordx4 v[90:91], v[56:59], off offset:256
	s_nop 1
	v_mov_b32_e32 v57, v48
	v_mov_b32_e32 v48, v53
	v_mov_b32_e32 v53, v50
	v_mov_b32_e32 v50, v55
	v_mov_b32_e32 v56, v52
	v_pk_mul_f32 v[48:49], v[48:49], v[48:49]
	v_mov_b32_e32 v52, v54
	v_pk_mul_f32 v[50:51], v[50:51], v[50:51]
	v_pk_fma_f32 v[48:49], v[56:57], v[56:57], v[48:49]
	v_pk_fma_f32 v[50:51], v[52:53], v[52:53], v[50:51]
	s_nop 0
	v_pk_add_f32 v[48:49], v[48:49], v[50:51]
	s_nop 0
	v_add_f32_e32 v48, v48, v49
	v_add_f32_e32 v78, v48, v78
	s_and_b64 vcc, exec, s[44:45]
	s_cbranch_vccnz .LBB0_276

.LBB0_278:
	s_andn2_b64 vcc, exec, s[78:79]
	v_mov_b32_e32 v62, 0
	s_cbranch_vccnz .LBB0_280
	v_cvt_pk_bf16_f32 v68, v44, v45
	v_cvt_pk_bf16_f32 v69, v46, v47
	v_cvt_pk_bf16_f32 v70, v40, v41
	v_cvt_pk_bf16_f32 v71, v42, v43
	v_mov_b32_e32 v63, v40
	v_mov_b32_e32 v40, v45
	v_mov_b32_e32 v45, v42
	v_mov_b32_e32 v42, v47
	v_mov_b32_e32 v62, v44
	v_pk_mul_f32 v[40:41], v[40:41], v[40:41]
	v_mov_b32_e32 v44, v46
	v_pk_mul_f32 v[42:43], v[42:43], v[42:43]
	v_pk_fma_f32 v[40:41], v[62:63], v[62:63], v[40:41]
	v_pk_fma_f32 v[42:43], v[44:45], v[44:45], v[42:43]
	global_store_dwordx4 v[72:73], v[68:71], off
	v_pk_add_f32 v[40:41], v[40:41], v[42:43]
	s_nop 0
	v_add_f32_e32 v62, v40, v41

.LBB0_284:
	s_nop 0
	v_cvt_pk_bf16_f32 v40, v36, v37
	v_cvt_pk_bf16_f32 v41, v38, v39
	v_cvt_pk_bf16_f32 v42, v32, v33
	v_cvt_pk_bf16_f32 v43, v34, v35
	global_store_dwordx4 v[72:73], v[40:43], off offset:256
	s_nop 1
	v_mov_b32_e32 v41, v32
	v_mov_b32_e32 v32, v37
	v_mov_b32_e32 v37, v34
	v_mov_b32_e32 v34, v39
	v_mov_b32_e32 v40, v36
	v_pk_mul_f32 v[32:33], v[32:33], v[32:33]
	v_mov_b32_e32 v36, v38
	v_pk_mul_f32 v[34:35], v[34:35], v[34:35]
	v_pk_fma_f32 v[32:33], v[40:41], v[40:41], v[32:33]
	v_pk_fma_f32 v[34:35], v[36:37], v[36:37], v[34:35]
	s_nop 0
	v_pk_add_f32 v[32:33], v[32:33], v[34:35]
	s_nop 0
	v_add_f32_e32 v32, v32, v33
	v_add_f32_e32 v62, v32, v62
	s_and_b64 vcc, exec, s[44:45]
	s_cbranch_vccnz .LBB0_288

.LBB0_290:
	s_andn2_b64 vcc, exec, s[78:79]
	v_mov_b32_e32 v46, 0
	s_cbranch_vccnz .LBB0_292
	v_cvt_pk_bf16_f32 v52, v28, v29
	v_cvt_pk_bf16_f32 v53, v30, v31
	v_cvt_pk_bf16_f32 v54, v24, v25
	v_cvt_pk_bf16_f32 v55, v26, v27
	v_mov_b32_e32 v47, v24
	v_mov_b32_e32 v24, v29
	v_mov_b32_e32 v29, v26
	v_mov_b32_e32 v26, v31
	v_mov_b32_e32 v46, v28
	v_pk_mul_f32 v[24:25], v[24:25], v[24:25]
	v_mov_b32_e32 v28, v30
	v_pk_mul_f32 v[26:27], v[26:27], v[26:27]
	v_pk_fma_f32 v[24:25], v[46:47], v[46:47], v[24:25]
	v_pk_fma_f32 v[26:27], v[28:29], v[28:29], v[26:27]
	global_store_dwordx4 v[56:57], v[52:55], off
	v_pk_add_f32 v[24:25], v[24:25], v[26:27]
	s_nop 0
	v_add_f32_e32 v46, v24, v25

.LBB0_296:
	s_nop 0
	v_cvt_pk_bf16_f32 v24, v20, v21
	v_cvt_pk_bf16_f32 v25, v22, v23
	v_cvt_pk_bf16_f32 v26, v16, v17
	v_cvt_pk_bf16_f32 v27, v18, v19
	global_store_dwordx4 v[56:57], v[24:27], off offset:256
	s_nop 1
	v_mov_b32_e32 v25, v16
	v_mov_b32_e32 v16, v21
	v_mov_b32_e32 v21, v18
	v_mov_b32_e32 v18, v23
	v_mov_b32_e32 v24, v20
	v_pk_mul_f32 v[16:17], v[16:17], v[16:17]
	v_mov_b32_e32 v20, v22
	v_pk_mul_f32 v[18:19], v[18:19], v[18:19]
	v_pk_fma_f32 v[16:17], v[24:25], v[24:25], v[16:17]
	v_pk_fma_f32 v[18:19], v[20:21], v[20:21], v[18:19]
	s_nop 0
	v_pk_add_f32 v[16:17], v[16:17], v[18:19]
	s_nop 0
	v_add_f32_e32 v16, v16, v17
	v_add_f32_e32 v46, v16, v46
	s_and_b64 vcc, exec, s[44:45]
	s_cbranch_vccnz .LBB0_300

.LBB0_302:
	s_andn2_b64 vcc, exec, s[78:79]
	v_mov_b32_e32 v18, 0
	s_cbranch_vccnz .LBB0_304
	v_cvt_pk_bf16_f32 v18, v12, v13
	v_cvt_pk_bf16_f32 v19, v14, v15
	v_cvt_pk_bf16_f32 v20, v8, v9
	v_cvt_pk_bf16_f32 v21, v10, v11
	global_store_dwordx4 v[40:41], v[18:21], off
	s_nop 1
	v_mov_b32_e32 v19, v8
	v_mov_b32_e32 v8, v13
	v_mov_b32_e32 v13, v10
	v_mov_b32_e32 v10, v15
	v_mov_b32_e32 v18, v12
	v_pk_mul_f32 v[8:9], v[8:9], v[8:9]
	v_mov_b32_e32 v12, v14
	v_pk_mul_f32 v[10:11], v[10:11], v[10:11]
	v_pk_fma_f32 v[8:9], v[18:19], v[18:19], v[8:9]
	v_pk_fma_f32 v[10:11], v[12:13], v[12:13], v[10:11]
	s_nop 0
	v_pk_add_f32 v[8:9], v[8:9], v[10:11]
	s_nop 0
	v_add_f32_e32 v18, v8, v9

.LBB0_308:
	s_nop 0
	v_cvt_pk_bf16_f32 v8, v4, v5
	v_cvt_pk_bf16_f32 v9, v6, v7
	v_cvt_pk_bf16_f32 v10, v0, v1
	v_cvt_pk_bf16_f32 v11, v2, v3
	global_store_dwordx4 v[40:41], v[8:11], off offset:256
	s_nop 1
	v_mov_b32_e32 v9, v0
	v_mov_b32_e32 v0, v5
	v_mov_b32_e32 v5, v2
	v_mov_b32_e32 v2, v7
	v_mov_b32_e32 v8, v4
	v_pk_mul_f32 v[0:1], v[0:1], v[0:1]
	v_mov_b32_e32 v4, v6
	v_pk_mul_f32 v[2:3], v[2:3], v[2:3]
	v_pk_fma_f32 v[0:1], v[8:9], v[8:9], v[0:1]
	v_pk_fma_f32 v[2:3], v[4:5], v[4:5], v[2:3]
	s_nop 0
	v_pk_add_f32 v[0:1], v[0:1], v[2:3]
	s_nop 0
	v_add_f32_e32 v0, v0, v1
	v_add_f32_e32 v18, v0, v18
	s_and_b64 vcc, exec, s[44:45]
	s_cbranch_vccnz .LBB0_183

.LBB0_326:
	s_add_u32 s27, s52, 0xfffc0080
	s_addc_u32 s35, s53, -1
	s_add_i32 s36, 0, 0x10000
	v_add_u32_e32 v140, s36, v216
	ds_read_b128 v[128:131], v140
	ds_read_b128 v[132:135], v140 offset:1024
	ds_read_b128 v[136:139], v140 offset:2048
	ds_read_b128 v[140:143], v140 offset:3072
	s_cmp_eq_u32 s34, 12
	s_cselect_b32 s75, s1, s35
	s_cselect_b32 s74, s11, s27
	s_cselect_b32 s73, s25, s33
	s_cselect_b32 s72, s30, s31
	v_lshl_add_u64 v[168:169], s[52:53], 0, v[152:153]
	s_add_i32 m0, s83, 0xc000
	ds_read_b128 v[156:159], v217
	ds_read_b128 v[160:163], v217 offset:1024
	ds_read_b128 v[164:167], v217 offset:2048
	ds_read_b128 v[188:191], v217 offset:3072
	ds_read_b128 v[192:195], v217 offset:4096
	ds_read_b128 v[196:199], v217 offset:5120
	ds_read_b128 v[200:203], v217 offset:6144
	ds_read_b128 v[204:207], v217 offset:7168
	global_load_lds_dwordx4 v[168:169], off
	v_lshl_add_u64 v[168:169], s[52:53], 0, v[154:155]
	s_add_i32 m0, s83, 0xe000
	s_nop 0
	global_load_lds_dwordx4 v[168:169], off
	s_waitcnt lgkmcnt(8)
	s_barrier
	s_waitcnt lgkmcnt(0)
	s_setprio 1
	s_waitcnt lgkmcnt(0)
	v_mfma_f32_16x16x32_bf16 v[124:127], v[128:131], v[156:159], v[124:127]
	v_mfma_f32_16x16x32_bf16 v[120:123], v[136:139], v[156:159], v[120:123]
	v_mfma_f32_16x16x32_bf16 v[108:111], v[128:131], v[164:167], v[108:111]
	v_mfma_f32_16x16x32_bf16 v[104:107], v[136:139], v[164:167], v[104:107]
	v_mfma_f32_16x16x32_bf16 v[92:95], v[128:131], v[192:195], v[92:95]
	v_mfma_f32_16x16x32_bf16 v[88:91], v[136:139], v[192:195], v[88:91]
	v_mfma_f32_16x16x32_bf16 v[76:79], v[128:131], v[200:203], v[76:79]
	v_mfma_f32_16x16x32_bf16 v[72:75], v[136:139], v[200:203], v[72:75]
	v_mfma_f32_16x16x32_bf16 v[124:127], v[132:135], v[160:163], v[124:127]
	v_mfma_f32_16x16x32_bf16 v[120:123], v[140:143], v[160:163], v[120:123]
	v_mfma_f32_16x16x32_bf16 v[108:111], v[132:135], v[188:191], v[108:111]
	v_mfma_f32_16x16x32_bf16 v[104:107], v[140:143], v[188:191], v[104:107]
	v_mfma_f32_16x16x32_bf16 v[92:95], v[132:135], v[196:199], v[92:95]
	v_mfma_f32_16x16x32_bf16 v[88:91], v[140:143], v[196:199], v[88:91]
	v_mfma_f32_16x16x32_bf16 v[76:79], v[132:135], v[204:207], v[76:79]
	v_mfma_f32_16x16x32_bf16 v[72:75], v[140:143], v[204:207], v[72:75]
	s_setprio 0
	s_barrier
	s_add_i32 s27, 0, 0x14000
	s_add_i32 s35, s36, s81
	v_add_u32_e32 v144, s27, v216
	v_lshl_add_u64 v[168:169], s[72:73], 0, v[148:149]
	s_mov_b32 m0, s35
	ds_read_b128 v[220:223], v144
	ds_read_b128 v[228:231], v144 offset:1024
	ds_read_b128 v[232:235], v144 offset:2048
	ds_read_b128 v[236:239], v144 offset:3072
	global_load_lds_dwordx4 v[168:169], off
	v_lshl_add_u64 v[176:177], s[72:73], 0, v[146:147]
	s_add_i32 m0, s35, 0x2000
	s_nop 0
	global_load_lds_dwordx4 v[176:177], off
	s_barrier
	s_waitcnt lgkmcnt(0)
	s_setprio 1
	s_waitcnt lgkmcnt(0)
	v_mfma_f32_16x16x32_bf16 v[116:119], v[220:223], v[156:159], v[116:119]
	v_mfma_f32_16x16x32_bf16 v[112:115], v[232:235], v[156:159], v[112:115]
	v_mfma_f32_16x16x32_bf16 v[100:103], v[220:223], v[164:167], v[100:103]
	v_mfma_f32_16x16x32_bf16 v[96:99], v[232:235], v[164:167], v[96:99]
	v_mfma_f32_16x16x32_bf16 v[84:87], v[220:223], v[192:195], v[84:87]
	v_mfma_f32_16x16x32_bf16 v[80:83], v[232:235], v[192:195], v[80:83]
	v_mfma_f32_16x16x32_bf16 v[68:71], v[220:223], v[200:203], v[68:71]
	v_mfma_f32_16x16x32_bf16 v[64:67], v[232:235], v[200:203], v[64:67]
	v_mfma_f32_16x16x32_bf16 v[116:119], v[228:231], v[160:163], v[116:119]
	v_mfma_f32_16x16x32_bf16 v[112:115], v[236:239], v[160:163], v[112:115]
	v_mfma_f32_16x16x32_bf16 v[100:103], v[228:231], v[188:191], v[100:103]
	v_mfma_f32_16x16x32_bf16 v[96:99], v[236:239], v[188:191], v[96:99]
	v_mfma_f32_16x16x32_bf16 v[84:87], v[228:231], v[196:199], v[84:87]
	v_mfma_f32_16x16x32_bf16 v[80:83], v[236:239], v[196:199], v[80:83]
	v_mfma_f32_16x16x32_bf16 v[68:71], v[228:231], v[204:207], v[68:71]
	v_mfma_f32_16x16x32_bf16 v[64:67], v[236:239], v[204:207], v[64:67]
	s_setprio 0
	s_mov_b32 m0, s83
	v_lshl_add_u64 v[224:225], s[74:75], 0, v[148:149]
	s_barrier
	ds_read_b128 v[156:159], v217 offset:16384
	ds_read_b128 v[160:163], v217 offset:17408
	ds_read_b128 v[164:167], v217 offset:18432
	ds_read_b128 v[188:191], v217 offset:19456
	ds_read_b128 v[192:195], v217 offset:20480
	ds_read_b128 v[196:199], v217 offset:21504
	ds_read_b128 v[200:203], v217 offset:22528
	ds_read_b128 v[204:207], v217 offset:23552
	global_load_lds_dwordx4 v[224:225], off
	v_lshl_add_u64 v[240:241], s[74:75], 0, v[146:147]
	s_mov_b32 m0, s84
	s_nop 0
	global_load_lds_dwordx4 v[240:241], off
	s_barrier
	s_waitcnt lgkmcnt(0)
	s_setprio 1
	s_waitcnt lgkmcnt(0)
	v_mfma_f32_16x16x32_bf16 v[60:63], v[128:131], v[156:159], v[60:63]
	v_mfma_f32_16x16x32_bf16 v[56:59], v[136:139], v[156:159], v[56:59]
	v_mfma_f32_16x16x32_bf16 v[44:47], v[128:131], v[164:167], v[44:47]
	v_mfma_f32_16x16x32_bf16 v[40:43], v[136:139], v[164:167], v[40:43]
	v_mfma_f32_16x16x32_bf16 v[28:31], v[128:131], v[192:195], v[28:31]
	v_mfma_f32_16x16x32_bf16 v[24:27], v[136:139], v[192:195], v[24:27]
	v_mfma_f32_16x16x32_bf16 v[12:15], v[128:131], v[200:203], v[12:15]
	v_mfma_f32_16x16x32_bf16 v[8:11], v[136:139], v[200:203], v[8:11]
	v_mfma_f32_16x16x32_bf16 v[60:63], v[132:135], v[160:163], v[60:63]
	v_mfma_f32_16x16x32_bf16 v[56:59], v[140:143], v[160:163], v[56:59]
	v_mfma_f32_16x16x32_bf16 v[44:47], v[132:135], v[188:191], v[44:47]
	v_mfma_f32_16x16x32_bf16 v[40:43], v[140:143], v[188:191], v[40:43]
	v_mfma_f32_16x16x32_bf16 v[28:31], v[132:135], v[196:199], v[28:31]
	v_mfma_f32_16x16x32_bf16 v[24:27], v[140:143], v[196:199], v[24:27]
	v_mfma_f32_16x16x32_bf16 v[12:15], v[132:135], v[204:207], v[12:15]
	v_mfma_f32_16x16x32_bf16 v[8:11], v[140:143], v[204:207], v[8:11]
	s_setprio 0
	s_barrier
	s_add_u32 s36, s72, 0x40000
	s_addc_u32 s37, s73, 0
	s_add_i32 s27, s27, s81
	v_lshl_add_u64 v[128:129], s[36:37], 0, v[148:149]
	s_mov_b32 m0, s27
	s_nop 0
	global_load_lds_dwordx4 v[128:129], off
	v_lshl_add_u64 v[128:129], s[36:37], 0, v[146:147]
	s_add_i32 m0, s27, 0x2000
	s_nop 0
	global_load_lds_dwordx4 v[128:129], off
	s_waitcnt vmcnt(6)
	s_barrier
	s_setprio 1
	v_mfma_f32_16x16x32_bf16 v[52:55], v[220:223], v[156:159], v[52:55]
	v_mfma_f32_16x16x32_bf16 v[48:51], v[232:235], v[156:159], v[48:51]
	v_mfma_f32_16x16x32_bf16 v[36:39], v[220:223], v[164:167], v[36:39]
	v_mfma_f32_16x16x32_bf16 v[32:35], v[232:235], v[164:167], v[32:35]
	v_mfma_f32_16x16x32_bf16 v[20:23], v[220:223], v[192:195], v[20:23]
	v_mfma_f32_16x16x32_bf16 v[16:19], v[232:235], v[192:195], v[16:19]
	v_mfma_f32_16x16x32_bf16 v[4:7], v[220:223], v[200:203], v[4:7]
	v_mfma_f32_16x16x32_bf16 v[0:3], v[232:235], v[200:203], v[0:3]
	v_mfma_f32_16x16x32_bf16 v[52:55], v[228:231], v[160:163], v[52:55]
	v_mfma_f32_16x16x32_bf16 v[48:51], v[236:239], v[160:163], v[48:51]
	v_mfma_f32_16x16x32_bf16 v[36:39], v[228:231], v[188:191], v[36:39]
	v_mfma_f32_16x16x32_bf16 v[32:35], v[236:239], v[188:191], v[32:35]
	v_mfma_f32_16x16x32_bf16 v[20:23], v[228:231], v[196:199], v[20:23]
	v_mfma_f32_16x16x32_bf16 v[16:19], v[236:239], v[196:199], v[16:19]
	v_mfma_f32_16x16x32_bf16 v[4:7], v[228:231], v[204:207], v[4:7]
	v_mfma_f32_16x16x32_bf16 v[0:3], v[236:239], v[204:207], v[0:3]
	s_setprio 0
	s_add_i32 s27, 0, 0x18000
	v_add_u32_e32 v140, s27, v216
	s_barrier
	ds_read_b128 v[128:131], v140
	ds_read_b128 v[132:135], v140 offset:1024
	ds_read_b128 v[136:139], v140 offset:2048
	ds_read_b128 v[140:143], v140 offset:3072
	s_add_u32 s36, s74, 0x40000
	s_addc_u32 s37, s75, 0
	s_mov_b32 m0, s85
	v_lshl_add_u64 v[220:221], s[36:37], 0, v[148:149]
	ds_read_b128 v[156:159], v217 offset:32768
	ds_read_b128 v[160:163], v217 offset:33792
	ds_read_b128 v[164:167], v217 offset:34816
	ds_read_b128 v[188:191], v217 offset:35840
	ds_read_b128 v[192:195], v217 offset:36864
	ds_read_b128 v[196:199], v217 offset:37888
	ds_read_b128 v[200:203], v217 offset:38912
	ds_read_b128 v[204:207], v217 offset:39936
	global_load_lds_dwordx4 v[220:221], off
	v_lshl_add_u64 v[220:221], s[36:37], 0, v[146:147]
	s_mov_b32 m0, s86
	s_nop 0
	global_load_lds_dwordx4 v[220:221], off
	s_waitcnt lgkmcnt(8)
	s_barrier
	s_waitcnt lgkmcnt(0)
	s_setprio 1
	s_waitcnt lgkmcnt(0)
	v_mfma_f32_16x16x32_bf16 v[124:127], v[128:131], v[156:159], v[124:127]
	v_mfma_f32_16x16x32_bf16 v[120:123], v[136:139], v[156:159], v[120:123]
	v_mfma_f32_16x16x32_bf16 v[108:111], v[128:131], v[164:167], v[108:111]
	v_mfma_f32_16x16x32_bf16 v[104:107], v[136:139], v[164:167], v[104:107]
	v_mfma_f32_16x16x32_bf16 v[92:95], v[128:131], v[192:195], v[92:95]
	v_mfma_f32_16x16x32_bf16 v[88:91], v[136:139], v[192:195], v[88:91]
	v_mfma_f32_16x16x32_bf16 v[76:79], v[128:131], v[200:203], v[76:79]
	v_mfma_f32_16x16x32_bf16 v[72:75], v[136:139], v[200:203], v[72:75]
	v_mfma_f32_16x16x32_bf16 v[124:127], v[132:135], v[160:163], v[124:127]
	v_mfma_f32_16x16x32_bf16 v[120:123], v[140:143], v[160:163], v[120:123]
	v_mfma_f32_16x16x32_bf16 v[108:111], v[132:135], v[188:191], v[108:111]
	v_mfma_f32_16x16x32_bf16 v[104:107], v[140:143], v[188:191], v[104:107]
	v_mfma_f32_16x16x32_bf16 v[92:95], v[132:135], v[196:199], v[92:95]
	v_mfma_f32_16x16x32_bf16 v[88:91], v[140:143], v[196:199], v[88:91]
	v_mfma_f32_16x16x32_bf16 v[76:79], v[132:135], v[204:207], v[76:79]
	v_mfma_f32_16x16x32_bf16 v[72:75], v[140:143], v[204:207], v[72:75]
	s_setprio 0
	s_barrier
	s_add_i32 s35, 0, 0x1c000
	s_add_i32 s27, s27, s81
	v_add_u32_e32 v144, s35, v216
	v_lshl_add_u64 v[168:169], v[168:169], 0, s[18:19]
	s_mov_b32 m0, s27
	ds_read_b128 v[220:223], v144
	ds_read_b128 v[228:231], v144 offset:1024
	ds_read_b128 v[232:235], v144 offset:2048
	ds_read_b128 v[236:239], v144 offset:3072
	global_load_lds_dwordx4 v[168:169], off
	v_lshl_add_u64 v[168:169], v[176:177], 0, s[18:19]
	s_add_i32 m0, s27, 0x2000
	s_nop 0
	global_load_lds_dwordx4 v[168:169], off
	s_barrier
	s_waitcnt lgkmcnt(0)
	s_setprio 1
	s_waitcnt lgkmcnt(0)
	v_mfma_f32_16x16x32_bf16 v[116:119], v[220:223], v[156:159], v[116:119]
	v_mfma_f32_16x16x32_bf16 v[112:115], v[232:235], v[156:159], v[112:115]
	v_mfma_f32_16x16x32_bf16 v[100:103], v[220:223], v[164:167], v[100:103]
	v_mfma_f32_16x16x32_bf16 v[96:99], v[232:235], v[164:167], v[96:99]
	v_mfma_f32_16x16x32_bf16 v[84:87], v[220:223], v[192:195], v[84:87]
	v_mfma_f32_16x16x32_bf16 v[80:83], v[232:235], v[192:195], v[80:83]
	v_mfma_f32_16x16x32_bf16 v[68:71], v[220:223], v[200:203], v[68:71]
	v_mfma_f32_16x16x32_bf16 v[64:67], v[232:235], v[200:203], v[64:67]
	v_mfma_f32_16x16x32_bf16 v[116:119], v[228:231], v[160:163], v[116:119]
	v_mfma_f32_16x16x32_bf16 v[112:115], v[236:239], v[160:163], v[112:115]
	v_mfma_f32_16x16x32_bf16 v[100:103], v[228:231], v[188:191], v[100:103]
	v_mfma_f32_16x16x32_bf16 v[96:99], v[236:239], v[188:191], v[96:99]
	v_mfma_f32_16x16x32_bf16 v[84:87], v[228:231], v[196:199], v[84:87]
	v_mfma_f32_16x16x32_bf16 v[80:83], v[236:239], v[196:199], v[80:83]
	v_mfma_f32_16x16x32_bf16 v[68:71], v[228:231], v[204:207], v[68:71]
	v_mfma_f32_16x16x32_bf16 v[64:67], v[236:239], v[204:207], v[64:67]
	s_setprio 0
	s_mov_b32 m0, s87
	v_lshl_add_u64 v[168:169], v[224:225], 0, s[18:19]
	s_barrier
	ds_read_b128 v[156:159], v217 offset:49152
	ds_read_b128 v[160:163], v217 offset:50176
	ds_read_b128 v[164:167], v217 offset:51200
	ds_read_b128 v[188:191], v217 offset:52224
	ds_read_b128 v[192:195], v217 offset:53248
	ds_read_b128 v[196:199], v217 offset:54272
	ds_read_b128 v[200:203], v217 offset:55296
	ds_read_b128 v[204:207], v217 offset:56320
	global_load_lds_dwordx4 v[168:169], off
	v_lshl_add_u64 v[168:169], v[240:241], 0, s[18:19]
	s_mov_b32 m0, s79
	s_nop 0
	global_load_lds_dwordx4 v[168:169], off
	s_barrier
	s_waitcnt lgkmcnt(0)
	s_setprio 1
	s_waitcnt lgkmcnt(0)
	v_mfma_f32_16x16x32_bf16 v[60:63], v[128:131], v[156:159], v[60:63]
	v_mfma_f32_16x16x32_bf16 v[56:59], v[136:139], v[156:159], v[56:59]
	v_mfma_f32_16x16x32_bf16 v[44:47], v[128:131], v[164:167], v[44:47]
	v_mfma_f32_16x16x32_bf16 v[40:43], v[136:139], v[164:167], v[40:43]
	v_mfma_f32_16x16x32_bf16 v[28:31], v[128:131], v[192:195], v[28:31]
	v_mfma_f32_16x16x32_bf16 v[24:27], v[136:139], v[192:195], v[24:27]
	v_mfma_f32_16x16x32_bf16 v[12:15], v[128:131], v[200:203], v[12:15]
	v_mfma_f32_16x16x32_bf16 v[8:11], v[136:139], v[200:203], v[8:11]
	v_mfma_f32_16x16x32_bf16 v[60:63], v[132:135], v[160:163], v[60:63]
	v_mfma_f32_16x16x32_bf16 v[56:59], v[140:143], v[160:163], v[56:59]
	v_mfma_f32_16x16x32_bf16 v[44:47], v[132:135], v[188:191], v[44:47]
	v_mfma_f32_16x16x32_bf16 v[40:43], v[140:143], v[188:191], v[40:43]
	v_mfma_f32_16x16x32_bf16 v[28:31], v[132:135], v[196:199], v[28:31]
	v_mfma_f32_16x16x32_bf16 v[24:27], v[140:143], v[196:199], v[24:27]
	v_mfma_f32_16x16x32_bf16 v[12:15], v[132:135], v[204:207], v[12:15]
	v_mfma_f32_16x16x32_bf16 v[8:11], v[140:143], v[204:207], v[8:11]
	s_setprio 0
	s_barrier
	s_add_u32 s36, s72, 0x40080
	s_addc_u32 s37, s73, 0
	s_add_i32 s27, s35, s81
	v_lshl_add_u64 v[128:129], s[36:37], 0, v[148:149]
	s_mov_b32 m0, s27
	s_nop 0
	global_load_lds_dwordx4 v[128:129], off
	v_lshl_add_u64 v[128:129], s[36:37], 0, v[146:147]
	s_add_i32 m0, s27, 0x2000
	s_nop 0
	global_load_lds_dwordx4 v[128:129], off
	s_waitcnt vmcnt(6)
	s_barrier
	s_setprio 1
	v_mfma_f32_16x16x32_bf16 v[52:55], v[220:223], v[156:159], v[52:55]
	v_mfma_f32_16x16x32_bf16 v[48:51], v[232:235], v[156:159], v[48:51]
	v_mfma_f32_16x16x32_bf16 v[36:39], v[220:223], v[164:167], v[36:39]
	v_mfma_f32_16x16x32_bf16 v[32:35], v[232:235], v[164:167], v[32:35]
	v_mfma_f32_16x16x32_bf16 v[20:23], v[220:223], v[192:195], v[20:23]
	v_mfma_f32_16x16x32_bf16 v[16:19], v[232:235], v[192:195], v[16:19]
	v_mfma_f32_16x16x32_bf16 v[4:7], v[220:223], v[200:203], v[4:7]
	v_mfma_f32_16x16x32_bf16 v[0:3], v[232:235], v[200:203], v[0:3]
	v_mfma_f32_16x16x32_bf16 v[52:55], v[228:231], v[160:163], v[52:55]
	v_mfma_f32_16x16x32_bf16 v[48:51], v[236:239], v[160:163], v[48:51]
	v_mfma_f32_16x16x32_bf16 v[36:39], v[228:231], v[188:191], v[36:39]
	v_mfma_f32_16x16x32_bf16 v[32:35], v[236:239], v[188:191], v[32:35]
	v_mfma_f32_16x16x32_bf16 v[20:23], v[228:231], v[196:199], v[20:23]
	v_mfma_f32_16x16x32_bf16 v[16:19], v[236:239], v[196:199], v[16:19]
	v_mfma_f32_16x16x32_bf16 v[4:7], v[228:231], v[204:207], v[4:7]
	v_mfma_f32_16x16x32_bf16 v[0:3], v[236:239], v[204:207], v[0:3]
	s_setprio 0
	s_add_i32 s34, s34, 2
	s_add_u32 s52, s52, 0x100
	s_addc_u32 s53, s53, 0
	s_add_u32 s31, s31, 0x100
	s_addc_u32 s33, s33, 0
	s_cmp_gt_u32 s34, 13
	s_barrier
	s_cbranch_scc0 .LBB0_326
	v_lshl_add_u32 v128, s0, 8, v151
	v_readlane_b32 s0, v252, 36
	v_ashrrev_i32_e32 v129, 31, v128
	v_readlane_b32 s1, v252, 37
	v_or_b32_e32 v132, 16, v128
	v_or_b32_e32 v136, 32, v128
	v_lshl_add_u64 v[130:131], v[128:129], 3, s[0:1]
	v_ashrrev_i32_e32 v133, 31, v132
	v_ashrrev_i32_e32 v137, 31, v136
	v_or_b32_e32 v140, 48, v128
	v_lshl_add_u64 v[134:135], v[132:133], 3, s[0:1]
	v_lshl_add_u64 v[138:139], v[136:137], 3, s[0:1]
	v_ashrrev_i32_e32 v141, 31, v140
	global_load_dwordx2 v[202:203], v[130:131], off
	global_load_dwordx2 v[200:201], v[134:135], off
	global_load_dwordx2 v[192:193], v[138:139], off
	global_load_dwordx2 v[166:167], v[130:131], off offset:1024
	v_add_u32_e32 v164, 0x90, v128
	v_add_u32_e32 v158, 0xa0, v128
	v_add_u32_e32 v156, 0xb0, v128
	v_lshl_add_u64 v[142:143], v[140:141], 3, s[0:1]
	v_ashrrev_i32_e32 v165, 31, v164
	v_ashrrev_i32_e32 v159, 31, v158
	v_ashrrev_i32_e32 v157, 31, v156
	v_lshl_add_u64 v[130:131], v[164:165], 3, s[0:1]
	v_lshl_add_u64 v[134:135], v[158:159], 3, s[0:1]
	v_lshl_add_u64 v[138:139], v[156:157], 3, s[0:1]
	global_load_dwordx2 v[196:197], v[142:143], off
	global_load_dwordx2 v[188:189], v[130:131], off
	global_load_dwordx2 v[162:163], v[134:135], off
	global_load_dwordx2 v[160:161], v[138:139], off
	v_add_u32_e32 v168, 0x80, v128
	s_mov_b64 s[0:1], -1
	s_cmp_gt_u32 s10, 1
	v_lshlrev_b32_e32 v144, 1, v150
	v_ashrrev_i32_e32 v169, 31, v168
	v_lshlrev_b64 v[204:205], 10, v[128:129]
	v_lshlrev_b64 v[198:199], 10, v[132:133]
	v_lshlrev_b64 v[194:195], 10, v[136:137]
	v_lshlrev_b64 v[190:191], 10, v[140:141]
	s_waitcnt vmcnt(0)
	v_ffbh_u32_e32 v222, v203
	v_ffbh_u32_e32 v221, v201
	v_ffbh_u32_e32 v220, v193
	v_ffbh_u32_e32 v219, v197
	s_cbranch_scc0 .LBB0_329
	s_cmp_lt_u32 s10, 4
	s_cselect_b64 vcc, -1, 0
	v_readlane_b32 s56, v254, 23
	s_and_b64 s[0:1], vcc, exec
	v_readlane_b32 s70, v254, 37
	v_readlane_b32 s36, v252, 15
	v_readlane_b32 s71, v254, 38
	v_readlane_b32 s37, v252, 16
	s_cselect_b32 s0, s70, s36
	s_mov_b32 s11, 0x4400000
	v_readlane_b32 s30, v254, 62
	s_cselect_b32 s1, s71, s37
	s_cselect_b32 s11, s11, 0x4800000
	v_readlane_b32 s31, v254, 63
	s_add_u32 s0, s0, s30
	s_addc_u32 s1, s1, s31
	global_load_dwordx4 v[136:139], v218, s[0:1] offset:16
	global_load_dwordx4 v[140:143], v218, s[0:1]
	global_load_dwordx4 v[128:131], v218, s[0:1] offset:144
	global_load_dwordx4 v[132:135], v218, s[0:1] offset:128
	v_and_b32_e32 v177, 64, v214
	v_xor_b32_e32 v176, 16, v214
	v_add_u32_e32 v177, 64, v177
	v_cndmask_b32_e32 v223, 1.0, v215, vcc
	v_cmp_lt_i32_e32 vcc, v176, v177
	v_readlane_b32 s9, v254, 52
	s_add_u32 s11, s9, s11
	v_cndmask_b32_e32 v176, v214, v176, vcc
	v_lshlrev_b32_e32 v225, 2, v176
	v_xor_b32_e32 v176, 32, v214
	v_cmp_lt_i32_e32 vcc, v176, v177
	v_readlane_b32 s9, v254, 61
	s_addc_u32 s25, s9, 0
	v_cndmask_b32_e32 v176, v214, v176, vcc
	v_lshlrev_b32_e32 v224, 2, v176
	v_min_u32_e32 v176, 32, v222
	v_lshlrev_b64 v[228:229], v176, v[202:203]
	v_min_u32_e32 v177, 1, v228
	v_or_b32_e32 v177, v229, v177
	v_cvt_f32_u32_e32 v177, v177
	v_sub_u32_e32 v176, 32, v176
	s_lshl_b32 s0, s10, 9
	s_and_b32 s0, s0, 0x200
	v_ldexp_f32 v176, v177, v176
	v_mul_f32_e32 v176, 0x35800000, v176
	v_fmamk_f32 v176, v176, 0x3a800000, v210
	v_cmp_gt_f32_e32 vcc, s89, v176
	v_mul_f32_e32 v177, 0x4b800000, v176
	s_add_u32 s0, s11, s0
	v_cndmask_b32_e32 v176, v176, v177, vcc
	v_rsq_f32_e32 v176, v176
	s_addc_u32 s1, s25, 0
	v_lshl_add_u64 v[206:207], s[0:1], 0, v[144:145]
	v_readlane_b32 s48, v252, 27
	v_mul_f32_e32 v177, 0x45800000, v176
	v_cndmask_b32_e32 v228, v176, v177, vcc
	v_pk_mul_f32 v[230:231], v[124:125], v[228:229] op_sel_hi:[1,0]
	v_pk_mul_f32 v[232:233], v[126:127], v[228:229] op_sel_hi:[1,0]
	v_pk_mul_f32 v[236:237], v[230:231], v[230:231]
	v_pk_mul_f32 v[234:235], v[232:233], v[232:233]
	v_pk_mul_f32 v[250:251], v[114:115], v[228:229] op_sel_hi:[1,0]
	v_pk_mov_b32 v[238:239], v[236:237], v[234:235] op_sel:[1,0]
	v_mov_b32_e32 v237, v235
	v_pk_add_f32 v[234:235], v[238:239], v[236:237]
	v_pk_mul_f32 v[236:237], v[120:121], v[228:229] op_sel_hi:[1,0]
	v_pk_mul_f32 v[238:239], v[122:123], v[228:229] op_sel_hi:[1,0]
	v_pk_mul_f32 v[242:243], v[236:237], v[236:237]
	v_pk_mul_f32 v[240:241], v[238:239], v[238:239]
	v_pk_add_f32 v[234:235], v[234:235], v[234:235] op_sel_hi:[0,1]
	v_pk_mov_b32 v[244:245], v[242:243], v[240:241] op_sel:[1,0]
	v_mov_b32_e32 v243, v241
	v_pk_add_f32 v[240:241], v[244:245], v[242:243]
	v_pk_mul_f32 v[244:245], v[116:117], v[228:229] op_sel_hi:[1,0]
	v_pk_mul_f32 v[242:243], v[118:119], v[228:229] op_sel_hi:[1,0]
	v_mul_f32_e32 v234, v244, v244
	v_pk_fma_f32 v[246:247], v[244:245], v[244:245], v[234:235] op_sel_hi:[1,1,0]
	v_mul_f32_e32 v234, v242, v242
	v_pk_add_f32 v[240:241], v[240:241], v[240:241] op_sel_hi:[0,1]
	v_pk_fma_f32 v[248:249], v[242:243], v[242:243], v[234:235] op_sel_hi:[1,1,0]
	v_pk_mul_f32 v[176:177], v[112:113], v[228:229] op_sel_hi:[1,0]
	v_mul_f32_e32 v234, v250, v250
	v_mul_f32_e32 v246, v176, v176
	v_mul_f32_e32 v248, v177, v177
	v_mul_f32_e32 v240, v251, v251
	v_pk_add_f32 v[228:229], v[246:247], v[248:249]
	v_pk_add_f32 v[234:235], v[234:235], v[240:241]
	v_lshl_add_u64 v[240:241], v[206:207], 0, v[204:205]
	v_pk_add_f32 v[228:229], v[228:229], v[234:235]
	v_readlane_b32 s57, v254, 24
	v_add_f32_e32 v228, v228, v229
	ds_bpermute_b32 v229, v225, v228
	v_readlane_b32 s58, v254, 25
	v_readlane_b32 s59, v254, 26
	v_readlane_b32 s60, v254, 27
	v_readlane_b32 s61, v254, 28
	s_waitcnt lgkmcnt(0)
	v_add_f32_e32 v228, v228, v229
	ds_bpermute_b32 v229, v224, v228
	v_readlane_b32 s62, v254, 29
	v_readlane_b32 s63, v254, 30
	v_readlane_b32 s64, v254, 31
	v_readlane_b32 s65, v254, 32
	s_waitcnt lgkmcnt(0)
	v_add_f32_e32 v228, v228, v229
	v_fmamk_f32 v228, v228, 0x3c800000, v210
	v_cmp_gt_f32_e32 vcc, s89, v228
	v_mul_f32_e32 v229, 0x4b800000, v228
	v_readlane_b32 s66, v254, 33
	v_cndmask_b32_e32 v228, v228, v229, vcc
	v_rsq_f32_e32 v228, v228
	v_readlane_b32 s67, v254, 34
	v_readlane_b32 s68, v254, 35
	v_readlane_b32 s69, v254, 36
	v_mul_f32_e32 v229, 0x45800000, v228
	v_cndmask_b32_e32 v228, v228, v229, vcc
	v_mul_f32_e32 v234, v223, v228
	v_pk_mul_f32 v[228:229], v[230:231], v[234:235] op_sel_hi:[1,0]
	v_pk_mul_f32 v[230:231], v[232:233], v[234:235] op_sel_hi:[1,0]
	s_waitcnt vmcnt(2)
	v_pk_mul_f32 v[228:229], v[140:141], v[228:229]
	v_pk_mul_f32 v[230:231], v[142:143], v[230:231]
	v_pk_mul_f32 v[232:233], v[236:237], v[234:235] op_sel_hi:[1,0]
	v_pk_mul_f32 v[236:237], v[238:239], v[234:235] op_sel_hi:[1,0]
	v_cvt_pk_bf16_f32 v228, v228, v229
	v_cvt_pk_bf16_f32 v229, v230, v231
	v_pk_mul_f32 v[232:233], v[136:137], v[232:233]
	v_pk_mul_f32 v[236:237], v[138:139], v[236:237]
	v_cvt_pk_bf16_f32 v230, v232, v233
	v_pk_mul_f32 v[176:177], v[176:177], v[234:235] op_sel_hi:[1,0]
	v_cvt_pk_bf16_f32 v231, v236, v237
	global_store_dwordx4 v[240:241], v[228:231], off
	v_pk_mul_f32 v[232:233], v[250:251], v[234:235] op_sel_hi:[1,0]
	s_waitcnt vmcnt(2)
	v_pk_mul_f32 v[176:177], v[128:129], v[176:177]
	v_pk_mul_f32 v[228:229], v[244:245], v[234:235] op_sel_hi:[1,0]
	v_pk_mul_f32 v[230:231], v[242:243], v[234:235] op_sel_hi:[1,0]
	s_waitcnt vmcnt(1)
	v_pk_mul_f32 v[228:229], v[132:133], v[228:229]
	v_pk_mul_f32 v[230:231], v[134:135], v[230:231]
	v_cvt_pk_bf16_f32 v228, v228, v229
	v_pk_mul_f32 v[232:233], v[130:131], v[232:233]
	v_cvt_pk_bf16_f32 v229, v230, v231
	v_cvt_pk_bf16_f32 v230, v176, v177
	s_nop 1
	v_readlane_b32 s38, v252, 17
	v_cvt_pk_bf16_f32 v231, v232, v233
	s_nop 1
	global_store_dwordx4 v[240:241], v[228:231], off offset:64
	v_readlane_b32 s39, v252, 18
	v_readlane_b32 s40, v252, 19
	v_min_u32_e32 v228, 32, v221
	v_lshlrev_b64 v[176:177], v228, v[200:201]
	v_min_u32_e32 v176, 1, v176
	v_or_b32_e32 v176, v177, v176
	v_cvt_f32_u32_e32 v176, v176
	v_sub_u32_e32 v177, 32, v228
	v_readlane_b32 s41, v252, 20
	v_readlane_b32 s42, v252, 21
	v_ldexp_f32 v176, v176, v177
	v_mul_f32_e32 v176, 0x35800000, v176
	v_fmamk_f32 v176, v176, 0x3a800000, v210
	v_cmp_gt_f32_e32 vcc, s89, v176
	v_mul_f32_e32 v177, 0x4b800000, v176
	v_readlane_b32 s43, v252, 22
	v_cndmask_b32_e32 v176, v176, v177, vcc
	v_rsq_f32_e32 v176, v176
	v_readlane_b32 s44, v252, 23
	v_readlane_b32 s45, v252, 24
	v_readlane_b32 s46, v252, 25
	v_mul_f32_e32 v177, 0x45800000, v176
	v_cndmask_b32_e32 v176, v176, v177, vcc
	v_pk_mul_f32 v[228:229], v[108:109], v[176:177] op_sel_hi:[1,0]
	v_pk_mul_f32 v[230:231], v[110:111], v[176:177] op_sel_hi:[1,0]
	v_pk_mul_f32 v[234:235], v[228:229], v[228:229]
	v_pk_mul_f32 v[232:233], v[230:231], v[230:231]
	v_pk_mul_f32 v[248:249], v[98:99], v[176:177] op_sel_hi:[1,0]
	v_pk_mov_b32 v[236:237], v[234:235], v[232:233] op_sel:[1,0]
	v_mov_b32_e32 v235, v233
	v_pk_add_f32 v[232:233], v[236:237], v[234:235]
	v_pk_mul_f32 v[234:235], v[104:105], v[176:177] op_sel_hi:[1,0]
	v_pk_mul_f32 v[236:237], v[106:107], v[176:177] op_sel_hi:[1,0]
	v_pk_mul_f32 v[240:241], v[234:235], v[234:235]
	v_pk_mul_f32 v[238:239], v[236:237], v[236:237]
	v_pk_add_f32 v[232:233], v[232:233], v[232:233] op_sel_hi:[0,1]
	v_pk_mov_b32 v[242:243], v[240:241], v[238:239] op_sel:[1,0]
	v_mov_b32_e32 v241, v239
	v_pk_add_f32 v[238:239], v[242:243], v[240:241]
	v_pk_mul_f32 v[242:243], v[100:101], v[176:177] op_sel_hi:[1,0]
	v_pk_mul_f32 v[240:241], v[102:103], v[176:177] op_sel_hi:[1,0]
	v_mul_f32_e32 v232, v242, v242
	v_pk_fma_f32 v[244:245], v[242:243], v[242:243], v[232:233] op_sel_hi:[1,1,0]
	v_mul_f32_e32 v232, v240, v240
	v_pk_add_f32 v[238:239], v[238:239], v[238:239] op_sel_hi:[0,1]
	v_pk_fma_f32 v[246:247], v[240:241], v[240:241], v[232:233] op_sel_hi:[1,1,0]
	v_pk_mul_f32 v[176:177], v[96:97], v[176:177] op_sel_hi:[1,0]
	v_mul_f32_e32 v232, v248, v248
	v_mul_f32_e32 v244, v176, v176
	v_mul_f32_e32 v246, v177, v177
	v_mul_f32_e32 v238, v249, v249
	v_pk_add_f32 v[244:245], v[244:245], v[246:247]
	v_pk_add_f32 v[232:233], v[232:233], v[238:239]
	v_lshl_add_u64 v[238:239], v[206:207], 0, v[198:199]
	v_pk_add_f32 v[232:233], v[244:245], v[232:233]
	v_readlane_b32 s47, v252, 26
	v_add_f32_e32 v232, v232, v233
	ds_bpermute_b32 v233, v225, v232
	v_readlane_b32 s49, v252, 28
	v_readlane_b32 s50, v252, 29
	v_readlane_b32 s51, v252, 30
	v_readlane_b32 s48, v252, 40
	s_waitcnt lgkmcnt(0)
	v_add_f32_e32 v232, v232, v233
	ds_bpermute_b32 v233, v224, v232
	s_mov_b64 s[0:1], 0
	s_waitcnt lgkmcnt(0)
	v_add_f32_e32 v232, v232, v233
	v_fmamk_f32 v232, v232, 0x3c800000, v210
	v_cmp_gt_f32_e32 vcc, s89, v232
	v_mul_f32_e32 v233, 0x4b800000, v232
	s_nop 0
	v_cndmask_b32_e32 v232, v232, v233, vcc
	v_rsq_f32_e32 v232, v232
	s_nop 0
	v_mul_f32_e32 v233, 0x45800000, v232
	v_cndmask_b32_e32 v232, v232, v233, vcc
	v_mul_f32_e32 v232, v223, v232
	v_pk_mul_f32 v[228:229], v[228:229], v[232:233] op_sel_hi:[1,0]
	v_pk_mul_f32 v[230:231], v[230:231], v[232:233] op_sel_hi:[1,0]
	v_pk_mul_f32 v[228:229], v[140:141], v[228:229]
	v_pk_mul_f32 v[230:231], v[142:143], v[230:231]
	v_pk_mul_f32 v[234:235], v[234:235], v[232:233] op_sel_hi:[1,0]
	v_pk_mul_f32 v[236:237], v[236:237], v[232:233] op_sel_hi:[1,0]
	v_cvt_pk_bf16_f32 v228, v228, v229
	v_cvt_pk_bf16_f32 v229, v230, v231
	v_pk_mul_f32 v[234:235], v[136:137], v[234:235]
	v_pk_mul_f32 v[236:237], v[138:139], v[236:237]
	v_cvt_pk_bf16_f32 v230, v234, v235
	v_pk_mul_f32 v[176:177], v[176:177], v[232:233] op_sel_hi:[1,0]
	v_cvt_pk_bf16_f32 v231, v236, v237
	global_store_dwordx4 v[238:239], v[228:231], off
	v_pk_mul_f32 v[176:177], v[128:129], v[176:177]
	s_nop 0
	v_pk_mul_f32 v[228:229], v[242:243], v[232:233] op_sel_hi:[1,0]
	v_pk_mul_f32 v[230:231], v[240:241], v[232:233] op_sel_hi:[1,0]
	v_pk_mul_f32 v[228:229], v[132:133], v[228:229]
	v_pk_mul_f32 v[230:231], v[134:135], v[230:231]
	v_pk_mul_f32 v[232:233], v[248:249], v[232:233] op_sel_hi:[1,0]
	v_cvt_pk_bf16_f32 v228, v228, v229
	v_cvt_pk_bf16_f32 v229, v230, v231
	v_cvt_pk_bf16_f32 v230, v176, v177
	s_nop 0
	v_pk_mul_f32 v[232:233], v[130:131], v[232:233]
	s_nop 0
	v_cvt_pk_bf16_f32 v231, v232, v233
	global_store_dwordx4 v[238:239], v[228:231], off offset:64
	s_nop 1
	v_min_u32_e32 v228, 32, v220
	v_lshlrev_b64 v[176:177], v228, v[192:193]
	v_min_u32_e32 v176, 1, v176
	v_or_b32_e32 v176, v177, v176
	v_cvt_f32_u32_e32 v176, v176
	v_sub_u32_e32 v177, 32, v228
	v_ldexp_f32 v176, v176, v177
	v_mul_f32_e32 v176, 0x35800000, v176
	v_fmamk_f32 v176, v176, 0x3a800000, v210
	v_cmp_gt_f32_e32 vcc, s89, v176
	v_mul_f32_e32 v177, 0x4b800000, v176
	s_nop 0
	v_cndmask_b32_e32 v176, v176, v177, vcc
	v_rsq_f32_e32 v176, v176
	s_nop 0
	v_mul_f32_e32 v177, 0x45800000, v176
	v_cndmask_b32_e32 v176, v176, v177, vcc
	v_pk_mul_f32 v[228:229], v[92:93], v[176:177] op_sel_hi:[1,0]
	v_pk_mul_f32 v[230:231], v[94:95], v[176:177] op_sel_hi:[1,0]
	v_pk_mul_f32 v[234:235], v[228:229], v[228:229]
	v_pk_mul_f32 v[232:233], v[230:231], v[230:231]
	v_pk_mul_f32 v[248:249], v[82:83], v[176:177] op_sel_hi:[1,0]
	v_pk_mov_b32 v[236:237], v[234:235], v[232:233] op_sel:[1,0]
	v_mov_b32_e32 v235, v233
	v_pk_add_f32 v[232:233], v[236:237], v[234:235]
	v_pk_mul_f32 v[234:235], v[88:89], v[176:177] op_sel_hi:[1,0]
	v_pk_mul_f32 v[236:237], v[90:91], v[176:177] op_sel_hi:[1,0]
	v_pk_mul_f32 v[240:241], v[234:235], v[234:235]
	v_pk_mul_f32 v[238:239], v[236:237], v[236:237]
	v_pk_add_f32 v[232:233], v[232:233], v[232:233] op_sel_hi:[0,1]
	v_pk_mov_b32 v[242:243], v[240:241], v[238:239] op_sel:[1,0]
	v_mov_b32_e32 v241, v239
	v_pk_add_f32 v[238:239], v[242:243], v[240:241]
	v_pk_mul_f32 v[242:243], v[84:85], v[176:177] op_sel_hi:[1,0]
	v_pk_mul_f32 v[240:241], v[86:87], v[176:177] op_sel_hi:[1,0]
	v_mul_f32_e32 v232, v242, v242
	v_pk_fma_f32 v[244:245], v[242:243], v[242:243], v[232:233] op_sel_hi:[1,1,0]
	v_mul_f32_e32 v232, v240, v240
	v_pk_add_f32 v[238:239], v[238:239], v[238:239] op_sel_hi:[0,1]
	v_pk_fma_f32 v[246:247], v[240:241], v[240:241], v[232:233] op_sel_hi:[1,1,0]
	v_pk_mul_f32 v[176:177], v[80:81], v[176:177] op_sel_hi:[1,0]
	v_mul_f32_e32 v232, v248, v248
	v_mul_f32_e32 v244, v176, v176
	v_mul_f32_e32 v246, v177, v177
	v_mul_f32_e32 v238, v249, v249
	v_pk_add_f32 v[244:245], v[244:245], v[246:247]
	v_pk_add_f32 v[232:233], v[232:233], v[238:239]
	v_lshl_add_u64 v[238:239], v[206:207], 0, v[194:195]
	v_pk_add_f32 v[232:233], v[244:245], v[232:233]
	s_nop 0
	v_add_f32_e32 v232, v232, v233
	ds_bpermute_b32 v233, v225, v232
	s_waitcnt lgkmcnt(0)
	v_add_f32_e32 v232, v232, v233
	ds_bpermute_b32 v233, v224, v232
	s_waitcnt lgkmcnt(0)
	v_add_f32_e32 v232, v232, v233
	v_fmamk_f32 v232, v232, 0x3c800000, v210
	v_cmp_gt_f32_e32 vcc, s89, v232
	v_mul_f32_e32 v233, 0x4b800000, v232
	s_nop 0
	v_cndmask_b32_e32 v232, v232, v233, vcc
	v_rsq_f32_e32 v232, v232
	s_nop 0
	v_mul_f32_e32 v233, 0x45800000, v232
	v_cndmask_b32_e32 v232, v232, v233, vcc
	v_mul_f32_e32 v232, v223, v232
	v_pk_mul_f32 v[228:229], v[228:229], v[232:233] op_sel_hi:[1,0]
	v_pk_mul_f32 v[230:231], v[230:231], v[232:233] op_sel_hi:[1,0]
	v_pk_mul_f32 v[228:229], v[140:141], v[228:229]
	v_pk_mul_f32 v[230:231], v[142:143], v[230:231]
	v_pk_mul_f32 v[234:235], v[234:235], v[232:233] op_sel_hi:[1,0]
	v_pk_mul_f32 v[236:237], v[236:237], v[232:233] op_sel_hi:[1,0]
	v_cvt_pk_bf16_f32 v228, v228, v229
	v_cvt_pk_bf16_f32 v229, v230, v231
	v_pk_mul_f32 v[234:235], v[136:137], v[234:235]
	v_pk_mul_f32 v[236:237], v[138:139], v[236:237]
	v_cvt_pk_bf16_f32 v230, v234, v235
	v_pk_mul_f32 v[176:177], v[176:177], v[232:233] op_sel_hi:[1,0]
	v_cvt_pk_bf16_f32 v231, v236, v237
	global_store_dwordx4 v[238:239], v[228:231], off
	v_pk_mul_f32 v[176:177], v[128:129], v[176:177]
	s_nop 0
	v_pk_mul_f32 v[228:229], v[242:243], v[232:233] op_sel_hi:[1,0]
	v_pk_mul_f32 v[230:231], v[240:241], v[232:233] op_sel_hi:[1,0]
	v_pk_mul_f32 v[228:229], v[132:133], v[228:229]
	v_pk_mul_f32 v[230:231], v[134:135], v[230:231]
	v_pk_mul_f32 v[232:233], v[248:249], v[232:233] op_sel_hi:[1,0]
	v_cvt_pk_bf16_f32 v228, v228, v229
	v_cvt_pk_bf16_f32 v229, v230, v231
	v_cvt_pk_bf16_f32 v230, v176, v177
	s_nop 0
	v_pk_mul_f32 v[232:233], v[130:131], v[232:233]
	s_nop 0
	v_cvt_pk_bf16_f32 v231, v232, v233
	global_store_dwordx4 v[238:239], v[228:231], off offset:64
	s_nop 1
	v_min_u32_e32 v228, 32, v219
	v_lshlrev_b64 v[176:177], v228, v[196:197]
	v_min_u32_e32 v176, 1, v176
	v_or_b32_e32 v176, v177, v176
	v_cvt_f32_u32_e32 v176, v176
	v_sub_u32_e32 v177, 32, v228
	v_ldexp_f32 v176, v176, v177
	v_mul_f32_e32 v176, 0x35800000, v176
	v_fmamk_f32 v176, v176, 0x3a800000, v210
	v_cmp_gt_f32_e32 vcc, s89, v176
	v_mul_f32_e32 v177, 0x4b800000, v176
	s_nop 0
	v_cndmask_b32_e32 v176, v176, v177, vcc
	v_rsq_f32_e32 v176, v176
	s_nop 0
	v_mul_f32_e32 v177, 0x45800000, v176
	v_cndmask_b32_e32 v176, v176, v177, vcc
	v_pk_mul_f32 v[228:229], v[76:77], v[176:177] op_sel_hi:[1,0]
	v_pk_mul_f32 v[230:231], v[78:79], v[176:177] op_sel_hi:[1,0]
	v_pk_mul_f32 v[234:235], v[228:229], v[228:229]
	v_pk_mul_f32 v[232:233], v[230:231], v[230:231]
	v_pk_mul_f32 v[248:249], v[66:67], v[176:177] op_sel_hi:[1,0]
	v_pk_mov_b32 v[236:237], v[234:235], v[232:233] op_sel:[1,0]
	v_mov_b32_e32 v235, v233
	v_pk_add_f32 v[232:233], v[236:237], v[234:235]
	v_pk_mul_f32 v[234:235], v[72:73], v[176:177] op_sel_hi:[1,0]
	v_pk_mul_f32 v[236:237], v[74:75], v[176:177] op_sel_hi:[1,0]
	v_pk_mul_f32 v[240:241], v[234:235], v[234:235]
	v_pk_mul_f32 v[238:239], v[236:237], v[236:237]
	v_pk_add_f32 v[232:233], v[232:233], v[232:233] op_sel_hi:[0,1]
	v_pk_mov_b32 v[242:243], v[240:241], v[238:239] op_sel:[1,0]
	v_mov_b32_e32 v241, v239
	v_pk_add_f32 v[238:239], v[242:243], v[240:241]
	v_pk_mul_f32 v[242:243], v[68:69], v[176:177] op_sel_hi:[1,0]
	v_pk_mul_f32 v[240:241], v[70:71], v[176:177] op_sel_hi:[1,0]
	v_mul_f32_e32 v232, v242, v242
	v_pk_fma_f32 v[244:245], v[242:243], v[242:243], v[232:233] op_sel_hi:[1,1,0]
	v_mul_f32_e32 v232, v240, v240
	v_pk_add_f32 v[238:239], v[238:239], v[238:239] op_sel_hi:[0,1]
	v_pk_fma_f32 v[246:247], v[240:241], v[240:241], v[232:233] op_sel_hi:[1,1,0]
	v_pk_mul_f32 v[176:177], v[64:65], v[176:177] op_sel_hi:[1,0]
	v_mul_f32_e32 v232, v248, v248
	v_mul_f32_e32 v244, v176, v176
	v_mul_f32_e32 v246, v177, v177
	v_mul_f32_e32 v238, v249, v249
	v_pk_add_f32 v[244:245], v[244:245], v[246:247]
	v_pk_add_f32 v[232:233], v[232:233], v[238:239]
	v_lshl_add_u64 v[238:239], v[206:207], 0, v[190:191]
	v_pk_add_f32 v[232:233], v[244:245], v[232:233]
	s_nop 0
	v_add_f32_e32 v232, v232, v233
	ds_bpermute_b32 v233, v225, v232
	s_waitcnt lgkmcnt(0)
	v_add_f32_e32 v232, v232, v233
	ds_bpermute_b32 v233, v224, v232
	s_waitcnt lgkmcnt(0)
	v_add_f32_e32 v232, v232, v233
	v_fmamk_f32 v232, v232, 0x3c800000, v210
	v_cmp_gt_f32_e32 vcc, s89, v232
	v_mul_f32_e32 v233, 0x4b800000, v232
	s_nop 0
	v_cndmask_b32_e32 v232, v232, v233, vcc
	v_rsq_f32_e32 v232, v232
	s_nop 0
	v_mul_f32_e32 v233, 0x45800000, v232
	v_cndmask_b32_e32 v232, v232, v233, vcc
	v_mul_f32_e32 v232, v223, v232
	v_pk_mul_f32 v[228:229], v[228:229], v[232:233] op_sel_hi:[1,0]
	v_pk_mul_f32 v[230:231], v[230:231], v[232:233] op_sel_hi:[1,0]
	v_pk_mul_f32 v[228:229], v[140:141], v[228:229]
	v_pk_mul_f32 v[230:231], v[142:143], v[230:231]
	v_pk_mul_f32 v[234:235], v[234:235], v[232:233] op_sel_hi:[1,0]
	v_pk_mul_f32 v[236:237], v[236:237], v[232:233] op_sel_hi:[1,0]
	v_pk_mul_f32 v[234:235], v[136:137], v[234:235]
	v_pk_mul_f32 v[236:237], v[138:139], v[236:237]
	v_cvt_pk_bf16_f32 v228, v228, v229
	v_cvt_pk_bf16_f32 v229, v230, v231
	v_cvt_pk_bf16_f32 v230, v234, v235
	v_pk_mul_f32 v[176:177], v[176:177], v[232:233] op_sel_hi:[1,0]
	v_cvt_pk_bf16_f32 v231, v236, v237
	global_store_dwordx4 v[238:239], v[228:231], off
	v_pk_mul_f32 v[176:177], v[128:129], v[176:177]
	s_nop 0
	v_pk_mul_f32 v[228:229], v[242:243], v[232:233] op_sel_hi:[1,0]
	v_pk_mul_f32 v[230:231], v[240:241], v[232:233] op_sel_hi:[1,0]
	v_pk_mul_f32 v[228:229], v[132:133], v[228:229]
	v_pk_mul_f32 v[230:231], v[134:135], v[230:231]
	v_pk_mul_f32 v[232:233], v[248:249], v[232:233] op_sel_hi:[1,0]
	v_cvt_pk_bf16_f32 v228, v228, v229
	v_cvt_pk_bf16_f32 v229, v230, v231
	v_cvt_pk_bf16_f32 v230, v176, v177
	v_ffbh_u32_e32 v176, v167
	v_pk_mul_f32 v[232:233], v[130:131], v[232:233]
	s_nop 0
	v_cvt_pk_bf16_f32 v231, v232, v233
	global_store_dwordx4 v[238:239], v[228:231], off offset:64
	s_nop 1
	v_min_u32_e32 v228, 32, v176
	v_lshlrev_b64 v[176:177], v228, v[166:167]
	v_min_u32_e32 v176, 1, v176
	v_or_b32_e32 v176, v177, v176
	v_cvt_f32_u32_e32 v176, v176
	v_sub_u32_e32 v177, 32, v228
	v_ldexp_f32 v176, v176, v177
	v_mul_f32_e32 v176, 0x35800000, v176
	v_fmamk_f32 v176, v176, 0x3a800000, v210
	v_cmp_gt_f32_e32 vcc, s89, v176
	v_mul_f32_e32 v177, 0x4b800000, v176
	s_nop 0
	v_cndmask_b32_e32 v176, v176, v177, vcc
	v_rsq_f32_e32 v176, v176
	s_nop 0
	v_mul_f32_e32 v177, 0x45800000, v176
	v_cndmask_b32_e32 v176, v176, v177, vcc
	v_pk_mul_f32 v[228:229], v[60:61], v[176:177] op_sel_hi:[1,0]
	v_pk_mul_f32 v[230:231], v[62:63], v[176:177] op_sel_hi:[1,0]
	v_pk_mul_f32 v[234:235], v[228:229], v[228:229]
	v_pk_mul_f32 v[232:233], v[230:231], v[230:231]
	v_pk_mul_f32 v[248:249], v[50:51], v[176:177] op_sel_hi:[1,0]
	v_pk_mov_b32 v[236:237], v[234:235], v[232:233] op_sel:[1,0]
	v_mov_b32_e32 v235, v233
	v_pk_add_f32 v[232:233], v[236:237], v[234:235]
	v_pk_mul_f32 v[234:235], v[56:57], v[176:177] op_sel_hi:[1,0]
	v_pk_mul_f32 v[236:237], v[58:59], v[176:177] op_sel_hi:[1,0]
	v_pk_mul_f32 v[240:241], v[234:235], v[234:235]
	v_pk_mul_f32 v[238:239], v[236:237], v[236:237]
	v_pk_add_f32 v[232:233], v[232:233], v[232:233] op_sel_hi:[0,1]
	v_pk_mov_b32 v[242:243], v[240:241], v[238:239] op_sel:[1,0]
	v_mov_b32_e32 v241, v239
	v_pk_add_f32 v[238:239], v[242:243], v[240:241]
	v_pk_mul_f32 v[242:243], v[52:53], v[176:177] op_sel_hi:[1,0]
	v_pk_mul_f32 v[240:241], v[54:55], v[176:177] op_sel_hi:[1,0]
	v_mul_f32_e32 v232, v242, v242
	v_pk_fma_f32 v[244:245], v[242:243], v[242:243], v[232:233] op_sel_hi:[1,1,0]
	v_mul_f32_e32 v232, v240, v240
	v_pk_add_f32 v[238:239], v[238:239], v[238:239] op_sel_hi:[0,1]
	v_pk_fma_f32 v[246:247], v[240:241], v[240:241], v[232:233] op_sel_hi:[1,1,0]
	v_pk_mul_f32 v[176:177], v[48:49], v[176:177] op_sel_hi:[1,0]
	v_mul_f32_e32 v232, v248, v248
	v_mul_f32_e32 v244, v176, v176
	v_mul_f32_e32 v246, v177, v177
	v_mul_f32_e32 v238, v249, v249
	v_pk_add_f32 v[244:245], v[244:245], v[246:247]
	v_pk_add_f32 v[232:233], v[232:233], v[238:239]
	v_lshlrev_b64 v[238:239], 10, v[168:169]
	v_pk_add_f32 v[232:233], v[244:245], v[232:233]
	v_lshl_add_u64 v[238:239], v[206:207], 0, v[238:239]
	v_add_f32_e32 v232, v232, v233
	ds_bpermute_b32 v233, v225, v232
	s_waitcnt lgkmcnt(0)
	v_add_f32_e32 v232, v232, v233
	ds_bpermute_b32 v233, v224, v232
	s_waitcnt lgkmcnt(0)
	v_add_f32_e32 v232, v232, v233
	v_fmamk_f32 v232, v232, 0x3c800000, v210
	v_cmp_gt_f32_e32 vcc, s89, v232
	v_mul_f32_e32 v233, 0x4b800000, v232
	s_nop 0
	v_cndmask_b32_e32 v232, v232, v233, vcc
	v_rsq_f32_e32 v232, v232
	s_nop 0
	v_mul_f32_e32 v233, 0x45800000, v232
	v_cndmask_b32_e32 v232, v232, v233, vcc
	v_mul_f32_e32 v232, v223, v232
	v_pk_mul_f32 v[228:229], v[228:229], v[232:233] op_sel_hi:[1,0]
	v_pk_mul_f32 v[230:231], v[230:231], v[232:233] op_sel_hi:[1,0]
	v_pk_mul_f32 v[228:229], v[140:141], v[228:229]
	v_pk_mul_f32 v[230:231], v[142:143], v[230:231]
	v_pk_mul_f32 v[234:235], v[234:235], v[232:233] op_sel_hi:[1,0]
	v_pk_mul_f32 v[236:237], v[236:237], v[232:233] op_sel_hi:[1,0]
	v_pk_mul_f32 v[234:235], v[136:137], v[234:235]
	v_pk_mul_f32 v[236:237], v[138:139], v[236:237]
	v_cvt_pk_bf16_f32 v228, v228, v229
	v_cvt_pk_bf16_f32 v229, v230, v231
	v_cvt_pk_bf16_f32 v230, v234, v235
	v_pk_mul_f32 v[176:177], v[176:177], v[232:233] op_sel_hi:[1,0]
	v_cvt_pk_bf16_f32 v231, v236, v237
	global_store_dwordx4 v[238:239], v[228:231], off
	v_pk_mul_f32 v[176:177], v[128:129], v[176:177]
	s_nop 0
	v_pk_mul_f32 v[228:229], v[242:243], v[232:233] op_sel_hi:[1,0]
	v_pk_mul_f32 v[230:231], v[240:241], v[232:233] op_sel_hi:[1,0]
	v_pk_mul_f32 v[228:229], v[132:133], v[228:229]
	v_pk_mul_f32 v[230:231], v[134:135], v[230:231]
	v_pk_mul_f32 v[232:233], v[248:249], v[232:233] op_sel_hi:[1,0]
	v_cvt_pk_bf16_f32 v228, v228, v229
	v_cvt_pk_bf16_f32 v229, v230, v231
	v_cvt_pk_bf16_f32 v230, v176, v177
	v_ffbh_u32_e32 v176, v189
	v_pk_mul_f32 v[232:233], v[130:131], v[232:233]
	s_nop 0
	v_cvt_pk_bf16_f32 v231, v232, v233
	global_store_dwordx4 v[238:239], v[228:231], off offset:64
	s_nop 1
	v_min_u32_e32 v228, 32, v176
	v_lshlrev_b64 v[176:177], v228, v[188:189]
	v_min_u32_e32 v176, 1, v176
	v_or_b32_e32 v176, v177, v176
	v_cvt_f32_u32_e32 v176, v176
	v_sub_u32_e32 v177, 32, v228
	v_ldexp_f32 v176, v176, v177
	v_mul_f32_e32 v176, 0x35800000, v176
	v_fmamk_f32 v176, v176, 0x3a800000, v210
	v_cmp_gt_f32_e32 vcc, s89, v176
	v_mul_f32_e32 v177, 0x4b800000, v176
	s_nop 0
	v_cndmask_b32_e32 v176, v176, v177, vcc
	v_rsq_f32_e32 v176, v176
	s_nop 0
	v_mul_f32_e32 v177, 0x45800000, v176
	v_cndmask_b32_e32 v176, v176, v177, vcc
	v_pk_mul_f32 v[228:229], v[44:45], v[176:177] op_sel_hi:[1,0]
	v_pk_mul_f32 v[230:231], v[46:47], v[176:177] op_sel_hi:[1,0]
	v_pk_mul_f32 v[234:235], v[228:229], v[228:229]
	v_pk_mul_f32 v[232:233], v[230:231], v[230:231]
	v_pk_mul_f32 v[248:249], v[34:35], v[176:177] op_sel_hi:[1,0]
	v_pk_mov_b32 v[236:237], v[234:235], v[232:233] op_sel:[1,0]
	v_mov_b32_e32 v235, v233
	v_pk_add_f32 v[232:233], v[236:237], v[234:235]
	v_pk_mul_f32 v[234:235], v[40:41], v[176:177] op_sel_hi:[1,0]
	v_pk_mul_f32 v[236:237], v[42:43], v[176:177] op_sel_hi:[1,0]
	v_pk_mul_f32 v[240:241], v[234:235], v[234:235]
	v_pk_mul_f32 v[238:239], v[236:237], v[236:237]
	v_pk_add_f32 v[232:233], v[232:233], v[232:233] op_sel_hi:[0,1]
	v_pk_mov_b32 v[242:243], v[240:241], v[238:239] op_sel:[1,0]
	v_mov_b32_e32 v241, v239
	v_pk_add_f32 v[238:239], v[242:243], v[240:241]
	v_pk_mul_f32 v[242:243], v[36:37], v[176:177] op_sel_hi:[1,0]
	v_pk_mul_f32 v[240:241], v[38:39], v[176:177] op_sel_hi:[1,0]
	v_mul_f32_e32 v232, v242, v242
	v_pk_fma_f32 v[244:245], v[242:243], v[242:243], v[232:233] op_sel_hi:[1,1,0]
	v_mul_f32_e32 v232, v240, v240
	v_pk_add_f32 v[238:239], v[238:239], v[238:239] op_sel_hi:[0,1]
	v_pk_fma_f32 v[246:247], v[240:241], v[240:241], v[232:233] op_sel_hi:[1,1,0]
	v_pk_mul_f32 v[176:177], v[32:33], v[176:177] op_sel_hi:[1,0]
	v_mul_f32_e32 v232, v248, v248
	v_mul_f32_e32 v244, v176, v176
	v_mul_f32_e32 v246, v177, v177
	v_mul_f32_e32 v238, v249, v249
	v_pk_add_f32 v[244:245], v[244:245], v[246:247]
	v_pk_add_f32 v[232:233], v[232:233], v[238:239]
	v_lshlrev_b64 v[238:239], 10, v[164:165]
	v_pk_add_f32 v[232:233], v[244:245], v[232:233]
	v_lshl_add_u64 v[238:239], v[206:207], 0, v[238:239]
	v_add_f32_e32 v232, v232, v233
	ds_bpermute_b32 v233, v225, v232
	s_waitcnt lgkmcnt(0)
	v_add_f32_e32 v232, v232, v233
	ds_bpermute_b32 v233, v224, v232
	s_waitcnt lgkmcnt(0)
	v_add_f32_e32 v232, v232, v233
	v_fmamk_f32 v232, v232, 0x3c800000, v210
	v_cmp_gt_f32_e32 vcc, s89, v232
	v_mul_f32_e32 v233, 0x4b800000, v232
	s_nop 0
	v_cndmask_b32_e32 v232, v232, v233, vcc
	v_rsq_f32_e32 v232, v232
	s_nop 0
	v_mul_f32_e32 v233, 0x45800000, v232
	v_cndmask_b32_e32 v232, v232, v233, vcc
	v_mul_f32_e32 v232, v223, v232
	v_pk_mul_f32 v[228:229], v[228:229], v[232:233] op_sel_hi:[1,0]
	v_pk_mul_f32 v[230:231], v[230:231], v[232:233] op_sel_hi:[1,0]
	v_pk_mul_f32 v[228:229], v[140:141], v[228:229]
	v_pk_mul_f32 v[230:231], v[142:143], v[230:231]
	v_pk_mul_f32 v[234:235], v[234:235], v[232:233] op_sel_hi:[1,0]
	v_pk_mul_f32 v[236:237], v[236:237], v[232:233] op_sel_hi:[1,0]
	v_pk_mul_f32 v[234:235], v[136:137], v[234:235]
	v_pk_mul_f32 v[236:237], v[138:139], v[236:237]
	v_cvt_pk_bf16_f32 v228, v228, v229
	v_cvt_pk_bf16_f32 v229, v230, v231
	v_cvt_pk_bf16_f32 v230, v234, v235
	v_pk_mul_f32 v[176:177], v[176:177], v[232:233] op_sel_hi:[1,0]
	v_cvt_pk_bf16_f32 v231, v236, v237
	global_store_dwordx4 v[238:239], v[228:231], off
	v_pk_mul_f32 v[176:177], v[128:129], v[176:177]
	s_nop 0
	v_pk_mul_f32 v[228:229], v[242:243], v[232:233] op_sel_hi:[1,0]
	v_pk_mul_f32 v[230:231], v[240:241], v[232:233] op_sel_hi:[1,0]
	v_pk_mul_f32 v[228:229], v[132:133], v[228:229]
	v_pk_mul_f32 v[230:231], v[134:135], v[230:231]
	v_pk_mul_f32 v[232:233], v[248:249], v[232:233] op_sel_hi:[1,0]
	v_cvt_pk_bf16_f32 v228, v228, v229
	v_cvt_pk_bf16_f32 v229, v230, v231
	v_cvt_pk_bf16_f32 v230, v176, v177
	v_ffbh_u32_e32 v176, v163
	v_pk_mul_f32 v[232:233], v[130:131], v[232:233]
	s_nop 0
	v_cvt_pk_bf16_f32 v231, v232, v233
	global_store_dwordx4 v[238:239], v[228:231], off offset:64
	s_nop 1
	v_min_u32_e32 v228, 32, v176
	v_lshlrev_b64 v[176:177], v228, v[162:163]
	v_min_u32_e32 v176, 1, v176
	v_or_b32_e32 v176, v177, v176
	v_cvt_f32_u32_e32 v176, v176
	v_sub_u32_e32 v177, 32, v228
	v_ldexp_f32 v176, v176, v177
	v_mul_f32_e32 v176, 0x35800000, v176
	v_fmamk_f32 v176, v176, 0x3a800000, v210
	v_cmp_gt_f32_e32 vcc, s89, v176
	v_mul_f32_e32 v177, 0x4b800000, v176
	s_nop 0
	v_cndmask_b32_e32 v176, v176, v177, vcc
	v_rsq_f32_e32 v176, v176
	s_nop 0
	v_mul_f32_e32 v177, 0x45800000, v176
	v_cndmask_b32_e32 v176, v176, v177, vcc
	v_pk_mul_f32 v[228:229], v[28:29], v[176:177] op_sel_hi:[1,0]
	v_pk_mul_f32 v[230:231], v[30:31], v[176:177] op_sel_hi:[1,0]
	v_pk_mul_f32 v[234:235], v[228:229], v[228:229]
	v_pk_mul_f32 v[232:233], v[230:231], v[230:231]
	v_pk_mul_f32 v[248:249], v[18:19], v[176:177] op_sel_hi:[1,0]
	v_pk_mov_b32 v[236:237], v[234:235], v[232:233] op_sel:[1,0]
	v_mov_b32_e32 v235, v233
	v_pk_add_f32 v[232:233], v[236:237], v[234:235]
	v_pk_mul_f32 v[234:235], v[24:25], v[176:177] op_sel_hi:[1,0]
	v_pk_mul_f32 v[236:237], v[26:27], v[176:177] op_sel_hi:[1,0]
	v_pk_mul_f32 v[240:241], v[234:235], v[234:235]
	v_pk_mul_f32 v[238:239], v[236:237], v[236:237]
	v_pk_add_f32 v[232:233], v[232:233], v[232:233] op_sel_hi:[0,1]
	v_pk_mov_b32 v[242:243], v[240:241], v[238:239] op_sel:[1,0]
	v_mov_b32_e32 v241, v239
	v_pk_add_f32 v[238:239], v[242:243], v[240:241]
	v_pk_mul_f32 v[242:243], v[20:21], v[176:177] op_sel_hi:[1,0]
	v_pk_mul_f32 v[240:241], v[22:23], v[176:177] op_sel_hi:[1,0]
	v_mul_f32_e32 v232, v242, v242
	v_pk_fma_f32 v[244:245], v[242:243], v[242:243], v[232:233] op_sel_hi:[1,1,0]
	v_mul_f32_e32 v232, v240, v240
	v_pk_add_f32 v[238:239], v[238:239], v[238:239] op_sel_hi:[0,1]
	v_pk_fma_f32 v[246:247], v[240:241], v[240:241], v[232:233] op_sel_hi:[1,1,0]
	v_pk_mul_f32 v[176:177], v[16:17], v[176:177] op_sel_hi:[1,0]
	v_mul_f32_e32 v232, v248, v248
	v_mul_f32_e32 v244, v176, v176
	v_mul_f32_e32 v246, v177, v177
	v_mul_f32_e32 v238, v249, v249
	v_pk_add_f32 v[244:245], v[244:245], v[246:247]
	v_pk_add_f32 v[232:233], v[232:233], v[238:239]
	v_lshlrev_b64 v[238:239], 10, v[158:159]
	v_pk_add_f32 v[232:233], v[244:245], v[232:233]
	v_lshl_add_u64 v[238:239], v[206:207], 0, v[238:239]
	v_add_f32_e32 v232, v232, v233
	ds_bpermute_b32 v233, v225, v232
	s_waitcnt lgkmcnt(0)
	v_add_f32_e32 v232, v232, v233
	ds_bpermute_b32 v233, v224, v232
	s_waitcnt lgkmcnt(0)
	v_add_f32_e32 v232, v232, v233
	v_fmamk_f32 v232, v232, 0x3c800000, v210
	v_cmp_gt_f32_e32 vcc, s89, v232
	v_mul_f32_e32 v233, 0x4b800000, v232
	s_nop 0
	v_cndmask_b32_e32 v232, v232, v233, vcc
	v_rsq_f32_e32 v232, v232
	s_nop 0
	v_mul_f32_e32 v233, 0x45800000, v232
	v_cndmask_b32_e32 v232, v232, v233, vcc
	v_mul_f32_e32 v232, v223, v232
	v_pk_mul_f32 v[228:229], v[228:229], v[232:233] op_sel_hi:[1,0]
	v_pk_mul_f32 v[230:231], v[230:231], v[232:233] op_sel_hi:[1,0]
	v_pk_mul_f32 v[228:229], v[140:141], v[228:229]
	v_pk_mul_f32 v[230:231], v[142:143], v[230:231]
	v_pk_mul_f32 v[234:235], v[234:235], v[232:233] op_sel_hi:[1,0]
	v_pk_mul_f32 v[236:237], v[236:237], v[232:233] op_sel_hi:[1,0]
	v_pk_mul_f32 v[234:235], v[136:137], v[234:235]
	v_pk_mul_f32 v[236:237], v[138:139], v[236:237]
	v_cvt_pk_bf16_f32 v228, v228, v229
	v_cvt_pk_bf16_f32 v229, v230, v231
	v_cvt_pk_bf16_f32 v230, v234, v235
	v_pk_mul_f32 v[176:177], v[176:177], v[232:233] op_sel_hi:[1,0]
	v_cvt_pk_bf16_f32 v231, v236, v237
	global_store_dwordx4 v[238:239], v[228:231], off
	v_pk_mul_f32 v[176:177], v[128:129], v[176:177]
	s_nop 0
	v_pk_mul_f32 v[228:229], v[242:243], v[232:233] op_sel_hi:[1,0]
	v_pk_mul_f32 v[230:231], v[240:241], v[232:233] op_sel_hi:[1,0]
	v_pk_mul_f32 v[228:229], v[132:133], v[228:229]
	v_pk_mul_f32 v[230:231], v[134:135], v[230:231]
	v_pk_mul_f32 v[232:233], v[248:249], v[232:233] op_sel_hi:[1,0]
	v_cvt_pk_bf16_f32 v228, v228, v229
	v_cvt_pk_bf16_f32 v229, v230, v231
	v_cvt_pk_bf16_f32 v230, v176, v177
	v_ffbh_u32_e32 v176, v161
	v_pk_mul_f32 v[232:233], v[130:131], v[232:233]
	s_nop 0
	v_cvt_pk_bf16_f32 v231, v232, v233
	global_store_dwordx4 v[238:239], v[228:231], off offset:64
	s_nop 1
	v_min_u32_e32 v228, 32, v176
	v_lshlrev_b64 v[176:177], v228, v[160:161]
	v_min_u32_e32 v176, 1, v176
	v_or_b32_e32 v176, v177, v176
	v_cvt_f32_u32_e32 v176, v176
	v_sub_u32_e32 v177, 32, v228
	v_ldexp_f32 v176, v176, v177
	v_mul_f32_e32 v176, 0x35800000, v176
	v_fmamk_f32 v176, v176, 0x3a800000, v210
	v_cmp_gt_f32_e32 vcc, s89, v176
	v_mul_f32_e32 v177, 0x4b800000, v176
	s_nop 0
	v_cndmask_b32_e32 v176, v176, v177, vcc
	v_rsq_f32_e32 v176, v176
	s_nop 0
	v_mul_f32_e32 v177, 0x45800000, v176
	v_cndmask_b32_e32 v176, v176, v177, vcc
	v_pk_mul_f32 v[228:229], v[12:13], v[176:177] op_sel_hi:[1,0]
	v_pk_mul_f32 v[230:231], v[14:15], v[176:177] op_sel_hi:[1,0]
	v_pk_mul_f32 v[234:235], v[228:229], v[228:229]
	v_pk_mul_f32 v[232:233], v[230:231], v[230:231]
	v_pk_mul_f32 v[248:249], v[2:3], v[176:177] op_sel_hi:[1,0]
	v_pk_mov_b32 v[236:237], v[234:235], v[232:233] op_sel:[1,0]
	v_mov_b32_e32 v235, v233
	v_pk_add_f32 v[232:233], v[236:237], v[234:235]
	v_pk_mul_f32 v[234:235], v[8:9], v[176:177] op_sel_hi:[1,0]
	v_pk_mul_f32 v[236:237], v[10:11], v[176:177] op_sel_hi:[1,0]
	v_pk_mul_f32 v[240:241], v[234:235], v[234:235]
	v_pk_mul_f32 v[238:239], v[236:237], v[236:237]
	v_pk_add_f32 v[232:233], v[232:233], v[232:233] op_sel_hi:[0,1]
	v_pk_mov_b32 v[242:243], v[240:241], v[238:239] op_sel:[1,0]
	v_mov_b32_e32 v241, v239
	v_pk_add_f32 v[238:239], v[242:243], v[240:241]
	v_pk_mul_f32 v[242:243], v[4:5], v[176:177] op_sel_hi:[1,0]
	v_pk_mul_f32 v[240:241], v[6:7], v[176:177] op_sel_hi:[1,0]
	v_mul_f32_e32 v232, v242, v242
	v_pk_fma_f32 v[244:245], v[242:243], v[242:243], v[232:233] op_sel_hi:[1,1,0]
	v_mul_f32_e32 v232, v240, v240
	v_pk_add_f32 v[238:239], v[238:239], v[238:239] op_sel_hi:[0,1]
	v_pk_fma_f32 v[246:247], v[240:241], v[240:241], v[232:233] op_sel_hi:[1,1,0]
	v_pk_mul_f32 v[176:177], v[0:1], v[176:177] op_sel_hi:[1,0]
	v_mul_f32_e32 v232, v248, v248
	v_mul_f32_e32 v244, v176, v176
	v_mul_f32_e32 v246, v177, v177
	v_mul_f32_e32 v238, v249, v249
	v_pk_add_f32 v[244:245], v[244:245], v[246:247]
	v_pk_add_f32 v[232:233], v[232:233], v[238:239]
	s_nop 0
	v_pk_add_f32 v[232:233], v[244:245], v[232:233]
	s_nop 0
	v_add_f32_e32 v232, v232, v233
	ds_bpermute_b32 v225, v225, v232
	s_waitcnt lgkmcnt(0)
	v_add_f32_e32 v225, v232, v225
	ds_bpermute_b32 v224, v224, v225
	v_lshlrev_b64 v[232:233], 10, v[156:157]
	v_lshl_add_u64 v[206:207], v[206:207], 0, v[232:233]
	s_waitcnt lgkmcnt(0)
	v_add_f32_e32 v224, v225, v224
	v_fmamk_f32 v224, v224, 0x3c800000, v210
	v_cmp_gt_f32_e32 vcc, s89, v224
	v_mul_f32_e32 v225, 0x4b800000, v224
	s_nop 0
	v_cndmask_b32_e32 v224, v224, v225, vcc
	v_rsq_f32_e32 v224, v224
	s_nop 0
	v_mul_f32_e32 v225, 0x45800000, v224
	v_cndmask_b32_e32 v224, v224, v225, vcc
	v_mul_f32_e32 v224, v223, v224
	v_pk_mul_f32 v[228:229], v[228:229], v[224:225] op_sel_hi:[1,0]
	v_pk_mul_f32 v[230:231], v[230:231], v[224:225] op_sel_hi:[1,0]
	v_pk_mul_f32 v[140:141], v[140:141], v[228:229]
	v_pk_mul_f32 v[142:143], v[142:143], v[230:231]
	v_pk_mul_f32 v[228:229], v[234:235], v[224:225] op_sel_hi:[1,0]
	v_pk_mul_f32 v[230:231], v[236:237], v[224:225] op_sel_hi:[1,0]
	s_nop 0
	v_pk_mul_f32 v[230:231], v[138:139], v[230:231]
	v_pk_mul_f32 v[138:139], v[136:137], v[228:229]
	v_cvt_pk_bf16_f32 v136, v140, v141
	v_cvt_pk_bf16_f32 v137, v142, v143
	s_nop 0
	v_cvt_pk_bf16_f32 v138, v138, v139
	v_cvt_pk_bf16_f32 v139, v230, v231
	global_store_dwordx4 v[206:207], v[136:139], off
	s_nop 1
	v_pk_mul_f32 v[136:137], v[242:243], v[224:225] op_sel_hi:[1,0]
	v_pk_mul_f32 v[138:139], v[240:241], v[224:225] op_sel_hi:[1,0]
	v_pk_mul_f32 v[132:133], v[132:133], v[136:137]
	v_pk_mul_f32 v[134:135], v[134:135], v[138:139]
	v_pk_mul_f32 v[136:137], v[176:177], v[224:225] op_sel_hi:[1,0]
	v_pk_mul_f32 v[138:139], v[248:249], v[224:225] op_sel_hi:[1,0]
	s_nop 0
	v_pk_mul_f32 v[138:139], v[130:131], v[138:139]
	v_pk_mul_f32 v[130:131], v[128:129], v[136:137]
	v_cvt_pk_bf16_f32 v128, v132, v133
	v_cvt_pk_bf16_f32 v129, v134, v135
	s_nop 0
	v_cvt_pk_bf16_f32 v130, v130, v131
	v_cvt_pk_bf16_f32 v131, v138, v139
	s_nop 1
.LBB0_329:
	s_andn2_b64 vcc, exec, s[0:1]
	s_cbranch_vccnz .LBB0_322
	v_min_u32_e32 v130, 32, v222
	v_lshlrev_b64 v[128:129], v130, v[202:203]
	v_min_u32_e32 v128, 1, v128
	v_or_b32_e32 v128, v129, v128
	v_min_u32_e32 v132, 32, v221
	v_cvt_f32_u32_e32 v131, v128
	v_lshlrev_b64 v[128:129], v132, v[200:201]
	v_min_u32_e32 v128, 1, v128
	v_or_b32_e32 v128, v129, v128
	v_cvt_f32_u32_e32 v128, v128
	v_sub_u32_e32 v129, 32, v130
	v_sub_u32_e32 v130, 32, v132
	v_ldexp_f32 v129, v131, v129
	v_ldexp_f32 v128, v128, v130
	s_mov_b32 s30, 0x35800000
	s_mov_b32 s0, 0x358637bd
	v_pk_mul_f32 v[130:131], v[128:129], s[30:31] op_sel_hi:[1,0]
	v_mov_b64_e32 v[128:129], s[0:1]
	v_pk_fma_f32 v[130:131], v[130:131], s[2:3], v[128:129] op_sel_hi:[1,0,0]
	v_lshl_add_u64 v[132:133], s[96:97], 0, v[204:205]
	v_mul_f32_e32 v134, 0x4b800000, v131
	v_cmp_gt_f32_e32 vcc, s89, v131
	s_lshl_b32 s98, s10, 9
	v_lshl_add_u64 v[132:133], v[132:133], 0, s[98:99]
	v_cndmask_b32_e32 v131, v131, v134, vcc
	v_rsq_f32_e32 v131, v131
	v_lshl_add_u64 v[132:133], v[132:133], 0, v[144:145]
	v_mul_f32_e32 v134, 0x45800000, v131
	v_cndmask_b32_e32 v134, v131, v134, vcc
	v_pk_mul_f32 v[124:125], v[124:125], v[134:135] op_sel_hi:[1,0]
	v_pk_mul_f32 v[136:137], v[122:123], v[134:135] op_sel_hi:[1,0]
	v_fma_f32 v131, |v124|, s26, 1.0
	v_rcp_f32_e32 v131, v131
	v_pk_mul_f32 v[122:123], v[120:121], v[134:135] op_sel_hi:[1,0]
	v_mul_f32_e32 v121, v124, v124
	v_mul_f32_e32 v121, 0xbf38aa3b, v121
	v_fmamk_f32 v120, v131, 0x3f07dc22, v211
	v_fmaak_f32 v120, v131, v120, 0x3f35f0e3
	v_fmaak_f32 v120, v131, v120, 0xbe11a98e
	v_exp_f32_e32 v121, v121
	v_fmaak_f32 v120, v131, v120, 0x3e027906
	v_mul_f32_e32 v120, v131, v120
	v_fma_f32 v131, |v125|, s26, 1.0
	v_rcp_f32_e32 v131, v131
	v_mul_f32_e32 v120, v121, v120
	v_mul_f32_e32 v121, v124, v120
	v_fma_f32 v120, -v124, v120, v124
	v_cmp_gt_f32_e32 vcc, 0, v124
	v_mul_f32_e32 v124, v125, v125
	v_mul_f32_e32 v124, 0xbf38aa3b, v124
	v_cndmask_b32_e32 v120, v120, v121, vcc
	v_fmamk_f32 v121, v131, 0x3f07dc22, v211
	v_fmaak_f32 v121, v131, v121, 0x3f35f0e3
	v_exp_f32_e32 v124, v124
	v_fmaak_f32 v121, v131, v121, 0xbe11a98e
	v_pk_mul_f32 v[126:127], v[126:127], v[134:135] op_sel_hi:[1,0]
	v_fmaak_f32 v121, v131, v121, 0x3e027906
	v_mul_f32_e32 v121, v131, v121
	v_fma_f32 v131, |v126|, s26, 1.0
	v_rcp_f32_e32 v131, v131
	v_mul_f32_e32 v121, v124, v121
	v_mul_f32_e32 v124, v125, v121
	v_fma_f32 v121, -v125, v121, v125
	v_cmp_gt_f32_e32 vcc, 0, v125
	v_fma_f32 v125, |v127|, s26, 1.0
	v_rcp_f32_e32 v125, v125
	v_cndmask_b32_e32 v121, v121, v124, vcc
	v_mul_f32_e32 v124, v126, v126
	v_cvt_pk_bf16_f32 v120, v120, v121
	v_fmamk_f32 v121, v131, 0x3f07dc22, v211
	v_mul_f32_e32 v124, 0xbf38aa3b, v124
	v_fmaak_f32 v121, v131, v121, 0x3f35f0e3
	v_exp_f32_e32 v124, v124
	v_fmaak_f32 v121, v131, v121, 0xbe11a98e
	v_fmaak_f32 v121, v131, v121, 0x3e027906
	v_mul_f32_e32 v121, v131, v121
	v_mul_f32_e32 v121, v124, v121
	v_mul_f32_e32 v124, v126, v121
	v_fma_f32 v121, -v126, v121, v126
	v_cmp_gt_f32_e32 vcc, 0, v126
	v_mul_f32_e32 v126, v127, v127
	v_mul_f32_e32 v126, 0xbf38aa3b, v126
	v_cndmask_b32_e32 v121, v121, v124, vcc
	v_fmamk_f32 v124, v125, 0x3f07dc22, v211
	v_fmaak_f32 v124, v125, v124, 0x3f35f0e3
	v_exp_f32_e32 v126, v126
	v_fmaak_f32 v124, v125, v124, 0xbe11a98e
	v_fmaak_f32 v124, v125, v124, 0x3e027906
	v_mul_f32_e32 v124, v125, v124
	v_mul_f32_e32 v124, v126, v124
	v_fma_f32 v126, |v122|, s26, 1.0
	v_rcp_f32_e32 v126, v126
	v_mul_f32_e32 v125, v127, v124
	v_fma_f32 v124, -v127, v124, v127
	v_cmp_gt_f32_e32 vcc, 0, v127
	v_pk_mul_f32 v[116:117], v[116:117], v[134:135] op_sel_hi:[1,0]
	v_pk_mul_f32 v[118:119], v[118:119], v[134:135] op_sel_hi:[1,0]
	v_cndmask_b32_e32 v124, v124, v125, vcc
	v_cvt_pk_bf16_f32 v121, v121, v124
	v_fmamk_f32 v124, v126, 0x3f07dc22, v211
	v_fmaak_f32 v124, v126, v124, 0x3f35f0e3
	v_mul_f32_e32 v125, v122, v122
	v_mul_f32_e32 v125, 0xbf38aa3b, v125
	v_fmaak_f32 v124, v126, v124, 0xbe11a98e
	v_exp_f32_e32 v125, v125
	v_fmaak_f32 v124, v126, v124, 0x3e027906
	v_mul_f32_e32 v124, v126, v124
	v_fma_f32 v126, |v123|, s26, 1.0
	v_rcp_f32_e32 v126, v126
	v_mul_f32_e32 v124, v125, v124
	v_mul_f32_e32 v125, v122, v124
	v_fma_f32 v124, -v122, v124, v122
	v_cmp_gt_f32_e32 vcc, 0, v122
	s_nop 1
	v_cndmask_b32_e32 v122, v124, v125, vcc
	v_fmamk_f32 v124, v126, 0x3f07dc22, v211
	v_mul_f32_e32 v125, v123, v123
	v_fmaak_f32 v124, v126, v124, 0x3f35f0e3
	v_mul_f32_e32 v125, 0xbf38aa3b, v125
	v_exp_f32_e32 v125, v125
	v_fmaak_f32 v124, v126, v124, 0xbe11a98e
	v_fmaak_f32 v124, v126, v124, 0x3e027906
	v_mul_f32_e32 v124, v126, v124
	v_fma_f32 v126, |v136|, s26, 1.0
	v_rcp_f32_e32 v126, v126
	v_mul_f32_e32 v124, v125, v124
	v_mul_f32_e32 v125, v123, v124
	v_fma_f32 v124, -v123, v124, v123
	v_cmp_gt_f32_e32 vcc, 0, v123
	s_nop 1
	v_cndmask_b32_e32 v123, v124, v125, vcc
	v_mul_f32_e32 v124, v136, v136
	v_cvt_pk_bf16_f32 v122, v122, v123
	v_fmamk_f32 v123, v126, 0x3f07dc22, v211
	v_mul_f32_e32 v124, 0xbf38aa3b, v124
	v_fmaak_f32 v123, v126, v123, 0x3f35f0e3
	v_exp_f32_e32 v124, v124
	v_fmaak_f32 v123, v126, v123, 0xbe11a98e
	v_fma_f32 v125, |v137|, s26, 1.0
	v_fmaak_f32 v123, v126, v123, 0x3e027906
	v_rcp_f32_e32 v125, v125
	v_mul_f32_e32 v123, v126, v123
	v_mul_f32_e32 v123, v124, v123
	v_mul_f32_e32 v124, v136, v123
	v_fma_f32 v123, -v136, v123, v136
	v_cmp_gt_f32_e32 vcc, 0, v136
	v_mul_f32_e32 v126, v137, v137
	v_mul_f32_e32 v126, 0xbf38aa3b, v126
	v_cndmask_b32_e32 v123, v123, v124, vcc
	v_fmamk_f32 v124, v125, 0x3f07dc22, v211
	v_fmaak_f32 v124, v125, v124, 0x3f35f0e3
	v_exp_f32_e32 v126, v126
	v_fmaak_f32 v124, v125, v124, 0xbe11a98e
	v_fmaak_f32 v124, v125, v124, 0x3e027906
	v_mul_f32_e32 v124, v125, v124
	v_mul_f32_e32 v124, v126, v124
	v_mul_f32_e32 v125, v137, v124
	v_fma_f32 v124, -v137, v124, v137
	v_cmp_gt_f32_e32 vcc, 0, v137
	s_nop 1
	v_cndmask_b32_e32 v124, v124, v125, vcc
	v_cvt_pk_bf16_f32 v123, v123, v124
	global_store_dwordx4 v[132:133], v[120:123], off
	v_cmp_gt_f32_e32 vcc, 0, v116
	s_nop 0
	v_fma_f32 v120, |v116|, s26, 1.0
	v_rcp_f32_e32 v122, v120
	v_pk_mul_f32 v[120:121], v[114:115], v[134:135] op_sel_hi:[1,0]
	v_pk_mul_f32 v[114:115], v[112:113], v[134:135] op_sel_hi:[1,0]
	v_mul_f32_e32 v113, v116, v116
	v_fmamk_f32 v112, v122, 0x3f07dc22, v211
	v_fmaak_f32 v112, v122, v112, 0x3f35f0e3
	v_mul_f32_e32 v113, 0xbf38aa3b, v113
	v_fmaak_f32 v112, v122, v112, 0xbe11a98e
	v_exp_f32_e32 v113, v113
	v_fmaak_f32 v112, v122, v112, 0x3e027906
	v_mul_f32_e32 v112, v122, v112
	v_fma_f32 v122, |v117|, s26, 1.0
	v_rcp_f32_e32 v122, v122
	v_mul_f32_e32 v112, v113, v112
	v_mul_f32_e32 v113, v116, v112
	v_fma_f32 v112, -v116, v112, v116
	v_cndmask_b32_e32 v112, v112, v113, vcc
	v_fmamk_f32 v113, v122, 0x3f07dc22, v211
	v_mul_f32_e32 v116, v117, v117
	v_fmaak_f32 v113, v122, v113, 0x3f35f0e3
	v_mul_f32_e32 v116, 0xbf38aa3b, v116
	v_exp_f32_e32 v116, v116
	v_fmaak_f32 v113, v122, v113, 0xbe11a98e
	v_fmaak_f32 v113, v122, v113, 0x3e027906
	v_mul_f32_e32 v113, v122, v113
	v_fma_f32 v122, |v118|, s26, 1.0
	v_rcp_f32_e32 v122, v122
	v_mul_f32_e32 v113, v116, v113
	v_mul_f32_e32 v116, v117, v113
	v_fma_f32 v113, -v117, v113, v117
	v_cmp_gt_f32_e32 vcc, 0, v117
	v_fma_f32 v117, |v119|, s26, 1.0
	v_rcp_f32_e32 v117, v117
	v_cndmask_b32_e32 v113, v113, v116, vcc
	v_mul_f32_e32 v116, v118, v118
	v_cvt_pk_bf16_f32 v112, v112, v113
	v_fmamk_f32 v113, v122, 0x3f07dc22, v211
	v_mul_f32_e32 v116, 0xbf38aa3b, v116
	v_fmaak_f32 v113, v122, v113, 0x3f35f0e3
	v_exp_f32_e32 v116, v116
	v_fmaak_f32 v113, v122, v113, 0xbe11a98e
	v_fmaak_f32 v113, v122, v113, 0x3e027906
	v_mul_f32_e32 v113, v122, v113
	v_mul_f32_e32 v113, v116, v113
	v_mul_f32_e32 v116, v118, v113
	v_fma_f32 v113, -v118, v113, v118
	v_cmp_gt_f32_e32 vcc, 0, v118
	v_mul_f32_e32 v118, v119, v119
	v_mul_f32_e32 v118, 0xbf38aa3b, v118
	v_cndmask_b32_e32 v113, v113, v116, vcc
	v_fmamk_f32 v116, v117, 0x3f07dc22, v211
	v_fmaak_f32 v116, v117, v116, 0x3f35f0e3
	v_exp_f32_e32 v118, v118
	v_fmaak_f32 v116, v117, v116, 0xbe11a98e
	v_fmaak_f32 v116, v117, v116, 0x3e027906
	v_mul_f32_e32 v116, v117, v116
	v_mul_f32_e32 v116, v118, v116
	v_fma_f32 v118, |v114|, s26, 1.0
	v_rcp_f32_e32 v118, v118
	v_mul_f32_e32 v117, v119, v116
	v_fma_f32 v116, -v119, v116, v119
	v_cmp_gt_f32_e32 vcc, 0, v119
	v_cmp_gt_f32_e64 s[0:1], 0, v121
	s_nop 0
	v_cndmask_b32_e32 v116, v116, v117, vcc
	v_cvt_pk_bf16_f32 v113, v113, v116
	v_fmamk_f32 v116, v118, 0x3f07dc22, v211
	v_fmaak_f32 v116, v118, v116, 0x3f35f0e3
	v_mul_f32_e32 v117, v114, v114
	v_mul_f32_e32 v117, 0xbf38aa3b, v117
	v_fmaak_f32 v116, v118, v116, 0xbe11a98e
	v_exp_f32_e32 v117, v117
	v_fmaak_f32 v116, v118, v116, 0x3e027906
	v_mul_f32_e32 v116, v118, v116
	v_fma_f32 v118, |v115|, s26, 1.0
	v_rcp_f32_e32 v118, v118
	v_mul_f32_e32 v116, v117, v116
	v_mul_f32_e32 v117, v114, v116
	v_fma_f32 v116, -v114, v116, v114
	v_cmp_gt_f32_e32 vcc, 0, v114
	s_nop 1
	v_cndmask_b32_e32 v114, v116, v117, vcc
	v_fmamk_f32 v116, v118, 0x3f07dc22, v211
	v_mul_f32_e32 v117, v115, v115
	v_fmaak_f32 v116, v118, v116, 0x3f35f0e3
	v_mul_f32_e32 v117, 0xbf38aa3b, v117
	v_exp_f32_e32 v117, v117
	v_fmaak_f32 v116, v118, v116, 0xbe11a98e
	v_fmaak_f32 v116, v118, v116, 0x3e027906
	v_mul_f32_e32 v116, v118, v116
	v_fma_f32 v118, |v120|, s26, 1.0
	v_rcp_f32_e32 v118, v118
	v_mul_f32_e32 v116, v117, v116
	v_mul_f32_e32 v117, v115, v116
	v_fma_f32 v116, -v115, v116, v115
	v_cmp_gt_f32_e32 vcc, 0, v115
	s_nop 1
	v_cndmask_b32_e32 v115, v116, v117, vcc
	v_mul_f32_e32 v116, v120, v120
	v_cvt_pk_bf16_f32 v114, v114, v115
	v_fmamk_f32 v115, v118, 0x3f07dc22, v211
	v_mul_f32_e32 v116, 0xbf38aa3b, v116
	v_fmaak_f32 v115, v118, v115, 0x3f35f0e3
	v_exp_f32_e32 v116, v116
	v_fmaak_f32 v115, v118, v115, 0xbe11a98e
	v_fma_f32 v117, |v121|, s26, 1.0
	v_fmaak_f32 v115, v118, v115, 0x3e027906
	v_rcp_f32_e32 v117, v117
	v_mul_f32_e32 v115, v118, v115
	v_mul_f32_e32 v115, v116, v115
	v_mul_f32_e32 v116, v120, v115
	v_fma_f32 v115, -v120, v115, v120
	v_cmp_gt_f32_e32 vcc, 0, v120
	v_mul_f32_e32 v118, v121, v121
	v_mul_f32_e32 v118, 0xbf38aa3b, v118
	v_cndmask_b32_e32 v115, v115, v116, vcc
	v_fmamk_f32 v116, v117, 0x3f07dc22, v211
	v_fmaak_f32 v116, v117, v116, 0x3f35f0e3
	v_exp_f32_e32 v118, v118
	v_fmaak_f32 v116, v117, v116, 0xbe11a98e
	v_fmaak_f32 v116, v117, v116, 0x3e027906
	v_mul_f32_e32 v116, v117, v116
	v_mul_f32_e32 v116, v118, v116
	v_mul_f32_e32 v118, 0x4b800000, v130
	v_cmp_gt_f32_e32 vcc, s89, v130
	v_mul_f32_e32 v117, v121, v116
	v_fma_f32 v116, -v121, v116, v121
	v_cndmask_b32_e32 v118, v130, v118, vcc
	v_rsq_f32_e32 v118, v118
	v_cndmask_b32_e64 v116, v116, v117, s[0:1]
	v_cvt_pk_bf16_f32 v115, v115, v116
	global_store_dwordx4 v[132:133], v[112:115], off offset:64
	s_nop 1
	v_mul_f32_e32 v112, 0x45800000, v118
	v_cndmask_b32_e32 v112, v118, v112, vcc
	v_pk_mul_f32 v[108:109], v[108:109], v[112:113] op_sel_hi:[1,0]
	s_nop 0
	v_fma_f32 v113, |v108|, s26, 1.0
	v_rcp_f32_e32 v113, v113
	v_cmp_gt_f32_e32 vcc, 0, v108
	v_pk_mul_f32 v[114:115], v[106:107], v[112:113] op_sel_hi:[1,0]
	v_pk_mul_f32 v[106:107], v[104:105], v[112:113] op_sel_hi:[1,0]
	v_fmamk_f32 v104, v113, 0x3f07dc22, v211
	v_fmaak_f32 v104, v113, v104, 0x3f35f0e3
	v_mul_f32_e32 v105, v108, v108
	v_mul_f32_e32 v105, 0xbf38aa3b, v105
	v_fmaak_f32 v104, v113, v104, 0xbe11a98e
	v_exp_f32_e32 v105, v105
	v_fmaak_f32 v104, v113, v104, 0x3e027906
	v_pk_mul_f32 v[110:111], v[110:111], v[112:113] op_sel_hi:[1,0]
	v_mul_f32_e32 v104, v113, v104
	v_fma_f32 v113, |v109|, s26, 1.0
	v_rcp_f32_e32 v113, v113
	v_mul_f32_e32 v104, v105, v104
	v_mul_f32_e32 v105, v108, v104
	v_fma_f32 v104, -v108, v104, v108
	v_cndmask_b32_e32 v104, v104, v105, vcc
	v_fmamk_f32 v105, v113, 0x3f07dc22, v211
	v_mul_f32_e32 v108, v109, v109
	v_fmaak_f32 v105, v113, v105, 0x3f35f0e3
	v_mul_f32_e32 v108, 0xbf38aa3b, v108
	v_exp_f32_e32 v108, v108
	v_fmaak_f32 v105, v113, v105, 0xbe11a98e
	v_fmaak_f32 v105, v113, v105, 0x3e027906
	v_mul_f32_e32 v105, v113, v105
	v_fma_f32 v113, |v110|, s26, 1.0
	v_rcp_f32_e32 v113, v113
	v_mul_f32_e32 v105, v108, v105
	v_mul_f32_e32 v108, v109, v105
	v_fma_f32 v105, -v109, v105, v109
	v_cmp_gt_f32_e32 vcc, 0, v109
	v_fma_f32 v109, |v111|, s26, 1.0
	v_rcp_f32_e32 v109, v109
	v_cndmask_b32_e32 v105, v105, v108, vcc
	v_mul_f32_e32 v108, v110, v110
	v_cvt_pk_bf16_f32 v104, v104, v105
	v_fmamk_f32 v105, v113, 0x3f07dc22, v211
	v_mul_f32_e32 v108, 0xbf38aa3b, v108
	v_fmaak_f32 v105, v113, v105, 0x3f35f0e3
	v_exp_f32_e32 v108, v108
	v_fmaak_f32 v105, v113, v105, 0xbe11a98e
	v_fmaak_f32 v105, v113, v105, 0x3e027906
	v_mul_f32_e32 v105, v113, v105
	v_mul_f32_e32 v105, v108, v105
	v_mul_f32_e32 v108, v110, v105
	v_fma_f32 v105, -v110, v105, v110
	v_cmp_gt_f32_e32 vcc, 0, v110
	v_mul_f32_e32 v110, v111, v111
	v_mul_f32_e32 v110, 0xbf38aa3b, v110
	v_cndmask_b32_e32 v105, v105, v108, vcc
	v_fmamk_f32 v108, v109, 0x3f07dc22, v211
	v_fmaak_f32 v108, v109, v108, 0x3f35f0e3
	v_exp_f32_e32 v110, v110
	v_fmaak_f32 v108, v109, v108, 0xbe11a98e
	v_fmaak_f32 v108, v109, v108, 0x3e027906
	v_mul_f32_e32 v108, v109, v108
	v_mul_f32_e32 v108, v110, v108
	v_fma_f32 v110, |v106|, s26, 1.0
	v_rcp_f32_e32 v110, v110
	v_mul_f32_e32 v109, v111, v108
	v_fma_f32 v108, -v111, v108, v111
	v_cmp_gt_f32_e32 vcc, 0, v111
	v_pk_mul_f32 v[100:101], v[100:101], v[112:113] op_sel_hi:[1,0]
	v_pk_mul_f32 v[102:103], v[102:103], v[112:113] op_sel_hi:[1,0]
	v_cndmask_b32_e32 v108, v108, v109, vcc
	v_cvt_pk_bf16_f32 v105, v105, v108
	v_fmamk_f32 v108, v110, 0x3f07dc22, v211
	v_fmaak_f32 v108, v110, v108, 0x3f35f0e3
	v_mul_f32_e32 v109, v106, v106
	v_mul_f32_e32 v109, 0xbf38aa3b, v109
	v_fmaak_f32 v108, v110, v108, 0xbe11a98e
	v_exp_f32_e32 v109, v109
	v_fmaak_f32 v108, v110, v108, 0x3e027906
	v_mul_f32_e32 v108, v110, v108
	v_fma_f32 v110, |v107|, s26, 1.0
	v_rcp_f32_e32 v110, v110
	v_mul_f32_e32 v108, v109, v108
	v_mul_f32_e32 v109, v106, v108
	v_fma_f32 v108, -v106, v108, v106
	v_cmp_gt_f32_e32 vcc, 0, v106
	s_nop 1
	v_cndmask_b32_e32 v106, v108, v109, vcc
	v_fmamk_f32 v108, v110, 0x3f07dc22, v211
	v_mul_f32_e32 v109, v107, v107
	v_fmaak_f32 v108, v110, v108, 0x3f35f0e3
	v_mul_f32_e32 v109, 0xbf38aa3b, v109
	v_exp_f32_e32 v109, v109
	v_fmaak_f32 v108, v110, v108, 0xbe11a98e
	v_fmaak_f32 v108, v110, v108, 0x3e027906
	v_mul_f32_e32 v108, v110, v108
	v_fma_f32 v110, |v114|, s26, 1.0
	v_rcp_f32_e32 v110, v110
	v_mul_f32_e32 v108, v109, v108
	v_mul_f32_e32 v109, v107, v108
	v_fma_f32 v108, -v107, v108, v107
	v_cmp_gt_f32_e32 vcc, 0, v107
	s_nop 1
	v_cndmask_b32_e32 v107, v108, v109, vcc
	v_mul_f32_e32 v108, v114, v114
	v_cvt_pk_bf16_f32 v106, v106, v107
	v_fmamk_f32 v107, v110, 0x3f07dc22, v211
	v_mul_f32_e32 v108, 0xbf38aa3b, v108
	v_fmaak_f32 v107, v110, v107, 0x3f35f0e3
	v_exp_f32_e32 v108, v108
	v_fmaak_f32 v107, v110, v107, 0xbe11a98e
	v_fma_f32 v109, |v115|, s26, 1.0
	v_fmaak_f32 v107, v110, v107, 0x3e027906
	v_rcp_f32_e32 v109, v109
	v_mul_f32_e32 v107, v110, v107
	v_mul_f32_e32 v107, v108, v107
	v_mul_f32_e32 v108, v114, v107
	v_fma_f32 v107, -v114, v107, v114
	v_cmp_gt_f32_e32 vcc, 0, v114
	v_mul_f32_e32 v110, v115, v115
	v_mul_f32_e32 v110, 0xbf38aa3b, v110
	v_cndmask_b32_e32 v107, v107, v108, vcc
	v_fmamk_f32 v108, v109, 0x3f07dc22, v211
	v_fmaak_f32 v108, v109, v108, 0x3f35f0e3
	v_exp_f32_e32 v110, v110
	v_fmaak_f32 v108, v109, v108, 0xbe11a98e
	v_fmaak_f32 v108, v109, v108, 0x3e027906
	v_mul_f32_e32 v108, v109, v108
	v_mul_f32_e32 v108, v110, v108
	v_mul_f32_e32 v109, v115, v108
	v_fma_f32 v108, -v115, v108, v115
	v_cmp_gt_f32_e32 vcc, 0, v115
	s_nop 1
	v_cndmask_b32_e32 v108, v108, v109, vcc
	v_cvt_pk_bf16_f32 v107, v107, v108
	v_lshl_add_u64 v[108:109], s[96:97], 0, v[198:199]
	v_lshl_add_u64 v[108:109], v[108:109], 0, s[98:99]
	v_lshl_add_u64 v[108:109], v[108:109], 0, v[144:145]
	global_store_dwordx4 v[108:109], v[104:107], off
	v_cmp_gt_f32_e32 vcc, 0, v100
	s_nop 0
	v_fma_f32 v104, |v100|, s26, 1.0
	v_rcp_f32_e32 v106, v104
	v_pk_mul_f32 v[104:105], v[98:99], v[112:113] op_sel_hi:[1,0]
	v_pk_mul_f32 v[98:99], v[96:97], v[112:113] op_sel_hi:[1,0]
	v_mul_f32_e32 v97, v100, v100
	v_fmamk_f32 v96, v106, 0x3f07dc22, v211
	v_fmaak_f32 v96, v106, v96, 0x3f35f0e3
	v_mul_f32_e32 v97, 0xbf38aa3b, v97
	v_fmaak_f32 v96, v106, v96, 0xbe11a98e
	v_exp_f32_e32 v97, v97
	v_fmaak_f32 v96, v106, v96, 0x3e027906
	v_mul_f32_e32 v96, v106, v96
	v_fma_f32 v106, |v101|, s26, 1.0
	v_rcp_f32_e32 v106, v106
	v_mul_f32_e32 v96, v97, v96
	v_mul_f32_e32 v97, v100, v96
	v_fma_f32 v96, -v100, v96, v100
	v_cndmask_b32_e32 v96, v96, v97, vcc
	v_fmamk_f32 v97, v106, 0x3f07dc22, v211
	v_mul_f32_e32 v100, v101, v101
	v_fmaak_f32 v97, v106, v97, 0x3f35f0e3
	v_mul_f32_e32 v100, 0xbf38aa3b, v100
	v_exp_f32_e32 v100, v100
	v_fmaak_f32 v97, v106, v97, 0xbe11a98e
	v_fmaak_f32 v97, v106, v97, 0x3e027906
	v_mul_f32_e32 v97, v106, v97
	v_fma_f32 v106, |v102|, s26, 1.0
	v_rcp_f32_e32 v106, v106
	v_mul_f32_e32 v97, v100, v97
	v_mul_f32_e32 v100, v101, v97
	v_fma_f32 v97, -v101, v97, v101
	v_cmp_gt_f32_e32 vcc, 0, v101
	v_fma_f32 v101, |v103|, s26, 1.0
	v_rcp_f32_e32 v101, v101
	v_cndmask_b32_e32 v97, v97, v100, vcc
	v_mul_f32_e32 v100, v102, v102
	v_cvt_pk_bf16_f32 v96, v96, v97
	v_fmamk_f32 v97, v106, 0x3f07dc22, v211
	v_mul_f32_e32 v100, 0xbf38aa3b, v100
	v_fmaak_f32 v97, v106, v97, 0x3f35f0e3
	v_exp_f32_e32 v100, v100
	v_fmaak_f32 v97, v106, v97, 0xbe11a98e
	v_fmaak_f32 v97, v106, v97, 0x3e027906
	v_mul_f32_e32 v97, v106, v97
	v_mul_f32_e32 v97, v100, v97
	v_mul_f32_e32 v100, v102, v97
	v_fma_f32 v97, -v102, v97, v102
	v_cmp_gt_f32_e32 vcc, 0, v102
	v_mul_f32_e32 v102, v103, v103
	v_mul_f32_e32 v102, 0xbf38aa3b, v102
	v_cndmask_b32_e32 v97, v97, v100, vcc
	v_fmamk_f32 v100, v101, 0x3f07dc22, v211
	v_fmaak_f32 v100, v101, v100, 0x3f35f0e3
	v_exp_f32_e32 v102, v102
	v_fmaak_f32 v100, v101, v100, 0xbe11a98e
	v_fmaak_f32 v100, v101, v100, 0x3e027906
	v_mul_f32_e32 v100, v101, v100
	v_mul_f32_e32 v100, v102, v100
	v_fma_f32 v102, |v98|, s26, 1.0
	v_rcp_f32_e32 v102, v102
	v_mul_f32_e32 v101, v103, v100
	v_fma_f32 v100, -v103, v100, v103
	v_cmp_gt_f32_e32 vcc, 0, v103
	s_nop 1
	v_cndmask_b32_e32 v100, v100, v101, vcc
	v_cvt_pk_bf16_f32 v97, v97, v100
	v_fmamk_f32 v100, v102, 0x3f07dc22, v211
	v_fmaak_f32 v100, v102, v100, 0x3f35f0e3
	v_mul_f32_e32 v101, v98, v98
	v_mul_f32_e32 v101, 0xbf38aa3b, v101
	v_fmaak_f32 v100, v102, v100, 0xbe11a98e
	v_exp_f32_e32 v101, v101
	v_fmaak_f32 v100, v102, v100, 0x3e027906
	v_mul_f32_e32 v100, v102, v100
	v_fma_f32 v102, |v99|, s26, 1.0
	v_rcp_f32_e32 v102, v102
	v_mul_f32_e32 v100, v101, v100
	v_mul_f32_e32 v101, v98, v100
	v_fma_f32 v100, -v98, v100, v98
	v_cmp_gt_f32_e32 vcc, 0, v98
	s_nop 1
	v_cndmask_b32_e32 v98, v100, v101, vcc
	v_fmamk_f32 v100, v102, 0x3f07dc22, v211
	v_mul_f32_e32 v101, v99, v99
	v_fmaak_f32 v100, v102, v100, 0x3f35f0e3
	v_mul_f32_e32 v101, 0xbf38aa3b, v101
	v_exp_f32_e32 v101, v101
	v_fmaak_f32 v100, v102, v100, 0xbe11a98e
	v_fmaak_f32 v100, v102, v100, 0x3e027906
	v_mul_f32_e32 v100, v102, v100
	v_fma_f32 v102, |v104|, s26, 1.0
	v_rcp_f32_e32 v102, v102
	v_mul_f32_e32 v100, v101, v100
	v_mul_f32_e32 v101, v99, v100
	v_fma_f32 v100, -v99, v100, v99
	v_cmp_gt_f32_e32 vcc, 0, v99
	s_nop 1
	v_cndmask_b32_e32 v99, v100, v101, vcc
	v_mul_f32_e32 v100, v104, v104
	v_cvt_pk_bf16_f32 v98, v98, v99
	v_fmamk_f32 v99, v102, 0x3f07dc22, v211
	v_mul_f32_e32 v100, 0xbf38aa3b, v100
	v_fmaak_f32 v99, v102, v99, 0x3f35f0e3
	v_exp_f32_e32 v100, v100
	v_fmaak_f32 v99, v102, v99, 0xbe11a98e
	v_fma_f32 v101, |v105|, s26, 1.0
	v_fmaak_f32 v99, v102, v99, 0x3e027906
	v_rcp_f32_e32 v101, v101
	v_mul_f32_e32 v99, v102, v99
	v_mul_f32_e32 v99, v100, v99
	v_mul_f32_e32 v100, v104, v99
	v_fma_f32 v99, -v104, v99, v104
	v_cmp_gt_f32_e32 vcc, 0, v104
	v_mul_f32_e32 v102, v105, v105
	v_mul_f32_e32 v102, 0xbf38aa3b, v102
	v_cndmask_b32_e32 v99, v99, v100, vcc
	v_fmamk_f32 v100, v101, 0x3f07dc22, v211
	v_fmaak_f32 v100, v101, v100, 0x3f35f0e3
	v_exp_f32_e32 v102, v102
	v_fmaak_f32 v100, v101, v100, 0xbe11a98e
	v_fmaak_f32 v100, v101, v100, 0x3e027906
	v_mul_f32_e32 v100, v101, v100
	v_mul_f32_e32 v100, v102, v100
	v_mul_f32_e32 v101, v105, v100
	v_fma_f32 v100, -v105, v100, v105
	v_cmp_gt_f32_e32 vcc, 0, v105
	s_nop 1
	v_cndmask_b32_e32 v100, v100, v101, vcc
	v_cvt_pk_bf16_f32 v99, v99, v100
	global_store_dwordx4 v[108:109], v[96:99], off offset:64
	v_min_u32_e32 v100, 32, v219
	s_nop 0
	v_min_u32_e32 v98, 32, v220
	v_lshlrev_b64 v[96:97], v98, v[192:193]
	v_min_u32_e32 v96, 1, v96
	v_or_b32_e32 v96, v97, v96
	v_cvt_f32_u32_e32 v99, v96
	v_lshlrev_b64 v[96:97], v100, v[196:197]
	v_min_u32_e32 v96, 1, v96
	v_or_b32_e32 v96, v97, v96
	v_cvt_f32_u32_e32 v96, v96
	v_sub_u32_e32 v97, 32, v98
	v_sub_u32_e32 v98, 32, v100
	v_ldexp_f32 v97, v99, v97
	v_ldexp_f32 v96, v96, v98
	v_pk_mul_f32 v[96:97], v[96:97], s[30:31] op_sel_hi:[1,0]
	s_nop 0
	v_pk_fma_f32 v[96:97], v[96:97], s[2:3], v[128:129] op_sel_hi:[1,0,0]
	s_nop 0
	v_mul_f32_e32 v98, 0x4b800000, v97
	v_cmp_gt_f32_e32 vcc, s89, v97
	s_nop 1
	v_cndmask_b32_e32 v97, v97, v98, vcc
	v_rsq_f32_e32 v97, v97
	v_lshl_add_u64 v[98:99], s[96:97], 0, v[194:195]
	v_lshl_add_u64 v[98:99], v[98:99], 0, s[98:99]
	v_lshl_add_u64 v[98:99], v[98:99], 0, v[144:145]
	v_mul_f32_e32 v100, 0x45800000, v97
	v_cndmask_b32_e32 v100, v97, v100, vcc
	v_pk_mul_f32 v[92:93], v[92:93], v[100:101] op_sel_hi:[1,0]
	v_pk_mul_f32 v[102:103], v[90:91], v[100:101] op_sel_hi:[1,0]
	v_fma_f32 v97, |v92|, s26, 1.0
	v_rcp_f32_e32 v97, v97
	v_pk_mul_f32 v[90:91], v[88:89], v[100:101] op_sel_hi:[1,0]
	v_mul_f32_e32 v89, v92, v92
	v_mul_f32_e32 v89, 0xbf38aa3b, v89
	v_fmamk_f32 v88, v97, 0x3f07dc22, v211
	v_fmaak_f32 v88, v97, v88, 0x3f35f0e3
	v_fmaak_f32 v88, v97, v88, 0xbe11a98e
	v_exp_f32_e32 v89, v89
	v_fmaak_f32 v88, v97, v88, 0x3e027906
	v_mul_f32_e32 v88, v97, v88
	v_fma_f32 v97, |v93|, s26, 1.0
	v_rcp_f32_e32 v97, v97
	v_mul_f32_e32 v88, v89, v88
	v_mul_f32_e32 v89, v92, v88
	v_fma_f32 v88, -v92, v88, v92
	v_cmp_gt_f32_e32 vcc, 0, v92
	v_mul_f32_e32 v92, v93, v93
	v_mul_f32_e32 v92, 0xbf38aa3b, v92
	v_cndmask_b32_e32 v88, v88, v89, vcc
	v_fmamk_f32 v89, v97, 0x3f07dc22, v211
	v_fmaak_f32 v89, v97, v89, 0x3f35f0e3
	v_exp_f32_e32 v92, v92
	v_fmaak_f32 v89, v97, v89, 0xbe11a98e
	v_pk_mul_f32 v[94:95], v[94:95], v[100:101] op_sel_hi:[1,0]
	v_fmaak_f32 v89, v97, v89, 0x3e027906
	v_mul_f32_e32 v89, v97, v89
	v_fma_f32 v97, |v94|, s26, 1.0
	v_rcp_f32_e32 v97, v97
	v_mul_f32_e32 v89, v92, v89
	v_mul_f32_e32 v92, v93, v89
	v_fma_f32 v89, -v93, v89, v93
	v_cmp_gt_f32_e32 vcc, 0, v93
	v_fma_f32 v93, |v95|, s26, 1.0
	v_rcp_f32_e32 v93, v93
	v_cndmask_b32_e32 v89, v89, v92, vcc
	v_mul_f32_e32 v92, v94, v94
	v_cvt_pk_bf16_f32 v88, v88, v89
	v_fmamk_f32 v89, v97, 0x3f07dc22, v211
	v_mul_f32_e32 v92, 0xbf38aa3b, v92
	v_fmaak_f32 v89, v97, v89, 0x3f35f0e3
	v_exp_f32_e32 v92, v92
	v_fmaak_f32 v89, v97, v89, 0xbe11a98e
	v_fmaak_f32 v89, v97, v89, 0x3e027906
	v_mul_f32_e32 v89, v97, v89
	v_mul_f32_e32 v89, v92, v89
	v_mul_f32_e32 v92, v94, v89
	v_fma_f32 v89, -v94, v89, v94
	v_cmp_gt_f32_e32 vcc, 0, v94
	v_mul_f32_e32 v94, v95, v95
	v_mul_f32_e32 v94, 0xbf38aa3b, v94
	v_cndmask_b32_e32 v89, v89, v92, vcc
	v_fmamk_f32 v92, v93, 0x3f07dc22, v211
	v_fmaak_f32 v92, v93, v92, 0x3f35f0e3
	v_exp_f32_e32 v94, v94
	v_fmaak_f32 v92, v93, v92, 0xbe11a98e
	v_fmaak_f32 v92, v93, v92, 0x3e027906
	v_mul_f32_e32 v92, v93, v92
	v_mul_f32_e32 v92, v94, v92
	v_fma_f32 v94, |v90|, s26, 1.0
	v_rcp_f32_e32 v94, v94
	v_mul_f32_e32 v93, v95, v92
	v_fma_f32 v92, -v95, v92, v95
	v_cmp_gt_f32_e32 vcc, 0, v95
	v_pk_mul_f32 v[84:85], v[84:85], v[100:101] op_sel_hi:[1,0]
	v_pk_mul_f32 v[86:87], v[86:87], v[100:101] op_sel_hi:[1,0]
	v_cndmask_b32_e32 v92, v92, v93, vcc
	v_cvt_pk_bf16_f32 v89, v89, v92
	v_fmamk_f32 v92, v94, 0x3f07dc22, v211
	v_fmaak_f32 v92, v94, v92, 0x3f35f0e3
	v_mul_f32_e32 v93, v90, v90
	v_mul_f32_e32 v93, 0xbf38aa3b, v93
	v_fmaak_f32 v92, v94, v92, 0xbe11a98e
	v_exp_f32_e32 v93, v93
	v_fmaak_f32 v92, v94, v92, 0x3e027906
	v_mul_f32_e32 v92, v94, v92
	v_fma_f32 v94, |v91|, s26, 1.0
	v_rcp_f32_e32 v94, v94
	v_mul_f32_e32 v92, v93, v92
	v_mul_f32_e32 v93, v90, v92
	v_fma_f32 v92, -v90, v92, v90
	v_cmp_gt_f32_e32 vcc, 0, v90
	s_nop 1
	v_cndmask_b32_e32 v90, v92, v93, vcc
	v_fmamk_f32 v92, v94, 0x3f07dc22, v211
	v_mul_f32_e32 v93, v91, v91
	v_fmaak_f32 v92, v94, v92, 0x3f35f0e3
	v_mul_f32_e32 v93, 0xbf38aa3b, v93
	v_exp_f32_e32 v93, v93
	v_fmaak_f32 v92, v94, v92, 0xbe11a98e
	v_fmaak_f32 v92, v94, v92, 0x3e027906
	v_mul_f32_e32 v92, v94, v92
	v_fma_f32 v94, |v102|, s26, 1.0
	v_rcp_f32_e32 v94, v94
	v_mul_f32_e32 v92, v93, v92
	v_mul_f32_e32 v93, v91, v92
	v_fma_f32 v92, -v91, v92, v91
	v_cmp_gt_f32_e32 vcc, 0, v91
	s_nop 1
	v_cndmask_b32_e32 v91, v92, v93, vcc
	v_mul_f32_e32 v92, v102, v102
	v_cvt_pk_bf16_f32 v90, v90, v91
	v_fmamk_f32 v91, v94, 0x3f07dc22, v211
	v_mul_f32_e32 v92, 0xbf38aa3b, v92
	v_fmaak_f32 v91, v94, v91, 0x3f35f0e3
	v_exp_f32_e32 v92, v92
	v_fmaak_f32 v91, v94, v91, 0xbe11a98e
	v_fma_f32 v93, |v103|, s26, 1.0
	v_fmaak_f32 v91, v94, v91, 0x3e027906
	v_rcp_f32_e32 v93, v93
	v_mul_f32_e32 v91, v94, v91
	v_mul_f32_e32 v91, v92, v91
	v_mul_f32_e32 v92, v102, v91
	v_fma_f32 v91, -v102, v91, v102
	v_cmp_gt_f32_e32 vcc, 0, v102
	v_mul_f32_e32 v94, v103, v103
	v_mul_f32_e32 v94, 0xbf38aa3b, v94
	v_cndmask_b32_e32 v91, v91, v92, vcc
	v_fmamk_f32 v92, v93, 0x3f07dc22, v211
	v_fmaak_f32 v92, v93, v92, 0x3f35f0e3
	v_exp_f32_e32 v94, v94
	v_fmaak_f32 v92, v93, v92, 0xbe11a98e
	v_fmaak_f32 v92, v93, v92, 0x3e027906
	v_mul_f32_e32 v92, v93, v92
	v_mul_f32_e32 v92, v94, v92
	v_mul_f32_e32 v93, v103, v92
	v_fma_f32 v92, -v103, v92, v103
	v_cmp_gt_f32_e32 vcc, 0, v103
	s_nop 1
	v_cndmask_b32_e32 v92, v92, v93, vcc
	v_cvt_pk_bf16_f32 v91, v91, v92
	global_store_dwordx4 v[98:99], v[88:91], off
	v_cmp_gt_f32_e32 vcc, 0, v84
	s_nop 0
	v_fma_f32 v88, |v84|, s26, 1.0
	v_rcp_f32_e32 v90, v88
	v_pk_mul_f32 v[88:89], v[82:83], v[100:101] op_sel_hi:[1,0]
	v_pk_mul_f32 v[82:83], v[80:81], v[100:101] op_sel_hi:[1,0]
	v_mul_f32_e32 v81, v84, v84
	v_fmamk_f32 v80, v90, 0x3f07dc22, v211
	v_fmaak_f32 v80, v90, v80, 0x3f35f0e3
	v_mul_f32_e32 v81, 0xbf38aa3b, v81
	v_fmaak_f32 v80, v90, v80, 0xbe11a98e
	v_exp_f32_e32 v81, v81
	v_fmaak_f32 v80, v90, v80, 0x3e027906
	v_mul_f32_e32 v80, v90, v80
	v_fma_f32 v90, |v85|, s26, 1.0
	v_rcp_f32_e32 v90, v90
	v_mul_f32_e32 v80, v81, v80
	v_mul_f32_e32 v81, v84, v80
	v_fma_f32 v80, -v84, v80, v84
	v_cndmask_b32_e32 v80, v80, v81, vcc
	v_fmamk_f32 v81, v90, 0x3f07dc22, v211
	v_mul_f32_e32 v84, v85, v85
	v_fmaak_f32 v81, v90, v81, 0x3f35f0e3
	v_mul_f32_e32 v84, 0xbf38aa3b, v84
	v_exp_f32_e32 v84, v84
	v_fmaak_f32 v81, v90, v81, 0xbe11a98e
	v_fmaak_f32 v81, v90, v81, 0x3e027906
	v_mul_f32_e32 v81, v90, v81
	v_fma_f32 v90, |v86|, s26, 1.0
	v_rcp_f32_e32 v90, v90
	v_mul_f32_e32 v81, v84, v81
	v_mul_f32_e32 v84, v85, v81
	v_fma_f32 v81, -v85, v81, v85
	v_cmp_gt_f32_e32 vcc, 0, v85
	v_fma_f32 v85, |v87|, s26, 1.0
	v_rcp_f32_e32 v85, v85
	v_cndmask_b32_e32 v81, v81, v84, vcc
	v_mul_f32_e32 v84, v86, v86
	v_cvt_pk_bf16_f32 v80, v80, v81
	v_fmamk_f32 v81, v90, 0x3f07dc22, v211
	v_mul_f32_e32 v84, 0xbf38aa3b, v84
	v_fmaak_f32 v81, v90, v81, 0x3f35f0e3
	v_exp_f32_e32 v84, v84
	v_fmaak_f32 v81, v90, v81, 0xbe11a98e
	v_fmaak_f32 v81, v90, v81, 0x3e027906
	v_mul_f32_e32 v81, v90, v81
	v_mul_f32_e32 v81, v84, v81
	v_mul_f32_e32 v84, v86, v81
	v_fma_f32 v81, -v86, v81, v86
	v_cmp_gt_f32_e32 vcc, 0, v86
	v_mul_f32_e32 v86, v87, v87
	v_mul_f32_e32 v86, 0xbf38aa3b, v86
	v_cndmask_b32_e32 v81, v81, v84, vcc
	v_fmamk_f32 v84, v85, 0x3f07dc22, v211
	v_fmaak_f32 v84, v85, v84, 0x3f35f0e3
	v_exp_f32_e32 v86, v86
	v_fmaak_f32 v84, v85, v84, 0xbe11a98e
	v_fmaak_f32 v84, v85, v84, 0x3e027906
	v_mul_f32_e32 v84, v85, v84
	v_mul_f32_e32 v84, v86, v84
	v_fma_f32 v86, |v82|, s26, 1.0
	v_rcp_f32_e32 v86, v86
	v_mul_f32_e32 v85, v87, v84
	v_fma_f32 v84, -v87, v84, v87
	v_cmp_gt_f32_e32 vcc, 0, v87
	v_cmp_gt_f32_e64 s[0:1], 0, v89
	s_nop 0
	v_cndmask_b32_e32 v84, v84, v85, vcc
	v_cvt_pk_bf16_f32 v81, v81, v84
	v_fmamk_f32 v84, v86, 0x3f07dc22, v211
	v_fmaak_f32 v84, v86, v84, 0x3f35f0e3
	v_mul_f32_e32 v85, v82, v82
	v_mul_f32_e32 v85, 0xbf38aa3b, v85
	v_fmaak_f32 v84, v86, v84, 0xbe11a98e
	v_exp_f32_e32 v85, v85
	v_fmaak_f32 v84, v86, v84, 0x3e027906
	v_mul_f32_e32 v84, v86, v84
	v_fma_f32 v86, |v83|, s26, 1.0
	v_rcp_f32_e32 v86, v86
	v_mul_f32_e32 v84, v85, v84
	v_mul_f32_e32 v85, v82, v84
	v_fma_f32 v84, -v82, v84, v82
	v_cmp_gt_f32_e32 vcc, 0, v82
	s_nop 1
	v_cndmask_b32_e32 v82, v84, v85, vcc
	v_fmamk_f32 v84, v86, 0x3f07dc22, v211
	v_mul_f32_e32 v85, v83, v83
	v_fmaak_f32 v84, v86, v84, 0x3f35f0e3
	v_mul_f32_e32 v85, 0xbf38aa3b, v85
	v_exp_f32_e32 v85, v85
	v_fmaak_f32 v84, v86, v84, 0xbe11a98e
	v_fmaak_f32 v84, v86, v84, 0x3e027906
	v_mul_f32_e32 v84, v86, v84
	v_fma_f32 v86, |v88|, s26, 1.0
	v_rcp_f32_e32 v86, v86
	v_mul_f32_e32 v84, v85, v84
	v_mul_f32_e32 v85, v83, v84
	v_fma_f32 v84, -v83, v84, v83
	v_cmp_gt_f32_e32 vcc, 0, v83
	s_nop 1
	v_cndmask_b32_e32 v83, v84, v85, vcc
	v_mul_f32_e32 v84, v88, v88
	v_cvt_pk_bf16_f32 v82, v82, v83
	v_fmamk_f32 v83, v86, 0x3f07dc22, v211
	v_mul_f32_e32 v84, 0xbf38aa3b, v84
	v_fmaak_f32 v83, v86, v83, 0x3f35f0e3
	v_exp_f32_e32 v84, v84
	v_fmaak_f32 v83, v86, v83, 0xbe11a98e
	v_fma_f32 v85, |v89|, s26, 1.0
	v_fmaak_f32 v83, v86, v83, 0x3e027906
	v_rcp_f32_e32 v85, v85
	v_mul_f32_e32 v83, v86, v83
	v_mul_f32_e32 v83, v84, v83
	v_mul_f32_e32 v84, v88, v83
	v_fma_f32 v83, -v88, v83, v88
	v_cmp_gt_f32_e32 vcc, 0, v88
	v_mul_f32_e32 v86, v89, v89
	v_mul_f32_e32 v86, 0xbf38aa3b, v86
	v_cndmask_b32_e32 v83, v83, v84, vcc
	v_fmamk_f32 v84, v85, 0x3f07dc22, v211
	v_fmaak_f32 v84, v85, v84, 0x3f35f0e3
	v_exp_f32_e32 v86, v86
	v_fmaak_f32 v84, v85, v84, 0xbe11a98e
	v_fmaak_f32 v84, v85, v84, 0x3e027906
	v_mul_f32_e32 v84, v85, v84
	v_mul_f32_e32 v84, v86, v84
	v_mul_f32_e32 v86, 0x4b800000, v96
	v_cmp_gt_f32_e32 vcc, s89, v96
	v_mul_f32_e32 v85, v89, v84
	v_fma_f32 v84, -v89, v84, v89
	v_cndmask_b32_e32 v86, v96, v86, vcc
	v_rsq_f32_e32 v86, v86
	v_cndmask_b32_e64 v84, v84, v85, s[0:1]
	v_cvt_pk_bf16_f32 v83, v83, v84
	global_store_dwordx4 v[98:99], v[80:83], off offset:64
	s_nop 1
	v_mul_f32_e32 v80, 0x45800000, v86
	v_cndmask_b32_e32 v80, v86, v80, vcc
	v_pk_mul_f32 v[76:77], v[76:77], v[80:81] op_sel_hi:[1,0]
	s_nop 0
	v_fma_f32 v81, |v76|, s26, 1.0
	v_rcp_f32_e32 v81, v81
	v_cmp_gt_f32_e32 vcc, 0, v76
	v_pk_mul_f32 v[82:83], v[74:75], v[80:81] op_sel_hi:[1,0]
	v_pk_mul_f32 v[74:75], v[72:73], v[80:81] op_sel_hi:[1,0]
	v_fmamk_f32 v72, v81, 0x3f07dc22, v211
	v_fmaak_f32 v72, v81, v72, 0x3f35f0e3
	v_mul_f32_e32 v73, v76, v76
	v_mul_f32_e32 v73, 0xbf38aa3b, v73
	v_fmaak_f32 v72, v81, v72, 0xbe11a98e
	v_exp_f32_e32 v73, v73
	v_fmaak_f32 v72, v81, v72, 0x3e027906
	v_pk_mul_f32 v[78:79], v[78:79], v[80:81] op_sel_hi:[1,0]
	v_mul_f32_e32 v72, v81, v72
	v_fma_f32 v81, |v77|, s26, 1.0
	v_rcp_f32_e32 v81, v81
	v_mul_f32_e32 v72, v73, v72
	v_mul_f32_e32 v73, v76, v72
	v_fma_f32 v72, -v76, v72, v76
	v_cndmask_b32_e32 v72, v72, v73, vcc
	v_fmamk_f32 v73, v81, 0x3f07dc22, v211
	v_mul_f32_e32 v76, v77, v77
	v_fmaak_f32 v73, v81, v73, 0x3f35f0e3
	v_mul_f32_e32 v76, 0xbf38aa3b, v76
	v_exp_f32_e32 v76, v76
	v_fmaak_f32 v73, v81, v73, 0xbe11a98e
	v_fmaak_f32 v73, v81, v73, 0x3e027906
	v_mul_f32_e32 v73, v81, v73
	v_fma_f32 v81, |v78|, s26, 1.0
	v_rcp_f32_e32 v81, v81
	v_mul_f32_e32 v73, v76, v73
	v_mul_f32_e32 v76, v77, v73
	v_fma_f32 v73, -v77, v73, v77
	v_cmp_gt_f32_e32 vcc, 0, v77
	v_fma_f32 v77, |v79|, s26, 1.0
	v_rcp_f32_e32 v77, v77
	v_cndmask_b32_e32 v73, v73, v76, vcc
	v_mul_f32_e32 v76, v78, v78
	v_cvt_pk_bf16_f32 v72, v72, v73
	v_fmamk_f32 v73, v81, 0x3f07dc22, v211
	v_mul_f32_e32 v76, 0xbf38aa3b, v76
	v_fmaak_f32 v73, v81, v73, 0x3f35f0e3
	v_exp_f32_e32 v76, v76
	v_fmaak_f32 v73, v81, v73, 0xbe11a98e
	v_fmaak_f32 v73, v81, v73, 0x3e027906
	v_mul_f32_e32 v73, v81, v73
	v_mul_f32_e32 v73, v76, v73
	v_mul_f32_e32 v76, v78, v73
	v_fma_f32 v73, -v78, v73, v78
	v_cmp_gt_f32_e32 vcc, 0, v78
	v_mul_f32_e32 v78, v79, v79
	v_mul_f32_e32 v78, 0xbf38aa3b, v78
	v_cndmask_b32_e32 v73, v73, v76, vcc
	v_fmamk_f32 v76, v77, 0x3f07dc22, v211
	v_fmaak_f32 v76, v77, v76, 0x3f35f0e3
	v_exp_f32_e32 v78, v78
	v_fmaak_f32 v76, v77, v76, 0xbe11a98e
	v_fmaak_f32 v76, v77, v76, 0x3e027906
	v_mul_f32_e32 v76, v77, v76
	v_mul_f32_e32 v76, v78, v76
	v_fma_f32 v78, |v74|, s26, 1.0
	v_rcp_f32_e32 v78, v78
	v_mul_f32_e32 v77, v79, v76
	v_fma_f32 v76, -v79, v76, v79
	v_cmp_gt_f32_e32 vcc, 0, v79
	v_pk_mul_f32 v[68:69], v[68:69], v[80:81] op_sel_hi:[1,0]
	v_pk_mul_f32 v[70:71], v[70:71], v[80:81] op_sel_hi:[1,0]
	v_cndmask_b32_e32 v76, v76, v77, vcc
	v_cvt_pk_bf16_f32 v73, v73, v76
	v_fmamk_f32 v76, v78, 0x3f07dc22, v211
	v_fmaak_f32 v76, v78, v76, 0x3f35f0e3
	v_mul_f32_e32 v77, v74, v74
	v_mul_f32_e32 v77, 0xbf38aa3b, v77
	v_fmaak_f32 v76, v78, v76, 0xbe11a98e
	v_exp_f32_e32 v77, v77
	v_fmaak_f32 v76, v78, v76, 0x3e027906
	v_mul_f32_e32 v76, v78, v76
	v_fma_f32 v78, |v75|, s26, 1.0
	v_rcp_f32_e32 v78, v78
	v_mul_f32_e32 v76, v77, v76
	v_mul_f32_e32 v77, v74, v76
	v_fma_f32 v76, -v74, v76, v74
	v_cmp_gt_f32_e32 vcc, 0, v74
	s_nop 1
	v_cndmask_b32_e32 v74, v76, v77, vcc
	v_fmamk_f32 v76, v78, 0x3f07dc22, v211
	v_mul_f32_e32 v77, v75, v75
	v_fmaak_f32 v76, v78, v76, 0x3f35f0e3
	v_mul_f32_e32 v77, 0xbf38aa3b, v77
	v_exp_f32_e32 v77, v77
	v_fmaak_f32 v76, v78, v76, 0xbe11a98e
	v_fmaak_f32 v76, v78, v76, 0x3e027906
	v_mul_f32_e32 v76, v78, v76
	v_fma_f32 v78, |v82|, s26, 1.0
	v_rcp_f32_e32 v78, v78
	v_mul_f32_e32 v76, v77, v76
	v_mul_f32_e32 v77, v75, v76
	v_fma_f32 v76, -v75, v76, v75
	v_cmp_gt_f32_e32 vcc, 0, v75
	s_nop 1
	v_cndmask_b32_e32 v75, v76, v77, vcc
	v_mul_f32_e32 v76, v82, v82
	v_cvt_pk_bf16_f32 v74, v74, v75
	v_fmamk_f32 v75, v78, 0x3f07dc22, v211
	v_mul_f32_e32 v76, 0xbf38aa3b, v76
	v_fmaak_f32 v75, v78, v75, 0x3f35f0e3
	v_exp_f32_e32 v76, v76
	v_fmaak_f32 v75, v78, v75, 0xbe11a98e
	v_fma_f32 v77, |v83|, s26, 1.0
	v_fmaak_f32 v75, v78, v75, 0x3e027906
	v_rcp_f32_e32 v77, v77
	v_mul_f32_e32 v75, v78, v75
	v_mul_f32_e32 v75, v76, v75
	v_mul_f32_e32 v76, v82, v75
	v_fma_f32 v75, -v82, v75, v82
	v_cmp_gt_f32_e32 vcc, 0, v82
	v_mul_f32_e32 v78, v83, v83
	v_mul_f32_e32 v78, 0xbf38aa3b, v78
	v_cndmask_b32_e32 v75, v75, v76, vcc
	v_fmamk_f32 v76, v77, 0x3f07dc22, v211
	v_fmaak_f32 v76, v77, v76, 0x3f35f0e3
	v_exp_f32_e32 v78, v78
	v_fmaak_f32 v76, v77, v76, 0xbe11a98e
	v_fmaak_f32 v76, v77, v76, 0x3e027906
	v_mul_f32_e32 v76, v77, v76
	v_mul_f32_e32 v76, v78, v76
	v_mul_f32_e32 v77, v83, v76
	v_fma_f32 v76, -v83, v76, v83
	v_cmp_gt_f32_e32 vcc, 0, v83
	s_nop 1
	v_cndmask_b32_e32 v76, v76, v77, vcc
	v_cvt_pk_bf16_f32 v75, v75, v76
	v_lshl_add_u64 v[76:77], s[96:97], 0, v[190:191]
	v_lshl_add_u64 v[76:77], v[76:77], 0, s[98:99]
	v_lshl_add_u64 v[76:77], v[76:77], 0, v[144:145]
	global_store_dwordx4 v[76:77], v[72:75], off
	v_cmp_gt_f32_e32 vcc, 0, v68
	s_nop 0
	v_fma_f32 v72, |v68|, s26, 1.0
	v_rcp_f32_e32 v74, v72
	v_pk_mul_f32 v[72:73], v[66:67], v[80:81] op_sel_hi:[1,0]
	v_pk_mul_f32 v[66:67], v[64:65], v[80:81] op_sel_hi:[1,0]
	v_mul_f32_e32 v65, v68, v68
	v_fmamk_f32 v64, v74, 0x3f07dc22, v211
	v_fmaak_f32 v64, v74, v64, 0x3f35f0e3
	v_mul_f32_e32 v65, 0xbf38aa3b, v65
	v_fmaak_f32 v64, v74, v64, 0xbe11a98e
	v_exp_f32_e32 v65, v65
	v_fmaak_f32 v64, v74, v64, 0x3e027906
	v_mul_f32_e32 v64, v74, v64
	v_fma_f32 v74, |v69|, s26, 1.0
	v_rcp_f32_e32 v74, v74
	v_mul_f32_e32 v64, v65, v64
	v_mul_f32_e32 v65, v68, v64
	v_fma_f32 v64, -v68, v64, v68
	v_cndmask_b32_e32 v64, v64, v65, vcc
	v_fmamk_f32 v65, v74, 0x3f07dc22, v211
	v_mul_f32_e32 v68, v69, v69
	v_fmaak_f32 v65, v74, v65, 0x3f35f0e3
	v_mul_f32_e32 v68, 0xbf38aa3b, v68
	v_exp_f32_e32 v68, v68
	v_fmaak_f32 v65, v74, v65, 0xbe11a98e
	v_fmaak_f32 v65, v74, v65, 0x3e027906
	v_mul_f32_e32 v65, v74, v65
	v_fma_f32 v74, |v70|, s26, 1.0
	v_rcp_f32_e32 v74, v74
	v_mul_f32_e32 v65, v68, v65
	v_mul_f32_e32 v68, v69, v65
	v_fma_f32 v65, -v69, v65, v69
	v_cmp_gt_f32_e32 vcc, 0, v69
	v_fma_f32 v69, |v71|, s26, 1.0
	v_rcp_f32_e32 v69, v69
	v_cndmask_b32_e32 v65, v65, v68, vcc
	v_mul_f32_e32 v68, v70, v70
	v_cvt_pk_bf16_f32 v64, v64, v65
	v_fmamk_f32 v65, v74, 0x3f07dc22, v211
	v_mul_f32_e32 v68, 0xbf38aa3b, v68
	v_fmaak_f32 v65, v74, v65, 0x3f35f0e3
	v_exp_f32_e32 v68, v68
	v_fmaak_f32 v65, v74, v65, 0xbe11a98e
	v_fmaak_f32 v65, v74, v65, 0x3e027906
	v_mul_f32_e32 v65, v74, v65
	v_mul_f32_e32 v65, v68, v65
	v_mul_f32_e32 v68, v70, v65
	v_fma_f32 v65, -v70, v65, v70
	v_cmp_gt_f32_e32 vcc, 0, v70
	v_mul_f32_e32 v70, v71, v71
	v_mul_f32_e32 v70, 0xbf38aa3b, v70
	v_cndmask_b32_e32 v65, v65, v68, vcc
	v_fmamk_f32 v68, v69, 0x3f07dc22, v211
	v_fmaak_f32 v68, v69, v68, 0x3f35f0e3
	v_exp_f32_e32 v70, v70
	v_fmaak_f32 v68, v69, v68, 0xbe11a98e
	v_fmaak_f32 v68, v69, v68, 0x3e027906
	v_mul_f32_e32 v68, v69, v68
	v_mul_f32_e32 v68, v70, v68
	v_fma_f32 v70, |v66|, s26, 1.0
	v_rcp_f32_e32 v70, v70
	v_mul_f32_e32 v69, v71, v68
	v_fma_f32 v68, -v71, v68, v71
	v_cmp_gt_f32_e32 vcc, 0, v71
	s_nop 1
	v_cndmask_b32_e32 v68, v68, v69, vcc
	v_cvt_pk_bf16_f32 v65, v65, v68
	v_fmamk_f32 v68, v70, 0x3f07dc22, v211
	v_fmaak_f32 v68, v70, v68, 0x3f35f0e3
	v_mul_f32_e32 v69, v66, v66
	v_mul_f32_e32 v69, 0xbf38aa3b, v69
	v_fmaak_f32 v68, v70, v68, 0xbe11a98e
	v_exp_f32_e32 v69, v69
	v_fmaak_f32 v68, v70, v68, 0x3e027906
	v_mul_f32_e32 v68, v70, v68
	v_fma_f32 v70, |v67|, s26, 1.0
	v_rcp_f32_e32 v70, v70
	v_mul_f32_e32 v68, v69, v68
	v_mul_f32_e32 v69, v66, v68
	v_fma_f32 v68, -v66, v68, v66
	v_cmp_gt_f32_e32 vcc, 0, v66
	s_nop 1
	v_cndmask_b32_e32 v66, v68, v69, vcc
	v_fmamk_f32 v68, v70, 0x3f07dc22, v211
	v_mul_f32_e32 v69, v67, v67
	v_fmaak_f32 v68, v70, v68, 0x3f35f0e3
	v_mul_f32_e32 v69, 0xbf38aa3b, v69
	v_exp_f32_e32 v69, v69
	v_fmaak_f32 v68, v70, v68, 0xbe11a98e
	v_fmaak_f32 v68, v70, v68, 0x3e027906
	v_mul_f32_e32 v68, v70, v68
	v_fma_f32 v70, |v72|, s26, 1.0
	v_rcp_f32_e32 v70, v70
	v_mul_f32_e32 v68, v69, v68
	v_mul_f32_e32 v69, v67, v68
	v_fma_f32 v68, -v67, v68, v67
	v_cmp_gt_f32_e32 vcc, 0, v67
	s_nop 1
	v_cndmask_b32_e32 v67, v68, v69, vcc
	v_mul_f32_e32 v68, v72, v72
	v_cvt_pk_bf16_f32 v66, v66, v67
	v_fmamk_f32 v67, v70, 0x3f07dc22, v211
	v_mul_f32_e32 v68, 0xbf38aa3b, v68
	v_fmaak_f32 v67, v70, v67, 0x3f35f0e3
	v_exp_f32_e32 v68, v68
	v_fmaak_f32 v67, v70, v67, 0xbe11a98e
	v_fma_f32 v69, |v73|, s26, 1.0
	v_fmaak_f32 v67, v70, v67, 0x3e027906
	v_rcp_f32_e32 v69, v69
	v_mul_f32_e32 v67, v70, v67
	v_mul_f32_e32 v67, v68, v67
	v_mul_f32_e32 v68, v72, v67
	v_fma_f32 v67, -v72, v67, v72
	v_cmp_gt_f32_e32 vcc, 0, v72
	v_mul_f32_e32 v70, v73, v73
	v_mul_f32_e32 v70, 0xbf38aa3b, v70
	v_cndmask_b32_e32 v67, v67, v68, vcc
	v_fmamk_f32 v68, v69, 0x3f07dc22, v211
	v_fmaak_f32 v68, v69, v68, 0x3f35f0e3
	v_exp_f32_e32 v70, v70
	v_fmaak_f32 v68, v69, v68, 0xbe11a98e
	v_fmaak_f32 v68, v69, v68, 0x3e027906
	v_mul_f32_e32 v68, v69, v68
	v_mul_f32_e32 v68, v70, v68
	v_mul_f32_e32 v69, v73, v68
	v_fma_f32 v68, -v73, v68, v73
	v_cmp_gt_f32_e32 vcc, 0, v73
	s_nop 1
	v_cndmask_b32_e32 v68, v68, v69, vcc
	v_cvt_pk_bf16_f32 v67, v67, v68
	global_store_dwordx4 v[76:77], v[64:67], off offset:64
	s_nop 1
	v_ffbh_u32_e32 v64, v167
	v_min_u32_e32 v66, 32, v64
	v_lshlrev_b64 v[64:65], v66, v[166:167]
	v_min_u32_e32 v64, 1, v64
	v_or_b32_e32 v64, v65, v64
	v_cvt_f32_u32_e32 v67, v64
	v_ffbh_u32_e32 v64, v189
	v_min_u32_e32 v68, 32, v64
	v_lshlrev_b64 v[64:65], v68, v[188:189]
	v_min_u32_e32 v64, 1, v64
	v_or_b32_e32 v64, v65, v64
	v_cvt_f32_u32_e32 v64, v64
	v_sub_u32_e32 v65, 32, v66
	v_sub_u32_e32 v66, 32, v68
	v_ldexp_f32 v65, v67, v65
	v_ldexp_f32 v64, v64, v66
	v_pk_mul_f32 v[64:65], v[64:65], s[30:31] op_sel_hi:[1,0]
	v_lshlrev_b64 v[66:67], 10, v[168:169]
	v_pk_fma_f32 v[64:65], v[64:65], s[2:3], v[128:129] op_sel_hi:[1,0,0]
	v_lshl_add_u64 v[66:67], s[96:97], 0, v[66:67]
	v_mul_f32_e32 v68, 0x4b800000, v65
	v_cmp_gt_f32_e32 vcc, s89, v65
	v_lshl_add_u64 v[66:67], v[66:67], 0, s[98:99]
	v_lshl_add_u64 v[66:67], v[66:67], 0, v[144:145]
	v_cndmask_b32_e32 v65, v65, v68, vcc
	v_rsq_f32_e32 v65, v65
	s_nop 0
	v_mul_f32_e32 v68, 0x45800000, v65
	v_cndmask_b32_e32 v68, v65, v68, vcc
	v_pk_mul_f32 v[60:61], v[60:61], v[68:69] op_sel_hi:[1,0]
	v_pk_mul_f32 v[70:71], v[58:59], v[68:69] op_sel_hi:[1,0]
	v_fma_f32 v65, |v60|, s26, 1.0
	v_rcp_f32_e32 v65, v65
	v_pk_mul_f32 v[58:59], v[56:57], v[68:69] op_sel_hi:[1,0]
	v_mul_f32_e32 v57, v60, v60
	v_mul_f32_e32 v57, 0xbf38aa3b, v57
	v_fmamk_f32 v56, v65, 0x3f07dc22, v211
	v_fmaak_f32 v56, v65, v56, 0x3f35f0e3
	v_fmaak_f32 v56, v65, v56, 0xbe11a98e
	v_exp_f32_e32 v57, v57
	v_fmaak_f32 v56, v65, v56, 0x3e027906
	v_mul_f32_e32 v56, v65, v56
	v_fma_f32 v65, |v61|, s26, 1.0
	v_rcp_f32_e32 v65, v65
	v_mul_f32_e32 v56, v57, v56
	v_mul_f32_e32 v57, v60, v56
	v_fma_f32 v56, -v60, v56, v60
	v_cmp_gt_f32_e32 vcc, 0, v60
	v_mul_f32_e32 v60, v61, v61
	v_mul_f32_e32 v60, 0xbf38aa3b, v60
	v_cndmask_b32_e32 v56, v56, v57, vcc
	v_fmamk_f32 v57, v65, 0x3f07dc22, v211
	v_fmaak_f32 v57, v65, v57, 0x3f35f0e3
	v_exp_f32_e32 v60, v60
	v_fmaak_f32 v57, v65, v57, 0xbe11a98e
	v_pk_mul_f32 v[62:63], v[62:63], v[68:69] op_sel_hi:[1,0]
	v_fmaak_f32 v57, v65, v57, 0x3e027906
	v_mul_f32_e32 v57, v65, v57
	v_fma_f32 v65, |v62|, s26, 1.0
	v_rcp_f32_e32 v65, v65
	v_mul_f32_e32 v57, v60, v57
	v_mul_f32_e32 v60, v61, v57
	v_fma_f32 v57, -v61, v57, v61
	v_cmp_gt_f32_e32 vcc, 0, v61
	v_fma_f32 v61, |v63|, s26, 1.0
	v_rcp_f32_e32 v61, v61
	v_cndmask_b32_e32 v57, v57, v60, vcc
	v_mul_f32_e32 v60, v62, v62
	v_cvt_pk_bf16_f32 v56, v56, v57
	v_fmamk_f32 v57, v65, 0x3f07dc22, v211
	v_mul_f32_e32 v60, 0xbf38aa3b, v60
	v_fmaak_f32 v57, v65, v57, 0x3f35f0e3
	v_exp_f32_e32 v60, v60
	v_fmaak_f32 v57, v65, v57, 0xbe11a98e
	v_fmaak_f32 v57, v65, v57, 0x3e027906
	v_mul_f32_e32 v57, v65, v57
	v_mul_f32_e32 v57, v60, v57
	v_mul_f32_e32 v60, v62, v57
	v_fma_f32 v57, -v62, v57, v62
	v_cmp_gt_f32_e32 vcc, 0, v62
	v_mul_f32_e32 v62, v63, v63
	v_mul_f32_e32 v62, 0xbf38aa3b, v62
	v_cndmask_b32_e32 v57, v57, v60, vcc
	v_fmamk_f32 v60, v61, 0x3f07dc22, v211
	v_fmaak_f32 v60, v61, v60, 0x3f35f0e3
	v_exp_f32_e32 v62, v62
	v_fmaak_f32 v60, v61, v60, 0xbe11a98e
	v_fmaak_f32 v60, v61, v60, 0x3e027906
	v_mul_f32_e32 v60, v61, v60
	v_mul_f32_e32 v60, v62, v60
	v_fma_f32 v62, |v58|, s26, 1.0
	v_rcp_f32_e32 v62, v62
	v_mul_f32_e32 v61, v63, v60
	v_fma_f32 v60, -v63, v60, v63
	v_cmp_gt_f32_e32 vcc, 0, v63
	v_pk_mul_f32 v[52:53], v[52:53], v[68:69] op_sel_hi:[1,0]
	v_pk_mul_f32 v[54:55], v[54:55], v[68:69] op_sel_hi:[1,0]
	v_cndmask_b32_e32 v60, v60, v61, vcc
	v_cvt_pk_bf16_f32 v57, v57, v60
	v_fmamk_f32 v60, v62, 0x3f07dc22, v211
	v_fmaak_f32 v60, v62, v60, 0x3f35f0e3
	v_mul_f32_e32 v61, v58, v58
	v_mul_f32_e32 v61, 0xbf38aa3b, v61
	v_fmaak_f32 v60, v62, v60, 0xbe11a98e
	v_exp_f32_e32 v61, v61
	v_fmaak_f32 v60, v62, v60, 0x3e027906
	v_mul_f32_e32 v60, v62, v60
	v_fma_f32 v62, |v59|, s26, 1.0
	v_rcp_f32_e32 v62, v62
	v_mul_f32_e32 v60, v61, v60
	v_mul_f32_e32 v61, v58, v60
	v_fma_f32 v60, -v58, v60, v58
	v_cmp_gt_f32_e32 vcc, 0, v58
	s_nop 1
	v_cndmask_b32_e32 v58, v60, v61, vcc
	v_fmamk_f32 v60, v62, 0x3f07dc22, v211
	v_mul_f32_e32 v61, v59, v59
	v_fmaak_f32 v60, v62, v60, 0x3f35f0e3
	v_mul_f32_e32 v61, 0xbf38aa3b, v61
	v_exp_f32_e32 v61, v61
	v_fmaak_f32 v60, v62, v60, 0xbe11a98e
	v_fmaak_f32 v60, v62, v60, 0x3e027906
	v_mul_f32_e32 v60, v62, v60
	v_fma_f32 v62, |v70|, s26, 1.0
	v_rcp_f32_e32 v62, v62
	v_mul_f32_e32 v60, v61, v60
	v_mul_f32_e32 v61, v59, v60
	v_fma_f32 v60, -v59, v60, v59
	v_cmp_gt_f32_e32 vcc, 0, v59
	s_nop 1
	v_cndmask_b32_e32 v59, v60, v61, vcc
	v_mul_f32_e32 v60, v70, v70
	v_cvt_pk_bf16_f32 v58, v58, v59
	v_fmamk_f32 v59, v62, 0x3f07dc22, v211
	v_mul_f32_e32 v60, 0xbf38aa3b, v60
	v_fmaak_f32 v59, v62, v59, 0x3f35f0e3
	v_exp_f32_e32 v60, v60
	v_fmaak_f32 v59, v62, v59, 0xbe11a98e
	v_fma_f32 v61, |v71|, s26, 1.0
	v_fmaak_f32 v59, v62, v59, 0x3e027906
	v_rcp_f32_e32 v61, v61
	v_mul_f32_e32 v59, v62, v59
	v_mul_f32_e32 v59, v60, v59
	v_mul_f32_e32 v60, v70, v59
	v_fma_f32 v59, -v70, v59, v70
	v_cmp_gt_f32_e32 vcc, 0, v70
	v_mul_f32_e32 v62, v71, v71
	v_mul_f32_e32 v62, 0xbf38aa3b, v62
	v_cndmask_b32_e32 v59, v59, v60, vcc
	v_fmamk_f32 v60, v61, 0x3f07dc22, v211
	v_fmaak_f32 v60, v61, v60, 0x3f35f0e3
	v_exp_f32_e32 v62, v62
	v_fmaak_f32 v60, v61, v60, 0xbe11a98e
	v_fmaak_f32 v60, v61, v60, 0x3e027906
	v_mul_f32_e32 v60, v61, v60
	v_mul_f32_e32 v60, v62, v60
	v_mul_f32_e32 v61, v71, v60
	v_fma_f32 v60, -v71, v60, v71
	v_cmp_gt_f32_e32 vcc, 0, v71
	s_nop 1
	v_cndmask_b32_e32 v60, v60, v61, vcc
	v_cvt_pk_bf16_f32 v59, v59, v60
	global_store_dwordx4 v[66:67], v[56:59], off
	v_cmp_gt_f32_e32 vcc, 0, v52
	s_nop 0
	v_fma_f32 v56, |v52|, s26, 1.0
	v_rcp_f32_e32 v58, v56
	v_pk_mul_f32 v[56:57], v[50:51], v[68:69] op_sel_hi:[1,0]
	v_pk_mul_f32 v[50:51], v[48:49], v[68:69] op_sel_hi:[1,0]
	v_mul_f32_e32 v49, v52, v52
	v_fmamk_f32 v48, v58, 0x3f07dc22, v211
	v_fmaak_f32 v48, v58, v48, 0x3f35f0e3
	v_mul_f32_e32 v49, 0xbf38aa3b, v49
	v_fmaak_f32 v48, v58, v48, 0xbe11a98e
	v_exp_f32_e32 v49, v49
	v_fmaak_f32 v48, v58, v48, 0x3e027906
	v_mul_f32_e32 v48, v58, v48
	v_fma_f32 v58, |v53|, s26, 1.0
	v_rcp_f32_e32 v58, v58
	v_mul_f32_e32 v48, v49, v48
	v_mul_f32_e32 v49, v52, v48
	v_fma_f32 v48, -v52, v48, v52
	v_cndmask_b32_e32 v48, v48, v49, vcc
	v_fmamk_f32 v49, v58, 0x3f07dc22, v211
	v_mul_f32_e32 v52, v53, v53
	v_fmaak_f32 v49, v58, v49, 0x3f35f0e3
	v_mul_f32_e32 v52, 0xbf38aa3b, v52
	v_exp_f32_e32 v52, v52
	v_fmaak_f32 v49, v58, v49, 0xbe11a98e
	v_fmaak_f32 v49, v58, v49, 0x3e027906
	v_mul_f32_e32 v49, v58, v49
	v_fma_f32 v58, |v54|, s26, 1.0
	v_rcp_f32_e32 v58, v58
	v_mul_f32_e32 v49, v52, v49
	v_mul_f32_e32 v52, v53, v49
	v_fma_f32 v49, -v53, v49, v53
	v_cmp_gt_f32_e32 vcc, 0, v53
	v_fma_f32 v53, |v55|, s26, 1.0
	v_rcp_f32_e32 v53, v53
	v_cndmask_b32_e32 v49, v49, v52, vcc
	v_mul_f32_e32 v52, v54, v54
	v_cvt_pk_bf16_f32 v48, v48, v49
	v_fmamk_f32 v49, v58, 0x3f07dc22, v211
	v_mul_f32_e32 v52, 0xbf38aa3b, v52
	v_fmaak_f32 v49, v58, v49, 0x3f35f0e3
	v_exp_f32_e32 v52, v52
	v_fmaak_f32 v49, v58, v49, 0xbe11a98e
	v_fmaak_f32 v49, v58, v49, 0x3e027906
	v_mul_f32_e32 v49, v58, v49
	v_mul_f32_e32 v49, v52, v49
	v_mul_f32_e32 v52, v54, v49
	v_fma_f32 v49, -v54, v49, v54
	v_cmp_gt_f32_e32 vcc, 0, v54
	v_mul_f32_e32 v54, v55, v55
	v_mul_f32_e32 v54, 0xbf38aa3b, v54
	v_cndmask_b32_e32 v49, v49, v52, vcc
	v_fmamk_f32 v52, v53, 0x3f07dc22, v211
	v_fmaak_f32 v52, v53, v52, 0x3f35f0e3
	v_exp_f32_e32 v54, v54
	v_fmaak_f32 v52, v53, v52, 0xbe11a98e
	v_fmaak_f32 v52, v53, v52, 0x3e027906
	v_mul_f32_e32 v52, v53, v52
	v_mul_f32_e32 v52, v54, v52
	v_fma_f32 v54, |v50|, s26, 1.0
	v_rcp_f32_e32 v54, v54
	v_mul_f32_e32 v53, v55, v52
	v_fma_f32 v52, -v55, v52, v55
	v_cmp_gt_f32_e32 vcc, 0, v55
	v_cmp_gt_f32_e64 s[0:1], 0, v57
	s_nop 0
	v_cndmask_b32_e32 v52, v52, v53, vcc
	v_cvt_pk_bf16_f32 v49, v49, v52
	v_fmamk_f32 v52, v54, 0x3f07dc22, v211
	v_fmaak_f32 v52, v54, v52, 0x3f35f0e3
	v_mul_f32_e32 v53, v50, v50
	v_mul_f32_e32 v53, 0xbf38aa3b, v53
	v_fmaak_f32 v52, v54, v52, 0xbe11a98e
	v_exp_f32_e32 v53, v53
	v_fmaak_f32 v52, v54, v52, 0x3e027906
	v_mul_f32_e32 v52, v54, v52
	v_fma_f32 v54, |v51|, s26, 1.0
	v_rcp_f32_e32 v54, v54
	v_mul_f32_e32 v52, v53, v52
	v_mul_f32_e32 v53, v50, v52
	v_fma_f32 v52, -v50, v52, v50
	v_cmp_gt_f32_e32 vcc, 0, v50
	s_nop 1
	v_cndmask_b32_e32 v50, v52, v53, vcc
	v_fmamk_f32 v52, v54, 0x3f07dc22, v211
	v_mul_f32_e32 v53, v51, v51
	v_fmaak_f32 v52, v54, v52, 0x3f35f0e3
	v_mul_f32_e32 v53, 0xbf38aa3b, v53
	v_exp_f32_e32 v53, v53
	v_fmaak_f32 v52, v54, v52, 0xbe11a98e
	v_fmaak_f32 v52, v54, v52, 0x3e027906
	v_mul_f32_e32 v52, v54, v52
	v_fma_f32 v54, |v56|, s26, 1.0
	v_rcp_f32_e32 v54, v54
	v_mul_f32_e32 v52, v53, v52
	v_mul_f32_e32 v53, v51, v52
	v_fma_f32 v52, -v51, v52, v51
	v_cmp_gt_f32_e32 vcc, 0, v51
	s_nop 1
	v_cndmask_b32_e32 v51, v52, v53, vcc
	v_mul_f32_e32 v52, v56, v56
	v_cvt_pk_bf16_f32 v50, v50, v51
	v_fmamk_f32 v51, v54, 0x3f07dc22, v211
	v_mul_f32_e32 v52, 0xbf38aa3b, v52
	v_fmaak_f32 v51, v54, v51, 0x3f35f0e3
	v_exp_f32_e32 v52, v52
	v_fmaak_f32 v51, v54, v51, 0xbe11a98e
	v_fma_f32 v53, |v57|, s26, 1.0
	v_fmaak_f32 v51, v54, v51, 0x3e027906
	v_rcp_f32_e32 v53, v53
	v_mul_f32_e32 v51, v54, v51
	v_mul_f32_e32 v51, v52, v51
	v_mul_f32_e32 v52, v56, v51
	v_fma_f32 v51, -v56, v51, v56
	v_cmp_gt_f32_e32 vcc, 0, v56
	v_mul_f32_e32 v54, v57, v57
	v_mul_f32_e32 v54, 0xbf38aa3b, v54
	v_cndmask_b32_e32 v51, v51, v52, vcc
	v_fmamk_f32 v52, v53, 0x3f07dc22, v211
	v_fmaak_f32 v52, v53, v52, 0x3f35f0e3
	v_exp_f32_e32 v54, v54
	v_fmaak_f32 v52, v53, v52, 0xbe11a98e
	v_fmaak_f32 v52, v53, v52, 0x3e027906
	v_mul_f32_e32 v52, v53, v52
	v_mul_f32_e32 v52, v54, v52
	v_mul_f32_e32 v54, 0x4b800000, v64
	v_cmp_gt_f32_e32 vcc, s89, v64
	v_mul_f32_e32 v53, v57, v52
	v_fma_f32 v52, -v57, v52, v57
	v_cndmask_b32_e32 v54, v64, v54, vcc
	v_rsq_f32_e32 v54, v54
	v_cndmask_b32_e64 v52, v52, v53, s[0:1]
	v_cvt_pk_bf16_f32 v51, v51, v52
	global_store_dwordx4 v[66:67], v[48:51], off offset:64
	s_nop 1
	v_mul_f32_e32 v48, 0x45800000, v54
	v_cndmask_b32_e32 v48, v54, v48, vcc
	v_pk_mul_f32 v[44:45], v[44:45], v[48:49] op_sel_hi:[1,0]
	v_lshlrev_b64 v[50:51], 10, v[164:165]
	v_fma_f32 v49, |v44|, s26, 1.0
	v_rcp_f32_e32 v49, v49
	v_cmp_gt_f32_e32 vcc, 0, v44
	v_pk_mul_f32 v[52:53], v[42:43], v[48:49] op_sel_hi:[1,0]
	v_pk_mul_f32 v[42:43], v[40:41], v[48:49] op_sel_hi:[1,0]
	v_fmamk_f32 v40, v49, 0x3f07dc22, v211
	v_fmaak_f32 v40, v49, v40, 0x3f35f0e3
	v_mul_f32_e32 v41, v44, v44
	v_mul_f32_e32 v41, 0xbf38aa3b, v41
	v_fmaak_f32 v40, v49, v40, 0xbe11a98e
	v_exp_f32_e32 v41, v41
	v_fmaak_f32 v40, v49, v40, 0x3e027906
	v_pk_mul_f32 v[46:47], v[46:47], v[48:49] op_sel_hi:[1,0]
	v_mul_f32_e32 v40, v49, v40
	v_fma_f32 v49, |v45|, s26, 1.0
	v_rcp_f32_e32 v49, v49
	v_mul_f32_e32 v40, v41, v40
	v_mul_f32_e32 v41, v44, v40
	v_fma_f32 v40, -v44, v40, v44
	v_cndmask_b32_e32 v40, v40, v41, vcc
	v_fmamk_f32 v41, v49, 0x3f07dc22, v211
	v_mul_f32_e32 v44, v45, v45
	v_fmaak_f32 v41, v49, v41, 0x3f35f0e3
	v_mul_f32_e32 v44, 0xbf38aa3b, v44
	v_exp_f32_e32 v44, v44
	v_fmaak_f32 v41, v49, v41, 0xbe11a98e
	v_fmaak_f32 v41, v49, v41, 0x3e027906
	v_mul_f32_e32 v41, v49, v41
	v_fma_f32 v49, |v46|, s26, 1.0
	v_rcp_f32_e32 v49, v49
	v_mul_f32_e32 v41, v44, v41
	v_mul_f32_e32 v44, v45, v41
	v_fma_f32 v41, -v45, v41, v45
	v_cmp_gt_f32_e32 vcc, 0, v45
	v_fma_f32 v45, |v47|, s26, 1.0
	v_rcp_f32_e32 v45, v45
	v_cndmask_b32_e32 v41, v41, v44, vcc
	v_mul_f32_e32 v44, v46, v46
	v_cvt_pk_bf16_f32 v40, v40, v41
	v_fmamk_f32 v41, v49, 0x3f07dc22, v211
	v_mul_f32_e32 v44, 0xbf38aa3b, v44
	v_fmaak_f32 v41, v49, v41, 0x3f35f0e3
	v_exp_f32_e32 v44, v44
	v_fmaak_f32 v41, v49, v41, 0xbe11a98e
	v_fmaak_f32 v41, v49, v41, 0x3e027906
	v_mul_f32_e32 v41, v49, v41
	v_mul_f32_e32 v41, v44, v41
	v_mul_f32_e32 v44, v46, v41
	v_fma_f32 v41, -v46, v41, v46
	v_cmp_gt_f32_e32 vcc, 0, v46
	v_mul_f32_e32 v46, v47, v47
	v_mul_f32_e32 v46, 0xbf38aa3b, v46
	v_cndmask_b32_e32 v41, v41, v44, vcc
	v_fmamk_f32 v44, v45, 0x3f07dc22, v211
	v_fmaak_f32 v44, v45, v44, 0x3f35f0e3
	v_exp_f32_e32 v46, v46
	v_fmaak_f32 v44, v45, v44, 0xbe11a98e
	v_fmaak_f32 v44, v45, v44, 0x3e027906
	v_mul_f32_e32 v44, v45, v44
	v_mul_f32_e32 v44, v46, v44
	v_fma_f32 v46, |v42|, s26, 1.0
	v_rcp_f32_e32 v46, v46
	v_mul_f32_e32 v45, v47, v44
	v_fma_f32 v44, -v47, v44, v47
	v_cmp_gt_f32_e32 vcc, 0, v47
	v_pk_mul_f32 v[36:37], v[36:37], v[48:49] op_sel_hi:[1,0]
	v_pk_mul_f32 v[38:39], v[38:39], v[48:49] op_sel_hi:[1,0]
	v_cndmask_b32_e32 v44, v44, v45, vcc
	v_cvt_pk_bf16_f32 v41, v41, v44
	v_fmamk_f32 v44, v46, 0x3f07dc22, v211
	v_fmaak_f32 v44, v46, v44, 0x3f35f0e3
	v_mul_f32_e32 v45, v42, v42
	v_mul_f32_e32 v45, 0xbf38aa3b, v45
	v_fmaak_f32 v44, v46, v44, 0xbe11a98e
	v_exp_f32_e32 v45, v45
	v_fmaak_f32 v44, v46, v44, 0x3e027906
	v_mul_f32_e32 v44, v46, v44
	v_fma_f32 v46, |v43|, s26, 1.0
	v_rcp_f32_e32 v46, v46
	v_mul_f32_e32 v44, v45, v44
	v_mul_f32_e32 v45, v42, v44
	v_fma_f32 v44, -v42, v44, v42
	v_cmp_gt_f32_e32 vcc, 0, v42
	s_nop 1
	v_cndmask_b32_e32 v42, v44, v45, vcc
	v_fmamk_f32 v44, v46, 0x3f07dc22, v211
	v_mul_f32_e32 v45, v43, v43
	v_fmaak_f32 v44, v46, v44, 0x3f35f0e3
	v_mul_f32_e32 v45, 0xbf38aa3b, v45
	v_exp_f32_e32 v45, v45
	v_fmaak_f32 v44, v46, v44, 0xbe11a98e
	v_fmaak_f32 v44, v46, v44, 0x3e027906
	v_mul_f32_e32 v44, v46, v44
	v_fma_f32 v46, |v52|, s26, 1.0
	v_rcp_f32_e32 v46, v46
	v_mul_f32_e32 v44, v45, v44
	v_mul_f32_e32 v45, v43, v44
	v_fma_f32 v44, -v43, v44, v43
	v_cmp_gt_f32_e32 vcc, 0, v43
	s_nop 1
	v_cndmask_b32_e32 v43, v44, v45, vcc
	v_mul_f32_e32 v44, v52, v52
	v_cvt_pk_bf16_f32 v42, v42, v43
	v_fmamk_f32 v43, v46, 0x3f07dc22, v211
	v_mul_f32_e32 v44, 0xbf38aa3b, v44
	v_fmaak_f32 v43, v46, v43, 0x3f35f0e3
	v_exp_f32_e32 v44, v44
	v_fmaak_f32 v43, v46, v43, 0xbe11a98e
	v_fma_f32 v45, |v53|, s26, 1.0
	v_fmaak_f32 v43, v46, v43, 0x3e027906
	v_rcp_f32_e32 v45, v45
	v_mul_f32_e32 v43, v46, v43
	v_mul_f32_e32 v43, v44, v43
	v_mul_f32_e32 v44, v52, v43
	v_fma_f32 v43, -v52, v43, v52
	v_cmp_gt_f32_e32 vcc, 0, v52
	v_mul_f32_e32 v46, v53, v53
	v_mul_f32_e32 v46, 0xbf38aa3b, v46
	v_cndmask_b32_e32 v43, v43, v44, vcc
	v_fmamk_f32 v44, v45, 0x3f07dc22, v211
	v_fmaak_f32 v44, v45, v44, 0x3f35f0e3
	v_exp_f32_e32 v46, v46
	v_fmaak_f32 v44, v45, v44, 0xbe11a98e
	v_fmaak_f32 v44, v45, v44, 0x3e027906
	v_mul_f32_e32 v44, v45, v44
	v_mul_f32_e32 v44, v46, v44
	v_mul_f32_e32 v45, v53, v44
	v_fma_f32 v44, -v53, v44, v53
	v_cmp_gt_f32_e32 vcc, 0, v53
	s_nop 1
	v_cndmask_b32_e32 v44, v44, v45, vcc
	v_cvt_pk_bf16_f32 v43, v43, v44
	v_lshl_add_u64 v[44:45], s[96:97], 0, v[50:51]
	v_lshl_add_u64 v[44:45], v[44:45], 0, s[98:99]
	v_lshl_add_u64 v[44:45], v[44:45], 0, v[144:145]
	global_store_dwordx4 v[44:45], v[40:43], off
	v_cmp_gt_f32_e32 vcc, 0, v36
	s_nop 0
	v_fma_f32 v40, |v36|, s26, 1.0
	v_rcp_f32_e32 v42, v40
	v_pk_mul_f32 v[40:41], v[34:35], v[48:49] op_sel_hi:[1,0]
	v_pk_mul_f32 v[34:35], v[32:33], v[48:49] op_sel_hi:[1,0]
	v_mul_f32_e32 v33, v36, v36
	v_fmamk_f32 v32, v42, 0x3f07dc22, v211
	v_fmaak_f32 v32, v42, v32, 0x3f35f0e3
	v_mul_f32_e32 v33, 0xbf38aa3b, v33
	v_fmaak_f32 v32, v42, v32, 0xbe11a98e
	v_exp_f32_e32 v33, v33
	v_fmaak_f32 v32, v42, v32, 0x3e027906
	v_mul_f32_e32 v32, v42, v32
	v_fma_f32 v42, |v37|, s26, 1.0
	v_rcp_f32_e32 v42, v42
	v_mul_f32_e32 v32, v33, v32
	v_mul_f32_e32 v33, v36, v32
	v_fma_f32 v32, -v36, v32, v36
	v_cndmask_b32_e32 v32, v32, v33, vcc
	v_fmamk_f32 v33, v42, 0x3f07dc22, v211
	v_mul_f32_e32 v36, v37, v37
	v_fmaak_f32 v33, v42, v33, 0x3f35f0e3
	v_mul_f32_e32 v36, 0xbf38aa3b, v36
	v_exp_f32_e32 v36, v36
	v_fmaak_f32 v33, v42, v33, 0xbe11a98e
	v_fmaak_f32 v33, v42, v33, 0x3e027906
	v_mul_f32_e32 v33, v42, v33
	v_fma_f32 v42, |v38|, s26, 1.0
	v_rcp_f32_e32 v42, v42
	v_mul_f32_e32 v33, v36, v33
	v_mul_f32_e32 v36, v37, v33
	v_fma_f32 v33, -v37, v33, v37
	v_cmp_gt_f32_e32 vcc, 0, v37
	v_fma_f32 v37, |v39|, s26, 1.0
	v_rcp_f32_e32 v37, v37
	v_cndmask_b32_e32 v33, v33, v36, vcc
	v_mul_f32_e32 v36, v38, v38
	v_cvt_pk_bf16_f32 v32, v32, v33
	v_fmamk_f32 v33, v42, 0x3f07dc22, v211
	v_mul_f32_e32 v36, 0xbf38aa3b, v36
	v_fmaak_f32 v33, v42, v33, 0x3f35f0e3
	v_exp_f32_e32 v36, v36
	v_fmaak_f32 v33, v42, v33, 0xbe11a98e
	v_fmaak_f32 v33, v42, v33, 0x3e027906
	v_mul_f32_e32 v33, v42, v33
	v_mul_f32_e32 v33, v36, v33
	v_mul_f32_e32 v36, v38, v33
	v_fma_f32 v33, -v38, v33, v38
	v_cmp_gt_f32_e32 vcc, 0, v38
	v_mul_f32_e32 v38, v39, v39
	v_mul_f32_e32 v38, 0xbf38aa3b, v38
	v_cndmask_b32_e32 v33, v33, v36, vcc
	v_fmamk_f32 v36, v37, 0x3f07dc22, v211
	v_fmaak_f32 v36, v37, v36, 0x3f35f0e3
	v_exp_f32_e32 v38, v38
	v_fmaak_f32 v36, v37, v36, 0xbe11a98e
	v_fmaak_f32 v36, v37, v36, 0x3e027906
	v_mul_f32_e32 v36, v37, v36
	v_mul_f32_e32 v36, v38, v36
	v_fma_f32 v38, |v34|, s26, 1.0
	v_rcp_f32_e32 v38, v38
	v_mul_f32_e32 v37, v39, v36
	v_fma_f32 v36, -v39, v36, v39
	v_cmp_gt_f32_e32 vcc, 0, v39
	s_nop 1
	v_cndmask_b32_e32 v36, v36, v37, vcc
	v_cvt_pk_bf16_f32 v33, v33, v36
	v_fmamk_f32 v36, v38, 0x3f07dc22, v211
	v_fmaak_f32 v36, v38, v36, 0x3f35f0e3
	v_mul_f32_e32 v37, v34, v34
	v_mul_f32_e32 v37, 0xbf38aa3b, v37
	v_fmaak_f32 v36, v38, v36, 0xbe11a98e
	v_exp_f32_e32 v37, v37
	v_fmaak_f32 v36, v38, v36, 0x3e027906
	v_mul_f32_e32 v36, v38, v36
	v_fma_f32 v38, |v35|, s26, 1.0
	v_rcp_f32_e32 v38, v38
	v_mul_f32_e32 v36, v37, v36
	v_mul_f32_e32 v37, v34, v36
	v_fma_f32 v36, -v34, v36, v34
	v_cmp_gt_f32_e32 vcc, 0, v34
	s_nop 1
	v_cndmask_b32_e32 v34, v36, v37, vcc
	v_fmamk_f32 v36, v38, 0x3f07dc22, v211
	v_mul_f32_e32 v37, v35, v35
	v_fmaak_f32 v36, v38, v36, 0x3f35f0e3
	v_mul_f32_e32 v37, 0xbf38aa3b, v37
	v_exp_f32_e32 v37, v37
	v_fmaak_f32 v36, v38, v36, 0xbe11a98e
	v_fmaak_f32 v36, v38, v36, 0x3e027906
	v_mul_f32_e32 v36, v38, v36
	v_fma_f32 v38, |v40|, s26, 1.0
	v_rcp_f32_e32 v38, v38
	v_mul_f32_e32 v36, v37, v36
	v_mul_f32_e32 v37, v35, v36
	v_fma_f32 v36, -v35, v36, v35
	v_cmp_gt_f32_e32 vcc, 0, v35
	s_nop 1
	v_cndmask_b32_e32 v35, v36, v37, vcc
	v_mul_f32_e32 v36, v40, v40
	v_cvt_pk_bf16_f32 v34, v34, v35
	v_fmamk_f32 v35, v38, 0x3f07dc22, v211
	v_mul_f32_e32 v36, 0xbf38aa3b, v36
	v_fmaak_f32 v35, v38, v35, 0x3f35f0e3
	v_exp_f32_e32 v36, v36
	v_fmaak_f32 v35, v38, v35, 0xbe11a98e
	v_fma_f32 v37, |v41|, s26, 1.0
	v_fmaak_f32 v35, v38, v35, 0x3e027906
	v_rcp_f32_e32 v37, v37
	v_mul_f32_e32 v35, v38, v35
	v_mul_f32_e32 v35, v36, v35
	v_mul_f32_e32 v36, v40, v35
	v_fma_f32 v35, -v40, v35, v40
	v_cmp_gt_f32_e32 vcc, 0, v40
	v_mul_f32_e32 v38, v41, v41
	v_mul_f32_e32 v38, 0xbf38aa3b, v38
	v_cndmask_b32_e32 v35, v35, v36, vcc
	v_fmamk_f32 v36, v37, 0x3f07dc22, v211
	v_fmaak_f32 v36, v37, v36, 0x3f35f0e3
	v_exp_f32_e32 v38, v38
	v_fmaak_f32 v36, v37, v36, 0xbe11a98e
	v_fmaak_f32 v36, v37, v36, 0x3e027906
	v_mul_f32_e32 v36, v37, v36
	v_mul_f32_e32 v36, v38, v36
	v_mul_f32_e32 v37, v41, v36
	v_fma_f32 v36, -v41, v36, v41
	v_cmp_gt_f32_e32 vcc, 0, v41
	s_nop 1
	v_cndmask_b32_e32 v36, v36, v37, vcc
	v_cvt_pk_bf16_f32 v35, v35, v36
	global_store_dwordx4 v[44:45], v[32:35], off offset:64
	s_nop 1
	v_ffbh_u32_e32 v32, v163
	v_min_u32_e32 v34, 32, v32
	v_lshlrev_b64 v[32:33], v34, v[162:163]
	v_min_u32_e32 v32, 1, v32
	v_or_b32_e32 v32, v33, v32
	v_cvt_f32_u32_e32 v35, v32
	v_ffbh_u32_e32 v32, v161
	v_min_u32_e32 v36, 32, v32
	v_lshlrev_b64 v[32:33], v36, v[160:161]
	v_min_u32_e32 v32, 1, v32
	v_or_b32_e32 v32, v33, v32
	v_cvt_f32_u32_e32 v32, v32
	v_sub_u32_e32 v33, 32, v34
	v_sub_u32_e32 v34, 32, v36
	v_ldexp_f32 v33, v35, v33
	v_ldexp_f32 v32, v32, v34
	v_pk_mul_f32 v[32:33], v[32:33], s[30:31] op_sel_hi:[1,0]
	v_lshlrev_b64 v[34:35], 10, v[158:159]
	v_pk_fma_f32 v[32:33], v[32:33], s[2:3], v[128:129] op_sel_hi:[1,0,0]
	v_lshl_add_u64 v[34:35], s[96:97], 0, v[34:35]
	v_mul_f32_e32 v36, 0x4b800000, v33
	v_cmp_gt_f32_e32 vcc, s89, v33
	v_lshl_add_u64 v[34:35], v[34:35], 0, s[98:99]
	v_lshl_add_u64 v[34:35], v[34:35], 0, v[144:145]
	v_cndmask_b32_e32 v33, v33, v36, vcc
	v_rsq_f32_e32 v33, v33
	s_nop 0
	v_mul_f32_e32 v36, 0x45800000, v33
	v_cndmask_b32_e32 v36, v33, v36, vcc
	v_pk_mul_f32 v[28:29], v[28:29], v[36:37] op_sel_hi:[1,0]
	v_pk_mul_f32 v[38:39], v[26:27], v[36:37] op_sel_hi:[1,0]
	v_fma_f32 v33, |v28|, s26, 1.0
	v_rcp_f32_e32 v33, v33
	v_pk_mul_f32 v[26:27], v[24:25], v[36:37] op_sel_hi:[1,0]
	v_mul_f32_e32 v25, v28, v28
	v_mul_f32_e32 v25, 0xbf38aa3b, v25
	v_fmamk_f32 v24, v33, 0x3f07dc22, v211
	v_fmaak_f32 v24, v33, v24, 0x3f35f0e3
	v_fmaak_f32 v24, v33, v24, 0xbe11a98e
	v_exp_f32_e32 v25, v25
	v_fmaak_f32 v24, v33, v24, 0x3e027906
	v_mul_f32_e32 v24, v33, v24
	v_fma_f32 v33, |v29|, s26, 1.0
	v_rcp_f32_e32 v33, v33
	v_mul_f32_e32 v24, v25, v24
	v_mul_f32_e32 v25, v28, v24
	v_fma_f32 v24, -v28, v24, v28
	v_cmp_gt_f32_e32 vcc, 0, v28
	v_mul_f32_e32 v28, v29, v29
	v_mul_f32_e32 v28, 0xbf38aa3b, v28
	v_cndmask_b32_e32 v24, v24, v25, vcc
	v_fmamk_f32 v25, v33, 0x3f07dc22, v211
	v_fmaak_f32 v25, v33, v25, 0x3f35f0e3
	v_exp_f32_e32 v28, v28
	v_fmaak_f32 v25, v33, v25, 0xbe11a98e
	v_pk_mul_f32 v[30:31], v[30:31], v[36:37] op_sel_hi:[1,0]
	v_fmaak_f32 v25, v33, v25, 0x3e027906
	v_mul_f32_e32 v25, v33, v25
	v_fma_f32 v33, |v30|, s26, 1.0
	v_rcp_f32_e32 v33, v33
	v_mul_f32_e32 v25, v28, v25
	v_mul_f32_e32 v28, v29, v25
	v_fma_f32 v25, -v29, v25, v29
	v_cmp_gt_f32_e32 vcc, 0, v29
	v_fma_f32 v29, |v31|, s26, 1.0
	v_rcp_f32_e32 v29, v29
	v_cndmask_b32_e32 v25, v25, v28, vcc
	v_mul_f32_e32 v28, v30, v30
	v_cvt_pk_bf16_f32 v24, v24, v25
	v_fmamk_f32 v25, v33, 0x3f07dc22, v211
	v_mul_f32_e32 v28, 0xbf38aa3b, v28
	v_fmaak_f32 v25, v33, v25, 0x3f35f0e3
	v_exp_f32_e32 v28, v28
	v_fmaak_f32 v25, v33, v25, 0xbe11a98e
	v_fmaak_f32 v25, v33, v25, 0x3e027906
	v_mul_f32_e32 v25, v33, v25
	v_mul_f32_e32 v25, v28, v25
	v_mul_f32_e32 v28, v30, v25
	v_fma_f32 v25, -v30, v25, v30
	v_cmp_gt_f32_e32 vcc, 0, v30
	v_mul_f32_e32 v30, v31, v31
	v_mul_f32_e32 v30, 0xbf38aa3b, v30
	v_cndmask_b32_e32 v25, v25, v28, vcc
	v_fmamk_f32 v28, v29, 0x3f07dc22, v211
	v_fmaak_f32 v28, v29, v28, 0x3f35f0e3
	v_exp_f32_e32 v30, v30
	v_fmaak_f32 v28, v29, v28, 0xbe11a98e
	v_fmaak_f32 v28, v29, v28, 0x3e027906
	v_mul_f32_e32 v28, v29, v28
	v_mul_f32_e32 v28, v30, v28
	v_fma_f32 v30, |v26|, s26, 1.0
	v_rcp_f32_e32 v30, v30
	v_mul_f32_e32 v29, v31, v28
	v_fma_f32 v28, -v31, v28, v31
	v_cmp_gt_f32_e32 vcc, 0, v31
	v_pk_mul_f32 v[20:21], v[20:21], v[36:37] op_sel_hi:[1,0]
	v_pk_mul_f32 v[22:23], v[22:23], v[36:37] op_sel_hi:[1,0]
	v_cndmask_b32_e32 v28, v28, v29, vcc
	v_cvt_pk_bf16_f32 v25, v25, v28
	v_fmamk_f32 v28, v30, 0x3f07dc22, v211
	v_fmaak_f32 v28, v30, v28, 0x3f35f0e3
	v_mul_f32_e32 v29, v26, v26
	v_mul_f32_e32 v29, 0xbf38aa3b, v29
	v_fmaak_f32 v28, v30, v28, 0xbe11a98e
	v_exp_f32_e32 v29, v29
	v_fmaak_f32 v28, v30, v28, 0x3e027906
	v_mul_f32_e32 v28, v30, v28
	v_fma_f32 v30, |v27|, s26, 1.0
	v_rcp_f32_e32 v30, v30
	v_mul_f32_e32 v28, v29, v28
	v_mul_f32_e32 v29, v26, v28
	v_fma_f32 v28, -v26, v28, v26
	v_cmp_gt_f32_e32 vcc, 0, v26
	s_nop 1
	v_cndmask_b32_e32 v26, v28, v29, vcc
	v_fmamk_f32 v28, v30, 0x3f07dc22, v211
	v_mul_f32_e32 v29, v27, v27
	v_fmaak_f32 v28, v30, v28, 0x3f35f0e3
	v_mul_f32_e32 v29, 0xbf38aa3b, v29
	v_exp_f32_e32 v29, v29
	v_fmaak_f32 v28, v30, v28, 0xbe11a98e
	v_fmaak_f32 v28, v30, v28, 0x3e027906
	v_mul_f32_e32 v28, v30, v28
	v_fma_f32 v30, |v38|, s26, 1.0
	v_rcp_f32_e32 v30, v30
	v_mul_f32_e32 v28, v29, v28
	v_mul_f32_e32 v29, v27, v28
	v_fma_f32 v28, -v27, v28, v27
	v_cmp_gt_f32_e32 vcc, 0, v27
	s_nop 1
	v_cndmask_b32_e32 v27, v28, v29, vcc
	v_mul_f32_e32 v28, v38, v38
	v_cvt_pk_bf16_f32 v26, v26, v27
	v_fmamk_f32 v27, v30, 0x3f07dc22, v211
	v_mul_f32_e32 v28, 0xbf38aa3b, v28
	v_fmaak_f32 v27, v30, v27, 0x3f35f0e3
	v_exp_f32_e32 v28, v28
	v_fmaak_f32 v27, v30, v27, 0xbe11a98e
	v_fma_f32 v29, |v39|, s26, 1.0
	v_fmaak_f32 v27, v30, v27, 0x3e027906
	v_rcp_f32_e32 v29, v29
	v_mul_f32_e32 v27, v30, v27
	v_mul_f32_e32 v27, v28, v27
	v_mul_f32_e32 v28, v38, v27
	v_fma_f32 v27, -v38, v27, v38
	v_cmp_gt_f32_e32 vcc, 0, v38
	v_mul_f32_e32 v30, v39, v39
	v_mul_f32_e32 v30, 0xbf38aa3b, v30
	v_cndmask_b32_e32 v27, v27, v28, vcc
	v_fmamk_f32 v28, v29, 0x3f07dc22, v211
	v_fmaak_f32 v28, v29, v28, 0x3f35f0e3
	v_exp_f32_e32 v30, v30
	v_fmaak_f32 v28, v29, v28, 0xbe11a98e
	v_fmaak_f32 v28, v29, v28, 0x3e027906
	v_mul_f32_e32 v28, v29, v28
	v_mul_f32_e32 v28, v30, v28
	v_mul_f32_e32 v29, v39, v28
	v_fma_f32 v28, -v39, v28, v39
	v_cmp_gt_f32_e32 vcc, 0, v39
	s_nop 1
	v_cndmask_b32_e32 v28, v28, v29, vcc
	v_cvt_pk_bf16_f32 v27, v27, v28
	global_store_dwordx4 v[34:35], v[24:27], off
	v_cmp_gt_f32_e32 vcc, 0, v20
	s_nop 0
	v_fma_f32 v24, |v20|, s26, 1.0
	v_rcp_f32_e32 v26, v24
	v_pk_mul_f32 v[24:25], v[18:19], v[36:37] op_sel_hi:[1,0]
	v_pk_mul_f32 v[18:19], v[16:17], v[36:37] op_sel_hi:[1,0]
	v_mul_f32_e32 v17, v20, v20
	v_fmamk_f32 v16, v26, 0x3f07dc22, v211
	v_fmaak_f32 v16, v26, v16, 0x3f35f0e3
	v_mul_f32_e32 v17, 0xbf38aa3b, v17
	v_fmaak_f32 v16, v26, v16, 0xbe11a98e
	v_exp_f32_e32 v17, v17
	v_fmaak_f32 v16, v26, v16, 0x3e027906
	v_mul_f32_e32 v16, v26, v16
	v_fma_f32 v26, |v21|, s26, 1.0
	v_rcp_f32_e32 v26, v26
	v_mul_f32_e32 v16, v17, v16
	v_mul_f32_e32 v17, v20, v16
	v_fma_f32 v16, -v20, v16, v20
	v_cndmask_b32_e32 v16, v16, v17, vcc
	v_fmamk_f32 v17, v26, 0x3f07dc22, v211
	v_mul_f32_e32 v20, v21, v21
	v_fmaak_f32 v17, v26, v17, 0x3f35f0e3
	v_mul_f32_e32 v20, 0xbf38aa3b, v20
	v_exp_f32_e32 v20, v20
	v_fmaak_f32 v17, v26, v17, 0xbe11a98e
	v_fmaak_f32 v17, v26, v17, 0x3e027906
	v_mul_f32_e32 v17, v26, v17
	v_fma_f32 v26, |v22|, s26, 1.0
	v_rcp_f32_e32 v26, v26
	v_mul_f32_e32 v17, v20, v17
	v_mul_f32_e32 v20, v21, v17
	v_fma_f32 v17, -v21, v17, v21
	v_cmp_gt_f32_e32 vcc, 0, v21
	v_fma_f32 v21, |v23|, s26, 1.0
	v_rcp_f32_e32 v21, v21
	v_cndmask_b32_e32 v17, v17, v20, vcc
	v_mul_f32_e32 v20, v22, v22
	v_cvt_pk_bf16_f32 v16, v16, v17
	v_fmamk_f32 v17, v26, 0x3f07dc22, v211
	v_mul_f32_e32 v20, 0xbf38aa3b, v20
	v_fmaak_f32 v17, v26, v17, 0x3f35f0e3
	v_exp_f32_e32 v20, v20
	v_fmaak_f32 v17, v26, v17, 0xbe11a98e
	v_fmaak_f32 v17, v26, v17, 0x3e027906
	v_mul_f32_e32 v17, v26, v17
	v_mul_f32_e32 v17, v20, v17
	v_mul_f32_e32 v20, v22, v17
	v_fma_f32 v17, -v22, v17, v22
	v_cmp_gt_f32_e32 vcc, 0, v22
	v_mul_f32_e32 v22, v23, v23
	v_mul_f32_e32 v22, 0xbf38aa3b, v22
	v_cndmask_b32_e32 v17, v17, v20, vcc
	v_fmamk_f32 v20, v21, 0x3f07dc22, v211
	v_fmaak_f32 v20, v21, v20, 0x3f35f0e3
	v_exp_f32_e32 v22, v22
	v_fmaak_f32 v20, v21, v20, 0xbe11a98e
	v_fmaak_f32 v20, v21, v20, 0x3e027906
	v_mul_f32_e32 v20, v21, v20
	v_mul_f32_e32 v20, v22, v20
	v_fma_f32 v22, |v18|, s26, 1.0
	v_rcp_f32_e32 v22, v22
	v_mul_f32_e32 v21, v23, v20
	v_fma_f32 v20, -v23, v20, v23
	v_cmp_gt_f32_e32 vcc, 0, v23
	v_cmp_gt_f32_e64 s[0:1], 0, v25
	s_nop 0
	v_cndmask_b32_e32 v20, v20, v21, vcc
	v_cvt_pk_bf16_f32 v17, v17, v20
	v_fmamk_f32 v20, v22, 0x3f07dc22, v211
	v_fmaak_f32 v20, v22, v20, 0x3f35f0e3
	v_mul_f32_e32 v21, v18, v18
	v_mul_f32_e32 v21, 0xbf38aa3b, v21
	v_fmaak_f32 v20, v22, v20, 0xbe11a98e
	v_exp_f32_e32 v21, v21
	v_fmaak_f32 v20, v22, v20, 0x3e027906
	v_mul_f32_e32 v20, v22, v20
	v_fma_f32 v22, |v19|, s26, 1.0
	v_rcp_f32_e32 v22, v22
	v_mul_f32_e32 v20, v21, v20
	v_mul_f32_e32 v21, v18, v20
	v_fma_f32 v20, -v18, v20, v18
	v_cmp_gt_f32_e32 vcc, 0, v18
	s_nop 1
	v_cndmask_b32_e32 v18, v20, v21, vcc
	v_fmamk_f32 v20, v22, 0x3f07dc22, v211
	v_mul_f32_e32 v21, v19, v19
	v_fmaak_f32 v20, v22, v20, 0x3f35f0e3
	v_mul_f32_e32 v21, 0xbf38aa3b, v21
	v_exp_f32_e32 v21, v21
	v_fmaak_f32 v20, v22, v20, 0xbe11a98e
	v_fmaak_f32 v20, v22, v20, 0x3e027906
	v_mul_f32_e32 v20, v22, v20
	v_fma_f32 v22, |v24|, s26, 1.0
	v_rcp_f32_e32 v22, v22
	v_mul_f32_e32 v20, v21, v20
	v_mul_f32_e32 v21, v19, v20
	v_fma_f32 v20, -v19, v20, v19
	v_cmp_gt_f32_e32 vcc, 0, v19
	s_nop 1
	v_cndmask_b32_e32 v19, v20, v21, vcc
	v_mul_f32_e32 v20, v24, v24
	v_cvt_pk_bf16_f32 v18, v18, v19
	v_fmamk_f32 v19, v22, 0x3f07dc22, v211
	v_mul_f32_e32 v20, 0xbf38aa3b, v20
	v_fmaak_f32 v19, v22, v19, 0x3f35f0e3
	v_exp_f32_e32 v20, v20
	v_fmaak_f32 v19, v22, v19, 0xbe11a98e
	v_fma_f32 v21, |v25|, s26, 1.0
	v_fmaak_f32 v19, v22, v19, 0x3e027906
	v_rcp_f32_e32 v21, v21
	v_mul_f32_e32 v19, v22, v19
	v_mul_f32_e32 v19, v20, v19
	v_mul_f32_e32 v20, v24, v19
	v_fma_f32 v19, -v24, v19, v24
	v_cmp_gt_f32_e32 vcc, 0, v24
	v_mul_f32_e32 v22, v25, v25
	v_mul_f32_e32 v22, 0xbf38aa3b, v22
	v_cndmask_b32_e32 v19, v19, v20, vcc
	v_fmamk_f32 v20, v21, 0x3f07dc22, v211
	v_fmaak_f32 v20, v21, v20, 0x3f35f0e3
	v_exp_f32_e32 v22, v22
	v_fmaak_f32 v20, v21, v20, 0xbe11a98e
	v_fmaak_f32 v20, v21, v20, 0x3e027906
	v_mul_f32_e32 v20, v21, v20
	v_mul_f32_e32 v20, v22, v20
	v_mul_f32_e32 v22, 0x4b800000, v32
	v_cmp_gt_f32_e32 vcc, s89, v32
	v_mul_f32_e32 v21, v25, v20
	v_fma_f32 v20, -v25, v20, v25
	v_cndmask_b32_e32 v22, v32, v22, vcc
	v_rsq_f32_e32 v22, v22
	v_cndmask_b32_e64 v20, v20, v21, s[0:1]
	v_cvt_pk_bf16_f32 v19, v19, v20
	global_store_dwordx4 v[34:35], v[16:19], off offset:64
	s_nop 1
	v_mul_f32_e32 v16, 0x45800000, v22
	v_cndmask_b32_e32 v16, v22, v16, vcc
	v_pk_mul_f32 v[12:13], v[12:13], v[16:17] op_sel_hi:[1,0]
	v_lshlrev_b64 v[18:19], 10, v[156:157]
	v_fma_f32 v17, |v12|, s26, 1.0
	v_rcp_f32_e32 v17, v17
	v_cmp_gt_f32_e32 vcc, 0, v12
	v_pk_mul_f32 v[20:21], v[10:11], v[16:17] op_sel_hi:[1,0]
	v_pk_mul_f32 v[10:11], v[8:9], v[16:17] op_sel_hi:[1,0]
	v_fmamk_f32 v8, v17, 0x3f07dc22, v211
	v_fmaak_f32 v8, v17, v8, 0x3f35f0e3
	v_mul_f32_e32 v9, v12, v12
	v_mul_f32_e32 v9, 0xbf38aa3b, v9
	v_fmaak_f32 v8, v17, v8, 0xbe11a98e
	v_exp_f32_e32 v9, v9
	v_fmaak_f32 v8, v17, v8, 0x3e027906
	v_pk_mul_f32 v[14:15], v[14:15], v[16:17] op_sel_hi:[1,0]
	v_mul_f32_e32 v8, v17, v8
	v_fma_f32 v17, |v13|, s26, 1.0
	v_rcp_f32_e32 v17, v17
	v_mul_f32_e32 v8, v9, v8
	v_mul_f32_e32 v9, v12, v8
	v_fma_f32 v8, -v12, v8, v12
	v_cndmask_b32_e32 v8, v8, v9, vcc
	v_fmamk_f32 v9, v17, 0x3f07dc22, v211
	v_mul_f32_e32 v12, v13, v13
	v_fmaak_f32 v9, v17, v9, 0x3f35f0e3
	v_mul_f32_e32 v12, 0xbf38aa3b, v12
	v_exp_f32_e32 v12, v12
	v_fmaak_f32 v9, v17, v9, 0xbe11a98e
	v_fmaak_f32 v9, v17, v9, 0x3e027906
	v_mul_f32_e32 v9, v17, v9
	v_fma_f32 v17, |v14|, s26, 1.0
	v_rcp_f32_e32 v17, v17
	v_mul_f32_e32 v9, v12, v9
	v_mul_f32_e32 v12, v13, v9
	v_fma_f32 v9, -v13, v9, v13
	v_cmp_gt_f32_e32 vcc, 0, v13
	v_fma_f32 v13, |v15|, s26, 1.0
	v_rcp_f32_e32 v13, v13
	v_cndmask_b32_e32 v9, v9, v12, vcc
	v_mul_f32_e32 v12, v14, v14
	v_cvt_pk_bf16_f32 v8, v8, v9
	v_fmamk_f32 v9, v17, 0x3f07dc22, v211
	v_mul_f32_e32 v12, 0xbf38aa3b, v12
	v_fmaak_f32 v9, v17, v9, 0x3f35f0e3
	v_exp_f32_e32 v12, v12
	v_fmaak_f32 v9, v17, v9, 0xbe11a98e
	v_fmaak_f32 v9, v17, v9, 0x3e027906
	v_mul_f32_e32 v9, v17, v9
	v_mul_f32_e32 v9, v12, v9
	v_mul_f32_e32 v12, v14, v9
	v_fma_f32 v9, -v14, v9, v14
	v_cmp_gt_f32_e32 vcc, 0, v14
	v_mul_f32_e32 v14, v15, v15
	v_mul_f32_e32 v14, 0xbf38aa3b, v14
	v_cndmask_b32_e32 v9, v9, v12, vcc
	v_fmamk_f32 v12, v13, 0x3f07dc22, v211
	v_fmaak_f32 v12, v13, v12, 0x3f35f0e3
	v_exp_f32_e32 v14, v14
	v_fmaak_f32 v12, v13, v12, 0xbe11a98e
	v_fmaak_f32 v12, v13, v12, 0x3e027906
	v_mul_f32_e32 v12, v13, v12
	v_mul_f32_e32 v12, v14, v12
	v_fma_f32 v14, |v10|, s26, 1.0
	v_rcp_f32_e32 v14, v14
	v_mul_f32_e32 v13, v15, v12
	v_fma_f32 v12, -v15, v12, v15
	v_cmp_gt_f32_e32 vcc, 0, v15
	v_pk_mul_f32 v[4:5], v[4:5], v[16:17] op_sel_hi:[1,0]
	v_pk_mul_f32 v[6:7], v[6:7], v[16:17] op_sel_hi:[1,0]
	v_cndmask_b32_e32 v12, v12, v13, vcc
	v_cvt_pk_bf16_f32 v9, v9, v12
	v_fmamk_f32 v12, v14, 0x3f07dc22, v211
	v_fmaak_f32 v12, v14, v12, 0x3f35f0e3
	v_mul_f32_e32 v13, v10, v10
	v_mul_f32_e32 v13, 0xbf38aa3b, v13
	v_fmaak_f32 v12, v14, v12, 0xbe11a98e
	v_exp_f32_e32 v13, v13
	v_fmaak_f32 v12, v14, v12, 0x3e027906
	v_mul_f32_e32 v12, v14, v12
	v_fma_f32 v14, |v11|, s26, 1.0
	v_rcp_f32_e32 v14, v14
	v_mul_f32_e32 v12, v13, v12
	v_mul_f32_e32 v13, v10, v12
	v_fma_f32 v12, -v10, v12, v10
	v_cmp_gt_f32_e32 vcc, 0, v10
	v_pk_mul_f32 v[0:1], v[0:1], v[16:17] op_sel_hi:[1,0]
	v_pk_mul_f32 v[2:3], v[2:3], v[16:17] op_sel_hi:[1,0]
	v_cndmask_b32_e32 v10, v12, v13, vcc
	v_fmamk_f32 v12, v14, 0x3f07dc22, v211
	v_mul_f32_e32 v13, v11, v11
	v_fmaak_f32 v12, v14, v12, 0x3f35f0e3
	v_mul_f32_e32 v13, 0xbf38aa3b, v13
	v_exp_f32_e32 v13, v13
	v_fmaak_f32 v12, v14, v12, 0xbe11a98e
	v_fmaak_f32 v12, v14, v12, 0x3e027906
	v_mul_f32_e32 v12, v14, v12
	v_fma_f32 v14, |v20|, s26, 1.0
	v_rcp_f32_e32 v14, v14
	v_mul_f32_e32 v12, v13, v12
	v_mul_f32_e32 v13, v11, v12
	v_fma_f32 v12, -v11, v12, v11
	v_cmp_gt_f32_e32 vcc, 0, v11
	s_nop 1
	v_cndmask_b32_e32 v11, v12, v13, vcc
	v_mul_f32_e32 v12, v20, v20
	v_cvt_pk_bf16_f32 v10, v10, v11
	v_fmamk_f32 v11, v14, 0x3f07dc22, v211
	v_mul_f32_e32 v12, 0xbf38aa3b, v12
	v_fmaak_f32 v11, v14, v11, 0x3f35f0e3
	v_exp_f32_e32 v12, v12
	v_fmaak_f32 v11, v14, v11, 0xbe11a98e
	v_fma_f32 v13, |v21|, s26, 1.0
	v_fmaak_f32 v11, v14, v11, 0x3e027906
	v_rcp_f32_e32 v13, v13
	v_mul_f32_e32 v11, v14, v11
	v_mul_f32_e32 v11, v12, v11
	v_mul_f32_e32 v12, v20, v11
	v_fma_f32 v11, -v20, v11, v20
	v_cmp_gt_f32_e32 vcc, 0, v20
	v_mul_f32_e32 v14, v21, v21
	v_mul_f32_e32 v14, 0xbf38aa3b, v14
	v_cndmask_b32_e32 v11, v11, v12, vcc
	v_fmamk_f32 v12, v13, 0x3f07dc22, v211
	v_fmaak_f32 v12, v13, v12, 0x3f35f0e3
	v_exp_f32_e32 v14, v14
	v_fmaak_f32 v12, v13, v12, 0xbe11a98e
	v_fmaak_f32 v12, v13, v12, 0x3e027906
	v_mul_f32_e32 v12, v13, v12
	v_mul_f32_e32 v12, v14, v12
	v_mul_f32_e32 v13, v21, v12
	v_fma_f32 v12, -v21, v12, v21
	v_cmp_gt_f32_e32 vcc, 0, v21
	s_nop 1
	v_cndmask_b32_e32 v12, v12, v13, vcc
	v_cvt_pk_bf16_f32 v11, v11, v12
	v_lshl_add_u64 v[12:13], s[96:97], 0, v[18:19]
	v_lshl_add_u64 v[12:13], v[12:13], 0, s[98:99]
	v_lshl_add_u64 v[206:207], v[12:13], 0, v[144:145]
	global_store_dwordx4 v[206:207], v[8:11], off
	v_cmp_gt_f32_e32 vcc, 0, v4
	s_nop 0
	v_fma_f32 v8, |v4|, s26, 1.0
	v_rcp_f32_e32 v8, v8
	v_mul_f32_e32 v10, v4, v4
	v_mul_f32_e32 v10, 0xbf38aa3b, v10
	v_exp_f32_e32 v10, v10
	v_fmamk_f32 v9, v8, 0x3f07dc22, v211
	v_fmaak_f32 v9, v8, v9, 0x3f35f0e3
	v_fmaak_f32 v9, v8, v9, 0xbe11a98e
	v_fmaak_f32 v9, v8, v9, 0x3e027906
	v_mul_f32_e32 v8, v8, v9
	v_mul_f32_e32 v8, v10, v8
	v_fma_f32 v10, |v5|, s26, 1.0
	v_rcp_f32_e32 v10, v10
	v_mul_f32_e32 v9, v4, v8
	v_fma_f32 v8, -v4, v8, v4
	v_cndmask_b32_e32 v4, v8, v9, vcc
	v_mul_f32_e32 v9, v5, v5
	v_fmamk_f32 v8, v10, 0x3f07dc22, v211
	v_mul_f32_e32 v9, 0xbf38aa3b, v9
	v_fmaak_f32 v8, v10, v8, 0x3f35f0e3
	v_exp_f32_e32 v9, v9
	v_fmaak_f32 v8, v10, v8, 0xbe11a98e
	v_fmaak_f32 v8, v10, v8, 0x3e027906
	v_mul_f32_e32 v8, v10, v8
	v_fma_f32 v10, |v6|, s26, 1.0
	v_mul_f32_e32 v8, v9, v8
	v_rcp_f32_e32 v10, v10
	v_mul_f32_e32 v9, v5, v8
	v_fma_f32 v8, -v5, v8, v5
	v_cmp_gt_f32_e32 vcc, 0, v5
	s_nop 1
	v_cndmask_b32_e32 v5, v8, v9, vcc
	v_cvt_pk_bf16_f32 v128, v4, v5
	v_mul_f32_e32 v5, v6, v6
	v_fmamk_f32 v4, v10, 0x3f07dc22, v211
	v_mul_f32_e32 v5, 0xbf38aa3b, v5
	v_fmaak_f32 v4, v10, v4, 0x3f35f0e3
	v_exp_f32_e32 v5, v5
	v_fmaak_f32 v4, v10, v4, 0xbe11a98e
	v_fma_f32 v8, |v7|, s26, 1.0
	v_fmaak_f32 v4, v10, v4, 0x3e027906
	v_rcp_f32_e32 v8, v8
	v_mul_f32_e32 v4, v10, v4
	v_mul_f32_e32 v4, v5, v4
	v_mul_f32_e32 v5, v6, v4
	v_fma_f32 v4, -v6, v4, v6
	v_cmp_gt_f32_e32 vcc, 0, v6
	v_mul_f32_e32 v6, v7, v7
	v_mul_f32_e32 v6, 0xbf38aa3b, v6
	v_cndmask_b32_e32 v4, v4, v5, vcc
	v_fmamk_f32 v5, v8, 0x3f07dc22, v211
	v_fmaak_f32 v5, v8, v5, 0x3f35f0e3
	v_exp_f32_e32 v6, v6
	v_fmaak_f32 v5, v8, v5, 0xbe11a98e
	v_fmaak_f32 v5, v8, v5, 0x3e027906
	v_mul_f32_e32 v5, v8, v5
	v_fma_f32 v8, |v0|, s26, 1.0
	v_mul_f32_e32 v5, v6, v5
	v_rcp_f32_e32 v8, v8
	v_mul_f32_e32 v6, v7, v5
	v_fma_f32 v5, -v7, v5, v7
	v_cmp_gt_f32_e32 vcc, 0, v7
	s_nop 1
	v_cndmask_b32_e32 v5, v5, v6, vcc
	v_cvt_pk_bf16_f32 v129, v4, v5
	v_mul_f32_e32 v5, v0, v0
	v_fmamk_f32 v4, v8, 0x3f07dc22, v211
	v_mul_f32_e32 v5, 0xbf38aa3b, v5
	v_fmaak_f32 v4, v8, v4, 0x3f35f0e3
	v_exp_f32_e32 v5, v5
	v_fmaak_f32 v4, v8, v4, 0xbe11a98e
	v_fmaak_f32 v4, v8, v4, 0x3e027906
	v_fma_f32 v6, |v1|, s26, 1.0
	v_mul_f32_e32 v4, v8, v4
	v_rcp_f32_e32 v6, v6
	v_mul_f32_e32 v4, v5, v4
	v_mul_f32_e32 v5, v0, v4
	v_fma_f32 v4, -v0, v4, v0
	v_cmp_gt_f32_e32 vcc, 0, v0
	s_nop 1
	v_cndmask_b32_e32 v0, v4, v5, vcc
	v_mul_f32_e32 v5, v1, v1
	v_fmamk_f32 v4, v6, 0x3f07dc22, v211
	v_mul_f32_e32 v5, 0xbf38aa3b, v5
	v_fmaak_f32 v4, v6, v4, 0x3f35f0e3
	v_exp_f32_e32 v5, v5
	v_fmaak_f32 v4, v6, v4, 0xbe11a98e
	v_fmaak_f32 v4, v6, v4, 0x3e027906
	v_mul_f32_e32 v4, v6, v4
	v_fma_f32 v6, |v2|, s26, 1.0
	v_mul_f32_e32 v4, v5, v4
	v_rcp_f32_e32 v6, v6
	v_mul_f32_e32 v5, v1, v4
	v_fma_f32 v4, -v1, v4, v1
	v_cmp_gt_f32_e32 vcc, 0, v1
	s_nop 1
	v_cndmask_b32_e32 v1, v4, v5, vcc
	v_cvt_pk_bf16_f32 v130, v0, v1
	v_mul_f32_e32 v1, v2, v2
	v_fmamk_f32 v0, v6, 0x3f07dc22, v211
	v_mul_f32_e32 v1, 0xbf38aa3b, v1
	v_fmaak_f32 v0, v6, v0, 0x3f35f0e3
	v_exp_f32_e32 v1, v1
	v_fmaak_f32 v0, v6, v0, 0xbe11a98e
	v_fma_f32 v4, |v3|, s26, 1.0
	v_fmaak_f32 v0, v6, v0, 0x3e027906
	v_rcp_f32_e32 v4, v4
	v_mul_f32_e32 v0, v6, v0
	v_mul_f32_e32 v0, v1, v0
	v_mul_f32_e32 v1, v2, v0
	v_fma_f32 v0, -v2, v0, v2
	v_cmp_gt_f32_e32 vcc, 0, v2
	v_mul_f32_e32 v2, v3, v3
	v_mul_f32_e32 v2, 0xbf38aa3b, v2
	v_cndmask_b32_e32 v0, v0, v1, vcc
	v_fmamk_f32 v1, v4, 0x3f07dc22, v211
	v_fmaak_f32 v1, v4, v1, 0x3f35f0e3
	v_exp_f32_e32 v2, v2
	v_fmaak_f32 v1, v4, v1, 0xbe11a98e
	v_fmaak_f32 v1, v4, v1, 0x3e027906
	v_mul_f32_e32 v1, v4, v1
	v_mul_f32_e32 v1, v2, v1
	v_mul_f32_e32 v2, v3, v1
	v_fma_f32 v1, -v3, v1, v3
	v_cmp_gt_f32_e32 vcc, 0, v3
	s_nop 1
	v_cndmask_b32_e32 v1, v1, v2, vcc
	v_cvt_pk_bf16_f32 v131, v0, v1
	s_nop 1
	s_branch .LBB0_322

.LBB0_351:
	s_add_u32 s27, s0, 0xfffc0080
	s_addc_u32 s37, s1, -1
	s_add_i32 s47, 0, 0x10000
	v_add_u32_e32 v140, s47, v192
	ds_read_b128 v[128:131], v140
	ds_read_b128 v[132:135], v140 offset:1024
	ds_read_b128 v[136:139], v140 offset:2048
	ds_read_b128 v[140:143], v140 offset:3072
	s_cmp_eq_u32 s36, 12
	s_cselect_b32 s53, s25, s37
	s_cselect_b32 s52, s30, s27
	s_cselect_b32 s51, s31, s35
	s_cselect_b32 s50, s33, s34
	v_lshl_add_u64 v[176:177], s[0:1], 0, v[156:157]
	s_add_i32 m0, s77, 0xc000
	ds_read_b128 v[162:165], v194
	ds_read_b128 v[166:169], v194 offset:1024
	ds_read_b128 v[196:199], v194 offset:2048
	ds_read_b128 v[200:203], v194 offset:3072
	ds_read_b128 v[204:207], v194 offset:4096
	ds_read_b128 v[216:219], v194 offset:5120
	ds_read_b128 v[220:223], v194 offset:6144
	ds_read_b128 v[228:231], v194 offset:7168
	global_load_lds_dwordx4 v[176:177], off
	v_lshl_add_u64 v[176:177], s[0:1], 0, v[158:159]
	s_add_i32 m0, s77, 0xe000
	s_nop 0
	global_load_lds_dwordx4 v[176:177], off
	s_waitcnt lgkmcnt(8)
	s_barrier
	s_waitcnt lgkmcnt(0)
	s_setprio 1
	s_waitcnt lgkmcnt(0)
	v_mfma_f32_16x16x32_bf16 v[124:127], v[128:131], v[162:165], v[124:127]
	v_mfma_f32_16x16x32_bf16 v[120:123], v[136:139], v[162:165], v[120:123]
	v_mfma_f32_16x16x32_bf16 v[116:119], v[128:131], v[196:199], v[116:119]
	v_mfma_f32_16x16x32_bf16 v[112:115], v[136:139], v[196:199], v[112:115]
	v_mfma_f32_16x16x32_bf16 v[108:111], v[128:131], v[204:207], v[108:111]
	v_mfma_f32_16x16x32_bf16 v[104:107], v[136:139], v[204:207], v[104:107]
	v_mfma_f32_16x16x32_bf16 v[100:103], v[128:131], v[220:223], v[100:103]
	v_mfma_f32_16x16x32_bf16 v[96:99], v[136:139], v[220:223], v[96:99]
	v_mfma_f32_16x16x32_bf16 v[124:127], v[132:135], v[166:169], v[124:127]
	v_mfma_f32_16x16x32_bf16 v[120:123], v[140:143], v[166:169], v[120:123]
	v_mfma_f32_16x16x32_bf16 v[116:119], v[132:135], v[200:203], v[116:119]
	v_mfma_f32_16x16x32_bf16 v[112:115], v[140:143], v[200:203], v[112:115]
	v_mfma_f32_16x16x32_bf16 v[108:111], v[132:135], v[216:219], v[108:111]
	v_mfma_f32_16x16x32_bf16 v[104:107], v[140:143], v[216:219], v[104:107]
	v_mfma_f32_16x16x32_bf16 v[100:103], v[132:135], v[228:231], v[100:103]
	v_mfma_f32_16x16x32_bf16 v[96:99], v[140:143], v[228:231], v[96:99]
	s_setprio 0
	s_barrier
	s_add_i32 s27, 0, 0x14000
	s_add_i32 s37, s47, s76
	v_add_u32_e32 v161, s27, v192
	v_lshl_add_u64 v[176:177], s[50:51], 0, v[148:149]
	s_mov_b32 m0, s37
	ds_read_b128 v[232:235], v161
	ds_read_b128 v[236:239], v161 offset:1024
	ds_read_b128 v[240:243], v161 offset:2048
	ds_read_b128 v[244:247], v161 offset:3072
	global_load_lds_dwordx4 v[176:177], off
	v_lshl_add_u64 v[188:189], s[50:51], 0, v[152:153]
	s_add_i32 m0, s37, 0x2000
	s_nop 0
	global_load_lds_dwordx4 v[188:189], off
	s_barrier
	s_waitcnt lgkmcnt(0)
	s_setprio 1
	s_waitcnt lgkmcnt(0)
	v_mfma_f32_16x16x32_bf16 v[92:95], v[232:235], v[162:165], v[92:95]
	v_mfma_f32_16x16x32_bf16 v[88:91], v[240:243], v[162:165], v[88:91]
	v_mfma_f32_16x16x32_bf16 v[84:87], v[232:235], v[196:199], v[84:87]
	v_mfma_f32_16x16x32_bf16 v[80:83], v[240:243], v[196:199], v[80:83]
	v_mfma_f32_16x16x32_bf16 v[76:79], v[232:235], v[204:207], v[76:79]
	v_mfma_f32_16x16x32_bf16 v[72:75], v[240:243], v[204:207], v[72:75]
	v_mfma_f32_16x16x32_bf16 v[68:71], v[232:235], v[220:223], v[68:71]
	v_mfma_f32_16x16x32_bf16 v[64:67], v[240:243], v[220:223], v[64:67]
	v_mfma_f32_16x16x32_bf16 v[92:95], v[236:239], v[166:169], v[92:95]
	v_mfma_f32_16x16x32_bf16 v[88:91], v[244:247], v[166:169], v[88:91]
	v_mfma_f32_16x16x32_bf16 v[84:87], v[236:239], v[200:203], v[84:87]
	v_mfma_f32_16x16x32_bf16 v[80:83], v[244:247], v[200:203], v[80:83]
	v_mfma_f32_16x16x32_bf16 v[76:79], v[236:239], v[216:219], v[76:79]
	v_mfma_f32_16x16x32_bf16 v[72:75], v[244:247], v[216:219], v[72:75]
	v_mfma_f32_16x16x32_bf16 v[68:71], v[236:239], v[228:231], v[68:71]
	v_mfma_f32_16x16x32_bf16 v[64:67], v[244:247], v[228:231], v[64:67]
	s_setprio 0
	s_mov_b32 m0, s77
	v_lshl_add_u64 v[224:225], s[52:53], 0, v[146:147]
	s_barrier
	ds_read_b128 v[162:165], v194 offset:16384
	ds_read_b128 v[166:169], v194 offset:17408
	ds_read_b128 v[196:199], v194 offset:18432
	ds_read_b128 v[200:203], v194 offset:19456
	ds_read_b128 v[204:207], v194 offset:20480
	ds_read_b128 v[216:219], v194 offset:21504
	ds_read_b128 v[220:223], v194 offset:22528
	ds_read_b128 v[228:231], v194 offset:23552
	global_load_lds_dwordx4 v[224:225], off
	v_lshl_add_u64 v[248:249], s[52:53], 0, v[150:151]
	s_mov_b32 m0, s78
	s_nop 0
	global_load_lds_dwordx4 v[248:249], off
	s_barrier
	s_waitcnt lgkmcnt(0)
	s_setprio 1
	s_waitcnt lgkmcnt(0)
	v_mfma_f32_16x16x32_bf16 v[60:63], v[128:131], v[162:165], v[60:63]
	v_mfma_f32_16x16x32_bf16 v[56:59], v[136:139], v[162:165], v[56:59]
	v_mfma_f32_16x16x32_bf16 v[52:55], v[128:131], v[196:199], v[52:55]
	v_mfma_f32_16x16x32_bf16 v[48:51], v[136:139], v[196:199], v[48:51]
	v_mfma_f32_16x16x32_bf16 v[44:47], v[128:131], v[204:207], v[44:47]
	v_mfma_f32_16x16x32_bf16 v[40:43], v[136:139], v[204:207], v[40:43]
	v_mfma_f32_16x16x32_bf16 v[36:39], v[128:131], v[220:223], v[36:39]
	v_mfma_f32_16x16x32_bf16 v[32:35], v[136:139], v[220:223], v[32:35]
	v_mfma_f32_16x16x32_bf16 v[60:63], v[132:135], v[166:169], v[60:63]
	v_mfma_f32_16x16x32_bf16 v[56:59], v[140:143], v[166:169], v[56:59]
	v_mfma_f32_16x16x32_bf16 v[52:55], v[132:135], v[200:203], v[52:55]
	v_mfma_f32_16x16x32_bf16 v[48:51], v[140:143], v[200:203], v[48:51]
	v_mfma_f32_16x16x32_bf16 v[44:47], v[132:135], v[216:219], v[44:47]
	v_mfma_f32_16x16x32_bf16 v[40:43], v[140:143], v[216:219], v[40:43]
	v_mfma_f32_16x16x32_bf16 v[36:39], v[132:135], v[228:231], v[36:39]
	v_mfma_f32_16x16x32_bf16 v[32:35], v[140:143], v[228:231], v[32:35]
	s_setprio 0
	s_barrier
	s_add_u32 s56, s50, 0x40000
	s_addc_u32 s57, s51, 0
	s_add_i32 s27, s27, s76
	v_lshl_add_u64 v[128:129], s[56:57], 0, v[148:149]
	s_mov_b32 m0, s27
	s_nop 0
	global_load_lds_dwordx4 v[128:129], off
	v_lshl_add_u64 v[128:129], s[56:57], 0, v[152:153]
	s_add_i32 m0, s27, 0x2000
	s_nop 0
	global_load_lds_dwordx4 v[128:129], off
	s_waitcnt vmcnt(6)
	s_barrier
	s_setprio 1
	v_mfma_f32_16x16x32_bf16 v[28:31], v[232:235], v[162:165], v[28:31]
	v_mfma_f32_16x16x32_bf16 v[24:27], v[240:243], v[162:165], v[24:27]
	v_mfma_f32_16x16x32_bf16 v[20:23], v[232:235], v[196:199], v[20:23]
	v_mfma_f32_16x16x32_bf16 v[16:19], v[240:243], v[196:199], v[16:19]
	v_mfma_f32_16x16x32_bf16 v[12:15], v[232:235], v[204:207], v[12:15]
	v_mfma_f32_16x16x32_bf16 v[8:11], v[240:243], v[204:207], v[8:11]
	v_mfma_f32_16x16x32_bf16 v[4:7], v[232:235], v[220:223], v[4:7]
	v_mfma_f32_16x16x32_bf16 v[0:3], v[240:243], v[220:223], v[0:3]
	v_mfma_f32_16x16x32_bf16 v[28:31], v[236:239], v[166:169], v[28:31]
	v_mfma_f32_16x16x32_bf16 v[24:27], v[244:247], v[166:169], v[24:27]
	v_mfma_f32_16x16x32_bf16 v[20:23], v[236:239], v[200:203], v[20:23]
	v_mfma_f32_16x16x32_bf16 v[16:19], v[244:247], v[200:203], v[16:19]
	v_mfma_f32_16x16x32_bf16 v[12:15], v[236:239], v[216:219], v[12:15]
	v_mfma_f32_16x16x32_bf16 v[8:11], v[244:247], v[216:219], v[8:11]
	v_mfma_f32_16x16x32_bf16 v[4:7], v[236:239], v[228:231], v[4:7]
	v_mfma_f32_16x16x32_bf16 v[0:3], v[244:247], v[228:231], v[0:3]
	s_setprio 0
	s_add_i32 s27, 0, 0x18000
	v_add_u32_e32 v140, s27, v192
	s_barrier
	ds_read_b128 v[128:131], v140
	ds_read_b128 v[132:135], v140 offset:1024
	ds_read_b128 v[136:139], v140 offset:2048
	ds_read_b128 v[140:143], v140 offset:3072
	s_add_u32 s52, s52, 0x40000
	s_addc_u32 s53, s53, 0
	s_mov_b32 m0, s81
	v_lshl_add_u64 v[232:233], s[52:53], 0, v[146:147]
	ds_read_b128 v[162:165], v194 offset:32768
	ds_read_b128 v[166:169], v194 offset:33792
	ds_read_b128 v[196:199], v194 offset:34816
	ds_read_b128 v[200:203], v194 offset:35840
	ds_read_b128 v[204:207], v194 offset:36864
	ds_read_b128 v[216:219], v194 offset:37888
	ds_read_b128 v[220:223], v194 offset:38912
	ds_read_b128 v[228:231], v194 offset:39936
	global_load_lds_dwordx4 v[232:233], off
	v_lshl_add_u64 v[232:233], s[52:53], 0, v[150:151]
	s_mov_b32 m0, s82
	s_nop 0
	global_load_lds_dwordx4 v[232:233], off
	s_waitcnt lgkmcnt(8)
	s_barrier
	s_waitcnt lgkmcnt(0)
	s_setprio 1
	s_waitcnt lgkmcnt(0)
	v_mfma_f32_16x16x32_bf16 v[124:127], v[128:131], v[162:165], v[124:127]
	v_mfma_f32_16x16x32_bf16 v[120:123], v[136:139], v[162:165], v[120:123]
	v_mfma_f32_16x16x32_bf16 v[116:119], v[128:131], v[196:199], v[116:119]
	v_mfma_f32_16x16x32_bf16 v[112:115], v[136:139], v[196:199], v[112:115]
	v_mfma_f32_16x16x32_bf16 v[108:111], v[128:131], v[204:207], v[108:111]
	v_mfma_f32_16x16x32_bf16 v[104:107], v[136:139], v[204:207], v[104:107]
	v_mfma_f32_16x16x32_bf16 v[100:103], v[128:131], v[220:223], v[100:103]
	v_mfma_f32_16x16x32_bf16 v[96:99], v[136:139], v[220:223], v[96:99]
	v_mfma_f32_16x16x32_bf16 v[124:127], v[132:135], v[166:169], v[124:127]
	v_mfma_f32_16x16x32_bf16 v[120:123], v[140:143], v[166:169], v[120:123]
	v_mfma_f32_16x16x32_bf16 v[116:119], v[132:135], v[200:203], v[116:119]
	v_mfma_f32_16x16x32_bf16 v[112:115], v[140:143], v[200:203], v[112:115]
	v_mfma_f32_16x16x32_bf16 v[108:111], v[132:135], v[216:219], v[108:111]
	v_mfma_f32_16x16x32_bf16 v[104:107], v[140:143], v[216:219], v[104:107]
	v_mfma_f32_16x16x32_bf16 v[100:103], v[132:135], v[228:231], v[100:103]
	v_mfma_f32_16x16x32_bf16 v[96:99], v[140:143], v[228:231], v[96:99]
	s_setprio 0
	s_barrier
	s_add_i32 s37, 0, 0x1c000
	s_add_i32 s27, s27, s76
	v_add_u32_e32 v161, s37, v192
	v_lshl_add_u64 v[176:177], v[176:177], 0, s[18:19]
	s_mov_b32 m0, s27
	ds_read_b128 v[232:235], v161
	ds_read_b128 v[236:239], v161 offset:1024
	ds_read_b128 v[240:243], v161 offset:2048
	ds_read_b128 v[244:247], v161 offset:3072
	global_load_lds_dwordx4 v[176:177], off
	v_lshl_add_u64 v[176:177], v[188:189], 0, s[18:19]
	s_add_i32 m0, s27, 0x2000
	s_nop 0
	global_load_lds_dwordx4 v[176:177], off
	s_barrier
	s_waitcnt lgkmcnt(0)
	s_setprio 1
	s_waitcnt lgkmcnt(0)
	v_mfma_f32_16x16x32_bf16 v[92:95], v[232:235], v[162:165], v[92:95]
	v_mfma_f32_16x16x32_bf16 v[88:91], v[240:243], v[162:165], v[88:91]
	v_mfma_f32_16x16x32_bf16 v[84:87], v[232:235], v[196:199], v[84:87]
	v_mfma_f32_16x16x32_bf16 v[80:83], v[240:243], v[196:199], v[80:83]
	v_mfma_f32_16x16x32_bf16 v[76:79], v[232:235], v[204:207], v[76:79]
	v_mfma_f32_16x16x32_bf16 v[72:75], v[240:243], v[204:207], v[72:75]
	v_mfma_f32_16x16x32_bf16 v[68:71], v[232:235], v[220:223], v[68:71]
	v_mfma_f32_16x16x32_bf16 v[64:67], v[240:243], v[220:223], v[64:67]
	v_mfma_f32_16x16x32_bf16 v[92:95], v[236:239], v[166:169], v[92:95]
	v_mfma_f32_16x16x32_bf16 v[88:91], v[244:247], v[166:169], v[88:91]
	v_mfma_f32_16x16x32_bf16 v[84:87], v[236:239], v[200:203], v[84:87]
	v_mfma_f32_16x16x32_bf16 v[80:83], v[244:247], v[200:203], v[80:83]
	v_mfma_f32_16x16x32_bf16 v[76:79], v[236:239], v[216:219], v[76:79]
	v_mfma_f32_16x16x32_bf16 v[72:75], v[244:247], v[216:219], v[72:75]
	v_mfma_f32_16x16x32_bf16 v[68:71], v[236:239], v[228:231], v[68:71]
	v_mfma_f32_16x16x32_bf16 v[64:67], v[244:247], v[228:231], v[64:67]
	s_setprio 0
	s_mov_b32 m0, s80
	v_lshl_add_u64 v[176:177], v[224:225], 0, s[18:19]
	s_barrier
	ds_read_b128 v[162:165], v194 offset:49152
	ds_read_b128 v[166:169], v194 offset:50176
	ds_read_b128 v[196:199], v194 offset:51200
	ds_read_b128 v[200:203], v194 offset:52224
	ds_read_b128 v[204:207], v194 offset:53248
	ds_read_b128 v[216:219], v194 offset:54272
	ds_read_b128 v[220:223], v194 offset:55296
	ds_read_b128 v[228:231], v194 offset:56320
	global_load_lds_dwordx4 v[176:177], off
	v_lshl_add_u64 v[176:177], v[248:249], 0, s[18:19]
	s_mov_b32 m0, s83
	s_nop 0
	global_load_lds_dwordx4 v[176:177], off
	s_barrier
	s_waitcnt lgkmcnt(0)
	s_setprio 1
	s_waitcnt lgkmcnt(0)
	v_mfma_f32_16x16x32_bf16 v[60:63], v[128:131], v[162:165], v[60:63]
	v_mfma_f32_16x16x32_bf16 v[56:59], v[136:139], v[162:165], v[56:59]
	v_mfma_f32_16x16x32_bf16 v[52:55], v[128:131], v[196:199], v[52:55]
	v_mfma_f32_16x16x32_bf16 v[48:51], v[136:139], v[196:199], v[48:51]
	v_mfma_f32_16x16x32_bf16 v[44:47], v[128:131], v[204:207], v[44:47]
	v_mfma_f32_16x16x32_bf16 v[40:43], v[136:139], v[204:207], v[40:43]
	v_mfma_f32_16x16x32_bf16 v[36:39], v[128:131], v[220:223], v[36:39]
	v_mfma_f32_16x16x32_bf16 v[32:35], v[136:139], v[220:223], v[32:35]
	v_mfma_f32_16x16x32_bf16 v[60:63], v[132:135], v[166:169], v[60:63]
	v_mfma_f32_16x16x32_bf16 v[56:59], v[140:143], v[166:169], v[56:59]
	v_mfma_f32_16x16x32_bf16 v[52:55], v[132:135], v[200:203], v[52:55]
	v_mfma_f32_16x16x32_bf16 v[48:51], v[140:143], v[200:203], v[48:51]
	v_mfma_f32_16x16x32_bf16 v[44:47], v[132:135], v[216:219], v[44:47]
	v_mfma_f32_16x16x32_bf16 v[40:43], v[140:143], v[216:219], v[40:43]
	v_mfma_f32_16x16x32_bf16 v[36:39], v[132:135], v[228:231], v[36:39]
	v_mfma_f32_16x16x32_bf16 v[32:35], v[140:143], v[228:231], v[32:35]
	s_setprio 0
	s_barrier
	s_add_u32 s50, s50, 0x40080
	s_addc_u32 s51, s51, 0
	s_add_i32 s27, s37, s76
	v_lshl_add_u64 v[128:129], s[50:51], 0, v[148:149]
	s_mov_b32 m0, s27
	s_nop 0
	global_load_lds_dwordx4 v[128:129], off
	v_lshl_add_u64 v[128:129], s[50:51], 0, v[152:153]
	s_add_i32 m0, s27, 0x2000
	s_nop 0
	global_load_lds_dwordx4 v[128:129], off
	s_waitcnt vmcnt(6)
	s_barrier
	s_setprio 1
	v_mfma_f32_16x16x32_bf16 v[28:31], v[232:235], v[162:165], v[28:31]
	v_mfma_f32_16x16x32_bf16 v[24:27], v[240:243], v[162:165], v[24:27]
	v_mfma_f32_16x16x32_bf16 v[20:23], v[232:235], v[196:199], v[20:23]
	v_mfma_f32_16x16x32_bf16 v[16:19], v[240:243], v[196:199], v[16:19]
	v_mfma_f32_16x16x32_bf16 v[12:15], v[232:235], v[204:207], v[12:15]
	v_mfma_f32_16x16x32_bf16 v[8:11], v[240:243], v[204:207], v[8:11]
	v_mfma_f32_16x16x32_bf16 v[4:7], v[232:235], v[220:223], v[4:7]
	v_mfma_f32_16x16x32_bf16 v[0:3], v[240:243], v[220:223], v[0:3]
	v_mfma_f32_16x16x32_bf16 v[28:31], v[236:239], v[166:169], v[28:31]
	v_mfma_f32_16x16x32_bf16 v[24:27], v[244:247], v[166:169], v[24:27]
	v_mfma_f32_16x16x32_bf16 v[20:23], v[236:239], v[200:203], v[20:23]
	v_mfma_f32_16x16x32_bf16 v[16:19], v[244:247], v[200:203], v[16:19]
	v_mfma_f32_16x16x32_bf16 v[12:15], v[236:239], v[216:219], v[12:15]
	v_mfma_f32_16x16x32_bf16 v[8:11], v[244:247], v[216:219], v[8:11]
	v_mfma_f32_16x16x32_bf16 v[4:7], v[236:239], v[228:231], v[4:7]
	v_mfma_f32_16x16x32_bf16 v[0:3], v[244:247], v[228:231], v[0:3]
	s_setprio 0
	s_add_i32 s36, s36, 2
	s_add_u32 s0, s0, 0x100
	s_addc_u32 s1, s1, 0
	s_add_u32 s34, s34, 0x100
	s_addc_u32 s35, s35, 0
	s_cmp_gt_u32 s36, 13
	s_barrier
	s_cbranch_scc0 .LBB0_351
	s_lshl_b32 s0, s11, 8
	s_or_b32 s50, s0, s79
	s_ashr_i32 s51, s50, 31
	v_lshl_add_u64 v[140:141], s[50:51], 3, v[154:155]
	global_load_dwordx4 v[128:131], v[140:141], off offset:48
	global_load_dwordx4 v[132:135], v[140:141], off offset:32
	global_load_dwordx4 v[136:139], v[140:141], off offset:16
	global_load_dwordx4 v[162:165], v[140:141], off
	s_mov_b32 s34, 0x35800000
	s_mov_b32 s0, 0x358637bd
	v_mov_b64_e32 v[168:169], s[0:1]
	s_mov_b32 s30, 0x45800000
	s_cmp_lt_u32 s10, 2
	s_waitcnt vmcnt(0)
	v_ffbh_u32_e32 v142, v165
	v_min_u32_e32 v161, 32, v142
	v_lshlrev_b64 v[142:143], v161, v[164:165]
	v_min_u32_e32 v142, 1, v142
	v_or_b32_e32 v142, v143, v142
	v_cvt_f32_u32_e32 v142, v142
	v_sub_u32_e32 v143, 32, v161
	v_ldexp_f32 v143, v142, v143
	v_ffbh_u32_e32 v142, v163
	v_min_u32_e32 v142, 32, v142
	v_lshlrev_b64 v[162:163], v142, v[162:163]
	v_min_u32_e32 v161, 1, v162
	v_or_b32_e32 v161, v163, v161
	v_cvt_f32_u32_e32 v161, v161
	v_sub_u32_e32 v142, 32, v142
	v_ldexp_f32 v142, v161, v142
	v_pk_mul_f32 v[142:143], v[142:143], s[34:35] op_sel_hi:[1,0]
	s_nop 0
	v_pk_fma_f32 v[142:143], v[142:143], s[2:3], v[168:169] op_sel_hi:[1,0,0]
	s_nop 0
	v_mul_f32_e32 v161, 0x4b800000, v142
	v_cmp_gt_f32_e64 s[0:1], s89, v142
	v_cmp_gt_f32_e32 vcc, s89, v143
	s_nop 0
	v_cndmask_b32_e64 v142, v142, v161, s[0:1]
	v_mul_f32_e32 v161, 0x4b800000, v143
	v_cndmask_b32_e32 v143, v143, v161, vcc
	v_rsq_f32_e32 v142, v142
	v_rsq_f32_e32 v143, v143
	s_nop 0
	v_pk_mul_f32 v[162:163], v[142:143], s[30:31] op_sel_hi:[1,0]
	s_nop 0
	v_cndmask_b32_e64 v166, v142, v162, s[0:1]
	v_ffbh_u32_e32 v142, v139
	v_min_u32_e32 v142, 32, v142
	v_lshlrev_b64 v[138:139], v142, v[138:139]
	v_min_u32_e32 v138, 1, v138
	v_or_b32_e32 v138, v139, v138
	v_cvt_f32_u32_e32 v138, v138
	v_sub_u32_e32 v139, 32, v142
	v_cndmask_b32_e32 v167, v143, v163, vcc
	v_pk_mul_f32 v[60:61], v[60:61], v[166:167]
	v_ldexp_f32 v139, v138, v139
	v_ffbh_u32_e32 v138, v137
	v_min_u32_e32 v138, 32, v138
	v_lshlrev_b64 v[136:137], v138, v[136:137]
	v_min_u32_e32 v136, 1, v136
	v_or_b32_e32 v136, v137, v136
	v_cvt_f32_u32_e32 v136, v136
	v_sub_u32_e32 v137, 32, v138
	v_pk_mul_f32 v[52:53], v[52:53], v[166:167]
	v_pk_mul_f32 v[44:45], v[44:45], v[166:167]
	v_ldexp_f32 v138, v136, v137
	v_pk_mul_f32 v[136:137], v[138:139], s[34:35] op_sel_hi:[1,0]
	v_pk_mul_f32 v[36:37], v[36:37], v[166:167]
	v_pk_fma_f32 v[136:137], v[136:137], s[2:3], v[168:169] op_sel_hi:[1,0,0]
	s_nop 0
	v_mul_f32_e32 v138, 0x4b800000, v136
	v_cmp_gt_f32_e64 s[0:1], s89, v136
	v_cmp_gt_f32_e32 vcc, s89, v137
	s_nop 0
	v_cndmask_b32_e64 v136, v136, v138, s[0:1]
	v_mul_f32_e32 v138, 0x4b800000, v137
	v_cndmask_b32_e32 v137, v137, v138, vcc
	v_rsq_f32_e32 v136, v136
	v_rsq_f32_e32 v137, v137
	s_nop 0
	v_pk_mul_f32 v[138:139], v[136:137], s[30:31] op_sel_hi:[1,0]
	s_nop 0
	v_cndmask_b32_e64 v162, v136, v138, s[0:1]
	v_ffbh_u32_e32 v136, v135
	v_min_u32_e32 v136, 32, v136
	v_lshlrev_b64 v[134:135], v136, v[134:135]
	v_min_u32_e32 v134, 1, v134
	v_or_b32_e32 v134, v135, v134
	v_cvt_f32_u32_e32 v134, v134
	v_sub_u32_e32 v135, 32, v136
	v_cndmask_b32_e32 v163, v137, v139, vcc
	v_ldexp_f32 v135, v134, v135
	v_ffbh_u32_e32 v134, v133
	v_min_u32_e32 v134, 32, v134
	v_lshlrev_b64 v[132:133], v134, v[132:133]
	v_min_u32_e32 v132, 1, v132
	v_or_b32_e32 v132, v133, v132
	v_cvt_f32_u32_e32 v132, v132
	v_sub_u32_e32 v133, 32, v134
	v_ldexp_f32 v134, v132, v133
	v_pk_mul_f32 v[132:133], v[134:135], s[34:35] op_sel_hi:[1,0]
	s_nop 0
	v_pk_fma_f32 v[132:133], v[132:133], s[2:3], v[168:169] op_sel_hi:[1,0,0]
	s_nop 0
	v_mul_f32_e32 v134, 0x4b800000, v132
	v_cmp_gt_f32_e64 s[0:1], s89, v132
	v_cmp_gt_f32_e32 vcc, s89, v133
	s_nop 0
	v_cndmask_b32_e64 v132, v132, v134, s[0:1]
	v_mul_f32_e32 v134, 0x4b800000, v133
	v_cndmask_b32_e32 v133, v133, v134, vcc
	v_rsq_f32_e32 v132, v132
	v_rsq_f32_e32 v133, v133
	s_nop 0
	v_pk_mul_f32 v[134:135], v[132:133], s[30:31] op_sel_hi:[1,0]
	s_nop 0
	v_cndmask_b32_e64 v188, v132, v134, s[0:1]
	v_ffbh_u32_e32 v132, v131
	v_min_u32_e32 v132, 32, v132
	v_lshlrev_b64 v[130:131], v132, v[130:131]
	v_min_u32_e32 v130, 1, v130
	v_or_b32_e32 v130, v131, v130
	v_cvt_f32_u32_e32 v130, v130
	v_sub_u32_e32 v131, 32, v132
	v_cndmask_b32_e32 v189, v133, v135, vcc
	v_pk_mul_f32 v[56:57], v[56:57], v[188:189]
	v_ldexp_f32 v131, v130, v131
	v_ffbh_u32_e32 v130, v129
	v_min_u32_e32 v130, 32, v130
	v_lshlrev_b64 v[128:129], v130, v[128:129]
	v_min_u32_e32 v128, 1, v128
	v_or_b32_e32 v128, v129, v128
	v_cvt_f32_u32_e32 v128, v128
	v_sub_u32_e32 v129, 32, v130
	v_pk_mul_f32 v[48:49], v[48:49], v[188:189]
	v_pk_mul_f32 v[40:41], v[40:41], v[188:189]
	v_ldexp_f32 v130, v128, v129
	v_pk_mul_f32 v[128:129], v[130:131], s[34:35] op_sel_hi:[1,0]
	v_pk_mul_f32 v[32:33], v[32:33], v[188:189]
	v_pk_fma_f32 v[128:129], v[128:129], s[2:3], v[168:169] op_sel_hi:[1,0,0]
	s_nop 0
	v_mul_f32_e32 v130, 0x4b800000, v128
	v_cmp_gt_f32_e64 s[0:1], s89, v128
	v_cmp_gt_f32_e32 vcc, s89, v129
	s_nop 0
	v_cndmask_b32_e64 v128, v128, v130, s[0:1]
	v_mul_f32_e32 v130, 0x4b800000, v129
	v_cndmask_b32_e32 v129, v129, v130, vcc
	v_rsq_f32_e32 v128, v128
	v_rsq_f32_e32 v129, v129
	s_nop 0
	v_pk_mul_f32 v[130:131], v[128:129], s[30:31] op_sel_hi:[1,0]
	s_nop 0
	v_cndmask_b32_e32 v165, v129, v131, vcc
	v_cndmask_b32_e64 v164, v128, v130, s[0:1]
	global_load_dwordx4 v[128:131], v[140:141], off offset:1072
	global_load_dwordx4 v[132:135], v[140:141], off offset:1056
	global_load_dwordx4 v[136:139], v[140:141], off offset:1040
	s_nop 0
	global_load_dwordx4 v[140:143], v[140:141], off offset:1024
	s_waitcnt vmcnt(0)
	v_ffbh_u32_e32 v161, v143
	v_min_u32_e32 v161, 32, v161
	v_lshlrev_b64 v[142:143], v161, v[142:143]
	v_min_u32_e32 v142, 1, v142
	v_or_b32_e32 v142, v143, v142
	v_cvt_f32_u32_e32 v142, v142
	v_sub_u32_e32 v143, 32, v161
	v_ldexp_f32 v143, v142, v143
	v_ffbh_u32_e32 v142, v141
	v_min_u32_e32 v142, 32, v142
	v_lshlrev_b64 v[140:141], v142, v[140:141]
	v_min_u32_e32 v140, 1, v140
	v_or_b32_e32 v140, v141, v140
	v_cvt_f32_u32_e32 v140, v140
	v_sub_u32_e32 v141, 32, v142
	v_ldexp_f32 v142, v140, v141
	v_pk_mul_f32 v[140:141], v[142:143], s[34:35] op_sel_hi:[1,0]
	s_nop 0
	v_pk_fma_f32 v[140:141], v[140:141], s[2:3], v[168:169] op_sel_hi:[1,0,0]
	s_nop 0
	v_mul_f32_e32 v142, 0x4b800000, v140
	v_cmp_gt_f32_e64 s[0:1], s89, v140
	v_cmp_gt_f32_e32 vcc, s89, v141
	s_nop 0
	v_cndmask_b32_e64 v140, v140, v142, s[0:1]
	v_mul_f32_e32 v142, 0x4b800000, v141
	v_cndmask_b32_e32 v141, v141, v142, vcc
	v_rsq_f32_e32 v140, v140
	v_rsq_f32_e32 v141, v141
	s_nop 0
	v_pk_mul_f32 v[142:143], v[140:141], s[30:31] op_sel_hi:[1,0]
	s_nop 0
	v_cndmask_b32_e64 v142, v140, v142, s[0:1]
	v_ffbh_u32_e32 v140, v139
	v_min_u32_e32 v140, 32, v140
	v_lshlrev_b64 v[138:139], v140, v[138:139]
	v_min_u32_e32 v138, 1, v138
	v_or_b32_e32 v138, v139, v138
	v_cvt_f32_u32_e32 v138, v138
	v_sub_u32_e32 v139, 32, v140
	v_cndmask_b32_e32 v143, v141, v143, vcc
	v_pk_mul_f32 v[140:141], v[124:125], v[166:167]
	v_ldexp_f32 v139, v138, v139
	v_ffbh_u32_e32 v138, v137
	v_min_u32_e32 v138, 32, v138
	v_lshlrev_b64 v[136:137], v138, v[136:137]
	v_min_u32_e32 v136, 1, v136
	v_or_b32_e32 v136, v137, v136
	v_cvt_f32_u32_e32 v136, v136
	v_sub_u32_e32 v137, 32, v138
	v_pk_mul_f32 v[28:29], v[28:29], v[142:143]
	v_pk_mul_f32 v[20:21], v[20:21], v[142:143]
	v_ldexp_f32 v138, v136, v137
	v_pk_mul_f32 v[136:137], v[138:139], s[34:35] op_sel_hi:[1,0]
	v_pk_mul_f32 v[12:13], v[12:13], v[142:143]
	v_pk_fma_f32 v[136:137], v[136:137], s[2:3], v[168:169] op_sel_hi:[1,0,0]
	v_pk_mul_f32 v[4:5], v[4:5], v[142:143]
	v_mul_f32_e32 v138, 0x4b800000, v136
	v_cmp_gt_f32_e64 s[0:1], s89, v136
	v_cmp_gt_f32_e32 vcc, s89, v137
	s_nop 0
	v_cndmask_b32_e64 v136, v136, v138, s[0:1]
	v_mul_f32_e32 v138, 0x4b800000, v137
	v_cndmask_b32_e32 v137, v137, v138, vcc
	v_rsq_f32_e32 v136, v136
	v_rsq_f32_e32 v137, v137
	s_nop 0
	v_pk_mul_f32 v[138:139], v[136:137], s[30:31] op_sel_hi:[1,0]
	s_nop 0
	v_cndmask_b32_e64 v136, v136, v138, s[0:1]
	v_ffbh_u32_e32 v138, v135
	v_min_u32_e32 v138, 32, v138
	v_lshlrev_b64 v[134:135], v138, v[134:135]
	v_min_u32_e32 v134, 1, v134
	v_or_b32_e32 v134, v135, v134
	v_cvt_f32_u32_e32 v134, v134
	v_sub_u32_e32 v135, 32, v138
	v_cndmask_b32_e32 v137, v137, v139, vcc
	v_pk_mul_f32 v[138:139], v[120:121], v[188:189]
	v_ldexp_f32 v135, v134, v135
	v_ffbh_u32_e32 v134, v133
	v_min_u32_e32 v134, 32, v134
	v_lshlrev_b64 v[132:133], v134, v[132:133]
	v_min_u32_e32 v132, 1, v132
	v_or_b32_e32 v132, v133, v132
	v_cvt_f32_u32_e32 v132, v132
	v_sub_u32_e32 v133, 32, v134
	v_pk_mul_f32 v[120:121], v[84:85], v[142:143]
	v_ldexp_f32 v134, v132, v133
	v_pk_mul_f32 v[132:133], v[134:135], s[34:35] op_sel_hi:[1,0]
	s_nop 0
	v_pk_fma_f32 v[132:133], v[132:133], s[2:3], v[168:169] op_sel_hi:[1,0,0]
	s_nop 0
	v_mul_f32_e32 v134, 0x4b800000, v132
	v_cmp_gt_f32_e64 s[0:1], s89, v132
	v_cmp_gt_f32_e32 vcc, s89, v133
	s_nop 0
	v_cndmask_b32_e64 v132, v132, v134, s[0:1]
	v_mul_f32_e32 v134, 0x4b800000, v133
	v_cndmask_b32_e32 v133, v133, v134, vcc
	v_rsq_f32_e32 v132, v132
	v_rsq_f32_e32 v133, v133
	s_nop 0
	v_pk_mul_f32 v[134:135], v[132:133], s[30:31] op_sel_hi:[1,0]
	s_nop 0
	v_cndmask_b32_e64 v176, v132, v134, s[0:1]
	v_ffbh_u32_e32 v132, v131
	v_min_u32_e32 v132, 32, v132
	v_lshlrev_b64 v[130:131], v132, v[130:131]
	v_min_u32_e32 v130, 1, v130
	v_or_b32_e32 v130, v131, v130
	v_cvt_f32_u32_e32 v130, v130
	v_sub_u32_e32 v131, 32, v132
	v_cndmask_b32_e32 v177, v133, v135, vcc
	v_pk_mul_f32 v[124:125], v[88:89], v[176:177]
	v_ldexp_f32 v131, v130, v131
	v_ffbh_u32_e32 v130, v129
	v_min_u32_e32 v130, 32, v130
	v_lshlrev_b64 v[128:129], v130, v[128:129]
	v_min_u32_e32 v128, 1, v128
	v_or_b32_e32 v128, v129, v128
	v_cvt_f32_u32_e32 v128, v128
	v_sub_u32_e32 v129, 32, v130
	v_pk_mul_f32 v[134:135], v[116:117], v[166:167]
	v_pk_mul_f32 v[132:133], v[112:113], v[188:189]
	v_ldexp_f32 v130, v128, v129
	v_pk_mul_f32 v[128:129], v[130:131], s[34:35] op_sel_hi:[1,0]
	v_pk_mul_f32 v[116:117], v[80:81], v[176:177]
	v_pk_fma_f32 v[128:129], v[128:129], s[2:3], v[168:169] op_sel_hi:[1,0,0]
	v_pk_mul_f32 v[88:89], v[104:105], v[188:189]
	v_mul_f32_e32 v130, 0x4b800000, v128
	v_cmp_gt_f32_e64 s[0:1], s89, v128
	v_cmp_gt_f32_e32 vcc, s89, v129
	v_pk_mul_f32 v[112:113], v[76:77], v[142:143]
	v_cndmask_b32_e64 v128, v128, v130, s[0:1]
	v_mul_f32_e32 v130, 0x4b800000, v129
	v_cndmask_b32_e32 v129, v129, v130, vcc
	v_rsq_f32_e32 v128, v128
	v_rsq_f32_e32 v129, v129
	v_pk_mul_f32 v[76:77], v[100:101], v[166:167]
	v_pk_mul_f32 v[104:105], v[68:69], v[142:143]
	v_pk_mul_f32 v[24:25], v[24:25], v[176:177]
	v_pk_mul_f32 v[130:131], v[128:129], s[30:31] op_sel_hi:[1,0]
	v_pk_mul_f32 v[16:17], v[16:17], v[176:177]
	v_cndmask_b32_e32 v129, v129, v131, vcc
	v_cndmask_b32_e64 v128, v128, v130, s[0:1]
	s_mov_b64 s[0:1], -1
	v_pk_mul_f32 v[130:131], v[92:93], v[142:143]
	v_pk_mul_f32 v[92:93], v[108:109], v[166:167]
	v_pk_mul_f32 v[108:109], v[72:73], v[176:177]
	v_pk_mul_f32 v[72:73], v[96:97], v[188:189]
	v_pk_mul_f32 v[96:97], v[64:65], v[176:177]
	v_pk_mul_f32 v[8:9], v[8:9], v[176:177]
	v_pk_mul_f32 v[0:1], v[0:1], v[176:177]
	s_cbranch_scc1 .LBB0_354
	v_lshl_add_u32 v68, s10, 8, v193
	v_ashrrev_i32_e32 v69, 31, v68
	v_pk_mul_f32 v[64:65], v[126:127], v[162:163]
	v_cvt_pk_bf16_f32 v80, v140, v141
	s_lshl_b64 s[0:1], s[50:51], 1
	v_cvt_pk_bf16_f32 v81, v64, v65
	v_lshlrev_b64 v[64:65], 13, v[68:69]
	v_lshl_add_u64 v[64:65], s[44:45], 0, v[64:65]
	v_lshl_add_u64 v[64:65], v[64:65], 0, s[0:1]
	v_lshl_add_u64 v[64:65], v[64:65], 0, v[144:145]
	v_mov_b32_e32 v161, v145
	v_lshl_add_u64 v[64:65], v[64:65], 0, v[160:161]
	global_store_dwordx2 v[64:65], v[80:81], off
	v_pk_mul_f32 v[80:81], v[122:123], v[164:165]
	v_cvt_pk_bf16_f32 v84, v138, v139
	s_nop 0
	v_cvt_pk_bf16_f32 v85, v80, v81
	v_pk_mul_f32 v[80:81], v[94:95], v[136:137]
	global_store_dwordx2 v[64:65], v[84:85], off offset:16
	v_cvt_pk_bf16_f32 v84, v130, v131
	v_cvt_pk_bf16_f32 v85, v80, v81
	v_pk_mul_f32 v[80:81], v[90:91], v[128:129]
	global_store_dwordx2 v[64:65], v[84:85], off offset:256
	v_cvt_pk_bf16_f32 v84, v124, v125
	v_cvt_pk_bf16_f32 v85, v80, v81
	v_or_b32_e32 v80, 16, v68
	v_ashrrev_i32_e32 v81, 31, v80
	v_lshlrev_b64 v[80:81], 13, v[80:81]
	v_lshl_add_u64 v[80:81], s[44:45], 0, v[80:81]
	v_lshl_add_u64 v[80:81], v[80:81], 0, s[0:1]
	v_lshl_add_u64 v[80:81], v[80:81], 0, v[144:145]
	global_store_dwordx2 v[64:65], v[84:85], off offset:272
	v_pk_mul_f32 v[84:85], v[118:119], v[162:163]
	v_cvt_pk_bf16_f32 v100, v134, v135
	v_lshl_add_u64 v[80:81], v[80:81], 0, v[160:161]
	v_cvt_pk_bf16_f32 v101, v84, v85
	global_store_dwordx2 v[80:81], v[100:101], off
	v_pk_mul_f32 v[84:85], v[114:115], v[164:165]
	v_cvt_pk_bf16_f32 v100, v132, v133
	s_nop 0
	v_cvt_pk_bf16_f32 v101, v84, v85
	global_store_dwordx2 v[80:81], v[100:101], off offset:16
	v_pk_mul_f32 v[84:85], v[86:87], v[136:137]
	v_cvt_pk_bf16_f32 v100, v120, v121
	s_nop 0
	v_cvt_pk_bf16_f32 v101, v84, v85
	global_store_dwordx2 v[80:81], v[100:101], off offset:256
	v_pk_mul_f32 v[84:85], v[82:83], v[128:129]
	v_cvt_pk_bf16_f32 v100, v116, v117
	s_nop 0
	v_cvt_pk_bf16_f32 v101, v84, v85
	global_store_dwordx2 v[80:81], v[100:101], off offset:272
	v_or_b32_e32 v80, 32, v68
	v_ashrrev_i32_e32 v81, 31, v80
	v_lshlrev_b64 v[80:81], 13, v[80:81]
	v_lshl_add_u64 v[80:81], s[44:45], 0, v[80:81]
	v_or_b32_e32 v68, 48, v68
	v_lshl_add_u64 v[80:81], v[80:81], 0, s[0:1]
	v_ashrrev_i32_e32 v69, 31, v68
	v_pk_mul_f32 v[84:85], v[110:111], v[162:163]
	v_lshl_add_u64 v[80:81], v[80:81], 0, v[144:145]
	v_lshlrev_b64 v[68:69], 13, v[68:69]
	v_cvt_pk_bf16_f32 v100, v92, v93
	v_cvt_pk_bf16_f32 v101, v84, v85
	v_lshl_add_u64 v[80:81], v[80:81], 0, v[160:161]
	v_pk_mul_f32 v[84:85], v[106:107], v[164:165]
	v_lshl_add_u64 v[68:69], s[44:45], 0, v[68:69]
	global_store_dwordx2 v[80:81], v[100:101], off
	v_cvt_pk_bf16_f32 v100, v88, v89
	v_cvt_pk_bf16_f32 v101, v84, v85
	v_pk_mul_f32 v[84:85], v[78:79], v[136:137]
	v_lshl_add_u64 v[68:69], v[68:69], 0, s[0:1]
	global_store_dwordx2 v[80:81], v[100:101], off offset:16
	v_cvt_pk_bf16_f32 v100, v112, v113
	v_cvt_pk_bf16_f32 v101, v84, v85
	v_pk_mul_f32 v[84:85], v[74:75], v[128:129]
	v_lshl_add_u64 v[68:69], v[68:69], 0, v[144:145]
	global_store_dwordx2 v[80:81], v[100:101], off offset:256
	v_cvt_pk_bf16_f32 v100, v108, v109
	v_cvt_pk_bf16_f32 v101, v84, v85
	global_store_dwordx2 v[80:81], v[100:101], off offset:272
	v_cvt_pk_bf16_f32 v84, v76, v77
	v_lshl_add_u64 v[68:69], v[68:69], 0, v[160:161]
	v_pk_mul_f32 v[80:81], v[102:103], v[162:163]
	s_mov_b64 s[0:1], 0x100000
	v_cvt_pk_bf16_f32 v85, v80, v81
	global_store_dwordx2 v[68:69], v[84:85], off
	v_cvt_pk_bf16_f32 v84, v72, v73
	v_pk_mul_f32 v[80:81], v[98:99], v[164:165]
	s_nop 0
	v_cvt_pk_bf16_f32 v85, v80, v81
	global_store_dwordx2 v[68:69], v[84:85], off offset:16
	v_cvt_pk_bf16_f32 v84, v104, v105
	v_pk_mul_f32 v[80:81], v[70:71], v[136:137]
	s_nop 0
	v_cvt_pk_bf16_f32 v85, v80, v81
	global_store_dwordx2 v[68:69], v[84:85], off offset:256
	v_cvt_pk_bf16_f32 v84, v96, v97
	v_pk_mul_f32 v[80:81], v[66:67], v[128:129]
	s_nop 0
	v_cvt_pk_bf16_f32 v85, v80, v81
	global_store_dwordx2 v[68:69], v[84:85], off offset:272
	v_add_co_u32_e32 v84, vcc, s29, v64
	v_pk_mul_f32 v[68:69], v[62:63], v[162:163]
	s_nop 0
	v_addc_co_u32_e32 v85, vcc, 0, v65, vcc
	v_cvt_pk_bf16_f32 v80, v60, v61
	v_cvt_pk_bf16_f32 v81, v68, v69
	v_lshl_add_u64 v[68:69], v[64:65], 0, s[0:1]
	global_store_dwordx2 v[84:85], v[80:81], off
	v_cvt_pk_bf16_f32 v84, v56, v57
	v_pk_mul_f32 v[80:81], v[58:59], v[164:165]
	s_mov_b64 s[0:1], 0x120000
	v_cvt_pk_bf16_f32 v85, v80, v81
	global_store_dwordx2 v[68:69], v[84:85], off offset:16
	v_cvt_pk_bf16_f32 v84, v28, v29
	v_pk_mul_f32 v[80:81], v[30:31], v[136:137]
	s_nop 0
	v_cvt_pk_bf16_f32 v85, v80, v81
	global_store_dwordx2 v[68:69], v[84:85], off offset:256
	v_cvt_pk_bf16_f32 v84, v24, v25
	v_pk_mul_f32 v[80:81], v[26:27], v[128:129]
	s_nop 0
	v_cvt_pk_bf16_f32 v85, v80, v81
	global_store_dwordx2 v[68:69], v[84:85], off offset:272
	v_add_co_u32_e32 v84, vcc, s49, v64
	v_pk_mul_f32 v[68:69], v[54:55], v[162:163]
	v_cvt_pk_bf16_f32 v80, v52, v53
	s_nop 0
	v_addc_co_u32_e32 v85, vcc, 0, v65, vcc
	v_cvt_pk_bf16_f32 v81, v68, v69
	v_lshl_add_u64 v[68:69], v[64:65], 0, s[0:1]
	global_store_dwordx2 v[84:85], v[80:81], off
	v_pk_mul_f32 v[80:81], v[50:51], v[164:165]
	v_cvt_pk_bf16_f32 v84, v48, v49
	s_mov_b64 s[0:1], 0x140000
	v_cvt_pk_bf16_f32 v85, v80, v81
	global_store_dwordx2 v[68:69], v[84:85], off offset:16
	v_pk_mul_f32 v[80:81], v[22:23], v[136:137]
	v_cvt_pk_bf16_f32 v84, v20, v21
	s_nop 0
	v_cvt_pk_bf16_f32 v85, v80, v81
	global_store_dwordx2 v[68:69], v[84:85], off offset:256
	v_pk_mul_f32 v[80:81], v[18:19], v[128:129]
	v_cvt_pk_bf16_f32 v84, v16, v17
	s_nop 0
	v_cvt_pk_bf16_f32 v85, v80, v81
	global_store_dwordx2 v[68:69], v[84:85], off offset:272
	v_pk_mul_f32 v[68:69], v[46:47], v[162:163]
	v_cvt_pk_bf16_f32 v80, v44, v45
	s_nop 0
	v_cvt_pk_bf16_f32 v81, v68, v69
	v_lshl_add_u64 v[68:69], v[64:65], 0, s[0:1]
	s_mov_b32 s0, 0x140000
	v_add_co_u32_e32 v84, vcc, s0, v64
	s_mov_b64 s[0:1], 0x160000
	s_nop 0
	v_addc_co_u32_e32 v85, vcc, 0, v65, vcc
	global_store_dwordx2 v[84:85], v[80:81], off
	v_pk_mul_f32 v[80:81], v[42:43], v[164:165]
	v_cvt_pk_bf16_f32 v84, v40, v41
	s_nop 0
	v_cvt_pk_bf16_f32 v85, v80, v81
	global_store_dwordx2 v[68:69], v[84:85], off offset:16
	v_pk_mul_f32 v[80:81], v[14:15], v[136:137]
	v_cvt_pk_bf16_f32 v84, v12, v13
	s_nop 0
	v_cvt_pk_bf16_f32 v85, v80, v81
	global_store_dwordx2 v[68:69], v[84:85], off offset:256
	v_pk_mul_f32 v[80:81], v[10:11], v[128:129]
	v_cvt_pk_bf16_f32 v84, v8, v9
	s_nop 0
	v_cvt_pk_bf16_f32 v85, v80, v81
	global_store_dwordx2 v[68:69], v[84:85], off offset:272
	v_pk_mul_f32 v[68:69], v[38:39], v[162:163]
	v_cvt_pk_bf16_f32 v80, v36, v37
	s_nop 0
	v_cvt_pk_bf16_f32 v81, v68, v69
	v_lshl_add_u64 v[68:69], v[64:65], 0, s[0:1]
	s_mov_b32 s0, 0x160000
	v_add_co_u32_e32 v64, vcc, s0, v64
	s_mov_b64 s[0:1], 0
	s_nop 0
	v_addc_co_u32_e32 v65, vcc, 0, v65, vcc
	global_store_dwordx2 v[64:65], v[80:81], off
	v_pk_mul_f32 v[64:65], v[34:35], v[164:165]
	v_cvt_pk_bf16_f32 v80, v32, v33
	s_nop 0
	v_cvt_pk_bf16_f32 v81, v64, v65
	global_store_dwordx2 v[68:69], v[80:81], off offset:16
	v_pk_mul_f32 v[64:65], v[6:7], v[136:137]
	v_cvt_pk_bf16_f32 v80, v4, v5
	s_nop 0
	v_cvt_pk_bf16_f32 v81, v64, v65
	global_store_dwordx2 v[68:69], v[80:81], off offset:256
	v_pk_mul_f32 v[64:65], v[2:3], v[128:129]
	v_cvt_pk_bf16_f32 v80, v0, v1
	s_nop 0
	v_cvt_pk_bf16_f32 v81, v64, v65
	s_nop 1
	global_store_dwordx2 v[68:69], v[80:81], off offset:272
.LBB0_354:
	s_andn2_b64 vcc, exec, s[0:1]
	s_cbranch_vccnz .LBB0_343
	v_fma_f32 v64, |v140|, s26, 1.0
	v_pk_mul_f32 v[100:101], v[122:123], v[164:165]
	v_rcp_f32_e32 v122, v64
	v_mul_f32_e32 v64, v140, v140
	v_mul_f32_e32 v64, 0xbf38aa3b, v64
	v_pk_mul_f32 v[68:69], v[126:127], v[162:163]
	v_exp_f32_e32 v126, v64
	v_fma_f32 v64, |v141|, s26, 1.0
	v_rcp_f32_e32 v123, v64
	v_mul_f32_e32 v64, v141, v141
	v_mul_f32_e32 v64, 0xbf38aa3b, v64
	s_mov_b32 s0, 0xbf3a00e3
	v_exp_f32_e32 v127, v64
	v_mov_b64_e32 v[64:65], s[0:1]
	v_pk_fma_f32 v[142:143], v[122:123], s[24:25], v[64:65] op_sel_hi:[1,0,0]
	v_cmp_gt_f32_e32 vcc, 0, v140
	v_pk_fma_f32 v[142:143], v[122:123], v[142:143], s[6:7] op_sel_hi:[1,1,0]
	v_fma_f32 v85, |v68|, s26, 1.0
	v_pk_fma_f32 v[142:143], v[122:123], v[142:143], s[88:89] op_sel_hi:[1,1,0]
	v_lshl_add_u32 v84, s10, 8, v190
	v_pk_fma_f32 v[142:143], v[122:123], v[142:143], s[90:91] op_sel_hi:[1,1,0]
	v_or_b32_e32 v80, s50, v191
	v_pk_mul_f32 v[122:123], v[122:123], v[142:143]
	v_ashrrev_i32_e32 v81, 31, v80
	v_pk_mul_f32 v[122:123], v[126:127], v[122:123]
	v_pk_mul_f32 v[118:119], v[118:119], v[162:163]
	v_pk_mul_f32 v[126:127], v[140:141], v[122:123]
	v_pk_fma_f32 v[122:123], v[140:141], v[122:123], v[140:141] neg_lo:[1,0,0] neg_hi:[1,0,0]
	v_pk_mul_f32 v[114:115], v[114:115], v[164:165]
	v_cndmask_b32_e32 v126, v122, v126, vcc
	v_rcp_f32_e32 v122, v85
	v_mul_f32_e32 v85, v68, v68
	v_mul_f32_e32 v85, 0xbf38aa3b, v85
	v_cmp_gt_f32_e32 vcc, 0, v141
	v_exp_f32_e32 v140, v85
	v_fma_f32 v85, |v69|, s26, 1.0
	v_cndmask_b32_e32 v127, v123, v127, vcc
	v_rcp_f32_e32 v123, v85
	v_mul_f32_e32 v85, v69, v69
	v_mul_f32_e32 v85, 0xbf38aa3b, v85
	v_exp_f32_e32 v141, v85
	v_pk_fma_f32 v[142:143], v[122:123], s[24:25], v[64:65] op_sel_hi:[1,0,0]
	v_cmp_gt_f32_e32 vcc, 0, v68
	v_pk_fma_f32 v[142:143], v[122:123], v[142:143], s[6:7] op_sel_hi:[1,1,0]
	v_mul_f32_e32 v85, v139, v139
	v_pk_fma_f32 v[142:143], v[122:123], v[142:143], s[88:89] op_sel_hi:[1,1,0]
	v_mul_f32_e32 v85, 0xbf38aa3b, v85
	v_pk_fma_f32 v[142:143], v[122:123], v[142:143], s[90:91] op_sel_hi:[1,1,0]
	v_pk_mul_f32 v[110:111], v[110:111], v[162:163]
	v_pk_mul_f32 v[122:123], v[122:123], v[142:143]
	v_pk_mul_f32 v[106:107], v[106:107], v[164:165]
	v_pk_mul_f32 v[122:123], v[140:141], v[122:123]
	v_pk_mul_f32 v[98:99], v[98:99], v[164:165]
	v_pk_mul_f32 v[140:141], v[68:69], v[122:123]
	v_pk_fma_f32 v[122:123], v[68:69], v[122:123], v[68:69] neg_lo:[1,0,0] neg_hi:[1,0,0]
	v_fma_f32 v68, |v138|, s26, 1.0
	v_cndmask_b32_e32 v142, v122, v140, vcc
	v_cmp_gt_f32_e32 vcc, 0, v69
	v_mul_f32_e32 v69, v138, v138
	v_mul_f32_e32 v69, 0xbf38aa3b, v69
	v_exp_f32_e32 v122, v69
	v_fma_f32 v69, |v139|, s26, 1.0
	v_rcp_f32_e32 v68, v68
	v_rcp_f32_e32 v69, v69
	v_cndmask_b32_e32 v143, v123, v141, vcc
	v_exp_f32_e32 v123, v85
	v_cmp_gt_f32_e32 vcc, 0, v138
	v_pk_fma_f32 v[140:141], v[68:69], s[24:25], v[64:65] op_sel_hi:[1,0,0]
	v_mul_f32_e32 v85, v101, v101
	v_pk_fma_f32 v[140:141], v[68:69], v[140:141], s[6:7] op_sel_hi:[1,1,0]
	v_mul_f32_e32 v85, 0xbf38aa3b, v85
	v_pk_fma_f32 v[140:141], v[68:69], v[140:141], s[88:89] op_sel_hi:[1,1,0]
	s_lshl_b32 s98, s10, 1
	v_pk_fma_f32 v[140:141], v[68:69], v[140:141], s[90:91] op_sel_hi:[1,1,0]
	s_nop 0
	v_pk_mul_f32 v[68:69], v[68:69], v[140:141]
	s_nop 0
	v_pk_mul_f32 v[68:69], v[122:123], v[68:69]
	s_nop 0
	v_pk_mul_f32 v[122:123], v[138:139], v[68:69]
	v_pk_fma_f32 v[68:69], v[138:139], v[68:69], v[138:139] neg_lo:[1,0,0] neg_hi:[1,0,0]
	s_nop 0
	v_cndmask_b32_e32 v166, v68, v122, vcc
	v_cmp_gt_f32_e32 vcc, 0, v139
	v_fma_f32 v68, |v100|, s26, 1.0
	v_rcp_f32_e32 v68, v68
	v_cndmask_b32_e32 v167, v69, v123, vcc
	v_mul_f32_e32 v69, v100, v100
	v_mul_f32_e32 v69, 0xbf38aa3b, v69
	v_exp_f32_e32 v122, v69
	v_fma_f32 v69, |v101|, s26, 1.0
	v_rcp_f32_e32 v69, v69
	v_exp_f32_e32 v123, v85
	v_cmp_gt_f32_e32 vcc, 0, v100
	v_ashrrev_i32_e32 v85, 31, v84
	v_pk_fma_f32 v[138:139], v[68:69], s[24:25], v[64:65] op_sel_hi:[1,0,0]
	s_nop 0
	v_pk_fma_f32 v[138:139], v[68:69], v[138:139], s[6:7] op_sel_hi:[1,1,0]
	s_nop 0
	v_pk_fma_f32 v[138:139], v[68:69], v[138:139], s[88:89] op_sel_hi:[1,1,0]
	s_nop 0
	v_pk_fma_f32 v[138:139], v[68:69], v[138:139], s[90:91] op_sel_hi:[1,1,0]
	s_nop 0
	v_pk_mul_f32 v[68:69], v[68:69], v[138:139]
	v_cvt_pk_bf16_f32 v138, v126, v127
	v_cvt_pk_bf16_f32 v139, v142, v143
	v_cvt_pk_bf16_f32 v140, v166, v167
	s_nop 0
	v_pk_mul_f32 v[68:69], v[122:123], v[68:69]
	s_nop 0
	v_pk_mul_f32 v[122:123], v[100:101], v[68:69]
	v_pk_fma_f32 v[68:69], v[100:101], v[68:69], v[100:101] neg_lo:[1,0,0] neg_hi:[1,0,0]
	s_nop 0
	v_cndmask_b32_e32 v100, v68, v122, vcc
	v_cmp_gt_f32_e32 vcc, 0, v101
	s_nop 1
	v_cndmask_b32_e32 v101, v69, v123, vcc
	v_lshlrev_b64 v[68:69], 13, v[84:85]
	v_lshl_add_u64 v[122:123], s[42:43], 0, v[68:69]
	v_lshlrev_b64 v[68:69], 1, v[80:81]
	v_lshl_add_u64 v[122:123], v[122:123], 0, v[68:69]
	v_cvt_pk_bf16_f32 v141, v100, v101
	global_store_dwordx4 v[122:123], v[138:141], off
	v_cmp_gt_f32_e32 vcc, 0, v134
	s_nop 0
	v_fma_f32 v139, |v134|, s26, 1.0
	v_rcp_f32_e32 v140, v139
	v_mul_f32_e32 v139, v134, v134
	v_mul_f32_e32 v139, 0xbf38aa3b, v139
	v_exp_f32_e32 v168, v139
	v_fma_f32 v139, |v135|, s26, 1.0
	v_rcp_f32_e32 v141, v139
	v_mul_f32_e32 v139, v135, v135
	v_mul_f32_e32 v139, 0xbf38aa3b, v139
	v_exp_f32_e32 v169, v139
	v_pk_fma_f32 v[176:177], v[140:141], s[24:25], v[64:65] op_sel_hi:[1,0,0]
	v_mul_f32_e32 v139, v119, v119
	v_pk_fma_f32 v[176:177], v[140:141], v[176:177], s[6:7] op_sel_hi:[1,1,0]
	v_mul_f32_e32 v139, 0xbf38aa3b, v139
	v_pk_fma_f32 v[176:177], v[140:141], v[176:177], s[88:89] op_sel_hi:[1,1,0]
	v_or_b32_e32 v138, 16, v84
	v_pk_fma_f32 v[176:177], v[140:141], v[176:177], s[90:91] op_sel_hi:[1,1,0]
	s_nop 0
	v_pk_mul_f32 v[140:141], v[140:141], v[176:177]
	s_nop 0
	v_pk_mul_f32 v[140:141], v[168:169], v[140:141]
	s_nop 0
	v_pk_mul_f32 v[168:169], v[134:135], v[140:141]
	v_pk_fma_f32 v[140:141], v[134:135], v[140:141], v[134:135] neg_lo:[1,0,0] neg_hi:[1,0,0]
	v_fma_f32 v134, |v118|, s26, 1.0
	v_cndmask_b32_e32 v140, v140, v168, vcc
	v_cmp_gt_f32_e32 vcc, 0, v135
	v_mul_f32_e32 v135, v118, v118
	v_mul_f32_e32 v135, 0xbf38aa3b, v135
	v_exp_f32_e32 v168, v135
	v_fma_f32 v135, |v119|, s26, 1.0
	v_rcp_f32_e32 v134, v134
	v_rcp_f32_e32 v135, v135
	v_cndmask_b32_e32 v141, v141, v169, vcc
	v_exp_f32_e32 v169, v139
	v_cmp_gt_f32_e32 vcc, 0, v118
	v_pk_fma_f32 v[176:177], v[134:135], s[24:25], v[64:65] op_sel_hi:[1,0,0]
	v_mul_f32_e32 v139, v133, v133
	v_pk_fma_f32 v[176:177], v[134:135], v[176:177], s[6:7] op_sel_hi:[1,1,0]
	v_mul_f32_e32 v139, 0xbf38aa3b, v139
	v_pk_fma_f32 v[176:177], v[134:135], v[176:177], s[88:89] op_sel_hi:[1,1,0]
	s_nop 0
	v_pk_fma_f32 v[176:177], v[134:135], v[176:177], s[90:91] op_sel_hi:[1,1,0]
	s_nop 0
	v_pk_mul_f32 v[134:135], v[134:135], v[176:177]
	s_nop 0
	v_pk_mul_f32 v[134:135], v[168:169], v[134:135]
	s_nop 0
	v_pk_mul_f32 v[168:169], v[118:119], v[134:135]
	v_pk_fma_f32 v[134:135], v[118:119], v[134:135], v[118:119] neg_lo:[1,0,0] neg_hi:[1,0,0]
	s_nop 0
	v_cndmask_b32_e32 v118, v134, v168, vcc
	v_cmp_gt_f32_e32 vcc, 0, v119
	v_fma_f32 v134, |v132|, s26, 1.0
	v_rcp_f32_e32 v134, v134
	v_cndmask_b32_e32 v119, v135, v169, vcc
	v_mul_f32_e32 v135, v132, v132
	v_mul_f32_e32 v135, 0xbf38aa3b, v135
	v_exp_f32_e32 v168, v135
	v_fma_f32 v135, |v133|, s26, 1.0
	v_rcp_f32_e32 v135, v135
	v_exp_f32_e32 v169, v139
	v_cmp_gt_f32_e32 vcc, 0, v132
	v_ashrrev_i32_e32 v139, 31, v138
	v_pk_fma_f32 v[176:177], v[134:135], s[24:25], v[64:65] op_sel_hi:[1,0,0]
	s_nop 0
	v_pk_fma_f32 v[176:177], v[134:135], v[176:177], s[6:7] op_sel_hi:[1,1,0]
	s_nop 0
	v_pk_fma_f32 v[176:177], v[134:135], v[176:177], s[88:89] op_sel_hi:[1,1,0]
	s_nop 0
	v_pk_fma_f32 v[176:177], v[134:135], v[176:177], s[90:91] op_sel_hi:[1,1,0]
	s_nop 0
	v_pk_mul_f32 v[134:135], v[134:135], v[176:177]
	s_nop 0
	v_pk_mul_f32 v[134:135], v[168:169], v[134:135]
	s_nop 0
	v_pk_mul_f32 v[168:169], v[132:133], v[134:135]
	v_pk_fma_f32 v[134:135], v[132:133], v[134:135], v[132:133] neg_lo:[1,0,0] neg_hi:[1,0,0]
	v_fma_f32 v132, |v114|, s26, 1.0
	v_cndmask_b32_e32 v168, v134, v168, vcc
	v_cmp_gt_f32_e32 vcc, 0, v133
	v_mul_f32_e32 v133, v114, v114
	v_mul_f32_e32 v133, 0xbf38aa3b, v133
	v_exp_f32_e32 v134, v133
	v_fma_f32 v133, |v115|, s26, 1.0
	v_rcp_f32_e32 v132, v132
	v_rcp_f32_e32 v133, v133
	v_cndmask_b32_e32 v169, v135, v169, vcc
	v_mul_f32_e32 v135, v115, v115
	v_mul_f32_e32 v135, 0xbf38aa3b, v135
	v_pk_fma_f32 v[176:177], v[132:133], s[24:25], v[64:65] op_sel_hi:[1,0,0]
	v_exp_f32_e32 v135, v135
	v_pk_fma_f32 v[176:177], v[132:133], v[176:177], s[6:7] op_sel_hi:[1,1,0]
	v_cmp_gt_f32_e32 vcc, 0, v114
	v_pk_fma_f32 v[176:177], v[132:133], v[176:177], s[88:89] op_sel_hi:[1,1,0]
	s_nop 0
	v_pk_fma_f32 v[176:177], v[132:133], v[176:177], s[90:91] op_sel_hi:[1,1,0]
	s_nop 0
	v_pk_mul_f32 v[132:133], v[132:133], v[176:177]
	s_nop 0
	v_pk_mul_f32 v[132:133], v[134:135], v[132:133]
	s_nop 0
	v_pk_mul_f32 v[134:135], v[114:115], v[132:133]
	v_pk_fma_f32 v[132:133], v[114:115], v[132:133], v[114:115] neg_lo:[1,0,0] neg_hi:[1,0,0]
	s_nop 0
	v_cndmask_b32_e32 v176, v132, v134, vcc
	v_cmp_gt_f32_e32 vcc, 0, v115
	v_lshlrev_b64 v[114:115], 13, v[138:139]
	v_lshl_add_u64 v[114:115], s[42:43], 0, v[114:115]
	v_cndmask_b32_e32 v177, v133, v135, vcc
	v_cvt_pk_bf16_f32 v132, v140, v141
	v_cvt_pk_bf16_f32 v133, v118, v119
	v_lshl_add_u64 v[114:115], v[114:115], 0, v[68:69]
	v_cvt_pk_bf16_f32 v134, v168, v169
	v_cvt_pk_bf16_f32 v135, v176, v177
	global_store_dwordx4 v[114:115], v[132:135], off
	v_pk_mul_f32 v[118:119], v[118:119], v[118:119]
	v_cmp_gt_f32_e32 vcc, 0, v92
	v_pk_mul_f32 v[132:133], v[140:141], v[140:141]
	v_pk_mul_f32 v[134:135], v[168:169], v[168:169]
	v_pk_fma_f32 v[126:127], v[126:127], v[126:127], v[132:133]
	v_pk_mul_f32 v[132:133], v[176:177], v[176:177]
	v_pk_fma_f32 v[138:139], v[166:167], v[166:167], v[134:135]
	v_pk_fma_f32 v[100:101], v[100:101], v[100:101], v[132:133]
	v_mul_f32_e32 v133, v92, v92
	v_mul_f32_e32 v133, 0xbf38aa3b, v133
	v_fma_f32 v132, |v92|, s26, 1.0
	v_exp_f32_e32 v134, v133
	v_fma_f32 v133, |v93|, s26, 1.0
	v_rcp_f32_e32 v132, v132
	v_rcp_f32_e32 v133, v133
	v_mul_f32_e32 v135, v93, v93
	v_pk_fma_f32 v[118:119], v[142:143], v[142:143], v[118:119]
	v_mul_f32_e32 v135, 0xbf38aa3b, v135
	v_pk_fma_f32 v[142:143], v[132:133], s[24:25], v[64:65] op_sel_hi:[1,0,0]
	v_exp_f32_e32 v135, v135
	v_pk_fma_f32 v[142:143], v[132:133], v[142:143], s[6:7] op_sel_hi:[1,1,0]
	v_or_b32_e32 v140, 32, v84
	v_pk_fma_f32 v[142:143], v[132:133], v[142:143], s[88:89] op_sel_hi:[1,1,0]
	v_ashrrev_i32_e32 v141, 31, v140
	v_pk_fma_f32 v[142:143], v[132:133], v[142:143], s[90:91] op_sel_hi:[1,1,0]
	s_nop 0
	v_pk_mul_f32 v[132:133], v[132:133], v[142:143]
	s_nop 0
	v_pk_mul_f32 v[132:133], v[134:135], v[132:133]
	s_nop 0
	v_pk_mul_f32 v[134:135], v[92:93], v[132:133]
	v_pk_fma_f32 v[132:133], v[92:93], v[132:133], v[92:93] neg_lo:[1,0,0] neg_hi:[1,0,0]
	s_nop 0
	v_cndmask_b32_e32 v92, v132, v134, vcc
	v_cmp_gt_f32_e32 vcc, 0, v93
	v_fma_f32 v132, |v110|, s26, 1.0
	v_rcp_f32_e32 v132, v132
	v_cndmask_b32_e32 v93, v133, v135, vcc
	v_mul_f32_e32 v133, v110, v110
	v_mul_f32_e32 v133, 0xbf38aa3b, v133
	v_exp_f32_e32 v134, v133
	v_fma_f32 v133, |v111|, s26, 1.0
	v_rcp_f32_e32 v133, v133
	v_mul_f32_e32 v135, v111, v111
	v_mul_f32_e32 v135, 0xbf38aa3b, v135
	v_exp_f32_e32 v135, v135
	v_pk_fma_f32 v[142:143], v[132:133], s[24:25], v[64:65] op_sel_hi:[1,0,0]
	v_cmp_gt_f32_e32 vcc, 0, v110
	v_pk_fma_f32 v[142:143], v[132:133], v[142:143], s[6:7] op_sel_hi:[1,1,0]
	s_nop 0
	v_pk_fma_f32 v[142:143], v[132:133], v[142:143], s[88:89] op_sel_hi:[1,1,0]
	s_nop 0
	v_pk_fma_f32 v[142:143], v[132:133], v[142:143], s[90:91] op_sel_hi:[1,1,0]
	s_nop 0
	v_pk_mul_f32 v[132:133], v[132:133], v[142:143]
	s_nop 0
	v_pk_mul_f32 v[132:133], v[134:135], v[132:133]
	s_nop 0
	v_pk_mul_f32 v[134:135], v[110:111], v[132:133]
	v_pk_fma_f32 v[132:133], v[110:111], v[132:133], v[110:111] neg_lo:[1,0,0] neg_hi:[1,0,0]
	s_nop 0
	v_cndmask_b32_e32 v110, v132, v134, vcc
	v_cmp_gt_f32_e32 vcc, 0, v111
	v_fma_f32 v132, |v88|, s26, 1.0
	v_rcp_f32_e32 v132, v132
	v_cndmask_b32_e32 v111, v133, v135, vcc
	v_mul_f32_e32 v133, v88, v88
	v_mul_f32_e32 v133, 0xbf38aa3b, v133
	v_exp_f32_e32 v134, v133
	v_fma_f32 v133, |v89|, s26, 1.0
	v_rcp_f32_e32 v133, v133
	v_mul_f32_e32 v135, v89, v89
	v_mul_f32_e32 v135, 0xbf38aa3b, v135
	v_exp_f32_e32 v135, v135
	v_pk_fma_f32 v[142:143], v[132:133], s[24:25], v[64:65] op_sel_hi:[1,0,0]
	v_cmp_gt_f32_e32 vcc, 0, v88
	v_pk_fma_f32 v[142:143], v[132:133], v[142:143], s[6:7] op_sel_hi:[1,1,0]
	s_nop 0
	v_pk_fma_f32 v[142:143], v[132:133], v[142:143], s[88:89] op_sel_hi:[1,1,0]
	s_nop 0
	v_pk_fma_f32 v[142:143], v[132:133], v[142:143], s[90:91] op_sel_hi:[1,1,0]
	s_nop 0
	v_pk_mul_f32 v[132:133], v[132:133], v[142:143]
	s_nop 0
	v_pk_mul_f32 v[132:133], v[134:135], v[132:133]
	s_nop 0
	v_pk_mul_f32 v[134:135], v[88:89], v[132:133]
	v_pk_fma_f32 v[132:133], v[88:89], v[132:133], v[88:89] neg_lo:[1,0,0] neg_hi:[1,0,0]
	s_nop 0
	v_cndmask_b32_e32 v88, v132, v134, vcc
	v_cmp_gt_f32_e32 vcc, 0, v89
	v_fma_f32 v132, |v106|, s26, 1.0
	v_rcp_f32_e32 v132, v132
	v_cndmask_b32_e32 v89, v133, v135, vcc
	v_mul_f32_e32 v133, v106, v106
	v_mul_f32_e32 v133, 0xbf38aa3b, v133
	v_exp_f32_e32 v134, v133
	v_fma_f32 v133, |v107|, s26, 1.0
	v_rcp_f32_e32 v133, v133
	v_mul_f32_e32 v135, v107, v107
	v_mul_f32_e32 v135, 0xbf38aa3b, v135
	v_exp_f32_e32 v135, v135
	v_pk_fma_f32 v[142:143], v[132:133], s[24:25], v[64:65] op_sel_hi:[1,0,0]
	v_cmp_gt_f32_e32 vcc, 0, v106
	v_pk_fma_f32 v[142:143], v[132:133], v[142:143], s[6:7] op_sel_hi:[1,1,0]
	s_nop 0
	v_pk_fma_f32 v[142:143], v[132:133], v[142:143], s[88:89] op_sel_hi:[1,1,0]
	s_nop 0
	v_pk_fma_f32 v[142:143], v[132:133], v[142:143], s[90:91] op_sel_hi:[1,1,0]
	s_nop 0
	v_pk_mul_f32 v[132:133], v[132:133], v[142:143]
	s_nop 0
	v_pk_mul_f32 v[132:133], v[134:135], v[132:133]
	s_nop 0
	v_pk_mul_f32 v[134:135], v[106:107], v[132:133]
	v_pk_fma_f32 v[132:133], v[106:107], v[132:133], v[106:107] neg_lo:[1,0,0] neg_hi:[1,0,0]
	s_nop 0
	v_cndmask_b32_e32 v142, v132, v134, vcc
	v_cmp_gt_f32_e32 vcc, 0, v107
	v_lshlrev_b64 v[106:107], 13, v[140:141]
	v_cvt_pk_bf16_f32 v132, v92, v93
	v_lshl_add_u64 v[106:107], s[42:43], 0, v[106:107]
	v_cndmask_b32_e32 v143, v133, v135, vcc
	v_cvt_pk_bf16_f32 v133, v110, v111
	v_pk_fma_f32 v[110:111], v[110:111], v[110:111], v[118:119]
	v_pk_fma_f32 v[118:119], v[142:143], v[142:143], v[100:101]
	v_pk_mul_f32 v[100:101], v[102:103], v[162:163]
	v_mul_f32_e32 v103, v76, v76
	v_lshl_add_u64 v[106:107], v[106:107], 0, v[68:69]
	v_mul_f32_e32 v103, 0xbf38aa3b, v103
	v_cvt_pk_bf16_f32 v134, v88, v89
	v_cvt_pk_bf16_f32 v135, v142, v143
	global_store_dwordx4 v[106:107], v[132:135], off
	v_fma_f32 v102, |v76|, s26, 1.0
	v_rcp_f32_e32 v102, v102
	v_exp_f32_e32 v132, v103
	v_fma_f32 v103, |v77|, s26, 1.0
	v_rcp_f32_e32 v103, v103
	v_pk_fma_f32 v[92:93], v[92:93], v[92:93], v[126:127]
	v_mul_f32_e32 v127, v77, v77
	v_mul_f32_e32 v127, 0xbf38aa3b, v127
	v_pk_fma_f32 v[134:135], v[102:103], s[24:25], v[64:65] op_sel_hi:[1,0,0]
	v_exp_f32_e32 v133, v127
	v_pk_fma_f32 v[134:135], v[102:103], v[134:135], s[6:7] op_sel_hi:[1,1,0]
	v_cmp_gt_f32_e32 vcc, 0, v76
	v_pk_fma_f32 v[134:135], v[102:103], v[134:135], s[88:89] op_sel_hi:[1,1,0]
	v_mul_f32_e32 v127, v101, v101
	v_pk_fma_f32 v[134:135], v[102:103], v[134:135], s[90:91] op_sel_hi:[1,1,0]
	v_mul_f32_e32 v127, 0xbf38aa3b, v127
	v_pk_mul_f32 v[102:103], v[102:103], v[134:135]
	v_or_b32_e32 v126, 48, v84
	v_pk_mul_f32 v[102:103], v[132:133], v[102:103]
	v_pk_fma_f32 v[88:89], v[88:89], v[88:89], v[138:139]
	v_pk_mul_f32 v[132:133], v[76:77], v[102:103]
	v_pk_fma_f32 v[102:103], v[76:77], v[102:103], v[76:77] neg_lo:[1,0,0] neg_hi:[1,0,0]
	s_nop 0
	v_cndmask_b32_e32 v76, v102, v132, vcc
	v_cmp_gt_f32_e32 vcc, 0, v77
	v_fma_f32 v102, |v100|, s26, 1.0
	v_rcp_f32_e32 v102, v102
	v_cndmask_b32_e32 v77, v103, v133, vcc
	v_mul_f32_e32 v103, v100, v100
	v_mul_f32_e32 v103, 0xbf38aa3b, v103
	v_exp_f32_e32 v132, v103
	v_fma_f32 v103, |v101|, s26, 1.0
	v_rcp_f32_e32 v103, v103
	v_exp_f32_e32 v133, v127
	v_cmp_gt_f32_e32 vcc, 0, v100
	v_ashrrev_i32_e32 v127, 31, v126
	v_pk_fma_f32 v[134:135], v[102:103], s[24:25], v[64:65] op_sel_hi:[1,0,0]
	s_nop 0
	v_pk_fma_f32 v[134:135], v[102:103], v[134:135], s[6:7] op_sel_hi:[1,1,0]
	s_nop 0
	v_pk_fma_f32 v[134:135], v[102:103], v[134:135], s[88:89] op_sel_hi:[1,1,0]
	s_nop 0
	v_pk_fma_f32 v[134:135], v[102:103], v[134:135], s[90:91] op_sel_hi:[1,1,0]
	s_nop 0
	v_pk_mul_f32 v[102:103], v[102:103], v[134:135]
	s_nop 0
	v_pk_mul_f32 v[102:103], v[132:133], v[102:103]
	s_nop 0
	v_pk_mul_f32 v[132:133], v[100:101], v[102:103]
	v_pk_fma_f32 v[102:103], v[100:101], v[102:103], v[100:101] neg_lo:[1,0,0] neg_hi:[1,0,0]
	v_fma_f32 v100, |v72|, s26, 1.0
	v_cndmask_b32_e32 v132, v102, v132, vcc
	v_cmp_gt_f32_e32 vcc, 0, v101
	v_mul_f32_e32 v101, v72, v72
	v_mul_f32_e32 v101, 0xbf38aa3b, v101
	v_exp_f32_e32 v102, v101
	v_fma_f32 v101, |v73|, s26, 1.0
	v_rcp_f32_e32 v100, v100
	v_rcp_f32_e32 v101, v101
	v_cndmask_b32_e32 v133, v103, v133, vcc
	v_mul_f32_e32 v103, v73, v73
	v_mul_f32_e32 v103, 0xbf38aa3b, v103
	v_pk_fma_f32 v[134:135], v[100:101], s[24:25], v[64:65] op_sel_hi:[1,0,0]
	v_exp_f32_e32 v103, v103
	v_pk_fma_f32 v[134:135], v[100:101], v[134:135], s[6:7] op_sel_hi:[1,1,0]
	v_cmp_gt_f32_e32 vcc, 0, v72
	v_pk_fma_f32 v[134:135], v[100:101], v[134:135], s[88:89] op_sel_hi:[1,1,0]
	s_nop 0
	v_pk_fma_f32 v[134:135], v[100:101], v[134:135], s[90:91] op_sel_hi:[1,1,0]
	s_nop 0
	v_pk_mul_f32 v[100:101], v[100:101], v[134:135]
	v_mov_b32_e32 v134, v145
	v_pk_mul_f32 v[100:101], v[102:103], v[100:101]
	s_nop 0
	v_pk_mul_f32 v[102:103], v[72:73], v[100:101]
	v_pk_fma_f32 v[100:101], v[72:73], v[100:101], v[72:73] neg_lo:[1,0,0] neg_hi:[1,0,0]
	s_nop 0
	v_cndmask_b32_e32 v72, v100, v102, vcc
	v_cmp_gt_f32_e32 vcc, 0, v73
	v_fma_f32 v100, |v98|, s26, 1.0
	v_rcp_f32_e32 v100, v100
	v_cndmask_b32_e32 v73, v101, v103, vcc
	v_mul_f32_e32 v101, v98, v98
	v_mul_f32_e32 v101, 0xbf38aa3b, v101
	v_exp_f32_e32 v102, v101
	v_fma_f32 v101, |v99|, s26, 1.0
	v_rcp_f32_e32 v101, v101
	v_mul_f32_e32 v103, v99, v99
	v_mul_f32_e32 v103, 0xbf38aa3b, v103
	v_exp_f32_e32 v103, v103
	v_pk_fma_f32 v[64:65], v[100:101], s[24:25], v[64:65] op_sel_hi:[1,0,0]
	v_cmp_gt_f32_e32 vcc, 0, v98
	v_pk_fma_f32 v[64:65], v[100:101], v[64:65], s[6:7] op_sel_hi:[1,1,0]
	s_nop 0
	v_pk_fma_f32 v[64:65], v[100:101], v[64:65], s[88:89] op_sel_hi:[1,1,0]
	s_nop 0
	v_pk_fma_f32 v[64:65], v[100:101], v[64:65], s[90:91] op_sel_hi:[1,1,0]
	s_nop 0
	v_pk_mul_f32 v[64:65], v[100:101], v[64:65]
	s_nop 0
	v_pk_mul_f32 v[64:65], v[102:103], v[64:65]
	v_lshlrev_b64 v[102:103], 13, v[126:127]
	v_pk_mul_f32 v[100:101], v[98:99], v[64:65]
	v_pk_fma_f32 v[64:65], v[98:99], v[64:65], v[98:99] neg_lo:[1,0,0] neg_hi:[1,0,0]
	v_lshl_add_u64 v[102:103], s[42:43], 0, v[102:103]
	v_cndmask_b32_e32 v64, v64, v100, vcc
	v_cmp_gt_f32_e32 vcc, 0, v99
	v_cvt_pk_bf16_f32 v98, v76, v77
	v_cvt_pk_bf16_f32 v99, v132, v133
	v_cvt_pk_bf16_f32 v100, v72, v73
	v_lshl_add_u64 v[102:103], v[102:103], 0, v[68:69]
	v_pk_fma_f32 v[76:77], v[76:77], v[76:77], v[92:93]
	v_cndmask_b32_e32 v65, v65, v101, vcc
	v_cvt_pk_bf16_f32 v101, v64, v65
	global_store_dwordx4 v[102:103], v[98:101], off
	v_mov_b32_e32 v69, v145
	v_mov_b32_e32 v93, v145
	v_pk_fma_f32 v[100:101], v[132:133], v[132:133], v[110:111]
	v_pk_fma_f32 v[132:133], v[64:65], v[64:65], v[118:119]
	v_add_f32_dpp v64, v76, v76 row_ror:8 row_mask:0xf bank_mask:0xf bound_ctrl:1
	v_pk_fma_f32 v[98:99], v[72:73], v[72:73], v[88:89]
	v_mov_b32_e32 v89, v145
	v_add_f32_dpp v64, v64, v64 row_ror:4 row_mask:0xf bank_mask:0xf bound_ctrl:1
	v_mov_b32_e32 v111, v145
	v_mov_b32_e32 v118, v145
	v_add_f32_dpp v65, v64, v64 row_ror:2 row_mask:0xf bank_mask:0xf bound_ctrl:1
	v_add_f32_dpp v64, v98, v98 row_ror:8 row_mask:0xf bank_mask:0xf bound_ctrl:1
	v_mov_b32_e32 v126, v145
	v_mov_b32_dpp v69, v65 row_ror:1 row_mask:0xf bank_mask:0xf
	v_add_f32_dpp v64, v64, v64 row_ror:4 row_mask:0xf bank_mask:0xf bound_ctrl:1
	v_or_b32_e32 v98, 4, v80
	v_or_b32_e32 v92, 1, v80
	v_add_f32_dpp v73, v64, v64 row_ror:2 row_mask:0xf bank_mask:0xf bound_ctrl:1
	v_add_f32_dpp v64, v77, v77 row_ror:8 row_mask:0xf bank_mask:0xf bound_ctrl:1
	v_or_b32_e32 v88, 5, v80
	v_mov_b32_dpp v89, v73 row_ror:1 row_mask:0xf bank_mask:0xf
	v_add_f32_dpp v64, v64, v64 row_ror:4 row_mask:0xf bank_mask:0xf bound_ctrl:1
	v_or_b32_e32 v76, 2, v80
	v_or_b32_e32 v72, 6, v80
	v_add_f32_dpp v77, v64, v64 row_ror:2 row_mask:0xf bank_mask:0xf bound_ctrl:1
	v_add_f32_dpp v64, v99, v99 row_ror:8 row_mask:0xf bank_mask:0xf bound_ctrl:1
	v_or_b32_e32 v68, 3, v80
	v_mov_b32_dpp v93, v77 row_ror:1 row_mask:0xf bank_mask:0xf
	v_add_f32_dpp v64, v64, v64 row_ror:4 row_mask:0xf bank_mask:0xf bound_ctrl:1
	s_nop 1
	v_add_f32_dpp v99, v64, v64 row_ror:2 row_mask:0xf bank_mask:0xf bound_ctrl:1
	v_add_f32_dpp v64, v100, v100 row_ror:8 row_mask:0xf bank_mask:0xf bound_ctrl:1
	s_nop 0
	v_mov_b32_dpp v111, v99 row_ror:1 row_mask:0xf bank_mask:0xf
	v_add_f32_dpp v64, v64, v64 row_ror:4 row_mask:0xf bank_mask:0xf bound_ctrl:1
	s_nop 1
	v_add_f32_dpp v110, v64, v64 row_ror:2 row_mask:0xf bank_mask:0xf bound_ctrl:1
	v_add_f32_dpp v64, v132, v132 row_ror:8 row_mask:0xf bank_mask:0xf bound_ctrl:1
	v_mov_b32_e32 v132, v145
	v_mov_b32_dpp v118, v110 row_ror:1 row_mask:0xf bank_mask:0xf
	v_add_f32_dpp v64, v64, v64 row_ror:4 row_mask:0xf bank_mask:0xf bound_ctrl:1
	s_nop 1
	v_add_f32_dpp v119, v64, v64 row_ror:2 row_mask:0xf bank_mask:0xf bound_ctrl:1
	v_add_f32_dpp v64, v101, v101 row_ror:8 row_mask:0xf bank_mask:0xf bound_ctrl:1
	v_lshlrev_b64 v[100:101], 5, v[80:81]
	v_mov_b32_dpp v126, v119 row_ror:1 row_mask:0xf bank_mask:0xf
	v_add_f32_dpp v64, v64, v64 row_ror:4 row_mask:0xf bank_mask:0xf bound_ctrl:1
	v_lshl_add_u64 v[100:101], s[96:97], 0, v[100:101]
	s_nop 0
	v_add_f32_dpp v127, v64, v64 row_ror:2 row_mask:0xf bank_mask:0xf bound_ctrl:1
	v_add_f32_dpp v64, v133, v133 row_ror:8 row_mask:0xf bank_mask:0xf bound_ctrl:1
	s_nop 0
	v_mov_b32_dpp v132, v127 row_ror:1 row_mask:0xf bank_mask:0xf
	v_add_f32_dpp v64, v64, v64 row_ror:4 row_mask:0xf bank_mask:0xf bound_ctrl:1
	s_nop 1
	v_add_f32_dpp v133, v64, v64 row_ror:2 row_mask:0xf bank_mask:0xf bound_ctrl:1
	v_or_b32_e32 v64, 7, v80
	s_nop 0
	v_mov_b32_dpp v134, v133 row_ror:1 row_mask:0xf bank_mask:0xf
	s_and_saveexec_b64 s[0:1], s[38:39]
	s_cbranch_execz .LBB0_357
	v_add_f32_e32 v65, v65, v69
	v_fma_f32 v65, v65, s91, 0.5
	v_trunc_f32_e32 v65, v65
	v_add_f32_e32 v69, v77, v93
	v_mul_f32_e32 v77, 0x2f800000, v65
	v_floor_f32_e32 v77, v77
	v_add_f32_e32 v73, v73, v89
	v_fmac_f32_e32 v65, 0xcf800000, v77
	v_add_f32_e32 v127, v127, v132
	v_add_f32_e32 v132, v110, v118
	v_cvt_u32_f32_e32 v118, v65
	v_fma_f32 v65, v73, s91, 0.5
	v_add_f32_e32 v126, v119, v126
	v_cvt_u32_f32_e32 v119, v77
	v_trunc_f32_e32 v65, v65
	v_mul_f32_e32 v73, 0x2f800000, v65
	s_lshl_b64 s[50:51], s[98:99], 3
	v_floor_f32_e32 v73, v73
	v_add_f32_e32 v133, v133, v134
	v_add_f32_e32 v134, v99, v111
	v_lshl_add_u64 v[110:111], v[100:101], 0, s[50:51]
	v_fmac_f32_e32 v65, 0xcf800000, v73
	global_atomic_add_x2 v[110:111], v[118:119], off
	v_cvt_u32_f32_e32 v118, v65
	v_fma_f32 v65, v69, s91, 0.5
	v_ashrrev_i32_e32 v99, 31, v98
	v_cvt_u32_f32_e32 v119, v73
	v_trunc_f32_e32 v65, v65
	v_lshlrev_b64 v[110:111], 5, v[98:99]
	v_mul_f32_e32 v69, 0x2f800000, v65
	v_lshl_add_u64 v[110:111], s[96:97], 0, v[110:111]
	v_floor_f32_e32 v69, v69
	v_lshl_add_u64 v[110:111], v[110:111], 0, s[50:51]
	v_fmac_f32_e32 v65, 0xcf800000, v69
	global_atomic_add_x2 v[110:111], v[118:119], off
	v_cvt_u32_f32_e32 v118, v65
	v_fma_f32 v65, v134, s91, 0.5
	v_ashrrev_i32_e32 v93, 31, v92
	v_cvt_u32_f32_e32 v119, v69
	v_trunc_f32_e32 v65, v65
	v_lshlrev_b64 v[110:111], 5, v[92:93]
	v_mul_f32_e32 v69, 0x2f800000, v65
	v_lshl_add_u64 v[110:111], s[96:97], 0, v[110:111]
	v_floor_f32_e32 v69, v69
	v_lshl_add_u64 v[110:111], v[110:111], 0, s[50:51]
	v_fmac_f32_e32 v65, 0xcf800000, v69
	global_atomic_add_x2 v[110:111], v[118:119], off
	v_cvt_u32_f32_e32 v118, v65
	v_fma_f32 v65, v132, s91, 0.5
	v_ashrrev_i32_e32 v89, 31, v88
	v_cvt_u32_f32_e32 v119, v69
	v_trunc_f32_e32 v65, v65
	v_lshlrev_b64 v[110:111], 5, v[88:89]
	v_mul_f32_e32 v69, 0x2f800000, v65
	v_lshl_add_u64 v[110:111], s[96:97], 0, v[110:111]
	v_floor_f32_e32 v69, v69
	v_lshl_add_u64 v[110:111], v[110:111], 0, s[50:51]
	v_fmac_f32_e32 v65, 0xcf800000, v69
	global_atomic_add_x2 v[110:111], v[118:119], off
	v_cvt_u32_f32_e32 v118, v65
	v_fma_f32 v65, v126, s91, 0.5
	v_ashrrev_i32_e32 v77, 31, v76
	v_cvt_u32_f32_e32 v119, v69
	v_trunc_f32_e32 v65, v65
	v_lshlrev_b64 v[110:111], 5, v[76:77]
	v_mul_f32_e32 v69, 0x2f800000, v65
	v_lshl_add_u64 v[110:111], s[96:97], 0, v[110:111]
	v_floor_f32_e32 v69, v69
	v_lshl_add_u64 v[110:111], v[110:111], 0, s[50:51]
	v_fmac_f32_e32 v65, 0xcf800000, v69
	global_atomic_add_x2 v[110:111], v[118:119], off
	v_ashrrev_i32_e32 v73, 31, v72
	v_cvt_u32_f32_e32 v118, v65
	v_cvt_u32_f32_e32 v119, v69
	v_lshlrev_b64 v[110:111], 5, v[72:73]
	v_lshl_add_u64 v[110:111], s[96:97], 0, v[110:111]
	v_fma_f32 v65, v127, s91, 0.5
	v_lshl_add_u64 v[110:111], v[110:111], 0, s[50:51]
	v_ashrrev_i32_e32 v69, 31, v68
	v_trunc_f32_e32 v65, v65
	global_atomic_add_x2 v[110:111], v[118:119], off
	v_lshlrev_b64 v[110:111], 5, v[68:69]
	v_mul_f32_e32 v69, 0x2f800000, v65
	v_floor_f32_e32 v69, v69
	v_fmac_f32_e32 v65, 0xcf800000, v69
	v_cvt_u32_f32_e32 v118, v65
	v_cvt_u32_f32_e32 v119, v69
	v_lshl_add_u64 v[110:111], s[96:97], 0, v[110:111]
	v_lshl_add_u64 v[110:111], v[110:111], 0, s[50:51]
	v_ashrrev_i32_e32 v65, 31, v64
	global_atomic_add_x2 v[110:111], v[118:119], off
	v_lshlrev_b64 v[110:111], 5, v[64:65]
	v_fma_f32 v65, v133, s91, 0.5
	v_trunc_f32_e32 v65, v65
	v_mul_f32_e32 v69, 0x2f800000, v65
	v_floor_f32_e32 v69, v69
	v_fmac_f32_e32 v65, 0xcf800000, v69
	v_cvt_u32_f32_e32 v118, v65
	v_cvt_u32_f32_e32 v119, v69
	v_lshl_add_u64 v[110:111], s[96:97], 0, v[110:111]
	v_lshl_add_u64 v[110:111], v[110:111], 0, s[50:51]
	global_atomic_add_x2 v[110:111], v[118:119], off
.LBB0_357:
	s_or_b64 exec, exec, s[0:1]
	v_fma_f32 v65, |v130|, s26, 1.0
	v_rcp_f32_e32 v126, v65
	v_mul_f32_e32 v65, v130, v130
	v_mul_f32_e32 v65, 0xbf38aa3b, v65
	v_exp_f32_e32 v132, v65
	v_fma_f32 v65, |v131|, s26, 1.0
	v_rcp_f32_e32 v127, v65
	s_mov_b32 s0, 0xbf3a00e3
	v_pk_mul_f32 v[118:119], v[90:91], v[128:129]
	v_mul_f32_e32 v65, v131, v131
	v_mov_b64_e32 v[90:91], s[0:1]
	v_mul_f32_e32 v65, 0xbf38aa3b, v65
	v_pk_fma_f32 v[134:135], v[126:127], s[24:25], v[90:91] op_sel_hi:[1,0,0]
	v_exp_f32_e32 v133, v65
	v_pk_fma_f32 v[134:135], v[126:127], v[134:135], s[6:7] op_sel_hi:[1,1,0]
	v_pk_mul_f32 v[94:95], v[94:95], v[136:137]
	v_pk_fma_f32 v[134:135], v[126:127], v[134:135], s[88:89] op_sel_hi:[1,1,0]
	v_cmp_gt_f32_e32 vcc, 0, v130
	v_pk_fma_f32 v[134:135], v[126:127], v[134:135], s[90:91] op_sel_hi:[1,1,0]
	v_fma_f32 v65, |v94|, s26, 1.0
	v_pk_mul_f32 v[126:127], v[126:127], v[134:135]
	v_pk_mul_f32 v[86:87], v[86:87], v[136:137]
	v_pk_mul_f32 v[126:127], v[132:133], v[126:127]
	v_pk_mul_f32 v[82:83], v[82:83], v[128:129]
	v_pk_mul_f32 v[132:133], v[130:131], v[126:127]
	v_pk_fma_f32 v[126:127], v[130:131], v[126:127], v[130:131] neg_lo:[1,0,0] neg_hi:[1,0,0]
	v_pk_mul_f32 v[78:79], v[78:79], v[136:137]
	v_cndmask_b32_e32 v130, v126, v132, vcc
	v_rcp_f32_e32 v126, v65
	v_mul_f32_e32 v65, v94, v94
	v_mul_f32_e32 v65, 0xbf38aa3b, v65
	v_cmp_gt_f32_e32 vcc, 0, v131
	v_exp_f32_e32 v132, v65
	v_fma_f32 v65, |v95|, s26, 1.0
	v_cndmask_b32_e32 v131, v127, v133, vcc
	v_rcp_f32_e32 v127, v65
	v_mul_f32_e32 v65, v95, v95
	v_mul_f32_e32 v65, 0xbf38aa3b, v65
	v_exp_f32_e32 v133, v65
	v_pk_fma_f32 v[134:135], v[126:127], s[24:25], v[90:91] op_sel_hi:[1,0,0]
	v_cmp_gt_f32_e32 vcc, 0, v94
	v_pk_fma_f32 v[134:135], v[126:127], v[134:135], s[6:7] op_sel_hi:[1,1,0]
	v_fma_f32 v65, |v124|, s26, 1.0
	v_pk_fma_f32 v[134:135], v[126:127], v[134:135], s[88:89] op_sel_hi:[1,1,0]
	v_pk_mul_f32 v[74:75], v[74:75], v[128:129]
	v_pk_fma_f32 v[134:135], v[126:127], v[134:135], s[90:91] op_sel_hi:[1,1,0]
	v_pk_mul_f32 v[70:71], v[70:71], v[136:137]
	v_pk_mul_f32 v[126:127], v[126:127], v[134:135]
	v_pk_mul_f32 v[66:67], v[66:67], v[128:129]
	v_pk_mul_f32 v[126:127], v[132:133], v[126:127]
	v_or_b32_e32 v110, 0x80, v80
	v_pk_mul_f32 v[132:133], v[94:95], v[126:127]
	v_pk_fma_f32 v[126:127], v[94:95], v[126:127], v[94:95] neg_lo:[1,0,0] neg_hi:[1,0,0]
	v_ashrrev_i32_e32 v111, 31, v110
	v_cndmask_b32_e32 v94, v126, v132, vcc
	v_rcp_f32_e32 v126, v65
	v_mul_f32_e32 v65, v124, v124
	v_mul_f32_e32 v65, 0xbf38aa3b, v65
	v_cmp_gt_f32_e32 vcc, 0, v95
	v_exp_f32_e32 v132, v65
	v_fma_f32 v65, |v125|, s26, 1.0
	v_cndmask_b32_e32 v95, v127, v133, vcc
	v_rcp_f32_e32 v127, v65
	v_mul_f32_e32 v65, v125, v125
	v_mul_f32_e32 v65, 0xbf38aa3b, v65
	v_exp_f32_e32 v133, v65
	v_pk_fma_f32 v[134:135], v[126:127], s[24:25], v[90:91] op_sel_hi:[1,0,0]
	v_fma_f32 v65, |v118|, s26, 1.0
	v_pk_fma_f32 v[134:135], v[126:127], v[134:135], s[6:7] op_sel_hi:[1,1,0]
	v_cmp_gt_f32_e32 vcc, 0, v124
	v_pk_fma_f32 v[134:135], v[126:127], v[134:135], s[88:89] op_sel_hi:[1,1,0]
	v_mov_b32_e32 v73, v145
	v_pk_fma_f32 v[134:135], v[126:127], v[134:135], s[90:91] op_sel_hi:[1,1,0]
	v_mov_b32_e32 v99, v145
	v_pk_mul_f32 v[126:127], v[126:127], v[134:135]
	s_nop 0
	v_pk_mul_f32 v[126:127], v[132:133], v[126:127]
	s_nop 0
	v_pk_mul_f32 v[132:133], v[124:125], v[126:127]
	v_pk_fma_f32 v[126:127], v[124:125], v[126:127], v[124:125] neg_lo:[1,0,0] neg_hi:[1,0,0]
	v_rcp_f32_e32 v124, v65
	v_mul_f32_e32 v65, v118, v118
	v_mul_f32_e32 v65, 0xbf38aa3b, v65
	v_cndmask_b32_e32 v132, v126, v132, vcc
	v_exp_f32_e32 v126, v65
	v_fma_f32 v65, |v119|, s26, 1.0
	v_cmp_gt_f32_e32 vcc, 0, v125
	v_rcp_f32_e32 v125, v65
	v_mul_f32_e32 v65, v119, v119
	v_mul_f32_e32 v65, 0xbf38aa3b, v65
	v_cndmask_b32_e32 v133, v127, v133, vcc
	v_pk_fma_f32 v[134:135], v[124:125], s[24:25], v[90:91] op_sel_hi:[1,0,0]
	v_exp_f32_e32 v127, v65
	v_pk_fma_f32 v[134:135], v[124:125], v[134:135], s[6:7] op_sel_hi:[1,1,0]
	v_fma_f32 v65, |v120|, s26, 1.0
	v_pk_fma_f32 v[134:135], v[124:125], v[134:135], s[88:89] op_sel_hi:[1,1,0]
	v_cmp_gt_f32_e32 vcc, 0, v118
	v_pk_fma_f32 v[134:135], v[124:125], v[134:135], s[90:91] op_sel_hi:[1,1,0]
	s_nop 0
	v_pk_mul_f32 v[124:125], v[124:125], v[134:135]
	s_nop 0
	v_pk_mul_f32 v[124:125], v[126:127], v[124:125]
	s_nop 0
	v_pk_mul_f32 v[126:127], v[118:119], v[124:125]
	v_pk_fma_f32 v[124:125], v[118:119], v[124:125], v[118:119] neg_lo:[1,0,0] neg_hi:[1,0,0]
	v_rcp_f32_e32 v118, v65
	v_mul_f32_e32 v65, v120, v120
	v_cndmask_b32_e32 v134, v124, v126, vcc
	v_cmp_gt_f32_e32 vcc, 0, v119
	v_mul_f32_e32 v65, 0xbf38aa3b, v65
	v_cvt_pk_bf16_f32 v124, v130, v131
	s_nop 0
	v_cndmask_b32_e32 v135, v125, v127, vcc
	v_cvt_pk_bf16_f32 v125, v94, v95
	v_cvt_pk_bf16_f32 v126, v132, v133
	v_cvt_pk_bf16_f32 v127, v134, v135
	global_store_dwordx4 v[122:123], v[124:127], off offset:256
	v_exp_f32_e32 v122, v65
	v_fma_f32 v65, |v121|, s26, 1.0
	v_rcp_f32_e32 v119, v65
	v_mul_f32_e32 v65, v121, v121
	v_mul_f32_e32 v65, 0xbf38aa3b, v65
	v_exp_f32_e32 v123, v65
	v_pk_fma_f32 v[124:125], v[118:119], s[24:25], v[90:91] op_sel_hi:[1,0,0]
	v_cmp_gt_f32_e32 vcc, 0, v120
	v_pk_fma_f32 v[124:125], v[118:119], v[124:125], s[6:7] op_sel_hi:[1,1,0]
	v_fma_f32 v65, |v86|, s26, 1.0
	v_pk_fma_f32 v[124:125], v[118:119], v[124:125], s[88:89] op_sel_hi:[1,1,0]
	s_nop 0
	v_pk_fma_f32 v[124:125], v[118:119], v[124:125], s[90:91] op_sel_hi:[1,1,0]
	s_nop 0
	v_pk_mul_f32 v[118:119], v[118:119], v[124:125]
	s_nop 0
	v_pk_mul_f32 v[118:119], v[122:123], v[118:119]
	s_nop 0
	v_pk_mul_f32 v[122:123], v[120:121], v[118:119]
	v_pk_fma_f32 v[118:119], v[120:121], v[118:119], v[120:121] neg_lo:[1,0,0] neg_hi:[1,0,0]
	s_nop 0
	v_cndmask_b32_e32 v120, v118, v122, vcc
	v_rcp_f32_e32 v118, v65
	v_mul_f32_e32 v65, v86, v86
	v_mul_f32_e32 v65, 0xbf38aa3b, v65
	v_cmp_gt_f32_e32 vcc, 0, v121
	v_exp_f32_e32 v122, v65
	v_fma_f32 v65, |v87|, s26, 1.0
	v_cndmask_b32_e32 v121, v119, v123, vcc
	v_rcp_f32_e32 v119, v65
	v_mul_f32_e32 v65, v87, v87
	v_mul_f32_e32 v65, 0xbf38aa3b, v65
	v_exp_f32_e32 v123, v65
	v_pk_fma_f32 v[124:125], v[118:119], s[24:25], v[90:91] op_sel_hi:[1,0,0]
	v_cmp_gt_f32_e32 vcc, 0, v86
	v_pk_fma_f32 v[124:125], v[118:119], v[124:125], s[6:7] op_sel_hi:[1,1,0]
	v_fma_f32 v65, |v116|, s26, 1.0
	v_pk_fma_f32 v[124:125], v[118:119], v[124:125], s[88:89] op_sel_hi:[1,1,0]
	s_nop 0
	v_pk_fma_f32 v[124:125], v[118:119], v[124:125], s[90:91] op_sel_hi:[1,1,0]
	s_nop 0
	v_pk_mul_f32 v[118:119], v[118:119], v[124:125]
	s_nop 0
	v_pk_mul_f32 v[118:119], v[122:123], v[118:119]
	s_nop 0
	v_pk_mul_f32 v[122:123], v[86:87], v[118:119]
	v_pk_fma_f32 v[118:119], v[86:87], v[118:119], v[86:87] neg_lo:[1,0,0] neg_hi:[1,0,0]
	s_nop 0
	v_cndmask_b32_e32 v86, v118, v122, vcc
	v_rcp_f32_e32 v118, v65
	v_mul_f32_e32 v65, v116, v116
	v_mul_f32_e32 v65, 0xbf38aa3b, v65
	v_cmp_gt_f32_e32 vcc, 0, v87
	v_exp_f32_e32 v122, v65
	v_fma_f32 v65, |v117|, s26, 1.0
	v_cndmask_b32_e32 v87, v119, v123, vcc
	v_rcp_f32_e32 v119, v65
	v_mul_f32_e32 v65, v117, v117
	v_mul_f32_e32 v65, 0xbf38aa3b, v65
	v_exp_f32_e32 v123, v65
	v_pk_fma_f32 v[124:125], v[118:119], s[24:25], v[90:91] op_sel_hi:[1,0,0]
	v_fma_f32 v65, |v82|, s26, 1.0
	v_pk_fma_f32 v[124:125], v[118:119], v[124:125], s[6:7] op_sel_hi:[1,1,0]
	v_cmp_gt_f32_e32 vcc, 0, v116
	v_pk_fma_f32 v[124:125], v[118:119], v[124:125], s[88:89] op_sel_hi:[1,1,0]
	s_nop 0
	v_pk_fma_f32 v[124:125], v[118:119], v[124:125], s[90:91] op_sel_hi:[1,1,0]
	s_nop 0
	v_pk_mul_f32 v[118:119], v[118:119], v[124:125]
	s_nop 0
	v_pk_mul_f32 v[118:119], v[122:123], v[118:119]
	s_nop 0
	v_pk_mul_f32 v[122:123], v[116:117], v[118:119]
	v_pk_fma_f32 v[118:119], v[116:117], v[118:119], v[116:117] neg_lo:[1,0,0] neg_hi:[1,0,0]
	v_rcp_f32_e32 v116, v65
	v_mul_f32_e32 v65, v82, v82
	v_mul_f32_e32 v65, 0xbf38aa3b, v65
	v_cndmask_b32_e32 v122, v118, v122, vcc
	v_exp_f32_e32 v118, v65
	v_fma_f32 v65, |v83|, s26, 1.0
	v_cmp_gt_f32_e32 vcc, 0, v117
	v_rcp_f32_e32 v117, v65
	v_mul_f32_e32 v65, v83, v83
	v_mul_f32_e32 v65, 0xbf38aa3b, v65
	v_cndmask_b32_e32 v123, v119, v123, vcc
	v_pk_fma_f32 v[124:125], v[116:117], s[24:25], v[90:91] op_sel_hi:[1,0,0]
	v_exp_f32_e32 v119, v65
	v_pk_fma_f32 v[124:125], v[116:117], v[124:125], s[6:7] op_sel_hi:[1,1,0]
	v_cmp_gt_f32_e32 vcc, 0, v82
	v_pk_fma_f32 v[124:125], v[116:117], v[124:125], s[88:89] op_sel_hi:[1,1,0]
	v_fma_f32 v65, |v112|, s26, 1.0
	v_pk_fma_f32 v[124:125], v[116:117], v[124:125], s[90:91] op_sel_hi:[1,1,0]
	s_nop 0
	v_pk_mul_f32 v[116:117], v[116:117], v[124:125]
	s_nop 0
	v_pk_mul_f32 v[116:117], v[118:119], v[116:117]
	s_nop 0
	v_pk_mul_f32 v[118:119], v[82:83], v[116:117]
	v_pk_fma_f32 v[116:117], v[82:83], v[116:117], v[82:83] neg_lo:[1,0,0] neg_hi:[1,0,0]
	s_nop 0
	v_cndmask_b32_e32 v82, v116, v118, vcc
	v_cmp_gt_f32_e32 vcc, 0, v83
	v_cvt_pk_bf16_f32 v116, v120, v121
	s_nop 1
	v_cndmask_b32_e32 v83, v117, v119, vcc
	v_cvt_pk_bf16_f32 v117, v86, v87
	v_cvt_pk_bf16_f32 v118, v122, v123
	v_cvt_pk_bf16_f32 v119, v82, v83
	global_store_dwordx4 v[114:115], v[116:119], off offset:256
	v_pk_mul_f32 v[86:87], v[86:87], v[86:87]
	v_pk_mul_f32 v[114:115], v[120:121], v[120:121]
	v_pk_fma_f32 v[86:87], v[94:95], v[94:95], v[86:87]
	v_pk_fma_f32 v[94:95], v[130:131], v[130:131], v[114:115]
	v_pk_mul_f32 v[114:115], v[122:123], v[122:123]
	v_cmp_gt_f32_e32 vcc, 0, v112
	v_pk_fma_f32 v[116:117], v[132:133], v[132:133], v[114:115]
	v_rcp_f32_e32 v114, v65
	v_mul_f32_e32 v65, v112, v112
	v_mul_f32_e32 v65, 0xbf38aa3b, v65
	v_exp_f32_e32 v118, v65
	v_fma_f32 v65, |v113|, s26, 1.0
	v_rcp_f32_e32 v115, v65
	v_mul_f32_e32 v65, v113, v113
	v_mul_f32_e32 v65, 0xbf38aa3b, v65
	v_exp_f32_e32 v119, v65
	v_pk_fma_f32 v[120:121], v[114:115], s[24:25], v[90:91] op_sel_hi:[1,0,0]
	v_fma_f32 v65, |v78|, s26, 1.0
	v_pk_fma_f32 v[120:121], v[114:115], v[120:121], s[6:7] op_sel_hi:[1,1,0]
	v_pk_mul_f32 v[82:83], v[82:83], v[82:83]
	v_pk_fma_f32 v[120:121], v[114:115], v[120:121], s[88:89] op_sel_hi:[1,1,0]
	v_pk_fma_f32 v[82:83], v[134:135], v[134:135], v[82:83]
	v_pk_fma_f32 v[120:121], v[114:115], v[120:121], s[90:91] op_sel_hi:[1,1,0]
	s_nop 0
	v_pk_mul_f32 v[114:115], v[114:115], v[120:121]
	s_nop 0
	v_pk_mul_f32 v[114:115], v[118:119], v[114:115]
	s_nop 0
	v_pk_mul_f32 v[118:119], v[112:113], v[114:115]
	v_pk_fma_f32 v[114:115], v[112:113], v[114:115], v[112:113] neg_lo:[1,0,0] neg_hi:[1,0,0]
	v_rcp_f32_e32 v112, v65
	v_mul_f32_e32 v65, v78, v78
	v_mul_f32_e32 v65, 0xbf38aa3b, v65
	v_cndmask_b32_e32 v118, v114, v118, vcc
	v_exp_f32_e32 v114, v65
	v_fma_f32 v65, |v79|, s26, 1.0
	v_cmp_gt_f32_e32 vcc, 0, v113
	v_rcp_f32_e32 v113, v65
	v_mul_f32_e32 v65, v79, v79
	v_mul_f32_e32 v65, 0xbf38aa3b, v65
	v_cndmask_b32_e32 v119, v115, v119, vcc
	v_pk_fma_f32 v[120:121], v[112:113], s[24:25], v[90:91] op_sel_hi:[1,0,0]
	v_exp_f32_e32 v115, v65
	v_pk_fma_f32 v[120:121], v[112:113], v[120:121], s[6:7] op_sel_hi:[1,1,0]
	v_cmp_gt_f32_e32 vcc, 0, v78
	v_pk_fma_f32 v[120:121], v[112:113], v[120:121], s[88:89] op_sel_hi:[1,1,0]
	v_fma_f32 v65, |v108|, s26, 1.0
	v_pk_fma_f32 v[120:121], v[112:113], v[120:121], s[90:91] op_sel_hi:[1,1,0]
	s_nop 0
	v_pk_mul_f32 v[112:113], v[112:113], v[120:121]
	s_nop 0
	v_pk_mul_f32 v[112:113], v[114:115], v[112:113]
	s_nop 0
	v_pk_mul_f32 v[114:115], v[78:79], v[112:113]
	v_pk_fma_f32 v[112:113], v[78:79], v[112:113], v[78:79] neg_lo:[1,0,0] neg_hi:[1,0,0]
	s_nop 0
	v_cndmask_b32_e32 v78, v112, v114, vcc
	v_rcp_f32_e32 v112, v65
	v_mul_f32_e32 v65, v108, v108
	v_mul_f32_e32 v65, 0xbf38aa3b, v65
	v_cmp_gt_f32_e32 vcc, 0, v79
	v_exp_f32_e32 v114, v65
	v_fma_f32 v65, |v109|, s26, 1.0
	v_cndmask_b32_e32 v79, v113, v115, vcc
	v_rcp_f32_e32 v113, v65
	v_mul_f32_e32 v65, v109, v109
	v_mul_f32_e32 v65, 0xbf38aa3b, v65
	v_exp_f32_e32 v115, v65
	v_pk_fma_f32 v[120:121], v[112:113], s[24:25], v[90:91] op_sel_hi:[1,0,0]
	v_cmp_gt_f32_e32 vcc, 0, v108
	v_pk_fma_f32 v[120:121], v[112:113], v[120:121], s[6:7] op_sel_hi:[1,1,0]
	v_fma_f32 v65, |v74|, s26, 1.0
	v_pk_fma_f32 v[120:121], v[112:113], v[120:121], s[88:89] op_sel_hi:[1,1,0]
	s_nop 0
	v_pk_fma_f32 v[120:121], v[112:113], v[120:121], s[90:91] op_sel_hi:[1,1,0]
	s_nop 0
	v_pk_mul_f32 v[112:113], v[112:113], v[120:121]
	s_nop 0
	v_pk_mul_f32 v[112:113], v[114:115], v[112:113]
	s_nop 0
	v_pk_mul_f32 v[114:115], v[108:109], v[112:113]
	v_pk_fma_f32 v[112:113], v[108:109], v[112:113], v[108:109] neg_lo:[1,0,0] neg_hi:[1,0,0]
	s_nop 0
	v_cndmask_b32_e32 v108, v112, v114, vcc
	v_rcp_f32_e32 v112, v65
	v_mul_f32_e32 v65, v74, v74
	v_mul_f32_e32 v65, 0xbf38aa3b, v65
	v_cmp_gt_f32_e32 vcc, 0, v109
	v_exp_f32_e32 v114, v65
	v_fma_f32 v65, |v75|, s26, 1.0
	v_cndmask_b32_e32 v109, v113, v115, vcc
	v_rcp_f32_e32 v113, v65
	v_mul_f32_e32 v65, v75, v75
	v_mul_f32_e32 v65, 0xbf38aa3b, v65
	v_exp_f32_e32 v115, v65
	v_pk_fma_f32 v[120:121], v[112:113], s[24:25], v[90:91] op_sel_hi:[1,0,0]
	v_cmp_gt_f32_e32 vcc, 0, v74
	v_pk_fma_f32 v[120:121], v[112:113], v[120:121], s[6:7] op_sel_hi:[1,1,0]
	v_fma_f32 v65, |v104|, s26, 1.0
	v_pk_fma_f32 v[120:121], v[112:113], v[120:121], s[88:89] op_sel_hi:[1,1,0]
	s_nop 0
	v_pk_fma_f32 v[120:121], v[112:113], v[120:121], s[90:91] op_sel_hi:[1,1,0]
	s_nop 0
	v_pk_mul_f32 v[112:113], v[112:113], v[120:121]
	s_nop 0
	v_pk_mul_f32 v[112:113], v[114:115], v[112:113]
	s_nop 0
	v_pk_mul_f32 v[114:115], v[74:75], v[112:113]
	v_pk_fma_f32 v[112:113], v[74:75], v[112:113], v[74:75] neg_lo:[1,0,0] neg_hi:[1,0,0]
	s_nop 0
	v_cndmask_b32_e32 v74, v112, v114, vcc
	v_cmp_gt_f32_e32 vcc, 0, v75
	v_cvt_pk_bf16_f32 v112, v118, v119
	s_nop 1
	v_cndmask_b32_e32 v75, v113, v115, vcc
	v_cvt_pk_bf16_f32 v113, v78, v79
	v_pk_fma_f32 v[78:79], v[78:79], v[78:79], v[86:87]
	v_pk_fma_f32 v[86:87], v[118:119], v[118:119], v[94:95]
	v_rcp_f32_e32 v94, v65
	v_mul_f32_e32 v65, v104, v104
	v_mul_f32_e32 v65, 0xbf38aa3b, v65
	v_cvt_pk_bf16_f32 v114, v108, v109
	v_cvt_pk_bf16_f32 v115, v74, v75
	global_store_dwordx4 v[106:107], v[112:115], off offset:256
	v_exp_f32_e32 v106, v65
	v_fma_f32 v65, |v105|, s26, 1.0
	v_rcp_f32_e32 v95, v65
	v_mul_f32_e32 v65, v105, v105
	v_pk_fma_f32 v[74:75], v[74:75], v[74:75], v[82:83]
	v_pk_fma_f32 v[82:83], v[108:109], v[108:109], v[116:117]
	v_mul_f32_e32 v65, 0xbf38aa3b, v65
	v_pk_fma_f32 v[108:109], v[94:95], s[24:25], v[90:91] op_sel_hi:[1,0,0]
	v_exp_f32_e32 v107, v65
	v_pk_fma_f32 v[108:109], v[94:95], v[108:109], s[6:7] op_sel_hi:[1,1,0]
	v_cmp_gt_f32_e32 vcc, 0, v104
	v_pk_fma_f32 v[108:109], v[94:95], v[108:109], s[88:89] op_sel_hi:[1,1,0]
	v_fma_f32 v65, |v70|, s26, 1.0
	v_pk_fma_f32 v[108:109], v[94:95], v[108:109], s[90:91] op_sel_hi:[1,1,0]
	s_nop 0
	v_pk_mul_f32 v[94:95], v[94:95], v[108:109]
	s_nop 0
	v_pk_mul_f32 v[94:95], v[106:107], v[94:95]
	s_nop 0
	v_pk_mul_f32 v[106:107], v[104:105], v[94:95]
	v_pk_fma_f32 v[94:95], v[104:105], v[94:95], v[104:105] neg_lo:[1,0,0] neg_hi:[1,0,0]
	s_nop 0
	v_cndmask_b32_e32 v104, v94, v106, vcc
	v_rcp_f32_e32 v94, v65
	v_mul_f32_e32 v65, v70, v70
	v_mul_f32_e32 v65, 0xbf38aa3b, v65
	v_cmp_gt_f32_e32 vcc, 0, v105
	v_exp_f32_e32 v106, v65
	v_fma_f32 v65, |v71|, s26, 1.0
	v_cndmask_b32_e32 v105, v95, v107, vcc
	v_rcp_f32_e32 v95, v65
	v_mul_f32_e32 v65, v71, v71
	v_mul_f32_e32 v65, 0xbf38aa3b, v65
	v_exp_f32_e32 v107, v65
	v_pk_fma_f32 v[108:109], v[94:95], s[24:25], v[90:91] op_sel_hi:[1,0,0]
	v_cmp_gt_f32_e32 vcc, 0, v70
	v_pk_fma_f32 v[108:109], v[94:95], v[108:109], s[6:7] op_sel_hi:[1,1,0]
	v_fma_f32 v65, |v96|, s26, 1.0
	v_pk_fma_f32 v[108:109], v[94:95], v[108:109], s[88:89] op_sel_hi:[1,1,0]
	s_nop 0
	v_pk_fma_f32 v[108:109], v[94:95], v[108:109], s[90:91] op_sel_hi:[1,1,0]
	s_nop 0
	v_pk_mul_f32 v[94:95], v[94:95], v[108:109]
	s_nop 0
	v_pk_mul_f32 v[94:95], v[106:107], v[94:95]
	s_nop 0
	v_pk_mul_f32 v[106:107], v[70:71], v[94:95]
	v_pk_fma_f32 v[94:95], v[70:71], v[94:95], v[70:71] neg_lo:[1,0,0] neg_hi:[1,0,0]
	s_nop 0
	v_cndmask_b32_e32 v70, v94, v106, vcc
	v_rcp_f32_e32 v94, v65
	v_mul_f32_e32 v65, v96, v96
	v_mul_f32_e32 v65, 0xbf38aa3b, v65
	v_cmp_gt_f32_e32 vcc, 0, v71
	v_exp_f32_e32 v106, v65
	v_fma_f32 v65, |v97|, s26, 1.0
	v_cndmask_b32_e32 v71, v95, v107, vcc
	v_rcp_f32_e32 v95, v65
	v_mul_f32_e32 v65, v97, v97
	v_mul_f32_e32 v65, 0xbf38aa3b, v65
	v_exp_f32_e32 v107, v65
	v_pk_fma_f32 v[108:109], v[94:95], s[24:25], v[90:91] op_sel_hi:[1,0,0]
	v_cmp_gt_f32_e32 vcc, 0, v96
	v_pk_fma_f32 v[108:109], v[94:95], v[108:109], s[6:7] op_sel_hi:[1,1,0]
	v_fma_f32 v65, |v66|, s26, 1.0
	v_pk_fma_f32 v[108:109], v[94:95], v[108:109], s[88:89] op_sel_hi:[1,1,0]
	s_nop 0
	v_pk_fma_f32 v[108:109], v[94:95], v[108:109], s[90:91] op_sel_hi:[1,1,0]
	s_nop 0
	v_pk_mul_f32 v[94:95], v[94:95], v[108:109]
	s_nop 0
	v_pk_mul_f32 v[94:95], v[106:107], v[94:95]
	s_nop 0
	v_pk_mul_f32 v[106:107], v[96:97], v[94:95]
	v_pk_fma_f32 v[94:95], v[96:97], v[94:95], v[96:97] neg_lo:[1,0,0] neg_hi:[1,0,0]
	s_nop 0
	v_cndmask_b32_e32 v106, v94, v106, vcc
	v_rcp_f32_e32 v94, v65
	v_mul_f32_e32 v65, v66, v66
	v_mul_f32_e32 v65, 0xbf38aa3b, v65
	v_cmp_gt_f32_e32 vcc, 0, v97
	v_exp_f32_e32 v96, v65
	v_fma_f32 v65, |v67|, s26, 1.0
	v_cndmask_b32_e32 v107, v95, v107, vcc
	v_rcp_f32_e32 v95, v65
	v_mul_f32_e32 v65, v67, v67
	v_mul_f32_e32 v65, 0xbf38aa3b, v65
	v_exp_f32_e32 v97, v65
	v_pk_fma_f32 v[90:91], v[94:95], s[24:25], v[90:91] op_sel_hi:[1,0,0]
	v_cmp_gt_f32_e32 vcc, 0, v66
	v_pk_fma_f32 v[90:91], v[94:95], v[90:91], s[6:7] op_sel_hi:[1,1,0]
	s_nop 0
	v_pk_fma_f32 v[90:91], v[94:95], v[90:91], s[88:89] op_sel_hi:[1,1,0]
	s_nop 0
	v_pk_fma_f32 v[90:91], v[94:95], v[90:91], s[90:91] op_sel_hi:[1,1,0]
	s_nop 0
	v_pk_mul_f32 v[90:91], v[94:95], v[90:91]
	s_nop 0
	v_pk_mul_f32 v[90:91], v[96:97], v[90:91]
	s_nop 0
	v_pk_mul_f32 v[94:95], v[66:67], v[90:91]
	v_pk_fma_f32 v[90:91], v[66:67], v[90:91], v[66:67] neg_lo:[1,0,0] neg_hi:[1,0,0]
	s_nop 0
	v_cndmask_b32_e32 v66, v90, v94, vcc
	v_cmp_gt_f32_e32 vcc, 0, v67
	v_cvt_pk_bf16_f32 v94, v104, v105
	v_or_b32_e32 v90, 0x84, v80
	s_nop 0
	v_cndmask_b32_e32 v67, v91, v95, vcc
	v_cvt_pk_bf16_f32 v95, v70, v71
	v_cvt_pk_bf16_f32 v96, v106, v107
	v_cvt_pk_bf16_f32 v97, v66, v67
	global_store_dwordx4 v[102:103], v[94:97], off offset:256
	v_mov_b32_e32 v91, v145
	s_nop 0
	v_pk_fma_f32 v[94:95], v[70:71], v[70:71], v[78:79]
	v_pk_fma_f32 v[78:79], v[106:107], v[106:107], v[82:83]
	v_pk_fma_f32 v[96:97], v[66:67], v[66:67], v[74:75]
	v_pk_fma_f32 v[70:71], v[104:105], v[104:105], v[86:87]
	v_add_f32_dpp v66, v78, v78 row_ror:8 row_mask:0xf bank_mask:0xf bound_ctrl:1
	v_mov_b32_e32 v67, v145
	v_add_f32_dpp v65, v70, v70 row_ror:8 row_mask:0xf bank_mask:0xf bound_ctrl:1
	v_add_f32_dpp v66, v66, v66 row_ror:4 row_mask:0xf bank_mask:0xf bound_ctrl:1
	v_mov_b32_e32 v75, v145
	v_add_f32_dpp v65, v65, v65 row_ror:4 row_mask:0xf bank_mask:0xf bound_ctrl:1
	v_add_f32_dpp v69, v66, v66 row_ror:2 row_mask:0xf bank_mask:0xf bound_ctrl:1
	v_add_f32_dpp v66, v71, v71 row_ror:8 row_mask:0xf bank_mask:0xf bound_ctrl:1
	v_add_f32_dpp v65, v65, v65 row_ror:2 row_mask:0xf bank_mask:0xf bound_ctrl:1
	v_mov_b32_e32 v83, v145
	v_add_f32_dpp v66, v66, v66 row_ror:4 row_mask:0xf bank_mask:0xf bound_ctrl:1
	v_mov_b32_e32 v87, v145
	v_mov_b32_dpp v67, v65 row_ror:1 row_mask:0xf bank_mask:0xf
	v_add_f32_dpp v71, v66, v66 row_ror:2 row_mask:0xf bank_mask:0xf bound_ctrl:1
	v_add_f32_dpp v66, v79, v79 row_ror:8 row_mask:0xf bank_mask:0xf bound_ctrl:1
	v_mov_b32_dpp v73, v69 row_ror:1 row_mask:0xf bank_mask:0xf
	v_mov_b32_dpp v75, v71 row_ror:1 row_mask:0xf bank_mask:0xf
	v_add_f32_dpp v66, v66, v66 row_ror:4 row_mask:0xf bank_mask:0xf bound_ctrl:1
	v_or_b32_e32 v86, 0x81, v80
	v_or_b32_e32 v82, 0x85, v80
	v_add_f32_dpp v77, v66, v66 row_ror:2 row_mask:0xf bank_mask:0xf bound_ctrl:1
	v_add_f32_dpp v66, v94, v94 row_ror:8 row_mask:0xf bank_mask:0xf bound_ctrl:1
	v_or_b32_e32 v78, 0x82, v80
	v_mov_b32_dpp v83, v77 row_ror:1 row_mask:0xf bank_mask:0xf
	v_add_f32_dpp v66, v66, v66 row_ror:4 row_mask:0xf bank_mask:0xf bound_ctrl:1
	v_or_b32_e32 v74, 0x86, v80
	v_or_b32_e32 v70, 0x83, v80
	v_add_f32_dpp v79, v66, v66 row_ror:2 row_mask:0xf bank_mask:0xf bound_ctrl:1
	v_add_f32_dpp v66, v96, v96 row_ror:8 row_mask:0xf bank_mask:0xf bound_ctrl:1
	v_mov_b32_e32 v96, v145
	v_mov_b32_dpp v87, v79 row_ror:1 row_mask:0xf bank_mask:0xf
	v_add_f32_dpp v66, v66, v66 row_ror:4 row_mask:0xf bank_mask:0xf bound_ctrl:1
	s_nop 1
	v_add_f32_dpp v89, v66, v66 row_ror:2 row_mask:0xf bank_mask:0xf bound_ctrl:1
	v_add_f32_dpp v66, v95, v95 row_ror:8 row_mask:0xf bank_mask:0xf bound_ctrl:1
	v_lshlrev_b64 v[94:95], 5, v[110:111]
	v_mov_b32_dpp v91, v89 row_ror:1 row_mask:0xf bank_mask:0xf
	v_add_f32_dpp v66, v66, v66 row_ror:4 row_mask:0xf bank_mask:0xf bound_ctrl:1
	v_lshl_add_u64 v[94:95], s[96:97], 0, v[94:95]
	s_nop 0
	v_add_f32_dpp v93, v66, v66 row_ror:2 row_mask:0xf bank_mask:0xf bound_ctrl:1
	v_add_f32_dpp v66, v97, v97 row_ror:8 row_mask:0xf bank_mask:0xf bound_ctrl:1
	s_nop 0
	v_mov_b32_dpp v96, v93 row_ror:1 row_mask:0xf bank_mask:0xf
	v_add_f32_dpp v66, v66, v66 row_ror:4 row_mask:0xf bank_mask:0xf bound_ctrl:1
	s_nop 1
	v_add_f32_dpp v97, v66, v66 row_ror:2 row_mask:0xf bank_mask:0xf bound_ctrl:1
	v_or_b32_e32 v66, 0x87, v80
	s_nop 0
	v_mov_b32_dpp v99, v97 row_ror:1 row_mask:0xf bank_mask:0xf
	s_and_saveexec_b64 s[0:1], s[38:39]
	s_cbranch_execz .LBB0_359
	v_add_f32_e32 v65, v65, v67
	v_fma_f32 v65, v65, s91, 0.5
	v_trunc_f32_e32 v65, v65
	v_add_f32_e32 v67, v71, v75
	v_mul_f32_e32 v75, 0x2f800000, v65
	v_floor_f32_e32 v75, v75
	v_add_f32_e32 v69, v69, v73
	v_fmac_f32_e32 v65, 0xcf800000, v75
	v_cvt_u32_f32_e32 v102, v65
	v_fma_f32 v65, v69, s91, 0.5
	v_cvt_u32_f32_e32 v103, v75
	v_trunc_f32_e32 v65, v65
	v_mul_f32_e32 v69, 0x2f800000, v65
	s_lshl_b64 s[50:51], s[98:99], 3
	v_floor_f32_e32 v69, v69
	v_add_f32_e32 v99, v97, v99
	v_add_f32_e32 v73, v77, v83
	v_add_f32_e32 v77, v89, v91
	v_add_f32_e32 v89, v93, v96
	v_lshl_add_u64 v[96:97], v[94:95], 0, s[50:51]
	v_fmac_f32_e32 v65, 0xcf800000, v69
	global_atomic_add_x2 v[96:97], v[102:103], off
	v_cvt_u32_f32_e32 v102, v65
	v_fma_f32 v65, v67, s91, 0.5
	v_ashrrev_i32_e32 v91, 31, v90
	v_cvt_u32_f32_e32 v103, v69
	v_trunc_f32_e32 v65, v65
	v_lshlrev_b64 v[96:97], 5, v[90:91]
	v_mul_f32_e32 v67, 0x2f800000, v65
	v_lshl_add_u64 v[96:97], s[96:97], 0, v[96:97]
	v_floor_f32_e32 v67, v67
	v_lshl_add_u64 v[96:97], v[96:97], 0, s[50:51]
	v_fmac_f32_e32 v65, 0xcf800000, v67
	global_atomic_add_x2 v[96:97], v[102:103], off
	v_cvt_u32_f32_e32 v102, v65
	v_fma_f32 v65, v73, s91, 0.5
	v_add_f32_e32 v71, v79, v87
	v_ashrrev_i32_e32 v87, 31, v86
	v_cvt_u32_f32_e32 v103, v67
	v_trunc_f32_e32 v65, v65
	v_lshlrev_b64 v[96:97], 5, v[86:87]
	v_mul_f32_e32 v67, 0x2f800000, v65
	v_lshl_add_u64 v[96:97], s[96:97], 0, v[96:97]
	v_floor_f32_e32 v67, v67
	v_lshl_add_u64 v[96:97], v[96:97], 0, s[50:51]
	v_fmac_f32_e32 v65, 0xcf800000, v67
	global_atomic_add_x2 v[96:97], v[102:103], off
	v_cvt_u32_f32_e32 v102, v65
	v_fma_f32 v65, v71, s91, 0.5
	v_ashrrev_i32_e32 v83, 31, v82
	v_cvt_u32_f32_e32 v103, v67
	v_trunc_f32_e32 v65, v65
	v_lshlrev_b64 v[96:97], 5, v[82:83]
	v_mul_f32_e32 v67, 0x2f800000, v65
	v_lshl_add_u64 v[96:97], s[96:97], 0, v[96:97]
	v_floor_f32_e32 v67, v67
	v_lshl_add_u64 v[96:97], v[96:97], 0, s[50:51]
	v_fmac_f32_e32 v65, 0xcf800000, v67
	global_atomic_add_x2 v[96:97], v[102:103], off
	v_cvt_u32_f32_e32 v102, v65
	v_fma_f32 v65, v77, s91, 0.5
	v_ashrrev_i32_e32 v79, 31, v78
	v_cvt_u32_f32_e32 v103, v67
	v_trunc_f32_e32 v65, v65
	v_lshlrev_b64 v[96:97], 5, v[78:79]
	v_mul_f32_e32 v67, 0x2f800000, v65
	v_lshl_add_u64 v[96:97], s[96:97], 0, v[96:97]
	v_floor_f32_e32 v67, v67
	v_lshl_add_u64 v[96:97], v[96:97], 0, s[50:51]
	v_fmac_f32_e32 v65, 0xcf800000, v67
	global_atomic_add_x2 v[96:97], v[102:103], off
	v_cvt_u32_f32_e32 v102, v65
	v_fma_f32 v65, v89, s91, 0.5
	v_ashrrev_i32_e32 v75, 31, v74
	v_cvt_u32_f32_e32 v103, v67
	v_trunc_f32_e32 v65, v65
	v_lshlrev_b64 v[96:97], 5, v[74:75]
	v_mul_f32_e32 v67, 0x2f800000, v65
	v_lshl_add_u64 v[96:97], s[96:97], 0, v[96:97]
	v_floor_f32_e32 v67, v67
	v_lshl_add_u64 v[96:97], v[96:97], 0, s[50:51]
	v_fmac_f32_e32 v65, 0xcf800000, v67
	global_atomic_add_x2 v[96:97], v[102:103], off
	v_ashrrev_i32_e32 v71, 31, v70
	v_cvt_u32_f32_e32 v102, v65
	v_cvt_u32_f32_e32 v103, v67
	v_lshlrev_b64 v[96:97], 5, v[70:71]
	v_lshl_add_u64 v[96:97], s[96:97], 0, v[96:97]
	v_fma_f32 v65, v99, s91, 0.5
	v_lshl_add_u64 v[96:97], v[96:97], 0, s[50:51]
	v_ashrrev_i32_e32 v67, 31, v66
	v_trunc_f32_e32 v65, v65
	global_atomic_add_x2 v[96:97], v[102:103], off
	v_lshlrev_b64 v[96:97], 5, v[66:67]
	v_mul_f32_e32 v67, 0x2f800000, v65
	v_floor_f32_e32 v67, v67
	v_fmac_f32_e32 v65, 0xcf800000, v67
	v_cvt_u32_f32_e32 v102, v65
	v_cvt_u32_f32_e32 v103, v67
	v_lshl_add_u64 v[96:97], s[96:97], 0, v[96:97]
	v_lshl_add_u64 v[96:97], v[96:97], 0, s[50:51]
	global_atomic_add_x2 v[96:97], v[102:103], off
.LBB0_359:
	s_or_b64 exec, exec, s[0:1]
	v_pk_mul_f32 v[96:97], v[58:59], v[164:165]
	v_fma_f32 v58, |v60|, s26, 1.0
	v_rcp_f32_e32 v102, v58
	v_mul_f32_e32 v58, v60, v60
	v_mul_f32_e32 v58, 0xbf38aa3b, v58
	v_exp_f32_e32 v104, v58
	v_fma_f32 v58, |v61|, s26, 1.0
	v_rcp_f32_e32 v103, v58
	v_mul_f32_e32 v58, v61, v61
	v_mul_f32_e32 v58, 0xbf38aa3b, v58
	s_mov_b32 s0, 0xbf3a00e3
	v_exp_f32_e32 v105, v58
	v_mov_b64_e32 v[58:59], s[0:1]
	v_pk_fma_f32 v[106:107], v[102:103], s[24:25], v[58:59] op_sel_hi:[1,0,0]
	v_pk_mul_f32 v[62:63], v[62:63], v[162:163]
	v_pk_fma_f32 v[106:107], v[102:103], v[106:107], s[6:7] op_sel_hi:[1,1,0]
	v_cmp_gt_f32_e32 vcc, 0, v60
	v_pk_fma_f32 v[106:107], v[102:103], v[106:107], s[88:89] op_sel_hi:[1,1,0]
	v_mul_f32_e32 v65, v63, v63
	v_pk_fma_f32 v[106:107], v[102:103], v[106:107], s[90:91] op_sel_hi:[1,1,0]
	v_mul_f32_e32 v65, 0xbf38aa3b, v65
	v_pk_mul_f32 v[102:103], v[102:103], v[106:107]
	v_pk_mul_f32 v[54:55], v[54:55], v[162:163]
	v_pk_mul_f32 v[102:103], v[104:105], v[102:103]
	v_pk_mul_f32 v[50:51], v[50:51], v[164:165]
	v_pk_mul_f32 v[104:105], v[60:61], v[102:103]
	v_pk_fma_f32 v[102:103], v[60:61], v[102:103], v[60:61] neg_lo:[1,0,0] neg_hi:[1,0,0]
	v_fma_f32 v60, |v62|, s26, 1.0
	v_cndmask_b32_e32 v102, v102, v104, vcc
	v_cmp_gt_f32_e32 vcc, 0, v61
	v_mul_f32_e32 v61, v62, v62
	v_mul_f32_e32 v61, 0xbf38aa3b, v61
	v_exp_f32_e32 v104, v61
	v_fma_f32 v61, |v63|, s26, 1.0
	v_rcp_f32_e32 v60, v60
	v_rcp_f32_e32 v61, v61
	v_cndmask_b32_e32 v103, v103, v105, vcc
	v_exp_f32_e32 v105, v65
	v_cmp_gt_f32_e32 vcc, 0, v62
	v_pk_fma_f32 v[106:107], v[60:61], s[24:25], v[58:59] op_sel_hi:[1,0,0]
	v_pk_mul_f32 v[46:47], v[46:47], v[162:163]
	v_pk_fma_f32 v[106:107], v[60:61], v[106:107], s[6:7] op_sel_hi:[1,1,0]
	v_pk_mul_f32 v[42:43], v[42:43], v[164:165]
	v_pk_fma_f32 v[106:107], v[60:61], v[106:107], s[88:89] op_sel_hi:[1,1,0]
	s_mov_b32 s0, 0x140000
	v_pk_fma_f32 v[106:107], v[60:61], v[106:107], s[90:91] op_sel_hi:[1,1,0]
	v_pk_mul_f32 v[38:39], v[38:39], v[162:163]
	v_pk_mul_f32 v[60:61], v[60:61], v[106:107]
	v_pk_mul_f32 v[34:35], v[34:35], v[164:165]
	v_pk_mul_f32 v[60:61], v[104:105], v[60:61]
	s_nop 0
	v_pk_mul_f32 v[104:105], v[62:63], v[60:61]
	v_pk_fma_f32 v[60:61], v[62:63], v[60:61], v[62:63] neg_lo:[1,0,0] neg_hi:[1,0,0]
	s_nop 0
	v_cndmask_b32_e32 v104, v60, v104, vcc
	v_cmp_gt_f32_e32 vcc, 0, v63
	v_fma_f32 v60, |v56|, s26, 1.0
	v_rcp_f32_e32 v60, v60
	v_cndmask_b32_e32 v105, v61, v105, vcc
	v_mul_f32_e32 v61, v56, v56
	v_mul_f32_e32 v61, 0xbf38aa3b, v61
	v_exp_f32_e32 v62, v61
	v_fma_f32 v61, |v57|, s26, 1.0
	v_rcp_f32_e32 v61, v61
	v_mul_f32_e32 v63, v57, v57
	v_mul_f32_e32 v63, 0xbf38aa3b, v63
	v_exp_f32_e32 v63, v63
	v_pk_fma_f32 v[106:107], v[60:61], s[24:25], v[58:59] op_sel_hi:[1,0,0]
	v_cmp_gt_f32_e32 vcc, 0, v56
	v_pk_fma_f32 v[106:107], v[60:61], v[106:107], s[6:7] op_sel_hi:[1,1,0]
	s_nop 0
	v_pk_fma_f32 v[106:107], v[60:61], v[106:107], s[88:89] op_sel_hi:[1,1,0]
	s_nop 0
	v_pk_fma_f32 v[106:107], v[60:61], v[106:107], s[90:91] op_sel_hi:[1,1,0]
	s_nop 0
	v_pk_mul_f32 v[60:61], v[60:61], v[106:107]
	s_nop 0
	v_pk_mul_f32 v[60:61], v[62:63], v[60:61]
	s_nop 0
	v_pk_mul_f32 v[62:63], v[56:57], v[60:61]
	v_pk_fma_f32 v[60:61], v[56:57], v[60:61], v[56:57] neg_lo:[1,0,0] neg_hi:[1,0,0]
	v_fma_f32 v56, |v96|, s26, 1.0
	v_cndmask_b32_e32 v106, v60, v62, vcc
	v_cmp_gt_f32_e32 vcc, 0, v57
	v_mul_f32_e32 v57, v96, v96
	v_mul_f32_e32 v57, 0xbf38aa3b, v57
	v_exp_f32_e32 v60, v57
	v_fma_f32 v57, |v97|, s26, 1.0
	v_rcp_f32_e32 v56, v56
	v_rcp_f32_e32 v57, v57
	v_cndmask_b32_e32 v107, v61, v63, vcc
	v_mul_f32_e32 v61, v97, v97
	v_mul_f32_e32 v61, 0xbf38aa3b, v61
	v_pk_fma_f32 v[62:63], v[56:57], s[24:25], v[58:59] op_sel_hi:[1,0,0]
	v_exp_f32_e32 v61, v61
	v_pk_fma_f32 v[62:63], v[56:57], v[62:63], s[6:7] op_sel_hi:[1,1,0]
	v_cmp_gt_f32_e32 vcc, 0, v96
	v_pk_fma_f32 v[62:63], v[56:57], v[62:63], s[88:89] op_sel_hi:[1,1,0]
	s_nop 0
	v_pk_fma_f32 v[62:63], v[56:57], v[62:63], s[90:91] op_sel_hi:[1,1,0]
	s_nop 0
	v_pk_mul_f32 v[56:57], v[56:57], v[62:63]
	s_nop 0
	v_pk_mul_f32 v[56:57], v[60:61], v[56:57]
	s_nop 0
	v_pk_mul_f32 v[60:61], v[96:97], v[56:57]
	v_pk_fma_f32 v[56:57], v[96:97], v[56:57], v[96:97] neg_lo:[1,0,0] neg_hi:[1,0,0]
	s_nop 0
	v_cndmask_b32_e32 v96, v56, v60, vcc
	v_cmp_gt_f32_e32 vcc, 0, v97
	v_cvt_pk_bf16_f32 v60, v102, v103
	s_nop 1
	v_cndmask_b32_e32 v97, v57, v61, vcc
	v_lshlrev_b64 v[56:57], 13, v[84:85]
	v_lshl_add_u64 v[56:57], s[42:43], 0, v[56:57]
	v_lshl_add_u64 v[56:57], v[80:81], 1, v[56:57]
	v_add_co_u32_e32 v80, vcc, s29, v56
	v_cvt_pk_bf16_f32 v61, v104, v105
	v_cvt_pk_bf16_f32 v62, v106, v107
	v_cvt_pk_bf16_f32 v63, v96, v97
	s_nop 1
	v_addc_co_u32_e32 v81, vcc, 0, v57, vcc
	global_store_dwordx4 v[80:81], v[60:63], off
	v_cmp_gt_f32_e32 vcc, 0, v52
	s_nop 0
	v_mul_f32_e32 v61, v52, v52
	v_mul_f32_e32 v61, 0xbf38aa3b, v61
	v_fma_f32 v60, |v52|, s26, 1.0
	v_exp_f32_e32 v62, v61
	v_fma_f32 v61, |v53|, s26, 1.0
	v_rcp_f32_e32 v60, v60
	v_rcp_f32_e32 v61, v61
	v_mul_f32_e32 v63, v53, v53
	v_mul_f32_e32 v63, 0xbf38aa3b, v63
	v_exp_f32_e32 v63, v63
	v_pk_fma_f32 v[80:81], v[60:61], s[24:25], v[58:59] op_sel_hi:[1,0,0]
	s_nop 0
	v_pk_fma_f32 v[80:81], v[60:61], v[80:81], s[6:7] op_sel_hi:[1,1,0]
	s_nop 0
	v_pk_fma_f32 v[80:81], v[60:61], v[80:81], s[88:89] op_sel_hi:[1,1,0]
	s_nop 0
	v_pk_fma_f32 v[80:81], v[60:61], v[80:81], s[90:91] op_sel_hi:[1,1,0]
	s_nop 0
	v_pk_mul_f32 v[60:61], v[60:61], v[80:81]
	s_nop 0
	v_pk_mul_f32 v[60:61], v[62:63], v[60:61]
	s_nop 0
	v_pk_mul_f32 v[62:63], v[52:53], v[60:61]
	v_pk_fma_f32 v[60:61], v[52:53], v[60:61], v[52:53] neg_lo:[1,0,0] neg_hi:[1,0,0]
	s_nop 0
	v_cndmask_b32_e32 v52, v60, v62, vcc
	v_cmp_gt_f32_e32 vcc, 0, v53
	v_fma_f32 v60, |v54|, s26, 1.0
	v_rcp_f32_e32 v60, v60
	v_cndmask_b32_e32 v53, v61, v63, vcc
	v_mul_f32_e32 v61, v54, v54
	v_mul_f32_e32 v61, 0xbf38aa3b, v61
	v_exp_f32_e32 v62, v61
	v_fma_f32 v61, |v55|, s26, 1.0
	v_rcp_f32_e32 v61, v61
	v_mul_f32_e32 v63, v55, v55
	v_mul_f32_e32 v63, 0xbf38aa3b, v63
	v_exp_f32_e32 v63, v63
	v_pk_fma_f32 v[80:81], v[60:61], s[24:25], v[58:59] op_sel_hi:[1,0,0]
	v_cmp_gt_f32_e32 vcc, 0, v54
	v_pk_fma_f32 v[80:81], v[60:61], v[80:81], s[6:7] op_sel_hi:[1,1,0]
	s_nop 0
	v_pk_fma_f32 v[80:81], v[60:61], v[80:81], s[88:89] op_sel_hi:[1,1,0]
	s_nop 0
	v_pk_fma_f32 v[80:81], v[60:61], v[80:81], s[90:91] op_sel_hi:[1,1,0]
	s_nop 0
	v_pk_mul_f32 v[60:61], v[60:61], v[80:81]
	s_nop 0
	v_pk_mul_f32 v[60:61], v[62:63], v[60:61]
	s_nop 0
	v_pk_mul_f32 v[62:63], v[54:55], v[60:61]
	v_pk_fma_f32 v[60:61], v[54:55], v[60:61], v[54:55] neg_lo:[1,0,0] neg_hi:[1,0,0]
	s_nop 0
	v_cndmask_b32_e32 v54, v60, v62, vcc
	v_cmp_gt_f32_e32 vcc, 0, v55
	v_fma_f32 v60, |v48|, s26, 1.0
	v_rcp_f32_e32 v60, v60
	v_cndmask_b32_e32 v55, v61, v63, vcc
	v_mul_f32_e32 v61, v48, v48
	v_mul_f32_e32 v61, 0xbf38aa3b, v61
	v_exp_f32_e32 v62, v61
	v_fma_f32 v61, |v49|, s26, 1.0
	v_rcp_f32_e32 v61, v61
	v_mul_f32_e32 v63, v49, v49
	v_mul_f32_e32 v63, 0xbf38aa3b, v63
	v_exp_f32_e32 v63, v63
	v_pk_fma_f32 v[80:81], v[60:61], s[24:25], v[58:59] op_sel_hi:[1,0,0]
	v_cmp_gt_f32_e32 vcc, 0, v48
	v_pk_fma_f32 v[80:81], v[60:61], v[80:81], s[6:7] op_sel_hi:[1,1,0]
	s_nop 0
	v_pk_fma_f32 v[80:81], v[60:61], v[80:81], s[88:89] op_sel_hi:[1,1,0]
	s_nop 0
	v_pk_fma_f32 v[80:81], v[60:61], v[80:81], s[90:91] op_sel_hi:[1,1,0]
	s_nop 0
	v_pk_mul_f32 v[60:61], v[60:61], v[80:81]
	s_nop 0
	v_pk_mul_f32 v[60:61], v[62:63], v[60:61]
	s_nop 0
	v_pk_mul_f32 v[62:63], v[48:49], v[60:61]
	v_pk_fma_f32 v[60:61], v[48:49], v[60:61], v[48:49] neg_lo:[1,0,0] neg_hi:[1,0,0]
	v_fma_f32 v48, |v50|, s26, 1.0
	v_cndmask_b32_e32 v60, v60, v62, vcc
	v_cmp_gt_f32_e32 vcc, 0, v49
	v_mul_f32_e32 v49, v50, v50
	v_mul_f32_e32 v49, 0xbf38aa3b, v49
	v_exp_f32_e32 v62, v49
	v_fma_f32 v49, |v51|, s26, 1.0
	v_rcp_f32_e32 v48, v48
	v_rcp_f32_e32 v49, v49
	v_cndmask_b32_e32 v61, v61, v63, vcc
	v_mul_f32_e32 v63, v51, v51
	v_mul_f32_e32 v63, 0xbf38aa3b, v63
	v_pk_fma_f32 v[80:81], v[48:49], s[24:25], v[58:59] op_sel_hi:[1,0,0]
	v_exp_f32_e32 v63, v63
	v_pk_fma_f32 v[80:81], v[48:49], v[80:81], s[6:7] op_sel_hi:[1,1,0]
	v_cmp_gt_f32_e32 vcc, 0, v50
	v_pk_fma_f32 v[80:81], v[48:49], v[80:81], s[88:89] op_sel_hi:[1,1,0]
	s_nop 0
	v_pk_fma_f32 v[80:81], v[48:49], v[80:81], s[90:91] op_sel_hi:[1,1,0]
	s_nop 0
	v_pk_mul_f32 v[48:49], v[48:49], v[80:81]
	s_nop 0
	v_pk_mul_f32 v[48:49], v[62:63], v[48:49]
	s_nop 0
	v_pk_mul_f32 v[62:63], v[50:51], v[48:49]
	v_pk_fma_f32 v[48:49], v[50:51], v[48:49], v[50:51] neg_lo:[1,0,0] neg_hi:[1,0,0]
	s_nop 0
	v_cndmask_b32_e32 v62, v48, v62, vcc
	v_cmp_gt_f32_e32 vcc, 0, v51
	v_cvt_pk_bf16_f32 v48, v52, v53
	s_nop 1
	v_cndmask_b32_e32 v63, v49, v63, vcc
	v_add_co_u32_e32 v80, vcc, s49, v56
	v_cvt_pk_bf16_f32 v49, v54, v55
	v_cvt_pk_bf16_f32 v50, v60, v61
	v_cvt_pk_bf16_f32 v51, v62, v63
	s_nop 1
	v_addc_co_u32_e32 v81, vcc, 0, v57, vcc
	global_store_dwordx4 v[80:81], v[48:51], off
	v_cmp_gt_f32_e32 vcc, 0, v44
	s_nop 0
	v_pk_mul_f32 v[48:49], v[54:55], v[54:55]
	v_pk_mul_f32 v[54:55], v[60:61], v[60:61]
	v_mul_f32_e32 v61, v44, v44
	v_mul_f32_e32 v61, 0xbf38aa3b, v61
	v_pk_mul_f32 v[50:51], v[52:53], v[52:53]
	v_pk_mul_f32 v[52:53], v[62:63], v[62:63]
	v_fma_f32 v60, |v44|, s26, 1.0
	v_exp_f32_e32 v62, v61
	v_fma_f32 v61, |v45|, s26, 1.0
	v_rcp_f32_e32 v60, v60
	v_rcp_f32_e32 v61, v61
	v_mul_f32_e32 v63, v45, v45
	v_mul_f32_e32 v63, 0xbf38aa3b, v63
	v_exp_f32_e32 v63, v63
	v_pk_fma_f32 v[80:81], v[60:61], s[24:25], v[58:59] op_sel_hi:[1,0,0]
	v_pk_fma_f32 v[48:49], v[104:105], v[104:105], v[48:49]
	v_pk_fma_f32 v[80:81], v[60:61], v[80:81], s[6:7] op_sel_hi:[1,1,0]
	v_pk_fma_f32 v[50:51], v[102:103], v[102:103], v[50:51]
	v_pk_fma_f32 v[80:81], v[60:61], v[80:81], s[88:89] op_sel_hi:[1,1,0]
	v_pk_fma_f32 v[52:53], v[96:97], v[96:97], v[52:53]
	v_pk_fma_f32 v[80:81], v[60:61], v[80:81], s[90:91] op_sel_hi:[1,1,0]
	v_pk_fma_f32 v[54:55], v[106:107], v[106:107], v[54:55]
	v_pk_mul_f32 v[60:61], v[60:61], v[80:81]
	s_nop 0
	v_pk_mul_f32 v[60:61], v[62:63], v[60:61]
	s_nop 0
	v_pk_mul_f32 v[62:63], v[44:45], v[60:61]
	v_pk_fma_f32 v[60:61], v[44:45], v[60:61], v[44:45] neg_lo:[1,0,0] neg_hi:[1,0,0]
	s_nop 0
	v_cndmask_b32_e32 v44, v60, v62, vcc
	v_cmp_gt_f32_e32 vcc, 0, v45
	v_fma_f32 v60, |v46|, s26, 1.0
	v_rcp_f32_e32 v60, v60
	v_cndmask_b32_e32 v45, v61, v63, vcc
	v_mul_f32_e32 v61, v46, v46
	v_mul_f32_e32 v61, 0xbf38aa3b, v61
	v_exp_f32_e32 v62, v61
	v_fma_f32 v61, |v47|, s26, 1.0
	v_rcp_f32_e32 v61, v61
	v_mul_f32_e32 v63, v47, v47
	v_mul_f32_e32 v63, 0xbf38aa3b, v63
	v_exp_f32_e32 v63, v63
	v_pk_fma_f32 v[80:81], v[60:61], s[24:25], v[58:59] op_sel_hi:[1,0,0]
	v_cmp_gt_f32_e32 vcc, 0, v46
	v_pk_fma_f32 v[80:81], v[60:61], v[80:81], s[6:7] op_sel_hi:[1,1,0]
	s_nop 0
	v_pk_fma_f32 v[80:81], v[60:61], v[80:81], s[88:89] op_sel_hi:[1,1,0]
	s_nop 0
	v_pk_fma_f32 v[80:81], v[60:61], v[80:81], s[90:91] op_sel_hi:[1,1,0]
	s_nop 0
	v_pk_mul_f32 v[60:61], v[60:61], v[80:81]
	s_nop 0
	v_pk_mul_f32 v[60:61], v[62:63], v[60:61]
	s_nop 0
	v_pk_mul_f32 v[62:63], v[46:47], v[60:61]
	v_pk_fma_f32 v[60:61], v[46:47], v[60:61], v[46:47] neg_lo:[1,0,0] neg_hi:[1,0,0]
	s_nop 0
	v_cndmask_b32_e32 v46, v60, v62, vcc
	v_cmp_gt_f32_e32 vcc, 0, v47
	v_fma_f32 v60, |v40|, s26, 1.0
	v_rcp_f32_e32 v60, v60
	v_cndmask_b32_e32 v47, v61, v63, vcc
	v_mul_f32_e32 v61, v40, v40
	v_mul_f32_e32 v61, 0xbf38aa3b, v61
	v_exp_f32_e32 v62, v61
	v_fma_f32 v61, |v41|, s26, 1.0
	v_rcp_f32_e32 v61, v61
	v_mul_f32_e32 v63, v41, v41
	v_mul_f32_e32 v63, 0xbf38aa3b, v63
	v_exp_f32_e32 v63, v63
	v_pk_fma_f32 v[80:81], v[60:61], s[24:25], v[58:59] op_sel_hi:[1,0,0]
	v_cmp_gt_f32_e32 vcc, 0, v40
	v_pk_fma_f32 v[80:81], v[60:61], v[80:81], s[6:7] op_sel_hi:[1,1,0]
	s_nop 0
	v_pk_fma_f32 v[80:81], v[60:61], v[80:81], s[88:89] op_sel_hi:[1,1,0]
	s_nop 0
	v_pk_fma_f32 v[80:81], v[60:61], v[80:81], s[90:91] op_sel_hi:[1,1,0]
	s_nop 0
	v_pk_mul_f32 v[60:61], v[60:61], v[80:81]
	s_nop 0
	v_pk_mul_f32 v[60:61], v[62:63], v[60:61]
	s_nop 0
	v_pk_mul_f32 v[62:63], v[40:41], v[60:61]
	v_pk_fma_f32 v[60:61], v[40:41], v[60:61], v[40:41] neg_lo:[1,0,0] neg_hi:[1,0,0]
	v_fma_f32 v40, |v42|, s26, 1.0
	v_cndmask_b32_e32 v60, v60, v62, vcc
	v_cmp_gt_f32_e32 vcc, 0, v41
	v_mul_f32_e32 v41, v42, v42
	v_mul_f32_e32 v41, 0xbf38aa3b, v41
	v_exp_f32_e32 v62, v41
	v_fma_f32 v41, |v43|, s26, 1.0
	v_rcp_f32_e32 v40, v40
	v_rcp_f32_e32 v41, v41
	v_cndmask_b32_e32 v61, v61, v63, vcc
	v_mul_f32_e32 v63, v43, v43
	v_mul_f32_e32 v63, 0xbf38aa3b, v63
	v_pk_fma_f32 v[80:81], v[40:41], s[24:25], v[58:59] op_sel_hi:[1,0,0]
	v_exp_f32_e32 v63, v63
	v_pk_fma_f32 v[80:81], v[40:41], v[80:81], s[6:7] op_sel_hi:[1,1,0]
	v_cmp_gt_f32_e32 vcc, 0, v42
	v_pk_fma_f32 v[80:81], v[40:41], v[80:81], s[88:89] op_sel_hi:[1,1,0]
	s_nop 0
	v_pk_fma_f32 v[80:81], v[40:41], v[80:81], s[90:91] op_sel_hi:[1,1,0]
	s_nop 0
	v_pk_mul_f32 v[40:41], v[40:41], v[80:81]
	s_nop 0
	v_pk_mul_f32 v[40:41], v[62:63], v[40:41]
	s_nop 0
	v_pk_mul_f32 v[62:63], v[42:43], v[40:41]
	v_pk_fma_f32 v[40:41], v[42:43], v[40:41], v[42:43] neg_lo:[1,0,0] neg_hi:[1,0,0]
	s_nop 0
	v_cndmask_b32_e32 v62, v40, v62, vcc
	v_cmp_gt_f32_e32 vcc, 0, v43
	v_cvt_pk_bf16_f32 v40, v44, v45
	s_nop 1
	v_cndmask_b32_e32 v63, v41, v63, vcc
	v_add_co_u32_e32 v80, vcc, s0, v56
	v_cvt_pk_bf16_f32 v41, v46, v47
	v_cvt_pk_bf16_f32 v42, v60, v61
	v_cvt_pk_bf16_f32 v43, v62, v63
	s_mov_b32 s0, 0x160000
	s_nop 0
	v_addc_co_u32_e32 v81, vcc, 0, v57, vcc
	global_store_dwordx4 v[80:81], v[40:43], off
	v_cmp_gt_f32_e32 vcc, 0, v36
	s_nop 0
	v_pk_fma_f32 v[40:41], v[46:47], v[46:47], v[48:49]
	v_mul_f32_e32 v49, v36, v36
	v_mul_f32_e32 v49, 0xbf38aa3b, v49
	v_pk_fma_f32 v[42:43], v[44:45], v[44:45], v[50:51]
	v_fma_f32 v48, |v36|, s26, 1.0
	v_exp_f32_e32 v50, v49
	v_fma_f32 v49, |v37|, s26, 1.0
	v_rcp_f32_e32 v48, v48
	v_rcp_f32_e32 v49, v49
	v_mul_f32_e32 v51, v37, v37
	v_pk_fma_f32 v[44:45], v[62:63], v[62:63], v[52:53]
	v_mul_f32_e32 v51, 0xbf38aa3b, v51
	v_pk_fma_f32 v[52:53], v[48:49], s[24:25], v[58:59] op_sel_hi:[1,0,0]
	v_exp_f32_e32 v51, v51
	v_pk_fma_f32 v[52:53], v[48:49], v[52:53], s[6:7] op_sel_hi:[1,1,0]
	v_pk_fma_f32 v[46:47], v[60:61], v[60:61], v[54:55]
	v_pk_fma_f32 v[52:53], v[48:49], v[52:53], s[88:89] op_sel_hi:[1,1,0]
	s_nop 0
	v_pk_fma_f32 v[52:53], v[48:49], v[52:53], s[90:91] op_sel_hi:[1,1,0]
	s_nop 0
	v_pk_mul_f32 v[48:49], v[48:49], v[52:53]
	s_nop 0
	v_pk_mul_f32 v[48:49], v[50:51], v[48:49]
	s_nop 0
	v_pk_mul_f32 v[50:51], v[36:37], v[48:49]
	v_pk_fma_f32 v[48:49], v[36:37], v[48:49], v[36:37] neg_lo:[1,0,0] neg_hi:[1,0,0]
	s_nop 0
	v_cndmask_b32_e32 v36, v48, v50, vcc
	v_cmp_gt_f32_e32 vcc, 0, v37
	v_fma_f32 v48, |v38|, s26, 1.0
	v_rcp_f32_e32 v48, v48
	v_cndmask_b32_e32 v37, v49, v51, vcc
	v_mul_f32_e32 v49, v38, v38
	v_mul_f32_e32 v49, 0xbf38aa3b, v49
	v_exp_f32_e32 v50, v49
	v_fma_f32 v49, |v39|, s26, 1.0
	v_rcp_f32_e32 v49, v49
	v_mul_f32_e32 v51, v39, v39
	v_mul_f32_e32 v51, 0xbf38aa3b, v51
	v_exp_f32_e32 v51, v51
	v_pk_fma_f32 v[52:53], v[48:49], s[24:25], v[58:59] op_sel_hi:[1,0,0]
	v_cmp_gt_f32_e32 vcc, 0, v38
	v_pk_fma_f32 v[52:53], v[48:49], v[52:53], s[6:7] op_sel_hi:[1,1,0]
	s_nop 0
	v_pk_fma_f32 v[52:53], v[48:49], v[52:53], s[88:89] op_sel_hi:[1,1,0]
	s_nop 0
	v_pk_fma_f32 v[52:53], v[48:49], v[52:53], s[90:91] op_sel_hi:[1,1,0]
	s_nop 0
	v_pk_mul_f32 v[48:49], v[48:49], v[52:53]
	s_nop 0
	v_pk_mul_f32 v[48:49], v[50:51], v[48:49]
	s_nop 0
	v_pk_mul_f32 v[50:51], v[38:39], v[48:49]
	v_pk_fma_f32 v[48:49], v[38:39], v[48:49], v[38:39] neg_lo:[1,0,0] neg_hi:[1,0,0]
	s_nop 0
	v_cndmask_b32_e32 v38, v48, v50, vcc
	v_cmp_gt_f32_e32 vcc, 0, v39
	v_fma_f32 v48, |v32|, s26, 1.0
	v_rcp_f32_e32 v48, v48
	v_cndmask_b32_e32 v39, v49, v51, vcc
	v_mul_f32_e32 v49, v32, v32
	v_mul_f32_e32 v49, 0xbf38aa3b, v49
	v_exp_f32_e32 v50, v49
	v_fma_f32 v49, |v33|, s26, 1.0
	v_rcp_f32_e32 v49, v49
	v_mul_f32_e32 v51, v33, v33
	v_mul_f32_e32 v51, 0xbf38aa3b, v51
	v_exp_f32_e32 v51, v51
	v_pk_fma_f32 v[52:53], v[48:49], s[24:25], v[58:59] op_sel_hi:[1,0,0]
	v_cmp_gt_f32_e32 vcc, 0, v32
	v_pk_fma_f32 v[52:53], v[48:49], v[52:53], s[6:7] op_sel_hi:[1,1,0]
	s_nop 0
	v_pk_fma_f32 v[52:53], v[48:49], v[52:53], s[88:89] op_sel_hi:[1,1,0]
	s_nop 0
	v_pk_fma_f32 v[52:53], v[48:49], v[52:53], s[90:91] op_sel_hi:[1,1,0]
	s_nop 0
	v_pk_mul_f32 v[48:49], v[48:49], v[52:53]
	s_nop 0
	v_pk_mul_f32 v[48:49], v[50:51], v[48:49]
	s_nop 0
	v_pk_mul_f32 v[50:51], v[32:33], v[48:49]
	v_pk_fma_f32 v[48:49], v[32:33], v[48:49], v[32:33] neg_lo:[1,0,0] neg_hi:[1,0,0]
	v_fma_f32 v32, |v34|, s26, 1.0
	v_cndmask_b32_e32 v48, v48, v50, vcc
	v_cmp_gt_f32_e32 vcc, 0, v33
	v_mul_f32_e32 v33, v34, v34
	v_mul_f32_e32 v33, 0xbf38aa3b, v33
	v_exp_f32_e32 v50, v33
	v_fma_f32 v33, |v35|, s26, 1.0
	v_rcp_f32_e32 v32, v32
	v_rcp_f32_e32 v33, v33
	v_cndmask_b32_e32 v49, v49, v51, vcc
	v_mul_f32_e32 v51, v35, v35
	v_mul_f32_e32 v51, 0xbf38aa3b, v51
	v_pk_fma_f32 v[52:53], v[32:33], s[24:25], v[58:59] op_sel_hi:[1,0,0]
	v_exp_f32_e32 v51, v51
	v_pk_fma_f32 v[52:53], v[32:33], v[52:53], s[6:7] op_sel_hi:[1,1,0]
	v_cmp_gt_f32_e32 vcc, 0, v34
	v_pk_fma_f32 v[52:53], v[32:33], v[52:53], s[88:89] op_sel_hi:[1,1,0]
	s_nop 0
	v_pk_fma_f32 v[52:53], v[32:33], v[52:53], s[90:91] op_sel_hi:[1,1,0]
	s_nop 0
	v_pk_mul_f32 v[32:33], v[32:33], v[52:53]
	s_nop 0
	v_pk_mul_f32 v[32:33], v[50:51], v[32:33]
	s_nop 0
	v_pk_mul_f32 v[50:51], v[34:35], v[32:33]
	v_pk_fma_f32 v[32:33], v[34:35], v[32:33], v[34:35] neg_lo:[1,0,0] neg_hi:[1,0,0]
	s_nop 0
	v_cndmask_b32_e32 v50, v32, v50, vcc
	v_cmp_gt_f32_e32 vcc, 0, v35
	v_cvt_pk_bf16_f32 v32, v36, v37
	s_nop 1
	v_cndmask_b32_e32 v51, v33, v51, vcc
	v_add_co_u32_e32 v52, vcc, s0, v56
	v_cvt_pk_bf16_f32 v33, v38, v39
	v_cvt_pk_bf16_f32 v34, v48, v49
	v_cvt_pk_bf16_f32 v35, v50, v51
	v_pk_fma_f32 v[50:51], v[50:51], v[50:51], v[44:45]
	s_nop 0
	v_addc_co_u32_e32 v53, vcc, 0, v57, vcc
	global_store_dwordx4 v[52:53], v[32:35], off
	v_pk_fma_f32 v[52:53], v[38:39], v[38:39], v[40:41]
	v_pk_fma_f32 v[38:39], v[48:49], v[48:49], v[46:47]
	v_pk_fma_f32 v[34:35], v[36:37], v[36:37], v[42:43]
	v_add_f32_dpp v42, v50, v50 row_ror:8 row_mask:0xf bank_mask:0xf bound_ctrl:1
	v_add_f32_dpp v44, v53, v53 row_ror:8 row_mask:0xf bank_mask:0xf bound_ctrl:1
	v_add_f32_dpp v32, v34, v34 row_ror:8 row_mask:0xf bank_mask:0xf bound_ctrl:1
	v_add_f32_dpp v34, v38, v38 row_ror:8 row_mask:0xf bank_mask:0xf bound_ctrl:1
	v_add_f32_dpp v35, v35, v35 row_ror:8 row_mask:0xf bank_mask:0xf bound_ctrl:1
	v_add_f32_dpp v38, v39, v39 row_ror:8 row_mask:0xf bank_mask:0xf bound_ctrl:1
	v_add_f32_dpp v39, v52, v52 row_ror:8 row_mask:0xf bank_mask:0xf bound_ctrl:1
	v_add_f32_dpp v46, v51, v51 row_ror:8 row_mask:0xf bank_mask:0xf bound_ctrl:1
	v_add_f32_dpp v32, v32, v32 row_ror:4 row_mask:0xf bank_mask:0xf bound_ctrl:1
	v_add_f32_dpp v34, v34, v34 row_ror:4 row_mask:0xf bank_mask:0xf bound_ctrl:1
	v_add_f32_dpp v35, v35, v35 row_ror:4 row_mask:0xf bank_mask:0xf bound_ctrl:1
	v_add_f32_dpp v38, v38, v38 row_ror:4 row_mask:0xf bank_mask:0xf bound_ctrl:1
	v_add_f32_dpp v39, v39, v39 row_ror:4 row_mask:0xf bank_mask:0xf bound_ctrl:1
	v_add_f32_dpp v42, v42, v42 row_ror:4 row_mask:0xf bank_mask:0xf bound_ctrl:1
	v_add_f32_dpp v44, v44, v44 row_ror:4 row_mask:0xf bank_mask:0xf bound_ctrl:1
	v_add_f32_dpp v46, v46, v46 row_ror:4 row_mask:0xf bank_mask:0xf bound_ctrl:1
	v_add_f32_dpp v32, v32, v32 row_ror:2 row_mask:0xf bank_mask:0xf bound_ctrl:1
	v_mov_b32_e32 v33, v145
	v_add_f32_dpp v34, v34, v34 row_ror:2 row_mask:0xf bank_mask:0xf bound_ctrl:1
	v_mov_b32_e32 v36, v145
	v_add_f32_dpp v35, v35, v35 row_ror:2 row_mask:0xf bank_mask:0xf bound_ctrl:1
	v_mov_b32_e32 v37, v145
	v_add_f32_dpp v38, v38, v38 row_ror:2 row_mask:0xf bank_mask:0xf bound_ctrl:1
	v_mov_b32_e32 v40, v145
	v_add_f32_dpp v39, v39, v39 row_ror:2 row_mask:0xf bank_mask:0xf bound_ctrl:1
	v_mov_b32_e32 v41, v145
	v_add_f32_dpp v42, v42, v42 row_ror:2 row_mask:0xf bank_mask:0xf bound_ctrl:1
	v_mov_b32_e32 v43, v145
	v_add_f32_dpp v44, v44, v44 row_ror:2 row_mask:0xf bank_mask:0xf bound_ctrl:1
	v_mov_b32_e32 v45, v145
	v_add_f32_dpp v46, v46, v46 row_ror:2 row_mask:0xf bank_mask:0xf bound_ctrl:1
	v_mov_b32_e32 v47, v145
	v_mov_b32_dpp v33, v32 row_ror:1 row_mask:0xf bank_mask:0xf
	v_mov_b32_dpp v36, v34 row_ror:1 row_mask:0xf bank_mask:0xf
	v_mov_b32_dpp v37, v35 row_ror:1 row_mask:0xf bank_mask:0xf
	v_mov_b32_dpp v40, v38 row_ror:1 row_mask:0xf bank_mask:0xf
	v_mov_b32_dpp v41, v39 row_ror:1 row_mask:0xf bank_mask:0xf
	v_mov_b32_dpp v43, v42 row_ror:1 row_mask:0xf bank_mask:0xf
	v_mov_b32_dpp v45, v44 row_ror:1 row_mask:0xf bank_mask:0xf
	v_mov_b32_dpp v47, v46 row_ror:1 row_mask:0xf bank_mask:0xf
	s_and_saveexec_b64 s[0:1], s[38:39]
	s_cbranch_execz .LBB0_361
	v_add_f32_e32 v36, v34, v36
	v_add_f32_e32 v34, v32, v33
	v_fma_f32 v34, v34, s91, 0.5
	v_trunc_f32_e32 v34, v34
	v_add_f32_e32 v37, v35, v37
	v_mul_f32_e32 v35, 0x2f800000, v34
	v_floor_f32_e32 v35, v35
	v_fmac_f32_e32 v34, 0xcf800000, v35
	v_cvt_u32_f32_e32 v34, v34
	v_cvt_u32_f32_e32 v35, v35
	s_lshl_b64 s[50:51], s[98:99], 3
	v_lshl_add_u64 v[32:33], v[100:101], 0, s[50:51]
	v_ashrrev_i32_e32 v99, 31, v98
	global_atomic_add_x2 v[32:33], v[34:35], off offset:8
	v_fma_f32 v34, v36, s91, 0.5
	v_trunc_f32_e32 v34, v34
	v_mul_f32_e32 v35, 0x2f800000, v34
	v_floor_f32_e32 v35, v35
	v_fmac_f32_e32 v34, 0xcf800000, v35
	v_cvt_u32_f32_e32 v34, v34
	v_cvt_u32_f32_e32 v35, v35
	v_lshlrev_b64 v[32:33], 5, v[98:99]
	v_lshl_add_u64 v[32:33], s[96:97], 0, v[32:33]
	v_lshl_add_u64 v[32:33], v[32:33], 0, s[50:51]
	global_atomic_add_x2 v[32:33], v[34:35], off offset:8
	v_fma_f32 v34, v37, s91, 0.5
	v_trunc_f32_e32 v34, v34
	v_mul_f32_e32 v35, 0x2f800000, v34
	v_floor_f32_e32 v35, v35
	v_fmac_f32_e32 v34, 0xcf800000, v35
	v_ashrrev_i32_e32 v93, 31, v92
	v_cvt_u32_f32_e32 v34, v34
	v_cvt_u32_f32_e32 v35, v35
	v_lshlrev_b64 v[32:33], 5, v[92:93]
	v_lshl_add_u64 v[32:33], s[96:97], 0, v[32:33]
	v_add_f32_e32 v38, v38, v40
	v_lshl_add_u64 v[32:33], v[32:33], 0, s[50:51]
	global_atomic_add_x2 v[32:33], v[34:35], off offset:8
	v_fma_f32 v34, v38, s91, 0.5
	v_trunc_f32_e32 v34, v34
	v_mul_f32_e32 v35, 0x2f800000, v34
	v_floor_f32_e32 v35, v35
	v_fmac_f32_e32 v34, 0xcf800000, v35
	v_ashrrev_i32_e32 v89, 31, v88
	v_cvt_u32_f32_e32 v34, v34
	v_cvt_u32_f32_e32 v35, v35
	v_lshlrev_b64 v[32:33], 5, v[88:89]
	v_lshl_add_u64 v[32:33], s[96:97], 0, v[32:33]
	v_add_f32_e32 v39, v39, v41
	v_lshl_add_u64 v[32:33], v[32:33], 0, s[50:51]
	global_atomic_add_x2 v[32:33], v[34:35], off offset:8
	v_fma_f32 v34, v39, s91, 0.5
	v_trunc_f32_e32 v34, v34
	v_mul_f32_e32 v35, 0x2f800000, v34
	v_floor_f32_e32 v35, v35
	v_fmac_f32_e32 v34, 0xcf800000, v35
	v_ashrrev_i32_e32 v77, 31, v76
	v_cvt_u32_f32_e32 v34, v34
	v_cvt_u32_f32_e32 v35, v35
	v_lshlrev_b64 v[32:33], 5, v[76:77]
	v_lshl_add_u64 v[32:33], s[96:97], 0, v[32:33]
	v_add_f32_e32 v40, v42, v43
	v_lshl_add_u64 v[32:33], v[32:33], 0, s[50:51]
	global_atomic_add_x2 v[32:33], v[34:35], off offset:8
	v_fma_f32 v34, v40, s91, 0.5
	v_trunc_f32_e32 v34, v34
	v_mul_f32_e32 v35, 0x2f800000, v34
	v_floor_f32_e32 v35, v35
	v_fmac_f32_e32 v34, 0xcf800000, v35
	v_ashrrev_i32_e32 v73, 31, v72
	v_cvt_u32_f32_e32 v34, v34
	v_cvt_u32_f32_e32 v35, v35
	v_lshlrev_b64 v[32:33], 5, v[72:73]
	v_lshl_add_u64 v[32:33], s[96:97], 0, v[32:33]
	v_add_f32_e32 v42, v44, v45
	v_lshl_add_u64 v[32:33], v[32:33], 0, s[50:51]
	global_atomic_add_x2 v[32:33], v[34:35], off offset:8
	v_fma_f32 v34, v42, s91, 0.5
	v_trunc_f32_e32 v34, v34
	v_mul_f32_e32 v35, 0x2f800000, v34
	v_floor_f32_e32 v35, v35
	v_fmac_f32_e32 v34, 0xcf800000, v35
	v_ashrrev_i32_e32 v69, 31, v68
	v_cvt_u32_f32_e32 v34, v34
	v_cvt_u32_f32_e32 v35, v35
	v_lshlrev_b64 v[32:33], 5, v[68:69]
	v_lshl_add_u64 v[32:33], s[96:97], 0, v[32:33]
	v_add_f32_e32 v46, v46, v47
	v_lshl_add_u64 v[32:33], v[32:33], 0, s[50:51]
	global_atomic_add_x2 v[32:33], v[34:35], off offset:8
	v_fma_f32 v34, v46, s91, 0.5
	v_trunc_f32_e32 v34, v34
	v_mul_f32_e32 v35, 0x2f800000, v34
	v_floor_f32_e32 v35, v35
	v_fmac_f32_e32 v34, 0xcf800000, v35
	v_ashrrev_i32_e32 v65, 31, v64
	v_cvt_u32_f32_e32 v34, v34
	v_cvt_u32_f32_e32 v35, v35
	v_lshlrev_b64 v[32:33], 5, v[64:65]
	v_lshl_add_u64 v[32:33], s[96:97], 0, v[32:33]
	v_lshl_add_u64 v[32:33], v[32:33], 0, s[50:51]
	global_atomic_add_x2 v[32:33], v[34:35], off offset:8
.LBB0_361:
	s_or_b64 exec, exec, s[0:1]
	v_pk_mul_f32 v[40:41], v[26:27], v[128:129]
	v_fma_f32 v26, |v28|, s26, 1.0
	v_rcp_f32_e32 v42, v26
	v_mul_f32_e32 v26, v28, v28
	s_mov_b64 s[0:1], 0x100000
	v_mul_f32_e32 v26, 0xbf38aa3b, v26
	v_lshl_add_u64 v[38:39], v[56:57], 0, s[0:1]
	s_mov_b64 s[0:1], 0x120000
	v_exp_f32_e32 v44, v26
	v_fma_f32 v26, |v29|, s26, 1.0
	v_lshl_add_u64 v[36:37], v[56:57], 0, s[0:1]
	s_mov_b64 s[0:1], 0x140000
	v_rcp_f32_e32 v43, v26
	v_lshl_add_u64 v[34:35], v[56:57], 0, s[0:1]
	s_mov_b64 s[0:1], 0x160000
	v_mul_f32_e32 v26, v29, v29
	v_lshl_add_u64 v[32:33], v[56:57], 0, s[0:1]
	v_mul_f32_e32 v26, 0xbf38aa3b, v26
	s_mov_b32 s0, 0xbf3a00e3
	v_exp_f32_e32 v45, v26
	v_mov_b64_e32 v[26:27], s[0:1]
	v_pk_fma_f32 v[46:47], v[42:43], s[24:25], v[26:27] op_sel_hi:[1,0,0]
	v_pk_mul_f32 v[30:31], v[30:31], v[136:137]
	v_pk_fma_f32 v[46:47], v[42:43], v[46:47], s[6:7] op_sel_hi:[1,1,0]
	v_cmp_gt_f32_e32 vcc, 0, v28
	v_pk_fma_f32 v[46:47], v[42:43], v[46:47], s[88:89] op_sel_hi:[1,1,0]
	v_pk_mul_f32 v[22:23], v[22:23], v[136:137]
	v_pk_fma_f32 v[46:47], v[42:43], v[46:47], s[90:91] op_sel_hi:[1,1,0]
	v_pk_mul_f32 v[18:19], v[18:19], v[128:129]
	v_pk_mul_f32 v[42:43], v[42:43], v[46:47]
	v_pk_mul_f32 v[14:15], v[14:15], v[136:137]
	v_pk_mul_f32 v[42:43], v[44:45], v[42:43]
	v_pk_mul_f32 v[10:11], v[10:11], v[128:129]
	v_pk_mul_f32 v[44:45], v[28:29], v[42:43]
	v_pk_fma_f32 v[42:43], v[28:29], v[42:43], v[28:29] neg_lo:[1,0,0] neg_hi:[1,0,0]
	v_fma_f32 v28, |v30|, s26, 1.0
	v_cndmask_b32_e32 v42, v42, v44, vcc
	v_cmp_gt_f32_e32 vcc, 0, v29
	v_mul_f32_e32 v29, v30, v30
	v_mul_f32_e32 v29, 0xbf38aa3b, v29
	v_exp_f32_e32 v44, v29
	v_fma_f32 v29, |v31|, s26, 1.0
	v_rcp_f32_e32 v28, v28
	v_rcp_f32_e32 v29, v29
	v_cndmask_b32_e32 v43, v43, v45, vcc
	v_mul_f32_e32 v45, v31, v31
	v_mul_f32_e32 v45, 0xbf38aa3b, v45
	v_pk_fma_f32 v[46:47], v[28:29], s[24:25], v[26:27] op_sel_hi:[1,0,0]
	v_exp_f32_e32 v45, v45
	v_pk_fma_f32 v[46:47], v[28:29], v[46:47], s[6:7] op_sel_hi:[1,1,0]
	v_cmp_gt_f32_e32 vcc, 0, v30
	v_pk_fma_f32 v[46:47], v[28:29], v[46:47], s[88:89] op_sel_hi:[1,1,0]
	v_pk_mul_f32 v[6:7], v[6:7], v[136:137]
	v_pk_fma_f32 v[46:47], v[28:29], v[46:47], s[90:91] op_sel_hi:[1,1,0]
	v_pk_mul_f32 v[2:3], v[2:3], v[128:129]
	v_pk_mul_f32 v[28:29], v[28:29], v[46:47]
	s_nop 0
	v_pk_mul_f32 v[28:29], v[44:45], v[28:29]
	s_nop 0
	v_pk_mul_f32 v[44:45], v[30:31], v[28:29]
	v_pk_fma_f32 v[28:29], v[30:31], v[28:29], v[30:31] neg_lo:[1,0,0] neg_hi:[1,0,0]
	s_nop 0
	v_cndmask_b32_e32 v44, v28, v44, vcc
	v_cmp_gt_f32_e32 vcc, 0, v31
	v_fma_f32 v28, |v24|, s26, 1.0
	v_rcp_f32_e32 v28, v28
	v_cndmask_b32_e32 v45, v29, v45, vcc
	v_mul_f32_e32 v29, v24, v24
	v_mul_f32_e32 v29, 0xbf38aa3b, v29
	v_exp_f32_e32 v30, v29
	v_fma_f32 v29, |v25|, s26, 1.0
	v_rcp_f32_e32 v29, v29
	v_mul_f32_e32 v31, v25, v25
	v_mul_f32_e32 v31, 0xbf38aa3b, v31
	v_exp_f32_e32 v31, v31
	v_pk_fma_f32 v[46:47], v[28:29], s[24:25], v[26:27] op_sel_hi:[1,0,0]
	v_cmp_gt_f32_e32 vcc, 0, v24
	v_pk_fma_f32 v[46:47], v[28:29], v[46:47], s[6:7] op_sel_hi:[1,1,0]
	s_nop 0
	v_pk_fma_f32 v[46:47], v[28:29], v[46:47], s[88:89] op_sel_hi:[1,1,0]
	s_nop 0
	v_pk_fma_f32 v[46:47], v[28:29], v[46:47], s[90:91] op_sel_hi:[1,1,0]
	s_nop 0
	v_pk_mul_f32 v[28:29], v[28:29], v[46:47]
	s_nop 0
	v_pk_mul_f32 v[28:29], v[30:31], v[28:29]
	s_nop 0
	v_pk_mul_f32 v[30:31], v[24:25], v[28:29]
	v_pk_fma_f32 v[28:29], v[24:25], v[28:29], v[24:25] neg_lo:[1,0,0] neg_hi:[1,0,0]
	s_nop 0
	v_cndmask_b32_e32 v24, v28, v30, vcc
	v_cmp_gt_f32_e32 vcc, 0, v25
	v_fma_f32 v28, |v40|, s26, 1.0
	v_rcp_f32_e32 v28, v28
	v_cndmask_b32_e32 v25, v29, v31, vcc
	v_mul_f32_e32 v29, v40, v40
	v_mul_f32_e32 v29, 0xbf38aa3b, v29
	v_exp_f32_e32 v30, v29
	v_fma_f32 v29, |v41|, s26, 1.0
	v_rcp_f32_e32 v29, v29
	v_mul_f32_e32 v31, v41, v41
	v_mul_f32_e32 v31, 0xbf38aa3b, v31
	v_exp_f32_e32 v31, v31
	v_pk_fma_f32 v[46:47], v[28:29], s[24:25], v[26:27] op_sel_hi:[1,0,0]
	v_cmp_gt_f32_e32 vcc, 0, v40
	v_pk_fma_f32 v[46:47], v[28:29], v[46:47], s[6:7] op_sel_hi:[1,1,0]
	s_nop 0
	v_pk_fma_f32 v[46:47], v[28:29], v[46:47], s[88:89] op_sel_hi:[1,1,0]
	s_nop 0
	v_pk_fma_f32 v[46:47], v[28:29], v[46:47], s[90:91] op_sel_hi:[1,1,0]
	s_nop 0
	v_pk_mul_f32 v[28:29], v[28:29], v[46:47]
	s_nop 0
	v_pk_mul_f32 v[28:29], v[30:31], v[28:29]
	s_nop 0
	v_pk_mul_f32 v[30:31], v[40:41], v[28:29]
	v_pk_fma_f32 v[28:29], v[40:41], v[28:29], v[40:41] neg_lo:[1,0,0] neg_hi:[1,0,0]
	s_nop 0
	v_cndmask_b32_e32 v40, v28, v30, vcc
	v_cmp_gt_f32_e32 vcc, 0, v41
	v_cvt_pk_bf16_f32 v28, v42, v43
	s_nop 1
	v_cndmask_b32_e32 v41, v29, v31, vcc
	v_cvt_pk_bf16_f32 v29, v44, v45
	v_cvt_pk_bf16_f32 v30, v24, v25
	v_cvt_pk_bf16_f32 v31, v40, v41
	global_store_dwordx4 v[38:39], v[28:31], off offset:256
	v_cmp_gt_f32_e32 vcc, 0, v20
	s_nop 0
	v_mul_f32_e32 v29, v20, v20
	v_mul_f32_e32 v29, 0xbf38aa3b, v29
	v_fma_f32 v28, |v20|, s26, 1.0
	v_exp_f32_e32 v30, v29
	v_fma_f32 v29, |v21|, s26, 1.0
	v_rcp_f32_e32 v28, v28
	v_rcp_f32_e32 v29, v29
	v_mul_f32_e32 v31, v21, v21
	v_mul_f32_e32 v31, 0xbf38aa3b, v31
	v_exp_f32_e32 v31, v31
	v_pk_fma_f32 v[38:39], v[28:29], s[24:25], v[26:27] op_sel_hi:[1,0,0]
	s_nop 0
	v_pk_fma_f32 v[38:39], v[28:29], v[38:39], s[6:7] op_sel_hi:[1,1,0]
	s_nop 0
	v_pk_fma_f32 v[38:39], v[28:29], v[38:39], s[88:89] op_sel_hi:[1,1,0]
	s_nop 0
	v_pk_fma_f32 v[38:39], v[28:29], v[38:39], s[90:91] op_sel_hi:[1,1,0]
	s_nop 0
	v_pk_mul_f32 v[28:29], v[28:29], v[38:39]
	s_nop 0
	v_pk_mul_f32 v[28:29], v[30:31], v[28:29]
	s_nop 0
	v_pk_mul_f32 v[30:31], v[20:21], v[28:29]
	v_pk_fma_f32 v[28:29], v[20:21], v[28:29], v[20:21] neg_lo:[1,0,0] neg_hi:[1,0,0]
	s_nop 0
	v_cndmask_b32_e32 v20, v28, v30, vcc
	v_cmp_gt_f32_e32 vcc, 0, v21
	v_fma_f32 v28, |v22|, s26, 1.0
	v_rcp_f32_e32 v28, v28
	v_cndmask_b32_e32 v21, v29, v31, vcc
	v_mul_f32_e32 v29, v22, v22
	v_mul_f32_e32 v29, 0xbf38aa3b, v29
	v_exp_f32_e32 v30, v29
	v_fma_f32 v29, |v23|, s26, 1.0
	v_rcp_f32_e32 v29, v29
	v_mul_f32_e32 v31, v23, v23
	v_mul_f32_e32 v31, 0xbf38aa3b, v31
	v_exp_f32_e32 v31, v31
	v_pk_fma_f32 v[38:39], v[28:29], s[24:25], v[26:27] op_sel_hi:[1,0,0]
	v_cmp_gt_f32_e32 vcc, 0, v22
	v_pk_fma_f32 v[38:39], v[28:29], v[38:39], s[6:7] op_sel_hi:[1,1,0]
	s_nop 0
	v_pk_fma_f32 v[38:39], v[28:29], v[38:39], s[88:89] op_sel_hi:[1,1,0]
	s_nop 0
	v_pk_fma_f32 v[38:39], v[28:29], v[38:39], s[90:91] op_sel_hi:[1,1,0]
	s_nop 0
	v_pk_mul_f32 v[28:29], v[28:29], v[38:39]
	s_nop 0
	v_pk_mul_f32 v[28:29], v[30:31], v[28:29]
	s_nop 0
	v_pk_mul_f32 v[30:31], v[22:23], v[28:29]
	v_pk_fma_f32 v[28:29], v[22:23], v[28:29], v[22:23] neg_lo:[1,0,0] neg_hi:[1,0,0]
	s_nop 0
	v_cndmask_b32_e32 v22, v28, v30, vcc
	v_cmp_gt_f32_e32 vcc, 0, v23
	v_fma_f32 v28, |v16|, s26, 1.0
	v_rcp_f32_e32 v28, v28
	v_cndmask_b32_e32 v23, v29, v31, vcc
	v_mul_f32_e32 v29, v16, v16
	v_mul_f32_e32 v29, 0xbf38aa3b, v29
	v_exp_f32_e32 v30, v29
	v_fma_f32 v29, |v17|, s26, 1.0
	v_rcp_f32_e32 v29, v29
	v_mul_f32_e32 v31, v17, v17
	v_mul_f32_e32 v31, 0xbf38aa3b, v31
	v_exp_f32_e32 v31, v31
	v_pk_fma_f32 v[38:39], v[28:29], s[24:25], v[26:27] op_sel_hi:[1,0,0]
	v_cmp_gt_f32_e32 vcc, 0, v16
	v_pk_fma_f32 v[38:39], v[28:29], v[38:39], s[6:7] op_sel_hi:[1,1,0]
	s_nop 0
	v_pk_fma_f32 v[38:39], v[28:29], v[38:39], s[88:89] op_sel_hi:[1,1,0]
	s_nop 0
	v_pk_fma_f32 v[38:39], v[28:29], v[38:39], s[90:91] op_sel_hi:[1,1,0]
	s_nop 0
	v_pk_mul_f32 v[28:29], v[28:29], v[38:39]
	s_nop 0
	v_pk_mul_f32 v[28:29], v[30:31], v[28:29]
	s_nop 0
	v_pk_mul_f32 v[30:31], v[16:17], v[28:29]
	v_pk_fma_f32 v[28:29], v[16:17], v[28:29], v[16:17] neg_lo:[1,0,0] neg_hi:[1,0,0]
	v_fma_f32 v16, |v18|, s26, 1.0
	v_cndmask_b32_e32 v28, v28, v30, vcc
	v_cmp_gt_f32_e32 vcc, 0, v17
	v_mul_f32_e32 v17, v18, v18
	v_mul_f32_e32 v17, 0xbf38aa3b, v17
	v_exp_f32_e32 v30, v17
	v_fma_f32 v17, |v19|, s26, 1.0
	v_rcp_f32_e32 v16, v16
	v_rcp_f32_e32 v17, v17
	v_cndmask_b32_e32 v29, v29, v31, vcc
	v_mul_f32_e32 v31, v19, v19
	v_mul_f32_e32 v31, 0xbf38aa3b, v31
	v_pk_fma_f32 v[38:39], v[16:17], s[24:25], v[26:27] op_sel_hi:[1,0,0]
	v_exp_f32_e32 v31, v31
	v_pk_fma_f32 v[38:39], v[16:17], v[38:39], s[6:7] op_sel_hi:[1,1,0]
	v_cmp_gt_f32_e32 vcc, 0, v18
	v_pk_fma_f32 v[38:39], v[16:17], v[38:39], s[88:89] op_sel_hi:[1,1,0]
	s_nop 0
	v_pk_fma_f32 v[38:39], v[16:17], v[38:39], s[90:91] op_sel_hi:[1,1,0]
	s_nop 0
	v_pk_mul_f32 v[16:17], v[16:17], v[38:39]
	s_nop 0
	v_pk_mul_f32 v[16:17], v[30:31], v[16:17]
	s_nop 0
	v_pk_mul_f32 v[30:31], v[18:19], v[16:17]
	v_pk_fma_f32 v[16:17], v[18:19], v[16:17], v[18:19] neg_lo:[1,0,0] neg_hi:[1,0,0]
	s_nop 0
	v_cndmask_b32_e32 v30, v16, v30, vcc
	v_cmp_gt_f32_e32 vcc, 0, v19
	v_cvt_pk_bf16_f32 v16, v20, v21
	s_nop 1
	v_cndmask_b32_e32 v31, v17, v31, vcc
	v_cvt_pk_bf16_f32 v17, v22, v23
	v_cvt_pk_bf16_f32 v18, v28, v29
	v_cvt_pk_bf16_f32 v19, v30, v31
	global_store_dwordx4 v[36:37], v[16:19], off offset:256
	v_cmp_gt_f32_e32 vcc, 0, v12
	s_nop 0
	v_pk_mul_f32 v[16:17], v[22:23], v[22:23]
	v_pk_mul_f32 v[22:23], v[28:29], v[28:29]
	v_mul_f32_e32 v29, v13, v13
	v_pk_fma_f32 v[22:23], v[24:25], v[24:25], v[22:23]
	v_mul_f32_e32 v25, v12, v12
	v_mul_f32_e32 v25, 0xbf38aa3b, v25
	v_fma_f32 v24, |v12|, s26, 1.0
	v_exp_f32_e32 v28, v25
	v_fma_f32 v25, |v13|, s26, 1.0
	v_rcp_f32_e32 v24, v24
	v_rcp_f32_e32 v25, v25
	v_pk_mul_f32 v[18:19], v[20:21], v[20:21]
	v_pk_mul_f32 v[20:21], v[30:31], v[30:31]
	v_mul_f32_e32 v29, 0xbf38aa3b, v29
	v_pk_fma_f32 v[30:31], v[24:25], s[24:25], v[26:27] op_sel_hi:[1,0,0]
	v_exp_f32_e32 v29, v29
	v_pk_fma_f32 v[30:31], v[24:25], v[30:31], s[6:7] op_sel_hi:[1,1,0]
	v_pk_fma_f32 v[16:17], v[44:45], v[44:45], v[16:17]
	v_pk_fma_f32 v[30:31], v[24:25], v[30:31], s[88:89] op_sel_hi:[1,1,0]
	v_pk_fma_f32 v[18:19], v[42:43], v[42:43], v[18:19]
	v_pk_fma_f32 v[30:31], v[24:25], v[30:31], s[90:91] op_sel_hi:[1,1,0]
	v_pk_fma_f32 v[20:21], v[40:41], v[40:41], v[20:21]
	v_pk_mul_f32 v[24:25], v[24:25], v[30:31]
	s_nop 0
	v_pk_mul_f32 v[24:25], v[28:29], v[24:25]
	s_nop 0
	v_pk_mul_f32 v[28:29], v[12:13], v[24:25]
	v_pk_fma_f32 v[24:25], v[12:13], v[24:25], v[12:13] neg_lo:[1,0,0] neg_hi:[1,0,0]
	s_nop 0
	v_cndmask_b32_e32 v12, v24, v28, vcc
	v_cmp_gt_f32_e32 vcc, 0, v13
	v_fma_f32 v24, |v14|, s26, 1.0
	v_rcp_f32_e32 v24, v24
	v_cndmask_b32_e32 v13, v25, v29, vcc
	v_mul_f32_e32 v25, v14, v14
	v_mul_f32_e32 v25, 0xbf38aa3b, v25
	v_exp_f32_e32 v28, v25
	v_fma_f32 v25, |v15|, s26, 1.0
	v_rcp_f32_e32 v25, v25
	v_mul_f32_e32 v29, v15, v15
	v_mul_f32_e32 v29, 0xbf38aa3b, v29
	v_exp_f32_e32 v29, v29
	v_pk_fma_f32 v[30:31], v[24:25], s[24:25], v[26:27] op_sel_hi:[1,0,0]
	v_cmp_gt_f32_e32 vcc, 0, v14
	v_pk_fma_f32 v[30:31], v[24:25], v[30:31], s[6:7] op_sel_hi:[1,1,0]
	s_nop 0
	v_pk_fma_f32 v[30:31], v[24:25], v[30:31], s[88:89] op_sel_hi:[1,1,0]
	s_nop 0
	v_pk_fma_f32 v[30:31], v[24:25], v[30:31], s[90:91] op_sel_hi:[1,1,0]
	s_nop 0
	v_pk_mul_f32 v[24:25], v[24:25], v[30:31]
	s_nop 0
	v_pk_mul_f32 v[24:25], v[28:29], v[24:25]
	s_nop 0
	v_pk_mul_f32 v[28:29], v[14:15], v[24:25]
	v_pk_fma_f32 v[24:25], v[14:15], v[24:25], v[14:15] neg_lo:[1,0,0] neg_hi:[1,0,0]
	s_nop 0
	v_cndmask_b32_e32 v14, v24, v28, vcc
	v_cmp_gt_f32_e32 vcc, 0, v15
	v_fma_f32 v24, |v8|, s26, 1.0
	v_rcp_f32_e32 v24, v24
	v_cndmask_b32_e32 v15, v25, v29, vcc
	v_mul_f32_e32 v25, v8, v8
	v_mul_f32_e32 v25, 0xbf38aa3b, v25
	v_exp_f32_e32 v28, v25
	v_fma_f32 v25, |v9|, s26, 1.0
	v_rcp_f32_e32 v25, v25
	v_mul_f32_e32 v29, v9, v9
	v_mul_f32_e32 v29, 0xbf38aa3b, v29
	v_exp_f32_e32 v29, v29
	v_pk_fma_f32 v[30:31], v[24:25], s[24:25], v[26:27] op_sel_hi:[1,0,0]
	v_cmp_gt_f32_e32 vcc, 0, v8
	v_pk_fma_f32 v[30:31], v[24:25], v[30:31], s[6:7] op_sel_hi:[1,1,0]
	s_nop 0
	v_pk_fma_f32 v[30:31], v[24:25], v[30:31], s[88:89] op_sel_hi:[1,1,0]
	s_nop 0
	v_pk_fma_f32 v[30:31], v[24:25], v[30:31], s[90:91] op_sel_hi:[1,1,0]
	s_nop 0
	v_pk_mul_f32 v[24:25], v[24:25], v[30:31]
	s_nop 0
	v_pk_mul_f32 v[24:25], v[28:29], v[24:25]
	s_nop 0
	v_pk_mul_f32 v[28:29], v[8:9], v[24:25]
	v_pk_fma_f32 v[24:25], v[8:9], v[24:25], v[8:9] neg_lo:[1,0,0] neg_hi:[1,0,0]
	v_fma_f32 v8, |v10|, s26, 1.0
	v_cndmask_b32_e32 v24, v24, v28, vcc
	v_cmp_gt_f32_e32 vcc, 0, v9
	v_mul_f32_e32 v9, v10, v10
	v_mul_f32_e32 v9, 0xbf38aa3b, v9
	v_exp_f32_e32 v28, v9
	v_fma_f32 v9, |v11|, s26, 1.0
	v_rcp_f32_e32 v8, v8
	v_rcp_f32_e32 v9, v9
	v_cndmask_b32_e32 v25, v25, v29, vcc
	v_mul_f32_e32 v29, v11, v11
	v_mul_f32_e32 v29, 0xbf38aa3b, v29
	v_pk_fma_f32 v[30:31], v[8:9], s[24:25], v[26:27] op_sel_hi:[1,0,0]
	v_exp_f32_e32 v29, v29
	v_pk_fma_f32 v[30:31], v[8:9], v[30:31], s[6:7] op_sel_hi:[1,1,0]
	v_cmp_gt_f32_e32 vcc, 0, v10
	v_pk_fma_f32 v[30:31], v[8:9], v[30:31], s[88:89] op_sel_hi:[1,1,0]
	s_nop 0
	v_pk_fma_f32 v[30:31], v[8:9], v[30:31], s[90:91] op_sel_hi:[1,1,0]
	s_nop 0
	v_pk_mul_f32 v[8:9], v[8:9], v[30:31]
	s_nop 0
	v_pk_mul_f32 v[8:9], v[28:29], v[8:9]
	s_nop 0
	v_pk_mul_f32 v[28:29], v[10:11], v[8:9]
	v_pk_fma_f32 v[8:9], v[10:11], v[8:9], v[10:11] neg_lo:[1,0,0] neg_hi:[1,0,0]
	s_nop 0
	v_cndmask_b32_e32 v28, v8, v28, vcc
	v_cmp_gt_f32_e32 vcc, 0, v11
	v_cvt_pk_bf16_f32 v8, v12, v13
	s_nop 1
	v_cndmask_b32_e32 v29, v9, v29, vcc
	v_cvt_pk_bf16_f32 v9, v14, v15
	v_cvt_pk_bf16_f32 v10, v24, v25
	v_cvt_pk_bf16_f32 v11, v28, v29
	global_store_dwordx4 v[34:35], v[8:11], off offset:256
	v_cmp_gt_f32_e32 vcc, 0, v4
	s_nop 0
	v_pk_fma_f32 v[8:9], v[14:15], v[14:15], v[16:17]
	v_mul_f32_e32 v17, v4, v4
	v_mul_f32_e32 v17, 0xbf38aa3b, v17
	v_pk_fma_f32 v[10:11], v[12:13], v[12:13], v[18:19]
	v_fma_f32 v16, |v4|, s26, 1.0
	v_exp_f32_e32 v18, v17
	v_fma_f32 v17, |v5|, s26, 1.0
	v_rcp_f32_e32 v16, v16
	v_rcp_f32_e32 v17, v17
	v_mul_f32_e32 v19, v5, v5
	v_pk_fma_f32 v[12:13], v[28:29], v[28:29], v[20:21]
	v_mul_f32_e32 v19, 0xbf38aa3b, v19
	v_pk_fma_f32 v[20:21], v[16:17], s[24:25], v[26:27] op_sel_hi:[1,0,0]
	v_exp_f32_e32 v19, v19
	v_pk_fma_f32 v[20:21], v[16:17], v[20:21], s[6:7] op_sel_hi:[1,1,0]
	v_pk_fma_f32 v[14:15], v[24:25], v[24:25], v[22:23]
	v_pk_fma_f32 v[20:21], v[16:17], v[20:21], s[88:89] op_sel_hi:[1,1,0]
	s_nop 0
	v_pk_fma_f32 v[20:21], v[16:17], v[20:21], s[90:91] op_sel_hi:[1,1,0]
	s_nop 0
	v_pk_mul_f32 v[16:17], v[16:17], v[20:21]
	s_nop 0
	v_pk_mul_f32 v[16:17], v[18:19], v[16:17]
	s_nop 0
	v_pk_mul_f32 v[18:19], v[4:5], v[16:17]
	v_pk_fma_f32 v[16:17], v[4:5], v[16:17], v[4:5] neg_lo:[1,0,0] neg_hi:[1,0,0]
	s_nop 0
	v_cndmask_b32_e32 v4, v16, v18, vcc
	v_cmp_gt_f32_e32 vcc, 0, v5
	v_fma_f32 v16, |v6|, s26, 1.0
	v_rcp_f32_e32 v16, v16
	v_cndmask_b32_e32 v5, v17, v19, vcc
	v_mul_f32_e32 v17, v6, v6
	v_mul_f32_e32 v17, 0xbf38aa3b, v17
	v_exp_f32_e32 v18, v17
	v_fma_f32 v17, |v7|, s26, 1.0
	v_rcp_f32_e32 v17, v17
	v_mul_f32_e32 v19, v7, v7
	v_mul_f32_e32 v19, 0xbf38aa3b, v19
	v_exp_f32_e32 v19, v19
	v_pk_fma_f32 v[20:21], v[16:17], s[24:25], v[26:27] op_sel_hi:[1,0,0]
	v_cmp_gt_f32_e32 vcc, 0, v6
	v_pk_fma_f32 v[20:21], v[16:17], v[20:21], s[6:7] op_sel_hi:[1,1,0]
	s_nop 0
	v_pk_fma_f32 v[20:21], v[16:17], v[20:21], s[88:89] op_sel_hi:[1,1,0]
	s_nop 0
	v_pk_fma_f32 v[20:21], v[16:17], v[20:21], s[90:91] op_sel_hi:[1,1,0]
	s_nop 0
	v_pk_mul_f32 v[16:17], v[16:17], v[20:21]
	s_nop 0
	v_pk_mul_f32 v[16:17], v[18:19], v[16:17]
	s_nop 0
	v_pk_mul_f32 v[18:19], v[6:7], v[16:17]
	v_pk_fma_f32 v[16:17], v[6:7], v[16:17], v[6:7] neg_lo:[1,0,0] neg_hi:[1,0,0]
	s_nop 0
	v_cndmask_b32_e32 v6, v16, v18, vcc
	v_cmp_gt_f32_e32 vcc, 0, v7
	v_fma_f32 v16, |v0|, s26, 1.0
	v_rcp_f32_e32 v16, v16
	v_cndmask_b32_e32 v7, v17, v19, vcc
	v_mul_f32_e32 v17, v0, v0
	v_mul_f32_e32 v17, 0xbf38aa3b, v17
	v_exp_f32_e32 v18, v17
	v_fma_f32 v17, |v1|, s26, 1.0
	v_rcp_f32_e32 v17, v17
	v_mul_f32_e32 v19, v1, v1
	v_mul_f32_e32 v19, 0xbf38aa3b, v19
	v_exp_f32_e32 v19, v19
	v_pk_fma_f32 v[20:21], v[16:17], s[24:25], v[26:27] op_sel_hi:[1,0,0]
	v_cmp_gt_f32_e32 vcc, 0, v0
	v_pk_fma_f32 v[20:21], v[16:17], v[20:21], s[6:7] op_sel_hi:[1,1,0]
	s_nop 0
	v_pk_fma_f32 v[20:21], v[16:17], v[20:21], s[88:89] op_sel_hi:[1,1,0]
	s_nop 0
	v_pk_fma_f32 v[20:21], v[16:17], v[20:21], s[90:91] op_sel_hi:[1,1,0]
	s_nop 0
	v_pk_mul_f32 v[16:17], v[16:17], v[20:21]
	s_nop 0
	v_pk_mul_f32 v[16:17], v[18:19], v[16:17]
	s_nop 0
	v_pk_mul_f32 v[18:19], v[0:1], v[16:17]
	v_pk_fma_f32 v[16:17], v[0:1], v[16:17], v[0:1] neg_lo:[1,0,0] neg_hi:[1,0,0]
	v_fma_f32 v0, |v2|, s26, 1.0
	v_cndmask_b32_e32 v16, v16, v18, vcc
	v_cmp_gt_f32_e32 vcc, 0, v1
	v_mul_f32_e32 v1, v2, v2
	v_mul_f32_e32 v1, 0xbf38aa3b, v1
	v_exp_f32_e32 v18, v1
	v_fma_f32 v1, |v3|, s26, 1.0
	v_rcp_f32_e32 v0, v0
	v_rcp_f32_e32 v1, v1
	v_cndmask_b32_e32 v17, v17, v19, vcc
	v_mul_f32_e32 v19, v3, v3
	v_mul_f32_e32 v19, 0xbf38aa3b, v19
	v_pk_fma_f32 v[20:21], v[0:1], s[24:25], v[26:27] op_sel_hi:[1,0,0]
	v_exp_f32_e32 v19, v19
	v_pk_fma_f32 v[20:21], v[0:1], v[20:21], s[6:7] op_sel_hi:[1,1,0]
	v_cmp_gt_f32_e32 vcc, 0, v2
	v_pk_fma_f32 v[20:21], v[0:1], v[20:21], s[88:89] op_sel_hi:[1,1,0]
	s_nop 0
	v_pk_fma_f32 v[20:21], v[0:1], v[20:21], s[90:91] op_sel_hi:[1,1,0]
	s_nop 0
	v_pk_mul_f32 v[0:1], v[0:1], v[20:21]
	v_pk_fma_f32 v[20:21], v[6:7], v[6:7], v[8:9]
	v_pk_mul_f32 v[0:1], v[18:19], v[0:1]
	v_mov_b32_e32 v8, v145
	v_pk_mul_f32 v[18:19], v[2:3], v[0:1]
	v_pk_fma_f32 v[0:1], v[2:3], v[0:1], v[2:3] neg_lo:[1,0,0] neg_hi:[1,0,0]
	v_mov_b32_e32 v9, v145
	v_cndmask_b32_e32 v18, v0, v18, vcc
	v_cmp_gt_f32_e32 vcc, 0, v3
	v_cvt_pk_bf16_f32 v0, v4, v5
	s_nop 1
	v_cndmask_b32_e32 v19, v1, v19, vcc
	v_cvt_pk_bf16_f32 v1, v6, v7
	v_cvt_pk_bf16_f32 v2, v16, v17
	v_cvt_pk_bf16_f32 v3, v18, v19
	global_store_dwordx4 v[32:33], v[0:3], off offset:256
	v_pk_fma_f32 v[18:19], v[18:19], v[18:19], v[12:13]
	v_pk_fma_f32 v[6:7], v[16:17], v[16:17], v[14:15]
	v_pk_fma_f32 v[2:3], v[4:5], v[4:5], v[10:11]
	v_add_f32_dpp v10, v18, v18 row_ror:8 row_mask:0xf bank_mask:0xf bound_ctrl:1
	v_add_f32_dpp v12, v21, v21 row_ror:8 row_mask:0xf bank_mask:0xf bound_ctrl:1
	v_add_f32_dpp v0, v2, v2 row_ror:8 row_mask:0xf bank_mask:0xf bound_ctrl:1
	v_add_f32_dpp v2, v6, v6 row_ror:8 row_mask:0xf bank_mask:0xf bound_ctrl:1
	v_add_f32_dpp v3, v3, v3 row_ror:8 row_mask:0xf bank_mask:0xf bound_ctrl:1
	v_add_f32_dpp v6, v7, v7 row_ror:8 row_mask:0xf bank_mask:0xf bound_ctrl:1
	v_add_f32_dpp v7, v20, v20 row_ror:8 row_mask:0xf bank_mask:0xf bound_ctrl:1
	v_add_f32_dpp v14, v19, v19 row_ror:8 row_mask:0xf bank_mask:0xf bound_ctrl:1
	v_add_f32_dpp v0, v0, v0 row_ror:4 row_mask:0xf bank_mask:0xf bound_ctrl:1
	v_add_f32_dpp v2, v2, v2 row_ror:4 row_mask:0xf bank_mask:0xf bound_ctrl:1
	v_add_f32_dpp v3, v3, v3 row_ror:4 row_mask:0xf bank_mask:0xf bound_ctrl:1
	v_add_f32_dpp v6, v6, v6 row_ror:4 row_mask:0xf bank_mask:0xf bound_ctrl:1
	v_add_f32_dpp v7, v7, v7 row_ror:4 row_mask:0xf bank_mask:0xf bound_ctrl:1
	v_add_f32_dpp v10, v10, v10 row_ror:4 row_mask:0xf bank_mask:0xf bound_ctrl:1
	v_add_f32_dpp v12, v12, v12 row_ror:4 row_mask:0xf bank_mask:0xf bound_ctrl:1
	v_add_f32_dpp v14, v14, v14 row_ror:4 row_mask:0xf bank_mask:0xf bound_ctrl:1
	v_add_f32_dpp v0, v0, v0 row_ror:2 row_mask:0xf bank_mask:0xf bound_ctrl:1
	v_mov_b32_e32 v1, v145
	v_add_f32_dpp v2, v2, v2 row_ror:2 row_mask:0xf bank_mask:0xf bound_ctrl:1
	v_mov_b32_e32 v4, v145
	v_add_f32_dpp v3, v3, v3 row_ror:2 row_mask:0xf bank_mask:0xf bound_ctrl:1
	v_mov_b32_e32 v5, v145
	v_add_f32_dpp v6, v6, v6 row_ror:2 row_mask:0xf bank_mask:0xf bound_ctrl:1
	v_add_f32_dpp v7, v7, v7 row_ror:2 row_mask:0xf bank_mask:0xf bound_ctrl:1
	v_add_f32_dpp v10, v10, v10 row_ror:2 row_mask:0xf bank_mask:0xf bound_ctrl:1
	v_mov_b32_e32 v11, v145
	v_add_f32_dpp v12, v12, v12 row_ror:2 row_mask:0xf bank_mask:0xf bound_ctrl:1
	v_mov_b32_e32 v13, v145
	v_add_f32_dpp v14, v14, v14 row_ror:2 row_mask:0xf bank_mask:0xf bound_ctrl:1
	v_mov_b32_e32 v15, v145
	v_mov_b32_dpp v1, v0 row_ror:1 row_mask:0xf bank_mask:0xf
	v_mov_b32_dpp v4, v2 row_ror:1 row_mask:0xf bank_mask:0xf
	v_mov_b32_dpp v5, v3 row_ror:1 row_mask:0xf bank_mask:0xf
	v_mov_b32_dpp v8, v6 row_ror:1 row_mask:0xf bank_mask:0xf
	v_mov_b32_dpp v9, v7 row_ror:1 row_mask:0xf bank_mask:0xf
	v_mov_b32_dpp v11, v10 row_ror:1 row_mask:0xf bank_mask:0xf
	v_mov_b32_dpp v13, v12 row_ror:1 row_mask:0xf bank_mask:0xf
	v_mov_b32_dpp v15, v14 row_ror:1 row_mask:0xf bank_mask:0xf
	s_and_saveexec_b64 s[0:1], s[38:39]
	s_cbranch_execz .LBB0_342
	v_add_f32_e32 v4, v2, v4
	v_add_f32_e32 v2, v0, v1
	v_fma_f32 v2, v2, s91, 0.5
	v_trunc_f32_e32 v2, v2
	v_add_f32_e32 v5, v3, v5
	v_mul_f32_e32 v3, 0x2f800000, v2
	v_floor_f32_e32 v3, v3
	v_fmac_f32_e32 v2, 0xcf800000, v3
	v_cvt_u32_f32_e32 v2, v2
	v_cvt_u32_f32_e32 v3, v3
	s_lshl_b64 s[50:51], s[98:99], 3
	v_lshl_add_u64 v[0:1], v[94:95], 0, s[50:51]
	v_ashrrev_i32_e32 v91, 31, v90
	global_atomic_add_x2 v[0:1], v[2:3], off offset:8
	v_fma_f32 v2, v4, s91, 0.5
	v_trunc_f32_e32 v2, v2
	v_mul_f32_e32 v3, 0x2f800000, v2
	v_floor_f32_e32 v3, v3
	v_fmac_f32_e32 v2, 0xcf800000, v3
	v_cvt_u32_f32_e32 v2, v2
	v_cvt_u32_f32_e32 v3, v3
	v_lshlrev_b64 v[0:1], 5, v[90:91]
	v_lshl_add_u64 v[0:1], s[96:97], 0, v[0:1]
	v_lshl_add_u64 v[0:1], v[0:1], 0, s[50:51]
	global_atomic_add_x2 v[0:1], v[2:3], off offset:8
	v_fma_f32 v2, v5, s91, 0.5
	v_trunc_f32_e32 v2, v2
	v_mul_f32_e32 v3, 0x2f800000, v2
	v_floor_f32_e32 v3, v3
	v_fmac_f32_e32 v2, 0xcf800000, v3
	v_ashrrev_i32_e32 v87, 31, v86
	v_cvt_u32_f32_e32 v2, v2
	v_cvt_u32_f32_e32 v3, v3
	v_lshlrev_b64 v[0:1], 5, v[86:87]
	v_lshl_add_u64 v[0:1], s[96:97], 0, v[0:1]
	v_add_f32_e32 v6, v6, v8
	v_lshl_add_u64 v[0:1], v[0:1], 0, s[50:51]
	global_atomic_add_x2 v[0:1], v[2:3], off offset:8
	v_fma_f32 v2, v6, s91, 0.5
	v_trunc_f32_e32 v2, v2
	v_mul_f32_e32 v3, 0x2f800000, v2
	v_floor_f32_e32 v3, v3
	v_fmac_f32_e32 v2, 0xcf800000, v3
	v_ashrrev_i32_e32 v83, 31, v82
	v_cvt_u32_f32_e32 v2, v2
	v_cvt_u32_f32_e32 v3, v3
	v_lshlrev_b64 v[0:1], 5, v[82:83]
	v_lshl_add_u64 v[0:1], s[96:97], 0, v[0:1]
	v_add_f32_e32 v7, v7, v9
	v_lshl_add_u64 v[0:1], v[0:1], 0, s[50:51]
	global_atomic_add_x2 v[0:1], v[2:3], off offset:8
	v_fma_f32 v2, v7, s91, 0.5
	v_trunc_f32_e32 v2, v2
	v_mul_f32_e32 v3, 0x2f800000, v2
	v_floor_f32_e32 v3, v3
	v_fmac_f32_e32 v2, 0xcf800000, v3
	v_ashrrev_i32_e32 v79, 31, v78
	v_cvt_u32_f32_e32 v2, v2
	v_cvt_u32_f32_e32 v3, v3
	v_lshlrev_b64 v[0:1], 5, v[78:79]
	v_lshl_add_u64 v[0:1], s[96:97], 0, v[0:1]
	v_add_f32_e32 v8, v10, v11
	v_lshl_add_u64 v[0:1], v[0:1], 0, s[50:51]
	global_atomic_add_x2 v[0:1], v[2:3], off offset:8
	v_fma_f32 v2, v8, s91, 0.5
	v_trunc_f32_e32 v2, v2
	v_mul_f32_e32 v3, 0x2f800000, v2
	v_floor_f32_e32 v3, v3
	v_fmac_f32_e32 v2, 0xcf800000, v3
	v_ashrrev_i32_e32 v75, 31, v74
	v_cvt_u32_f32_e32 v2, v2
	v_cvt_u32_f32_e32 v3, v3
	v_lshlrev_b64 v[0:1], 5, v[74:75]
	v_lshl_add_u64 v[0:1], s[96:97], 0, v[0:1]
	v_add_f32_e32 v10, v12, v13
	v_lshl_add_u64 v[0:1], v[0:1], 0, s[50:51]
	global_atomic_add_x2 v[0:1], v[2:3], off offset:8
	v_fma_f32 v2, v10, s91, 0.5
	v_trunc_f32_e32 v2, v2
	v_mul_f32_e32 v3, 0x2f800000, v2
	v_floor_f32_e32 v3, v3
	v_fmac_f32_e32 v2, 0xcf800000, v3
	v_ashrrev_i32_e32 v71, 31, v70
	v_cvt_u32_f32_e32 v2, v2
	v_cvt_u32_f32_e32 v3, v3
	v_lshlrev_b64 v[0:1], 5, v[70:71]
	v_lshl_add_u64 v[0:1], s[96:97], 0, v[0:1]
	v_add_f32_e32 v14, v14, v15
	v_lshl_add_u64 v[0:1], v[0:1], 0, s[50:51]
	global_atomic_add_x2 v[0:1], v[2:3], off offset:8
	v_fma_f32 v2, v14, s91, 0.5
	v_trunc_f32_e32 v2, v2
	v_mul_f32_e32 v3, 0x2f800000, v2
	v_floor_f32_e32 v3, v3
	v_fmac_f32_e32 v2, 0xcf800000, v3
	v_ashrrev_i32_e32 v67, 31, v66
	v_cvt_u32_f32_e32 v2, v2
	v_cvt_u32_f32_e32 v3, v3
	v_lshlrev_b64 v[0:1], 5, v[66:67]
	v_lshl_add_u64 v[0:1], s[96:97], 0, v[0:1]
	v_lshl_add_u64 v[0:1], v[0:1], 0, s[50:51]
	global_atomic_add_x2 v[0:1], v[2:3], off offset:8
	s_branch .LBB0_342

.LBB0_371:
	global_load_dwordx4 v[10:13], v[6:7], off offset:-3072
	s_waitcnt vmcnt(0)
	v_cvt_pk_bf16_f32 v14, v10, v11
	v_cvt_pk_bf16_f32 v15, v12, v13
	global_store_dwordx2 v[4:5], v[14:15], off offset:-1024
	global_load_dwordx4 v[14:17], v[6:7], off offset:-2048
	s_waitcnt vmcnt(0)
	v_cvt_pk_bf16_f32 v18, v14, v15
	v_cvt_pk_bf16_f32 v19, v16, v17
	global_store_dwordx2 v[4:5], v[18:19], off offset:-512
	global_load_dwordx4 v[18:21], v[6:7], off offset:-1024
	s_waitcnt vmcnt(0)
	v_cvt_pk_bf16_f32 v22, v18, v19
	v_cvt_pk_bf16_f32 v23, v20, v21
	global_store_dwordx2 v[4:5], v[22:23], off
	global_load_dwordx4 v[22:25], v[6:7], off
	v_and_b32_e32 v1, 64, v214
	s_waitcnt lgkmcnt(0)
	v_xor_b32_e32 v9, 32, v214
	v_add_u32_e32 v1, 64, v1
	v_cmp_lt_i32_e32 vcc, v9, v1
	v_mul_f32_e32 v11, v11, v11
	v_fmac_f32_e32 v11, v10, v10
	v_fmac_f32_e32 v11, v12, v12
	v_fmac_f32_e32 v11, v13, v13
	v_mul_f32_e32 v10, v15, v15
	v_fmac_f32_e32 v10, v14, v14
	v_fmac_f32_e32 v10, v16, v16
	v_fmac_f32_e32 v10, v17, v17
	v_add_f32_e32 v10, v11, v10
	v_mul_f32_e32 v11, v19, v19
	v_fmac_f32_e32 v11, v18, v18
	v_fmac_f32_e32 v11, v20, v20
	v_fmac_f32_e32 v11, v21, v21
	v_add_f32_e32 v10, v10, v11
	s_waitcnt vmcnt(0)
	v_mul_f32_e32 v11, v23, v23
	v_fmac_f32_e32 v11, v22, v22
	v_fmac_f32_e32 v11, v24, v24
	v_cndmask_b32_e32 v9, v214, v9, vcc
	v_fmac_f32_e32 v11, v25, v25
	v_lshlrev_b32_e32 v9, 2, v9
	v_add_f32_e32 v10, v10, v11
	ds_bpermute_b32 v9, v9, v10
	v_xor_b32_e32 v11, 16, v214
	v_cmp_lt_i32_e32 vcc, v11, v1
	s_waitcnt lgkmcnt(0)
	v_add_f32_e32 v9, v10, v9
	v_cndmask_b32_e32 v11, v214, v11, vcc
	v_lshlrev_b32_e32 v11, 2, v11
	ds_bpermute_b32 v10, v11, v9
	v_xor_b32_e32 v11, 8, v214
	v_cmp_lt_i32_e32 vcc, v11, v1
	s_waitcnt lgkmcnt(0)
	v_add_f32_e32 v9, v9, v10
	v_cndmask_b32_e32 v11, v214, v11, vcc
	v_lshlrev_b32_e32 v11, 2, v11
	ds_bpermute_b32 v10, v11, v9
	v_xor_b32_e32 v11, 4, v214
	v_cmp_lt_i32_e32 vcc, v11, v1
	s_waitcnt lgkmcnt(0)
	v_add_f32_e32 v9, v9, v10
	v_cndmask_b32_e32 v11, v214, v11, vcc
	v_lshlrev_b32_e32 v11, 2, v11
	ds_bpermute_b32 v10, v11, v9
	v_xor_b32_e32 v11, 2, v214
	v_cmp_lt_i32_e32 vcc, v11, v1
	s_waitcnt lgkmcnt(0)
	v_add_f32_e32 v9, v9, v10
	v_cndmask_b32_e32 v11, v214, v11, vcc
	v_lshlrev_b32_e32 v11, 2, v11
	ds_bpermute_b32 v10, v11, v9
	v_xor_b32_e32 v11, 1, v214
	v_cmp_lt_i32_e32 vcc, v11, v1
	s_waitcnt lgkmcnt(0)
	v_add_f32_e32 v1, v9, v10
	v_cndmask_b32_e32 v11, v214, v11, vcc
	v_lshlrev_b32_e32 v9, 2, v11
	ds_bpermute_b32 v9, v9, v1
	v_cvt_pk_bf16_f32 v10, v22, v23
	v_cvt_pk_bf16_f32 v11, v24, v25
	global_store_dwordx2 v[4:5], v[10:11], off offset:512
	s_mov_b64 s[40:41], exec
	v_readlane_b32 s10, v254, 21
	v_readlane_b32 s11, v254, 22
	s_and_b64 s[10:11], s[40:41], s[10:11]
	s_mov_b64 exec, s[10:11]
	s_cbranch_execz .LBB0_370
	s_waitcnt lgkmcnt(0)
	v_add_f32_e32 v1, v1, v9
	v_fma_f32 v1, v1, s91, 0.5
	v_trunc_f32_e32 v1, v1
	v_mul_f32_e32 v9, 0x2f800000, v1
	v_floor_f32_e32 v9, v9
	v_fmac_f32_e32 v1, 0xcf800000, v9
	v_cvt_u32_f32_e32 v10, v1
	v_cvt_u32_f32_e32 v11, v9
	global_store_dwordx2 v[2:3], v[10:11], off
	s_branch .LBB0_370

.LBB0_379:
	s_or_b64 exec, exec, s[40:41]
	s_waitcnt vmcnt(0)
	v_cvt_pk_bf16_f32 v94, v0, v8
	v_cvt_pk_bf16_f32 v95, v16, v28
	v_cvt_pk_bf16_f32 v96, v36, v44
	v_cvt_pk_bf16_f32 v97, v52, v56
	ds_write_b128 v90, v[94:97]
	v_cvt_pk_bf16_f32 v94, v4, v24
	v_cvt_pk_bf16_f32 v95, v12, v32
	v_cvt_pk_bf16_f32 v96, v20, v40
	v_cvt_pk_bf16_f32 v97, v48, v60
	ds_write_b128 v90, v[94:97] offset:16
	v_cvt_pk_bf16_f32 v94, v1, v9
	v_cvt_pk_bf16_f32 v95, v17, v29
	v_cvt_pk_bf16_f32 v96, v37, v45
	v_cvt_pk_bf16_f32 v97, v53, v57
	ds_write_b128 v90, v[94:97] offset:144
	v_cvt_pk_bf16_f32 v94, v5, v25
	v_cvt_pk_bf16_f32 v95, v13, v33
	v_cvt_pk_bf16_f32 v96, v21, v41
	v_cvt_pk_bf16_f32 v97, v49, v61
	ds_write_b128 v90, v[94:97] offset:160
	v_cvt_pk_bf16_f32 v94, v2, v10
	v_cvt_pk_bf16_f32 v95, v18, v30
	v_cvt_pk_bf16_f32 v96, v38, v46
	v_cvt_pk_bf16_f32 v97, v54, v58
	ds_write_b128 v90, v[94:97] offset:288
	v_cvt_pk_bf16_f32 v94, v6, v26
	v_cvt_pk_bf16_f32 v95, v14, v34
	v_cvt_pk_bf16_f32 v96, v22, v42
	v_cvt_pk_bf16_f32 v97, v50, v62
	ds_write_b128 v90, v[94:97] offset:304
	v_cvt_pk_bf16_f32 v0, v3, v11
	v_cvt_pk_bf16_f32 v1, v19, v31
	v_cvt_pk_bf16_f32 v2, v39, v47
	v_cvt_pk_bf16_f32 v3, v55, v59
	ds_write_b128 v90, v[0:3] offset:432
	v_cvt_pk_bf16_f32 v0, v7, v27
	v_cvt_pk_bf16_f32 v1, v15, v35
	v_cvt_pk_bf16_f32 v2, v23, v43
	v_cvt_pk_bf16_f32 v3, v51, v63
	ds_write_b128 v90, v[0:3] offset:448
	v_lshl_add_u64 v[0:1], v[74:75], 1, v[70:71]
	v_lshlrev_b32_e32 v12, 6, v92
	v_lshl_add_u64 v[8:9], v[0:1], 0, v[144:145]
	ds_read_b128 v[0:3], v91
	v_or_b32_e32 v4, v12, v82
	v_ashrrev_i32_e32 v5, 31, v12
	v_mul_lo_u32 v13, v72, v5
	v_mul_lo_u32 v6, v73, v4
	v_mad_u64_u32 v[4:5], s[10:11], v72, v4, 0
	v_add3_u32 v5, v5, v13, v6
	v_lshl_add_u64 v[10:11], v[4:5], 1, v[8:9]
	ds_read_b128 v[4:7], v91 offset:1152
	s_waitcnt lgkmcnt(1)
	global_store_dwordx4 v[10:11], v[0:3], off
	v_add_u32_e32 v67, s25, v67
	s_nop 0
	v_or_b32_e32 v0, v12, v83
	v_mul_lo_u32 v2, v73, v0
	v_mad_u64_u32 v[0:1], s[10:11], v72, v0, 0
	v_add3_u32 v1, v1, v13, v2
	v_lshl_add_u64 v[0:1], v[0:1], 1, v[8:9]
	s_waitcnt lgkmcnt(0)
	global_store_dwordx4 v[0:1], v[4:7], off
	ds_read_b128 v[0:3], v91 offset:2304
	s_nop 0
	v_or_b32_e32 v4, v12, v84
	v_mul_lo_u32 v6, v73, v4
	v_mad_u64_u32 v[4:5], s[10:11], v72, v4, 0
	v_add3_u32 v5, v5, v13, v6
	v_lshl_add_u64 v[10:11], v[4:5], 1, v[8:9]
	ds_read_b128 v[4:7], v91 offset:3456
	s_waitcnt lgkmcnt(1)
	global_store_dwordx4 v[10:11], v[0:3], off
	s_nop 1
	v_or_b32_e32 v0, v12, v85
	v_mul_lo_u32 v2, v73, v0
	v_mad_u64_u32 v[0:1], s[10:11], v72, v0, 0
	v_add3_u32 v1, v1, v13, v2
	v_lshl_add_u64 v[0:1], v[0:1], 1, v[8:9]
	s_waitcnt lgkmcnt(0)
	global_store_dwordx4 v[0:1], v[4:7], off
	ds_read_b128 v[0:3], v91 offset:4608
	s_nop 0
	v_or_b32_e32 v4, v12, v86
	v_mul_lo_u32 v6, v73, v4
	v_mad_u64_u32 v[4:5], s[10:11], v72, v4, 0
	v_add3_u32 v5, v5, v13, v6
	v_lshl_add_u64 v[10:11], v[4:5], 1, v[8:9]
	ds_read_b128 v[4:7], v91 offset:5760
	s_waitcnt lgkmcnt(1)
	global_store_dwordx4 v[10:11], v[0:3], off
	s_nop 1
	v_or_b32_e32 v0, v12, v87
	v_mul_lo_u32 v2, v73, v0
	v_mad_u64_u32 v[0:1], s[10:11], v72, v0, 0
	v_add3_u32 v1, v1, v13, v2
	v_lshl_add_u64 v[0:1], v[0:1], 1, v[8:9]
	s_waitcnt lgkmcnt(0)
	global_store_dwordx4 v[0:1], v[4:7], off
	ds_read_b128 v[0:3], v91 offset:6912
	s_nop 0
	v_or_b32_e32 v4, v12, v88
	v_mul_lo_u32 v6, v73, v4
	v_mad_u64_u32 v[4:5], s[10:11], v72, v4, 0
	v_add3_u32 v5, v5, v13, v6
	v_lshl_add_u64 v[10:11], v[4:5], 1, v[8:9]
	ds_read_b128 v[4:7], v91 offset:8064
	s_waitcnt lgkmcnt(1)
	global_store_dwordx4 v[10:11], v[0:3], off
	s_nop 1
	v_or_b32_e32 v0, v12, v89
	v_mul_lo_u32 v2, v73, v0
	v_mad_u64_u32 v[0:1], s[10:11], v72, v0, 0
	s_movk_i32 s10, 0x2eff
	v_add3_u32 v1, v1, v13, v2
	v_cmp_lt_i32_e32 vcc, s10, v67
	v_lshl_add_u64 v[0:1], v[0:1], 1, v[8:9]
	s_or_b64 s[38:39], vcc, s[38:39]
	s_waitcnt lgkmcnt(0)
	global_store_dwordx4 v[0:1], v[4:7], off
	s_andn2_b64 exec, exec, s[38:39]
	s_cbranch_execz .LBB0_398
